# combined file with the redundant s_setprio 0 / s_setprio 1 pair between the two MFMA clusters of each GEMM segment removed
# baseline (speedup 1.0000x reference)
; #define PG8_STAGE(bufoff, gbase, voff) do { _Pragma("unroll") for (int _i = 0; _i < 2; ++_i) \
;         __builtin_amdgcn_global_load_lds((const unsigned*)((const char*)(gbase) + (voff)[_i]), (PG8_LAS unsigned*)(lds + (bufoff) + ldsw + _i * 8192), 16, 0, 0); } while (0)
; #define PG8_LDA(dst, b, h) do { _Pragma("unroll") for (int m = 0; m < 4; ++m) _Pragma("unroll") for (int k = 0; k < 2; ++k) dst[m][k] = *(const PG8_LAS bf16x8*)(lds + PG8_SA(b, h) + aoff + m * 2048 + k * 1024); } while (0)
; #define PG8_LDB(dst, b, h) do { _Pragma("unroll") for (int n = 0; n < 2; ++n) _Pragma("unroll") for (int k = 0; k < 2; ++k) dst[n][k] = *(const PG8_LAS bf16x8*)(lds + PG8_SB(b, h) + boff + n * 2048 + k * 1024); } while (0)
; #define PG8_MMA(ai, bj, At, Bt) do { __builtin_amdgcn_s_setprio(1); _Pragma("unroll") for (int m = 0; m < 4; ++m) _Pragma("unroll") for (int n = 0; n < 2; ++n) _Pragma("unroll") for (int k = 0; k < 2; ++k) \
;         acc[ai][bj][m][n] = __builtin_amdgcn_mfma_f32_16x16x32_bf16(Bt[n][k], At[m][k], acc[ai][bj][m][n], 0, 0, 0); __builtin_amdgcn_s_setprio(0); } while (0)
; #define PG8_WAIT_V(n) asm volatile("s_waitcnt vmcnt(" #n ")" ::: "memory")
; #define PG8_WAIT_L(n) asm volatile("s_waitcnt lgkmcnt(" #n ")" ::: "memory")
; #define PG8_BAR __builtin_amdgcn_s_barrier()
; #define PG8_SCHED __builtin_amdgcn_sched_barrier(0)
; template <class Epi, class Sched, bool ALIGN_EPI = false, bool SP2 = false>
; __device__ __forceinline__ void gemm_phase(PG8_LAS unsigned char* lds, const Gemm g, const Sched& S, const Epi& E) {
;     ...
;             const bool last = (t == nt - 2);
;             const char* a1 = cA + (size_t)(t + 1) * kstep;
;             const char* a2 = last ? nA : cA + (size_t)(t + 2) * kstep; const char* b2 = last ? nB : cB + (size_t)(t + 2) * kstep;
;             const char* a3 = a2 + kstep; const char* b3 = b2 + kstep;
;             if (last && has_next) S.a_ready(nxt);
;             if constexpr (SP2) {
;             PG8_LDB(B0, 0, 0); PG8_LDB(B1, 0, 1); PG8_SCHED; PG8_LDA(At, 0, 0); PG8_STAGE(PG8_SA(1, 1), a1 + hstep, voffA);
;             PG8_WAIT_V(8); PG8_WAIT_L(0); PG8_BAR; PG8_MMA(0, 0, At, B0); PG8_MMA(0, 1, At, B1); PG8_BAR; PG8_SCHED;
;             PG8_LDA(At, 0, 1); PG8_STAGE(PG8_SB(0, 0), b2, voffB); PG8_STAGE(PG8_SB(0, 1), b2 + hstep, voffB); PG8_STAGE(PG8_SA(0, 0), a2, voffA);
.LBB0_85:
	ds_read_b128 v[146:149], v152
	ds_read_b128 v[156:159], v152 offset:1024
	ds_read_b128 v[160:163], v152 offset:2048
	ds_read_b128 v[164:167], v152 offset:3072
	ds_read_b128 v[168:171], v153
	ds_read_b128 v[172:175], v153 offset:1024
	ds_read_b128 v[176:179], v153 offset:2048
	ds_read_b128 v[180:183], v153 offset:3072
	s_add_u32 s22, s20, 0xfffc0080
	s_addc_u32 s23, s21, -1
	s_cmp_eq_u32 s50, 12
	s_cselect_b32 s25, s13, s23
	s_cselect_b32 s24, s42, s22
	s_cselect_b32 s23, s11, s49
	s_cselect_b32 s22, s43, s48
	v_lshl_add_u64 v[184:185], s[20:21], 0, v[138:139]
	s_add_i32 m0, s19, 0xc000
	ds_read_b128 v[188:191], v154
	ds_read_b128 v[192:195], v154 offset:1024
	ds_read_b128 v[196:199], v154 offset:2048
	ds_read_b128 v[200:203], v154 offset:3072
	ds_read_b128 v[204:207], v154 offset:4096
	ds_read_b128 v[208:211], v154 offset:5120
	ds_read_b128 v[212:215], v154 offset:6144
	ds_read_b128 v[216:219], v154 offset:7168
	global_load_lds_dwordx4 v[184:185], off
	v_lshl_add_u64 v[184:185], s[20:21], 0, v[140:141]
	s_add_i32 m0, s19, 0xe000
	s_nop 0
	global_load_lds_dwordx4 v[184:185], off
	s_waitcnt vmcnt(8)
	s_waitcnt lgkmcnt(0)
	s_barrier
	s_setprio 1
	s_waitcnt lgkmcnt(0)
	v_mfma_f32_16x16x32_bf16 v[126:129], v[146:149], v[188:191], v[126:129]
	v_mfma_f32_16x16x32_bf16 v[122:125], v[160:163], v[188:191], v[122:125]
	v_mfma_f32_16x16x32_bf16 v[110:113], v[146:149], v[196:199], v[110:113]
	v_mfma_f32_16x16x32_bf16 v[106:109], v[160:163], v[196:199], v[106:109]
	v_mfma_f32_16x16x32_bf16 v[94:97], v[146:149], v[204:207], v[94:97]
	v_mfma_f32_16x16x32_bf16 v[90:93], v[160:163], v[204:207], v[90:93]
	v_mfma_f32_16x16x32_bf16 v[78:81], v[146:149], v[212:215], v[78:81]
	v_mfma_f32_16x16x32_bf16 v[74:77], v[160:163], v[212:215], v[74:77]
	v_mfma_f32_16x16x32_bf16 v[126:129], v[156:159], v[192:195], v[126:129]
	v_mfma_f32_16x16x32_bf16 v[122:125], v[164:167], v[192:195], v[122:125]
	v_mfma_f32_16x16x32_bf16 v[110:113], v[156:159], v[200:203], v[110:113]
	v_mfma_f32_16x16x32_bf16 v[106:109], v[164:167], v[200:203], v[106:109]
	v_mfma_f32_16x16x32_bf16 v[94:97], v[156:159], v[208:211], v[94:97]
	v_mfma_f32_16x16x32_bf16 v[90:93], v[164:167], v[208:211], v[90:93]
	v_mfma_f32_16x16x32_bf16 v[78:81], v[156:159], v[216:219], v[78:81]
	v_mfma_f32_16x16x32_bf16 v[74:77], v[164:167], v[216:219], v[74:77]
	v_mfma_f32_16x16x32_bf16 v[118:121], v[168:171], v[188:191], v[118:121]
	v_mfma_f32_16x16x32_bf16 v[114:117], v[176:179], v[188:191], v[114:117]
	v_mfma_f32_16x16x32_bf16 v[102:105], v[168:171], v[196:199], v[102:105]
	v_mfma_f32_16x16x32_bf16 v[98:101], v[176:179], v[196:199], v[98:101]
	v_mfma_f32_16x16x32_bf16 v[86:89], v[168:171], v[204:207], v[86:89]
	v_mfma_f32_16x16x32_bf16 v[82:85], v[176:179], v[204:207], v[82:85]
	v_mfma_f32_16x16x32_bf16 v[70:73], v[168:171], v[212:215], v[70:73]
	v_mfma_f32_16x16x32_bf16 v[66:69], v[176:179], v[212:215], v[66:69]
	v_mfma_f32_16x16x32_bf16 v[118:121], v[172:175], v[192:195], v[118:121]
	v_mfma_f32_16x16x32_bf16 v[114:117], v[180:183], v[192:195], v[114:117]
	v_mfma_f32_16x16x32_bf16 v[102:105], v[172:175], v[200:203], v[102:105]
	v_mfma_f32_16x16x32_bf16 v[98:101], v[180:183], v[200:203], v[98:101]
	v_mfma_f32_16x16x32_bf16 v[86:89], v[172:175], v[208:211], v[86:89]
	v_mfma_f32_16x16x32_bf16 v[82:85], v[180:183], v[208:211], v[82:85]
	v_mfma_f32_16x16x32_bf16 v[70:73], v[172:175], v[216:219], v[70:73]
	v_mfma_f32_16x16x32_bf16 v[66:69], v[180:183], v[216:219], v[66:69]
	s_barrier
	s_setprio 0
	s_add_i32 s51, s38, s26
	v_lshl_add_u64 v[184:185], s[22:23], 0, v[134:135]
	s_mov_b32 m0, s51
	ds_read_b128 v[188:191], v154 offset:16384
	ds_read_b128 v[192:195], v154 offset:17408
	ds_read_b128 v[196:199], v154 offset:18432
	ds_read_b128 v[200:203], v154 offset:19456
	ds_read_b128 v[204:207], v154 offset:20480
	ds_read_b128 v[208:211], v154 offset:21504
	ds_read_b128 v[212:215], v154 offset:22528
	ds_read_b128 v[216:219], v154 offset:23552
	global_load_lds_dwordx4 v[184:185], off
	s_add_i32 m0, s51, 0x2000
	s_add_u32 s52, s22, 0x40000
	v_lshl_add_u64 v[220:221], s[22:23], 0, v[130:131]
	s_addc_u32 s53, s23, 0
	s_add_i32 s51, s39, s26
	global_load_lds_dwordx4 v[220:221], off
	v_lshl_add_u64 v[222:223], s[52:53], 0, v[134:135]
	s_mov_b32 m0, s51
	v_lshl_add_u64 v[224:225], s[24:25], 0, v[132:133]
	global_load_lds_dwordx4 v[222:223], off
	v_lshl_add_u64 v[222:223], s[52:53], 0, v[130:131]
	s_add_i32 m0, s51, 0x2000
	s_nop 0
	global_load_lds_dwordx4 v[222:223], off
	v_lshl_add_u64 v[222:223], s[24:25], 0, v[136:137]
	s_mov_b32 m0, s19
	s_nop 0
	global_load_lds_dwordx4 v[222:223], off
	s_mov_b32 m0, s29
	s_nop 0
	global_load_lds_dwordx4 v[224:225], off
	s_waitcnt vmcnt(8)
	s_waitcnt lgkmcnt(0)
	s_barrier
; #define PG8_STAGE(bufoff, gbase, voff) do { _Pragma("unroll") for (int _i = 0; _i < 2; ++_i) \
;         __builtin_amdgcn_global_load_lds((const unsigned*)((const char*)(gbase) + (voff)[_i]), (PG8_LAS unsigned*)(lds + (bufoff) + ldsw + _i * 8192), 16, 0, 0); } while (0)
; #define PG8_LDA(dst, b, h) do { _Pragma("unroll") for (int m = 0; m < 4; ++m) _Pragma("unroll") for (int k = 0; k < 2; ++k) dst[m][k] = *(const PG8_LAS bf16x8*)(lds + PG8_SA(b, h) + aoff + m * 2048 + k * 1024); } while (0)
; #define PG8_LDB(dst, b, h) do { _Pragma("unroll") for (int n = 0; n < 2; ++n) _Pragma("unroll") for (int k = 0; k < 2; ++k) dst[n][k] = *(const PG8_LAS bf16x8*)(lds + PG8_SB(b, h) + boff + n * 2048 + k * 1024); } while (0)
; #define PG8_MMA(ai, bj, At, Bt) do { __builtin_amdgcn_s_setprio(1); _Pragma("unroll") for (int m = 0; m < 4; ++m) _Pragma("unroll") for (int n = 0; n < 2; ++n) _Pragma("unroll") for (int k = 0; k < 2; ++k) \
;         acc[ai][bj][m][n] = __builtin_amdgcn_mfma_f32_16x16x32_bf16(Bt[n][k], At[m][k], acc[ai][bj][m][n], 0, 0, 0); __builtin_amdgcn_s_setprio(0); } while (0)
; #define PG8_WAIT_V(n) asm volatile("s_waitcnt vmcnt(" #n ")" ::: "memory")
; #define PG8_WAIT_L(n) asm volatile("s_waitcnt lgkmcnt(" #n ")" ::: "memory")
; #define PG8_BAR __builtin_amdgcn_s_barrier()
; #define PG8_SCHED __builtin_amdgcn_sched_barrier(0)
; template <class Epi, class Sched, bool ALIGN_EPI = false, bool SP2 = false>
; __device__ __forceinline__ void gemm_phase(PG8_LAS unsigned char* lds, const Gemm g, const Sched& S, const Epi& E) {
;     ...
;             PG8_WAIT_V(8); PG8_WAIT_L(0); PG8_BAR; PG8_MMA(1, 0, At, B0); PG8_MMA(1, 1, At, B1); PG8_BAR; PG8_SCHED;
;             PG8_LDB(B0, 1, 0); PG8_LDB(B1, 1, 1); PG8_SCHED; PG8_LDA(At, 1, 0); PG8_STAGE(PG8_SA(0, 1), a2 + hstep, voffA);
;             PG8_WAIT_V(8); PG8_WAIT_L(0); PG8_BAR; PG8_MMA(0, 0, At, B0); PG8_MMA(0, 1, At, B1); PG8_BAR; PG8_SCHED;
	s_setprio 1
	s_waitcnt lgkmcnt(0)
	v_mfma_f32_16x16x32_bf16 v[62:65], v[146:149], v[188:191], v[62:65]
	v_mfma_f32_16x16x32_bf16 v[58:61], v[160:163], v[188:191], v[58:61]
	v_mfma_f32_16x16x32_bf16 v[46:49], v[146:149], v[196:199], v[46:49]
	v_mfma_f32_16x16x32_bf16 v[42:45], v[160:163], v[196:199], v[42:45]
	v_mfma_f32_16x16x32_bf16 v[30:33], v[146:149], v[204:207], v[30:33]
	v_mfma_f32_16x16x32_bf16 v[26:29], v[160:163], v[204:207], v[26:29]
	v_mfma_f32_16x16x32_bf16 v[14:17], v[146:149], v[212:215], v[14:17]
	v_mfma_f32_16x16x32_bf16 v[10:13], v[160:163], v[212:215], v[10:13]
	v_mfma_f32_16x16x32_bf16 v[62:65], v[156:159], v[192:195], v[62:65]
	v_mfma_f32_16x16x32_bf16 v[58:61], v[164:167], v[192:195], v[58:61]
	v_mfma_f32_16x16x32_bf16 v[46:49], v[156:159], v[200:203], v[46:49]
	v_mfma_f32_16x16x32_bf16 v[42:45], v[164:167], v[200:203], v[42:45]
	v_mfma_f32_16x16x32_bf16 v[30:33], v[156:159], v[208:211], v[30:33]
	v_mfma_f32_16x16x32_bf16 v[26:29], v[164:167], v[208:211], v[26:29]
	v_mfma_f32_16x16x32_bf16 v[14:17], v[156:159], v[216:219], v[14:17]
	v_mfma_f32_16x16x32_bf16 v[10:13], v[164:167], v[216:219], v[10:13]
	v_mfma_f32_16x16x32_bf16 v[54:57], v[168:171], v[188:191], v[54:57]
	v_mfma_f32_16x16x32_bf16 v[50:53], v[176:179], v[188:191], v[50:53]
	v_mfma_f32_16x16x32_bf16 v[38:41], v[168:171], v[196:199], v[38:41]
	v_mfma_f32_16x16x32_bf16 v[34:37], v[176:179], v[196:199], v[34:37]
	v_mfma_f32_16x16x32_bf16 v[22:25], v[168:171], v[204:207], v[22:25]
	v_mfma_f32_16x16x32_bf16 v[18:21], v[176:179], v[204:207], v[18:21]
	v_mfma_f32_16x16x32_bf16 v[6:9], v[168:171], v[212:215], v[6:9]
	v_mfma_f32_16x16x32_bf16 v[2:5], v[176:179], v[212:215], v[2:5]
	v_mfma_f32_16x16x32_bf16 v[54:57], v[172:175], v[192:195], v[54:57]
	v_mfma_f32_16x16x32_bf16 v[50:53], v[180:183], v[192:195], v[50:53]
	v_mfma_f32_16x16x32_bf16 v[38:41], v[172:175], v[200:203], v[38:41]
	v_mfma_f32_16x16x32_bf16 v[34:37], v[180:183], v[200:203], v[34:37]
	v_mfma_f32_16x16x32_bf16 v[22:25], v[172:175], v[208:211], v[22:25]
	v_mfma_f32_16x16x32_bf16 v[18:21], v[180:183], v[208:211], v[18:21]
	v_mfma_f32_16x16x32_bf16 v[6:9], v[172:175], v[216:219], v[6:9]
	v_mfma_f32_16x16x32_bf16 v[2:5], v[180:183], v[216:219], v[2:5]
	s_barrier
	s_setprio 0
	s_add_i32 s51, 0, 0x18000
	v_add_u32_e32 v155, s51, v150
	s_add_i32 s52, 0, 0x1c000
	ds_read_b128 v[146:149], v155
	ds_read_b128 v[156:159], v155 offset:1024
	ds_read_b128 v[160:163], v155 offset:2048
	ds_read_b128 v[164:167], v155 offset:3072
	v_add_u32_e32 v155, s52, v150
	ds_read_b128 v[168:171], v155
	ds_read_b128 v[172:175], v155 offset:1024
	ds_read_b128 v[176:179], v155 offset:2048
	ds_read_b128 v[180:183], v155 offset:3072
	s_add_u32 s24, s24, 0x40000
	s_addc_u32 s25, s25, 0
	s_mov_b32 m0, s30
	v_lshl_add_u64 v[226:227], s[24:25], 0, v[136:137]
	ds_read_b128 v[188:191], v154 offset:32768
	ds_read_b128 v[192:195], v154 offset:33792
	ds_read_b128 v[196:199], v154 offset:34816
	ds_read_b128 v[200:203], v154 offset:35840
	ds_read_b128 v[204:207], v154 offset:36864
	ds_read_b128 v[208:211], v154 offset:37888
	ds_read_b128 v[212:215], v154 offset:38912
	ds_read_b128 v[216:219], v154 offset:39936
	global_load_lds_dwordx4 v[226:227], off
	v_lshl_add_u64 v[226:227], s[24:25], 0, v[132:133]
	s_mov_b32 m0, s31
	s_nop 0
	global_load_lds_dwordx4 v[226:227], off
	s_waitcnt vmcnt(8)
	s_waitcnt lgkmcnt(0)
	s_barrier
	s_setprio 1
	s_waitcnt lgkmcnt(0)
	v_mfma_f32_16x16x32_bf16 v[126:129], v[146:149], v[188:191], v[126:129]
	v_mfma_f32_16x16x32_bf16 v[122:125], v[160:163], v[188:191], v[122:125]
	v_mfma_f32_16x16x32_bf16 v[110:113], v[146:149], v[196:199], v[110:113]
	v_mfma_f32_16x16x32_bf16 v[106:109], v[160:163], v[196:199], v[106:109]
	v_mfma_f32_16x16x32_bf16 v[94:97], v[146:149], v[204:207], v[94:97]
	v_mfma_f32_16x16x32_bf16 v[90:93], v[160:163], v[204:207], v[90:93]
	v_mfma_f32_16x16x32_bf16 v[78:81], v[146:149], v[212:215], v[78:81]
	v_mfma_f32_16x16x32_bf16 v[74:77], v[160:163], v[212:215], v[74:77]
	v_mfma_f32_16x16x32_bf16 v[126:129], v[156:159], v[192:195], v[126:129]
	v_mfma_f32_16x16x32_bf16 v[122:125], v[164:167], v[192:195], v[122:125]
	v_mfma_f32_16x16x32_bf16 v[110:113], v[156:159], v[200:203], v[110:113]
	v_mfma_f32_16x16x32_bf16 v[106:109], v[164:167], v[200:203], v[106:109]
	v_mfma_f32_16x16x32_bf16 v[94:97], v[156:159], v[208:211], v[94:97]
	v_mfma_f32_16x16x32_bf16 v[90:93], v[164:167], v[208:211], v[90:93]
	v_mfma_f32_16x16x32_bf16 v[78:81], v[156:159], v[216:219], v[78:81]
	v_mfma_f32_16x16x32_bf16 v[74:77], v[164:167], v[216:219], v[74:77]
	v_mfma_f32_16x16x32_bf16 v[118:121], v[168:171], v[188:191], v[118:121]
	v_mfma_f32_16x16x32_bf16 v[114:117], v[176:179], v[188:191], v[114:117]
	v_mfma_f32_16x16x32_bf16 v[102:105], v[168:171], v[196:199], v[102:105]
	v_mfma_f32_16x16x32_bf16 v[98:101], v[176:179], v[196:199], v[98:101]
	v_mfma_f32_16x16x32_bf16 v[86:89], v[168:171], v[204:207], v[86:89]
	v_mfma_f32_16x16x32_bf16 v[82:85], v[176:179], v[204:207], v[82:85]
	v_mfma_f32_16x16x32_bf16 v[70:73], v[168:171], v[212:215], v[70:73]
	v_mfma_f32_16x16x32_bf16 v[66:69], v[176:179], v[212:215], v[66:69]
	v_mfma_f32_16x16x32_bf16 v[118:121], v[172:175], v[192:195], v[118:121]
	v_mfma_f32_16x16x32_bf16 v[114:117], v[180:183], v[192:195], v[114:117]
	v_mfma_f32_16x16x32_bf16 v[102:105], v[172:175], v[200:203], v[102:105]
	v_mfma_f32_16x16x32_bf16 v[98:101], v[180:183], v[200:203], v[98:101]
	v_mfma_f32_16x16x32_bf16 v[86:89], v[172:175], v[208:211], v[86:89]
	v_mfma_f32_16x16x32_bf16 v[82:85], v[180:183], v[208:211], v[82:85]
	v_mfma_f32_16x16x32_bf16 v[70:73], v[172:175], v[216:219], v[70:73]
	v_mfma_f32_16x16x32_bf16 v[66:69], v[180:183], v[216:219], v[66:69]
	s_barrier
; #define PG8_STAGE(bufoff, gbase, voff) do { _Pragma("unroll") for (int _i = 0; _i < 2; ++_i) \
;         __builtin_amdgcn_global_load_lds((const unsigned*)((const char*)(gbase) + (voff)[_i]), (PG8_LAS unsigned*)(lds + (bufoff) + ldsw + _i * 8192), 16, 0, 0); } while (0)
; #define PG8_LDA(dst, b, h) do { _Pragma("unroll") for (int m = 0; m < 4; ++m) _Pragma("unroll") for (int k = 0; k < 2; ++k) dst[m][k] = *(const PG8_LAS bf16x8*)(lds + PG8_SA(b, h) + aoff + m * 2048 + k * 1024); } while (0)
; #define PG8_WAIT_V(n) asm volatile("s_waitcnt vmcnt(" #n ")" ::: "memory")
; template <class Epi, class Sched, bool ALIGN_EPI = false, bool SP2 = false>
; __device__ __forceinline__ void gemm_phase(PG8_LAS unsigned char* lds, const Gemm g, const Sched& S, const Epi& E) {
;     ...
;             PG8_LDA(At, 1, 1); PG8_STAGE(PG8_SB(1, 0), b3, voffB); PG8_STAGE(PG8_SB(1, 1), b3 + hstep, voffB); PG8_STAGE(PG8_SA(1, 0), a3, voffA);
;             PG8_WAIT_V(8); PG8_WAIT_L(0); PG8_BAR; PG8_MMA(1, 0, At, B0); PG8_MMA(1, 1, At, B1); PG8_BAR; PG8_SCHED;
;             } else {
;             PG8_LDB(B0, 0, 0); PG8_SCHED; PG8_LDA(At, 0, 0); PG8_STAGE(PG8_SA(1, 1), a1 + hstep, voffA);
;             PG8_WAIT_L(8); PG8_BAR; PG8_WAIT_L(0); PG8_MMA(0, 0, At, B0); PG8_BAR; PG8_SCHED;
;             PG8_LDB(B1, 0, 1); PG8_STAGE(PG8_SB(0, 0), b2, voffB);
;             PG8_BAR; PG8_WAIT_L(0); PG8_MMA(0, 1, At, B1); PG8_BAR;
;             PG8_LDA(At, 0, 1); PG8_STAGE(PG8_SA(0, 0), a2, voffA);
;             PG8_BAR; PG8_WAIT_L(0); PG8_MMA(1, 0, At, B0); PG8_BAR; PG8_SCHED;
;             PG8_STAGE(PG8_SB(0, 1), b2 + hstep, voffB);
;             PG8_WAIT_V(6); PG8_BAR; PG8_MMA(1, 1, At, B1); PG8_BAR;
;             PG8_LDB(B0, 1, 0); PG8_SCHED; PG8_LDA(At, 1, 0); PG8_STAGE(PG8_SA(0, 1), a2 + hstep, voffA);
;             PG8_WAIT_L(8); PG8_BAR; PG8_WAIT_L(0); PG8_MMA(0, 0, At, B0); PG8_BAR; PG8_SCHED;
;             PG8_LDB(B1, 1, 1); PG8_STAGE(PG8_SB(1, 0), b3, voffB);
;             PG8_BAR; PG8_WAIT_L(0); PG8_MMA(0, 1, At, B1); PG8_BAR;
;             PG8_LDA(At, 1, 1); PG8_STAGE(PG8_SA(1, 0), a3, voffA);
;             PG8_BAR; PG8_WAIT_L(0); PG8_MMA(1, 0, At, B0); PG8_BAR; PG8_SCHED;
;             PG8_STAGE(PG8_SB(1, 1), b3 + hstep, voffB);
;             PG8_WAIT_V(6); PG8_BAR; PG8_MMA(1, 1, At, B1); PG8_BAR;
;             }
;         }
;         if constexpr (ALIGN_EPI) { if (wr == 0) PG8_BAR; }
	s_setprio 0
	s_add_i32 s24, s51, s26
	v_lshl_add_u64 v[184:185], v[184:185], 0, s[6:7]
	s_mov_b32 m0, s24
	ds_read_b128 v[188:191], v154 offset:49152
	ds_read_b128 v[192:195], v154 offset:50176
	ds_read_b128 v[196:199], v154 offset:51200
	ds_read_b128 v[200:203], v154 offset:52224
	ds_read_b128 v[204:207], v154 offset:53248
	ds_read_b128 v[208:211], v154 offset:54272
	ds_read_b128 v[212:215], v154 offset:55296
	ds_read_b128 v[216:219], v154 offset:56320
	global_load_lds_dwordx4 v[184:185], off
	s_add_i32 m0, s24, 0x2000
	s_add_u32 s22, s22, 0x40080
	v_lshl_add_u64 v[184:185], v[220:221], 0, s[6:7]
	s_addc_u32 s23, s23, 0
	s_add_i32 s24, s52, s26
	global_load_lds_dwordx4 v[184:185], off
	v_lshl_add_u64 v[184:185], s[22:23], 0, v[134:135]
	s_mov_b32 m0, s24
	s_nop 0
	global_load_lds_dwordx4 v[184:185], off
	v_lshl_add_u64 v[184:185], s[22:23], 0, v[130:131]
	s_add_i32 m0, s24, 0x2000
	s_nop 0
	global_load_lds_dwordx4 v[184:185], off
	v_lshl_add_u64 v[184:185], v[222:223], 0, s[6:7]
	s_mov_b32 m0, s35
	s_nop 0
	global_load_lds_dwordx4 v[184:185], off
	v_lshl_add_u64 v[184:185], v[224:225], 0, s[6:7]
	s_mov_b32 m0, s36
	s_nop 0
	global_load_lds_dwordx4 v[184:185], off
	s_waitcnt vmcnt(8)
	s_waitcnt lgkmcnt(0)
	s_barrier
	s_setprio 1
	s_waitcnt lgkmcnt(0)
	v_mfma_f32_16x16x32_bf16 v[62:65], v[146:149], v[188:191], v[62:65]
	v_mfma_f32_16x16x32_bf16 v[58:61], v[160:163], v[188:191], v[58:61]
	v_mfma_f32_16x16x32_bf16 v[46:49], v[146:149], v[196:199], v[46:49]
	v_mfma_f32_16x16x32_bf16 v[42:45], v[160:163], v[196:199], v[42:45]
	v_mfma_f32_16x16x32_bf16 v[30:33], v[146:149], v[204:207], v[30:33]
	v_mfma_f32_16x16x32_bf16 v[26:29], v[160:163], v[204:207], v[26:29]
	v_mfma_f32_16x16x32_bf16 v[14:17], v[146:149], v[212:215], v[14:17]
	v_mfma_f32_16x16x32_bf16 v[10:13], v[160:163], v[212:215], v[10:13]
	v_mfma_f32_16x16x32_bf16 v[62:65], v[156:159], v[192:195], v[62:65]
	v_mfma_f32_16x16x32_bf16 v[58:61], v[164:167], v[192:195], v[58:61]
	v_mfma_f32_16x16x32_bf16 v[46:49], v[156:159], v[200:203], v[46:49]
	v_mfma_f32_16x16x32_bf16 v[42:45], v[164:167], v[200:203], v[42:45]
	v_mfma_f32_16x16x32_bf16 v[30:33], v[156:159], v[208:211], v[30:33]
	v_mfma_f32_16x16x32_bf16 v[26:29], v[164:167], v[208:211], v[26:29]
	v_mfma_f32_16x16x32_bf16 v[14:17], v[156:159], v[216:219], v[14:17]
	v_mfma_f32_16x16x32_bf16 v[10:13], v[164:167], v[216:219], v[10:13]
	v_mfma_f32_16x16x32_bf16 v[54:57], v[168:171], v[188:191], v[54:57]
	v_mfma_f32_16x16x32_bf16 v[50:53], v[176:179], v[188:191], v[50:53]
	v_mfma_f32_16x16x32_bf16 v[38:41], v[168:171], v[196:199], v[38:41]
	v_mfma_f32_16x16x32_bf16 v[34:37], v[176:179], v[196:199], v[34:37]
	v_mfma_f32_16x16x32_bf16 v[22:25], v[168:171], v[204:207], v[22:25]
	v_mfma_f32_16x16x32_bf16 v[18:21], v[176:179], v[204:207], v[18:21]
	v_mfma_f32_16x16x32_bf16 v[6:9], v[168:171], v[212:215], v[6:9]
	v_mfma_f32_16x16x32_bf16 v[2:5], v[176:179], v[212:215], v[2:5]
	v_mfma_f32_16x16x32_bf16 v[54:57], v[172:175], v[192:195], v[54:57]
	v_mfma_f32_16x16x32_bf16 v[50:53], v[180:183], v[192:195], v[50:53]
	v_mfma_f32_16x16x32_bf16 v[38:41], v[172:175], v[200:203], v[38:41]
	v_mfma_f32_16x16x32_bf16 v[34:37], v[180:183], v[200:203], v[34:37]
	v_mfma_f32_16x16x32_bf16 v[22:25], v[172:175], v[208:211], v[22:25]
	v_mfma_f32_16x16x32_bf16 v[18:21], v[180:183], v[208:211], v[18:21]
	v_mfma_f32_16x16x32_bf16 v[6:9], v[172:175], v[216:219], v[6:9]
	v_mfma_f32_16x16x32_bf16 v[2:5], v[180:183], v[216:219], v[2:5]
	s_barrier
	s_setprio 0
	s_add_i32 s50, s50, 2
	s_add_u32 s20, s20, 0x100
	s_addc_u32 s21, s21, 0
	s_add_u32 s48, s48, 0x100
	s_addc_u32 s49, s49, 0
	s_cmp_gt_u32 s50, 13
	s_cbranch_scc0 .LBB0_85
	s_and_b64 vcc, exec, s[8:9]
	s_cbranch_vccz .LBB0_88
	s_barrier

; #define PG8_STAGE(bufoff, gbase, voff) do { _Pragma("unroll") for (int _i = 0; _i < 2; ++_i) \
;         __builtin_amdgcn_global_load_lds((const unsigned*)((const char*)(gbase) + (voff)[_i]), (PG8_LAS unsigned*)(lds + (bufoff) + ldsw + _i * 8192), 16, 0, 0); } while (0)
; #define PG8_LDA(dst, b, h) do { _Pragma("unroll") for (int m = 0; m < 4; ++m) _Pragma("unroll") for (int k = 0; k < 2; ++k) dst[m][k] = *(const PG8_LAS bf16x8*)(lds + PG8_SA(b, h) + aoff + m * 2048 + k * 1024); } while (0)
; #define PG8_LDB(dst, b, h) do { _Pragma("unroll") for (int n = 0; n < 2; ++n) _Pragma("unroll") for (int k = 0; k < 2; ++k) dst[n][k] = *(const PG8_LAS bf16x8*)(lds + PG8_SB(b, h) + boff + n * 2048 + k * 1024); } while (0)
; #define PG8_MMA(ai, bj, At, Bt) do { __builtin_amdgcn_s_setprio(1); _Pragma("unroll") for (int m = 0; m < 4; ++m) _Pragma("unroll") for (int n = 0; n < 2; ++n) _Pragma("unroll") for (int k = 0; k < 2; ++k) \
;         acc[ai][bj][m][n] = __builtin_amdgcn_mfma_f32_16x16x32_bf16(Bt[n][k], At[m][k], acc[ai][bj][m][n], 0, 0, 0); __builtin_amdgcn_s_setprio(0); } while (0)
; #define PG8_WAIT_V(n) asm volatile("s_waitcnt vmcnt(" #n ")" ::: "memory")
; #define PG8_WAIT_L(n) asm volatile("s_waitcnt lgkmcnt(" #n ")" ::: "memory")
; #define PG8_BAR __builtin_amdgcn_s_barrier()
; #define PG8_SCHED __builtin_amdgcn_sched_barrier(0)
; template <class Epi, class Sched, bool ALIGN_EPI = false, bool SP2 = false>
; __device__ __forceinline__ void gemm_phase(PG8_LAS unsigned char* lds, const Gemm g, const Sched& S, const Epi& E) {
;     ...
;             const bool last = (t == nt - 2);
;             const char* a1 = cA + (size_t)(t + 1) * kstep;
;             const char* a2 = last ? nA : cA + (size_t)(t + 2) * kstep; const char* b2 = last ? nB : cB + (size_t)(t + 2) * kstep;
;             const char* a3 = a2 + kstep; const char* b3 = b2 + kstep;
;             if (last && has_next) S.a_ready(nxt);
;             if constexpr (SP2) {
;             PG8_LDB(B0, 0, 0); PG8_LDB(B1, 0, 1); PG8_SCHED; PG8_LDA(At, 0, 0); PG8_STAGE(PG8_SA(1, 1), a1 + hstep, voffA);
;             PG8_WAIT_V(8); PG8_WAIT_L(0); PG8_BAR; PG8_MMA(0, 0, At, B0); PG8_MMA(0, 1, At, B1); PG8_BAR; PG8_SCHED;
;             PG8_LDA(At, 0, 1); PG8_STAGE(PG8_SB(0, 0), b2, voffB); PG8_STAGE(PG8_SB(0, 1), b2 + hstep, voffB); PG8_STAGE(PG8_SA(0, 0), a2, voffA);
.LBB0_207:
	ds_read_b128 v[144:147], v140
	ds_read_b128 v[148:151], v140 offset:1024
	ds_read_b128 v[152:155], v140 offset:2048
	ds_read_b128 v[156:159], v140 offset:3072
	ds_read_b128 v[160:163], v141
	ds_read_b128 v[164:167], v141 offset:1024
	ds_read_b128 v[168:171], v141 offset:2048
	ds_read_b128 v[172:175], v141 offset:3072
	s_add_i32 s68, s36, 2
	s_add_u32 s34, s30, 0x100
	s_addc_u32 s35, s31, 0
	s_cmp_eq_u32 s53, s36
	s_cselect_b32 s36, s28, s66
	s_cselect_b32 s39, s27, s35
	s_cselect_b32 s38, s26, s34
	s_cselect_b32 s37, s29, s67
	s_mov_b32 m0, s60
	v_lshl_add_u64 v[184:185], s[30:31], 0, v[134:135]
	ds_read_b128 v[176:179], v142
	ds_read_b128 v[180:183], v142 offset:1024
	ds_read_b128 v[188:191], v142 offset:2048
	ds_read_b128 v[192:195], v142 offset:3072
	ds_read_b128 v[196:199], v142 offset:4096
	ds_read_b128 v[200:203], v142 offset:5120
	ds_read_b128 v[204:207], v142 offset:6144
	ds_read_b128 v[208:211], v142 offset:7168
	global_load_lds_dwordx4 v[184:185], off
	v_lshl_add_u64 v[184:185], s[30:31], 0, v[136:137]
	s_add_i32 m0, s41, 0xe000
	s_nop 0
	global_load_lds_dwordx4 v[184:185], off
	s_waitcnt vmcnt(8)
	s_waitcnt lgkmcnt(0)
	s_barrier
	s_setprio 1
	s_waitcnt lgkmcnt(0)
	v_mfma_f32_16x16x32_bf16 v[126:129], v[144:147], v[176:179], v[126:129]
	v_mfma_f32_16x16x32_bf16 v[122:125], v[152:155], v[176:179], v[122:125]
	v_mfma_f32_16x16x32_bf16 v[110:113], v[144:147], v[188:191], v[110:113]
	v_mfma_f32_16x16x32_bf16 v[106:109], v[152:155], v[188:191], v[106:109]
	v_mfma_f32_16x16x32_bf16 v[94:97], v[144:147], v[196:199], v[94:97]
	v_mfma_f32_16x16x32_bf16 v[90:93], v[152:155], v[196:199], v[90:93]
	v_mfma_f32_16x16x32_bf16 v[78:81], v[144:147], v[204:207], v[78:81]
	v_mfma_f32_16x16x32_bf16 v[74:77], v[152:155], v[204:207], v[74:77]
	v_mfma_f32_16x16x32_bf16 v[126:129], v[148:151], v[180:183], v[126:129]
	v_mfma_f32_16x16x32_bf16 v[122:125], v[156:159], v[180:183], v[122:125]
	v_mfma_f32_16x16x32_bf16 v[110:113], v[148:151], v[192:195], v[110:113]
	v_mfma_f32_16x16x32_bf16 v[106:109], v[156:159], v[192:195], v[106:109]
	v_mfma_f32_16x16x32_bf16 v[94:97], v[148:151], v[200:203], v[94:97]
	v_mfma_f32_16x16x32_bf16 v[90:93], v[156:159], v[200:203], v[90:93]
	v_mfma_f32_16x16x32_bf16 v[78:81], v[148:151], v[208:211], v[78:81]
	v_mfma_f32_16x16x32_bf16 v[74:77], v[156:159], v[208:211], v[74:77]
	v_mfma_f32_16x16x32_bf16 v[118:121], v[160:163], v[176:179], v[118:121]
	v_mfma_f32_16x16x32_bf16 v[114:117], v[168:171], v[176:179], v[114:117]
	v_mfma_f32_16x16x32_bf16 v[102:105], v[160:163], v[188:191], v[102:105]
	v_mfma_f32_16x16x32_bf16 v[98:101], v[168:171], v[188:191], v[98:101]
	v_mfma_f32_16x16x32_bf16 v[86:89], v[160:163], v[196:199], v[86:89]
	v_mfma_f32_16x16x32_bf16 v[82:85], v[168:171], v[196:199], v[82:85]
	v_mfma_f32_16x16x32_bf16 v[70:73], v[160:163], v[204:207], v[70:73]
	v_mfma_f32_16x16x32_bf16 v[66:69], v[168:171], v[204:207], v[66:69]
	v_mfma_f32_16x16x32_bf16 v[118:121], v[164:167], v[180:183], v[118:121]
	v_mfma_f32_16x16x32_bf16 v[114:117], v[172:175], v[180:183], v[114:117]
	v_mfma_f32_16x16x32_bf16 v[102:105], v[164:167], v[192:195], v[102:105]
	v_mfma_f32_16x16x32_bf16 v[98:101], v[172:175], v[192:195], v[98:101]
	v_mfma_f32_16x16x32_bf16 v[86:89], v[164:167], v[200:203], v[86:89]
	v_mfma_f32_16x16x32_bf16 v[82:85], v[172:175], v[200:203], v[82:85]
	v_mfma_f32_16x16x32_bf16 v[70:73], v[164:167], v[208:211], v[70:73]
	v_mfma_f32_16x16x32_bf16 v[66:69], v[172:175], v[208:211], v[66:69]
	s_barrier
	s_setprio 0
	s_add_i32 s30, s54, s40
	v_lshl_add_u64 v[184:185], s[36:37], 0, v[132:133]
	s_mov_b32 m0, s30
	ds_read_b128 v[176:179], v142 offset:16384
	ds_read_b128 v[180:183], v142 offset:17408
	ds_read_b128 v[188:191], v142 offset:18432
	ds_read_b128 v[192:195], v142 offset:19456
	ds_read_b128 v[196:199], v142 offset:20480
	ds_read_b128 v[200:203], v142 offset:21504
	ds_read_b128 v[204:207], v142 offset:22528
	ds_read_b128 v[208:211], v142 offset:23552
	global_load_lds_dwordx4 v[184:185], off
	s_add_i32 m0, s30, 0x2000
	s_add_u32 s30, s36, 0xb0000
	v_lshl_add_u64 v[212:213], s[36:37], 0, v[130:131]
	s_addc_u32 s31, s37, 0
	s_add_i32 s69, s55, s40
	global_load_lds_dwordx4 v[212:213], off
	v_lshl_add_u64 v[214:215], s[30:31], 0, v[132:133]
	s_mov_b32 m0, s69
	v_lshl_add_u64 v[216:217], s[38:39], 0, v[130:131]
	global_load_lds_dwordx4 v[214:215], off
	v_lshl_add_u64 v[214:215], s[30:31], 0, v[130:131]
	s_add_i32 m0, s69, 0x2000
	s_nop 0
	global_load_lds_dwordx4 v[214:215], off
	v_lshl_add_u64 v[214:215], s[38:39], 0, v[132:133]
	s_mov_b32 m0, s41
	s_nop 0
	global_load_lds_dwordx4 v[214:215], off
	s_mov_b32 m0, s42
	s_nop 0
	global_load_lds_dwordx4 v[216:217], off
	s_waitcnt vmcnt(8)
	s_waitcnt lgkmcnt(0)
	s_barrier
; #define PG8_STAGE(bufoff, gbase, voff) do { _Pragma("unroll") for (int _i = 0; _i < 2; ++_i) \
;         __builtin_amdgcn_global_load_lds((const unsigned*)((const char*)(gbase) + (voff)[_i]), (PG8_LAS unsigned*)(lds + (bufoff) + ldsw + _i * 8192), 16, 0, 0); } while (0)
; #define PG8_LDA(dst, b, h) do { _Pragma("unroll") for (int m = 0; m < 4; ++m) _Pragma("unroll") for (int k = 0; k < 2; ++k) dst[m][k] = *(const PG8_LAS bf16x8*)(lds + PG8_SA(b, h) + aoff + m * 2048 + k * 1024); } while (0)
; #define PG8_LDB(dst, b, h) do { _Pragma("unroll") for (int n = 0; n < 2; ++n) _Pragma("unroll") for (int k = 0; k < 2; ++k) dst[n][k] = *(const PG8_LAS bf16x8*)(lds + PG8_SB(b, h) + boff + n * 2048 + k * 1024); } while (0)
; #define PG8_MMA(ai, bj, At, Bt) do { __builtin_amdgcn_s_setprio(1); _Pragma("unroll") for (int m = 0; m < 4; ++m) _Pragma("unroll") for (int n = 0; n < 2; ++n) _Pragma("unroll") for (int k = 0; k < 2; ++k) \
;         acc[ai][bj][m][n] = __builtin_amdgcn_mfma_f32_16x16x32_bf16(Bt[n][k], At[m][k], acc[ai][bj][m][n], 0, 0, 0); __builtin_amdgcn_s_setprio(0); } while (0)
; #define PG8_WAIT_V(n) asm volatile("s_waitcnt vmcnt(" #n ")" ::: "memory")
; #define PG8_WAIT_L(n) asm volatile("s_waitcnt lgkmcnt(" #n ")" ::: "memory")
; #define PG8_BAR __builtin_amdgcn_s_barrier()
; #define PG8_SCHED __builtin_amdgcn_sched_barrier(0)
; template <class Epi, class Sched, bool ALIGN_EPI = false, bool SP2 = false>
; __device__ __forceinline__ void gemm_phase(PG8_LAS unsigned char* lds, const Gemm g, const Sched& S, const Epi& E) {
;     ...
;             PG8_WAIT_V(8); PG8_WAIT_L(0); PG8_BAR; PG8_MMA(1, 0, At, B0); PG8_MMA(1, 1, At, B1); PG8_BAR; PG8_SCHED;
;             PG8_LDB(B0, 1, 0); PG8_LDB(B1, 1, 1); PG8_SCHED; PG8_LDA(At, 1, 0); PG8_STAGE(PG8_SA(0, 1), a2 + hstep, voffA);
;             PG8_WAIT_V(8); PG8_WAIT_L(0); PG8_BAR; PG8_MMA(0, 0, At, B0); PG8_MMA(0, 1, At, B1); PG8_BAR; PG8_SCHED;
	s_setprio 1
	s_waitcnt lgkmcnt(0)
	v_mfma_f32_16x16x32_bf16 v[62:65], v[144:147], v[176:179], v[62:65]
	v_mfma_f32_16x16x32_bf16 v[58:61], v[152:155], v[176:179], v[58:61]
	v_mfma_f32_16x16x32_bf16 v[46:49], v[144:147], v[188:191], v[46:49]
	v_mfma_f32_16x16x32_bf16 v[42:45], v[152:155], v[188:191], v[42:45]
	v_mfma_f32_16x16x32_bf16 v[30:33], v[144:147], v[196:199], v[30:33]
	v_mfma_f32_16x16x32_bf16 v[26:29], v[152:155], v[196:199], v[26:29]
	v_mfma_f32_16x16x32_bf16 v[14:17], v[144:147], v[204:207], v[14:17]
	v_mfma_f32_16x16x32_bf16 v[10:13], v[152:155], v[204:207], v[10:13]
	v_mfma_f32_16x16x32_bf16 v[62:65], v[148:151], v[180:183], v[62:65]
	v_mfma_f32_16x16x32_bf16 v[58:61], v[156:159], v[180:183], v[58:61]
	v_mfma_f32_16x16x32_bf16 v[46:49], v[148:151], v[192:195], v[46:49]
	v_mfma_f32_16x16x32_bf16 v[42:45], v[156:159], v[192:195], v[42:45]
	v_mfma_f32_16x16x32_bf16 v[30:33], v[148:151], v[200:203], v[30:33]
	v_mfma_f32_16x16x32_bf16 v[26:29], v[156:159], v[200:203], v[26:29]
	v_mfma_f32_16x16x32_bf16 v[14:17], v[148:151], v[208:211], v[14:17]
	v_mfma_f32_16x16x32_bf16 v[10:13], v[156:159], v[208:211], v[10:13]
	v_mfma_f32_16x16x32_bf16 v[54:57], v[160:163], v[176:179], v[54:57]
	v_mfma_f32_16x16x32_bf16 v[50:53], v[168:171], v[176:179], v[50:53]
	v_mfma_f32_16x16x32_bf16 v[38:41], v[160:163], v[188:191], v[38:41]
	v_mfma_f32_16x16x32_bf16 v[34:37], v[168:171], v[188:191], v[34:37]
	v_mfma_f32_16x16x32_bf16 v[22:25], v[160:163], v[196:199], v[22:25]
	v_mfma_f32_16x16x32_bf16 v[18:21], v[168:171], v[196:199], v[18:21]
	v_mfma_f32_16x16x32_bf16 v[6:9], v[160:163], v[204:207], v[6:9]
	v_mfma_f32_16x16x32_bf16 v[2:5], v[168:171], v[204:207], v[2:5]
	v_mfma_f32_16x16x32_bf16 v[54:57], v[164:167], v[180:183], v[54:57]
	v_mfma_f32_16x16x32_bf16 v[50:53], v[172:175], v[180:183], v[50:53]
	v_mfma_f32_16x16x32_bf16 v[38:41], v[164:167], v[192:195], v[38:41]
	v_mfma_f32_16x16x32_bf16 v[34:37], v[172:175], v[192:195], v[34:37]
	v_mfma_f32_16x16x32_bf16 v[22:25], v[164:167], v[200:203], v[22:25]
	v_mfma_f32_16x16x32_bf16 v[18:21], v[172:175], v[200:203], v[18:21]
	v_mfma_f32_16x16x32_bf16 v[6:9], v[164:167], v[208:211], v[6:9]
	v_mfma_f32_16x16x32_bf16 v[2:5], v[172:175], v[208:211], v[2:5]
	s_barrier
	s_setprio 0
	s_add_i32 s69, 0, 0x18000
	v_add_u32_e32 v143, s69, v1
	s_add_i32 s70, 0, 0x1c000
	ds_read_b128 v[144:147], v143
	ds_read_b128 v[148:151], v143 offset:1024
	ds_read_b128 v[152:155], v143 offset:2048
	ds_read_b128 v[156:159], v143 offset:3072
	v_add_u32_e32 v143, s70, v1
	ds_read_b128 v[160:163], v143
	ds_read_b128 v[164:167], v143 offset:1024
	ds_read_b128 v[168:171], v143 offset:2048
	ds_read_b128 v[172:175], v143 offset:3072
	s_add_u32 s30, s38, 0xb0000
	s_addc_u32 s31, s39, 0
	s_mov_b32 m0, s43
	v_lshl_add_u64 v[218:219], s[30:31], 0, v[132:133]
	ds_read_b128 v[176:179], v142 offset:32768
	ds_read_b128 v[180:183], v142 offset:33792
	ds_read_b128 v[188:191], v142 offset:34816
	ds_read_b128 v[192:195], v142 offset:35840
	ds_read_b128 v[196:199], v142 offset:36864
	ds_read_b128 v[200:203], v142 offset:37888
	ds_read_b128 v[204:207], v142 offset:38912
	ds_read_b128 v[208:211], v142 offset:39936
	global_load_lds_dwordx4 v[218:219], off
	v_lshl_add_u64 v[218:219], s[30:31], 0, v[130:131]
	s_mov_b32 m0, s48
	s_nop 0
	global_load_lds_dwordx4 v[218:219], off
	s_waitcnt vmcnt(8)
	s_waitcnt lgkmcnt(0)
	s_barrier
	s_setprio 1
	s_waitcnt lgkmcnt(0)
	v_mfma_f32_16x16x32_bf16 v[126:129], v[144:147], v[176:179], v[126:129]
	v_mfma_f32_16x16x32_bf16 v[122:125], v[152:155], v[176:179], v[122:125]
	v_mfma_f32_16x16x32_bf16 v[110:113], v[144:147], v[188:191], v[110:113]
	v_mfma_f32_16x16x32_bf16 v[106:109], v[152:155], v[188:191], v[106:109]
	v_mfma_f32_16x16x32_bf16 v[94:97], v[144:147], v[196:199], v[94:97]
	v_mfma_f32_16x16x32_bf16 v[90:93], v[152:155], v[196:199], v[90:93]
	v_mfma_f32_16x16x32_bf16 v[78:81], v[144:147], v[204:207], v[78:81]
	v_mfma_f32_16x16x32_bf16 v[74:77], v[152:155], v[204:207], v[74:77]
	v_mfma_f32_16x16x32_bf16 v[126:129], v[148:151], v[180:183], v[126:129]
	v_mfma_f32_16x16x32_bf16 v[122:125], v[156:159], v[180:183], v[122:125]
	v_mfma_f32_16x16x32_bf16 v[110:113], v[148:151], v[192:195], v[110:113]
	v_mfma_f32_16x16x32_bf16 v[106:109], v[156:159], v[192:195], v[106:109]
	v_mfma_f32_16x16x32_bf16 v[94:97], v[148:151], v[200:203], v[94:97]
	v_mfma_f32_16x16x32_bf16 v[90:93], v[156:159], v[200:203], v[90:93]
	v_mfma_f32_16x16x32_bf16 v[78:81], v[148:151], v[208:211], v[78:81]
	v_mfma_f32_16x16x32_bf16 v[74:77], v[156:159], v[208:211], v[74:77]
	v_mfma_f32_16x16x32_bf16 v[118:121], v[160:163], v[176:179], v[118:121]
	v_mfma_f32_16x16x32_bf16 v[114:117], v[168:171], v[176:179], v[114:117]
	v_mfma_f32_16x16x32_bf16 v[102:105], v[160:163], v[188:191], v[102:105]
	v_mfma_f32_16x16x32_bf16 v[98:101], v[168:171], v[188:191], v[98:101]
	v_mfma_f32_16x16x32_bf16 v[86:89], v[160:163], v[196:199], v[86:89]
	v_mfma_f32_16x16x32_bf16 v[82:85], v[168:171], v[196:199], v[82:85]
	v_mfma_f32_16x16x32_bf16 v[70:73], v[160:163], v[204:207], v[70:73]
	v_mfma_f32_16x16x32_bf16 v[66:69], v[168:171], v[204:207], v[66:69]
	v_mfma_f32_16x16x32_bf16 v[118:121], v[164:167], v[180:183], v[118:121]
	v_mfma_f32_16x16x32_bf16 v[114:117], v[172:175], v[180:183], v[114:117]
	v_mfma_f32_16x16x32_bf16 v[102:105], v[164:167], v[192:195], v[102:105]
	v_mfma_f32_16x16x32_bf16 v[98:101], v[172:175], v[192:195], v[98:101]
	v_mfma_f32_16x16x32_bf16 v[86:89], v[164:167], v[200:203], v[86:89]
	v_mfma_f32_16x16x32_bf16 v[82:85], v[172:175], v[200:203], v[82:85]
	v_mfma_f32_16x16x32_bf16 v[70:73], v[164:167], v[208:211], v[70:73]
	v_mfma_f32_16x16x32_bf16 v[66:69], v[172:175], v[208:211], v[66:69]
	s_barrier
; #define PG8_STAGE(bufoff, gbase, voff) do { _Pragma("unroll") for (int _i = 0; _i < 2; ++_i) \
;         __builtin_amdgcn_global_load_lds((const unsigned*)((const char*)(gbase) + (voff)[_i]), (PG8_LAS unsigned*)(lds + (bufoff) + ldsw + _i * 8192), 16, 0, 0); } while (0)
; #define PG8_LDA(dst, b, h) do { _Pragma("unroll") for (int m = 0; m < 4; ++m) _Pragma("unroll") for (int k = 0; k < 2; ++k) dst[m][k] = *(const PG8_LAS bf16x8*)(lds + PG8_SA(b, h) + aoff + m * 2048 + k * 1024); } while (0)
; #define PG8_WAIT_V(n) asm volatile("s_waitcnt vmcnt(" #n ")" ::: "memory")
; #define PG8_BAR __builtin_amdgcn_s_barrier()
; template <class Epi, class Sched, bool ALIGN_EPI = false, bool SP2 = false>
; __device__ __forceinline__ void gemm_phase(PG8_LAS unsigned char* lds, const Gemm g, const Sched& S, const Epi& E) {
;     ...
;             PG8_LDA(At, 1, 1); PG8_STAGE(PG8_SB(1, 0), b3, voffB); PG8_STAGE(PG8_SB(1, 1), b3 + hstep, voffB); PG8_STAGE(PG8_SA(1, 0), a3, voffA);
;             PG8_WAIT_V(8); PG8_WAIT_L(0); PG8_BAR; PG8_MMA(1, 0, At, B0); PG8_MMA(1, 1, At, B1); PG8_BAR; PG8_SCHED;
;             } else {
;             PG8_LDB(B0, 0, 0); PG8_SCHED; PG8_LDA(At, 0, 0); PG8_STAGE(PG8_SA(1, 1), a1 + hstep, voffA);
;             PG8_WAIT_L(8); PG8_BAR; PG8_WAIT_L(0); PG8_MMA(0, 0, At, B0); PG8_BAR; PG8_SCHED;
;             PG8_LDB(B1, 0, 1); PG8_STAGE(PG8_SB(0, 0), b2, voffB);
;             PG8_BAR; PG8_WAIT_L(0); PG8_MMA(0, 1, At, B1); PG8_BAR;
;             PG8_LDA(At, 0, 1); PG8_STAGE(PG8_SA(0, 0), a2, voffA);
;             PG8_BAR; PG8_WAIT_L(0); PG8_MMA(1, 0, At, B0); PG8_BAR; PG8_SCHED;
;             PG8_STAGE(PG8_SB(0, 1), b2 + hstep, voffB);
;             PG8_WAIT_V(6); PG8_BAR; PG8_MMA(1, 1, At, B1); PG8_BAR;
;             PG8_LDB(B0, 1, 0); PG8_SCHED; PG8_LDA(At, 1, 0); PG8_STAGE(PG8_SA(0, 1), a2 + hstep, voffA);
;             PG8_WAIT_L(8); PG8_BAR; PG8_WAIT_L(0); PG8_MMA(0, 0, At, B0); PG8_BAR; PG8_SCHED;
;             PG8_LDB(B1, 1, 1); PG8_STAGE(PG8_SB(1, 0), b3, voffB);
;             PG8_BAR; PG8_WAIT_L(0); PG8_MMA(0, 1, At, B1); PG8_BAR;
;             PG8_LDA(At, 1, 1); PG8_STAGE(PG8_SA(1, 0), a3, voffA);
;             PG8_BAR; PG8_WAIT_L(0); PG8_MMA(1, 0, At, B0); PG8_BAR; PG8_SCHED;
;             PG8_STAGE(PG8_SB(1, 1), b3 + hstep, voffB);
;             PG8_WAIT_V(6); PG8_BAR; PG8_MMA(1, 1, At, B1); PG8_BAR;
;             }
;         }
	s_setprio 0
	s_add_i32 s30, s69, s40
	v_lshl_add_u64 v[184:185], v[184:185], 0, s[14:15]
	s_mov_b32 m0, s30
	ds_read_b128 v[176:179], v142 offset:49152
	ds_read_b128 v[180:183], v142 offset:50176
	ds_read_b128 v[188:191], v142 offset:51200
	ds_read_b128 v[192:195], v142 offset:52224
	ds_read_b128 v[196:199], v142 offset:53248
	ds_read_b128 v[200:203], v142 offset:54272
	ds_read_b128 v[204:207], v142 offset:55296
	ds_read_b128 v[208:211], v142 offset:56320
	global_load_lds_dwordx4 v[184:185], off
	s_add_i32 m0, s30, 0x2000
	s_add_u32 s30, s36, 0xb0080
	v_lshl_add_u64 v[184:185], v[212:213], 0, s[14:15]
	s_addc_u32 s31, s37, 0
	s_add_i32 s36, s70, s40
	global_load_lds_dwordx4 v[184:185], off
	v_lshl_add_u64 v[184:185], s[30:31], 0, v[132:133]
	s_mov_b32 m0, s36
	s_nop 0
	global_load_lds_dwordx4 v[184:185], off
	v_lshl_add_u64 v[184:185], s[30:31], 0, v[130:131]
	s_add_i32 m0, s36, 0x2000
	s_nop 0
	global_load_lds_dwordx4 v[184:185], off
	v_lshl_add_u64 v[184:185], v[214:215], 0, s[14:15]
	s_mov_b32 m0, s51
	s_nop 0
	global_load_lds_dwordx4 v[184:185], off
	v_lshl_add_u64 v[184:185], v[216:217], 0, s[14:15]
	s_mov_b32 m0, s52
	s_nop 0
	global_load_lds_dwordx4 v[184:185], off
	s_waitcnt vmcnt(8)
	s_waitcnt lgkmcnt(0)
	s_barrier
	s_setprio 1
	s_waitcnt lgkmcnt(0)
	v_mfma_f32_16x16x32_bf16 v[62:65], v[144:147], v[176:179], v[62:65]
	v_mfma_f32_16x16x32_bf16 v[58:61], v[152:155], v[176:179], v[58:61]
	v_mfma_f32_16x16x32_bf16 v[46:49], v[144:147], v[188:191], v[46:49]
	v_mfma_f32_16x16x32_bf16 v[42:45], v[152:155], v[188:191], v[42:45]
	v_mfma_f32_16x16x32_bf16 v[30:33], v[144:147], v[196:199], v[30:33]
	v_mfma_f32_16x16x32_bf16 v[26:29], v[152:155], v[196:199], v[26:29]
	v_mfma_f32_16x16x32_bf16 v[14:17], v[144:147], v[204:207], v[14:17]
	v_mfma_f32_16x16x32_bf16 v[10:13], v[152:155], v[204:207], v[10:13]
	v_mfma_f32_16x16x32_bf16 v[62:65], v[148:151], v[180:183], v[62:65]
	v_mfma_f32_16x16x32_bf16 v[58:61], v[156:159], v[180:183], v[58:61]
	v_mfma_f32_16x16x32_bf16 v[46:49], v[148:151], v[192:195], v[46:49]
	v_mfma_f32_16x16x32_bf16 v[42:45], v[156:159], v[192:195], v[42:45]
	v_mfma_f32_16x16x32_bf16 v[30:33], v[148:151], v[200:203], v[30:33]
	v_mfma_f32_16x16x32_bf16 v[26:29], v[156:159], v[200:203], v[26:29]
	v_mfma_f32_16x16x32_bf16 v[14:17], v[148:151], v[208:211], v[14:17]
	v_mfma_f32_16x16x32_bf16 v[10:13], v[156:159], v[208:211], v[10:13]
	v_mfma_f32_16x16x32_bf16 v[54:57], v[160:163], v[176:179], v[54:57]
	v_mfma_f32_16x16x32_bf16 v[50:53], v[168:171], v[176:179], v[50:53]
	v_mfma_f32_16x16x32_bf16 v[38:41], v[160:163], v[188:191], v[38:41]
	v_mfma_f32_16x16x32_bf16 v[34:37], v[168:171], v[188:191], v[34:37]
	v_mfma_f32_16x16x32_bf16 v[22:25], v[160:163], v[196:199], v[22:25]
	v_mfma_f32_16x16x32_bf16 v[18:21], v[168:171], v[196:199], v[18:21]
	v_mfma_f32_16x16x32_bf16 v[6:9], v[160:163], v[204:207], v[6:9]
	v_mfma_f32_16x16x32_bf16 v[2:5], v[168:171], v[204:207], v[2:5]
	v_mfma_f32_16x16x32_bf16 v[54:57], v[164:167], v[180:183], v[54:57]
	v_mfma_f32_16x16x32_bf16 v[50:53], v[172:175], v[180:183], v[50:53]
	v_mfma_f32_16x16x32_bf16 v[38:41], v[164:167], v[192:195], v[38:41]
	v_mfma_f32_16x16x32_bf16 v[34:37], v[172:175], v[192:195], v[34:37]
	v_mfma_f32_16x16x32_bf16 v[22:25], v[164:167], v[200:203], v[22:25]
	v_mfma_f32_16x16x32_bf16 v[18:21], v[172:175], v[200:203], v[18:21]
	v_mfma_f32_16x16x32_bf16 v[6:9], v[164:167], v[208:211], v[6:9]
	v_mfma_f32_16x16x32_bf16 v[2:5], v[172:175], v[208:211], v[2:5]
	s_barrier
	s_setprio 0
	s_add_u32 s66, s66, 0x100
	s_addc_u32 s67, s67, 0
	s_cmp_ge_i32 s68, s50
	s_mov_b64 s[30:31], s[34:35]
	s_mov_b32 s36, s68
	s_cbranch_scc0 .LBB0_207

; #define PG8_STAGE(bufoff, gbase, voff) do { _Pragma("unroll") for (int _i = 0; _i < 2; ++_i) \
;         __builtin_amdgcn_global_load_lds((const unsigned*)((const char*)(gbase) + (voff)[_i]), (PG8_LAS unsigned*)(lds + (bufoff) + ldsw + _i * 8192), 16, 0, 0); } while (0)
; #define PG8_LDA(dst, b, h) do { _Pragma("unroll") for (int m = 0; m < 4; ++m) _Pragma("unroll") for (int k = 0; k < 2; ++k) dst[m][k] = *(const PG8_LAS bf16x8*)(lds + PG8_SA(b, h) + aoff + m * 2048 + k * 1024); } while (0)
; #define PG8_LDB(dst, b, h) do { _Pragma("unroll") for (int n = 0; n < 2; ++n) _Pragma("unroll") for (int k = 0; k < 2; ++k) dst[n][k] = *(const PG8_LAS bf16x8*)(lds + PG8_SB(b, h) + boff + n * 2048 + k * 1024); } while (0)
; #define PG8_MMA(ai, bj, At, Bt) do { __builtin_amdgcn_s_setprio(1); _Pragma("unroll") for (int m = 0; m < 4; ++m) _Pragma("unroll") for (int n = 0; n < 2; ++n) _Pragma("unroll") for (int k = 0; k < 2; ++k) \
;         acc[ai][bj][m][n] = __builtin_amdgcn_mfma_f32_16x16x32_bf16(Bt[n][k], At[m][k], acc[ai][bj][m][n], 0, 0, 0); __builtin_amdgcn_s_setprio(0); } while (0)
; #define PG8_WAIT_V(n) asm volatile("s_waitcnt vmcnt(" #n ")" ::: "memory")
; #define PG8_WAIT_L(n) asm volatile("s_waitcnt lgkmcnt(" #n ")" ::: "memory")
; #define PG8_BAR __builtin_amdgcn_s_barrier()
; #define PG8_SCHED __builtin_amdgcn_sched_barrier(0)
; template <class Epi, class Sched, bool ALIGN_EPI = false, bool SP2 = false>
; __device__ __forceinline__ void gemm_phase(PG8_LAS unsigned char* lds, const Gemm g, const Sched& S, const Epi& E) {
;     ...
;             const bool last = (t == nt - 2);
;             const char* a1 = cA + (size_t)(t + 1) * kstep;
;             const char* a2 = last ? nA : cA + (size_t)(t + 2) * kstep; const char* b2 = last ? nB : cB + (size_t)(t + 2) * kstep;
;             const char* a3 = a2 + kstep; const char* b3 = b2 + kstep;
;             if (last && has_next) S.a_ready(nxt);
;             if constexpr (SP2) {
;             PG8_LDB(B0, 0, 0); PG8_LDB(B1, 0, 1); PG8_SCHED; PG8_LDA(At, 0, 0); PG8_STAGE(PG8_SA(1, 1), a1 + hstep, voffA);
;             PG8_WAIT_V(8); PG8_WAIT_L(0); PG8_BAR; PG8_MMA(0, 0, At, B0); PG8_MMA(0, 1, At, B1); PG8_BAR; PG8_SCHED;
;             PG8_LDA(At, 0, 1); PG8_STAGE(PG8_SB(0, 0), b2, voffB); PG8_STAGE(PG8_SB(0, 1), b2 + hstep, voffB); PG8_STAGE(PG8_SA(0, 0), a2, voffA);
.LBB0_252:
	v_add_u32_e32 v162, s52, v148
	v_add_u32_e32 v178, s53, v148
	s_add_u32 s28, s20, s26
	ds_read_b128 v[150:153], v162
	ds_read_b128 v[154:157], v162 offset:1024
	ds_read_b128 v[158:161], v162 offset:2048
	ds_read_b128 v[162:165], v162 offset:3072
	ds_read_b128 v[166:169], v178
	ds_read_b128 v[170:173], v178 offset:1024
	ds_read_b128 v[174:177], v178 offset:2048
	ds_read_b128 v[178:181], v178 offset:3072
	s_addc_u32 s29, s21, s27
	s_add_u32 s28, s28, 0x100
	s_addc_u32 s29, s29, 0
	s_add_u32 s60, s57, s26
	s_addc_u32 s61, s58, s27
	s_cmpk_eq_i32 s26, 0x1500
	s_cselect_b32 s31, s25, s29
	s_cselect_b32 s30, s24, s28
	s_cselect_b32 s29, s9, s61
	s_cselect_b32 s28, s8, s60
	v_lshl_add_u64 v[216:217], v[142:143], 0, s[26:27]
	s_add_i32 m0, s40, 0xc000
	ds_read_b128 v[182:185], v149
	ds_read_b128 v[188:191], v149 offset:1024
	ds_read_b128 v[192:195], v149 offset:2048
	ds_read_b128 v[196:199], v149 offset:3072
	ds_read_b128 v[200:203], v149 offset:4096
	ds_read_b128 v[204:207], v149 offset:5120
	ds_read_b128 v[208:211], v149 offset:6144
	ds_read_b128 v[212:215], v149 offset:7168
	global_load_lds_dwordx4 v[216:217], off
	v_lshl_add_u64 v[216:217], v[144:145], 0, s[26:27]
	s_add_i32 m0, s40, 0xe000
	s_nop 0
	global_load_lds_dwordx4 v[216:217], off
	s_waitcnt vmcnt(8)
	s_waitcnt lgkmcnt(0)
	s_barrier
	s_setprio 1
	s_waitcnt lgkmcnt(0)
	v_mfma_f32_16x16x32_bf16 v[106:109], v[150:153], v[182:185], v[106:109]
	v_mfma_f32_16x16x32_bf16 v[66:69], v[158:161], v[182:185], v[66:69]
	v_mfma_f32_16x16x32_bf16 v[114:117], v[150:153], v[192:195], v[114:117]
	v_mfma_f32_16x16x32_bf16 v[86:89], v[158:161], v[192:195], v[86:89]
	v_mfma_f32_16x16x32_bf16 v[126:129], v[150:153], v[200:203], v[126:129]
	v_mfma_f32_16x16x32_bf16 v[110:113], v[158:161], v[200:203], v[110:113]
	v_mfma_f32_16x16x32_bf16 v[122:125], v[150:153], v[208:211], v[122:125]
	v_mfma_f32_16x16x32_bf16 v[118:121], v[158:161], v[208:211], v[118:121]
	v_mfma_f32_16x16x32_bf16 v[106:109], v[154:157], v[188:191], v[106:109]
	v_mfma_f32_16x16x32_bf16 v[66:69], v[162:165], v[188:191], v[66:69]
	v_mfma_f32_16x16x32_bf16 v[114:117], v[154:157], v[196:199], v[114:117]
	v_mfma_f32_16x16x32_bf16 v[86:89], v[162:165], v[196:199], v[86:89]
	v_mfma_f32_16x16x32_bf16 v[126:129], v[154:157], v[204:207], v[126:129]
	v_mfma_f32_16x16x32_bf16 v[110:113], v[162:165], v[204:207], v[110:113]
	v_mfma_f32_16x16x32_bf16 v[122:125], v[154:157], v[212:215], v[122:125]
	v_mfma_f32_16x16x32_bf16 v[118:121], v[162:165], v[212:215], v[118:121]
	v_mfma_f32_16x16x32_bf16 v[42:45], v[166:169], v[182:185], v[42:45]
	v_mfma_f32_16x16x32_bf16 v[18:21], v[174:177], v[182:185], v[18:21]
	v_mfma_f32_16x16x32_bf16 v[50:53], v[166:169], v[192:195], v[50:53]
	v_mfma_f32_16x16x32_bf16 v[30:33], v[174:177], v[192:195], v[30:33]
	v_mfma_f32_16x16x32_bf16 v[74:77], v[166:169], v[200:203], v[74:77]
	v_mfma_f32_16x16x32_bf16 v[46:49], v[174:177], v[200:203], v[46:49]
	v_mfma_f32_16x16x32_bf16 v[94:97], v[166:169], v[208:211], v[94:97]
	v_mfma_f32_16x16x32_bf16 v[54:57], v[174:177], v[208:211], v[54:57]
	v_mfma_f32_16x16x32_bf16 v[42:45], v[170:173], v[188:191], v[42:45]
	v_mfma_f32_16x16x32_bf16 v[18:21], v[178:181], v[188:191], v[18:21]
	v_mfma_f32_16x16x32_bf16 v[50:53], v[170:173], v[196:199], v[50:53]
	v_mfma_f32_16x16x32_bf16 v[30:33], v[178:181], v[196:199], v[30:33]
	v_mfma_f32_16x16x32_bf16 v[74:77], v[170:173], v[204:207], v[74:77]
	v_mfma_f32_16x16x32_bf16 v[46:49], v[178:181], v[204:207], v[46:49]
	v_mfma_f32_16x16x32_bf16 v[94:97], v[170:173], v[212:215], v[94:97]
	v_mfma_f32_16x16x32_bf16 v[54:57], v[178:181], v[212:215], v[54:57]
	s_barrier
	s_setprio 0
	s_add_i32 s60, s52, s39
	v_lshl_add_u64 v[216:217], s[28:29], 0, v[130:131]
	s_mov_b32 m0, s60
	ds_read_b128 v[182:185], v149 offset:16384
	ds_read_b128 v[188:191], v149 offset:17408
	ds_read_b128 v[192:195], v149 offset:18432
	ds_read_b128 v[196:199], v149 offset:19456
	ds_read_b128 v[200:203], v149 offset:20480
	ds_read_b128 v[204:207], v149 offset:21504
	ds_read_b128 v[208:211], v149 offset:22528
	ds_read_b128 v[212:215], v149 offset:23552
	global_load_lds_dwordx4 v[216:217], off
	s_add_i32 m0, s60, 0x2000
	s_add_u32 s60, s28, 0xb0000
	v_lshl_add_u64 v[218:219], s[28:29], 0, v[132:133]
	s_addc_u32 s61, s29, 0
	s_add_i32 s62, s53, s39
	global_load_lds_dwordx4 v[218:219], off
	v_lshl_add_u64 v[220:221], s[60:61], 0, v[130:131]
	s_mov_b32 m0, s62
	v_lshl_add_u64 v[222:223], s[30:31], 0, v[132:133]
	global_load_lds_dwordx4 v[220:221], off
	v_lshl_add_u64 v[220:221], s[60:61], 0, v[132:133]
	s_add_i32 m0, s62, 0x2000
	s_nop 0
	global_load_lds_dwordx4 v[220:221], off
	v_lshl_add_u64 v[220:221], s[30:31], 0, v[130:131]
	s_mov_b32 m0, s40
	s_nop 0
	global_load_lds_dwordx4 v[220:221], off
	s_mov_b32 m0, s41
	s_nop 0
	global_load_lds_dwordx4 v[222:223], off
	s_waitcnt vmcnt(8)
	s_waitcnt lgkmcnt(0)
	s_barrier
; #define PG8_STAGE(bufoff, gbase, voff) do { _Pragma("unroll") for (int _i = 0; _i < 2; ++_i) \
;         __builtin_amdgcn_global_load_lds((const unsigned*)((const char*)(gbase) + (voff)[_i]), (PG8_LAS unsigned*)(lds + (bufoff) + ldsw + _i * 8192), 16, 0, 0); } while (0)
; #define PG8_LDA(dst, b, h) do { _Pragma("unroll") for (int m = 0; m < 4; ++m) _Pragma("unroll") for (int k = 0; k < 2; ++k) dst[m][k] = *(const PG8_LAS bf16x8*)(lds + PG8_SA(b, h) + aoff + m * 2048 + k * 1024); } while (0)
; #define PG8_LDB(dst, b, h) do { _Pragma("unroll") for (int n = 0; n < 2; ++n) _Pragma("unroll") for (int k = 0; k < 2; ++k) dst[n][k] = *(const PG8_LAS bf16x8*)(lds + PG8_SB(b, h) + boff + n * 2048 + k * 1024); } while (0)
; #define PG8_MMA(ai, bj, At, Bt) do { __builtin_amdgcn_s_setprio(1); _Pragma("unroll") for (int m = 0; m < 4; ++m) _Pragma("unroll") for (int n = 0; n < 2; ++n) _Pragma("unroll") for (int k = 0; k < 2; ++k) \
;         acc[ai][bj][m][n] = __builtin_amdgcn_mfma_f32_16x16x32_bf16(Bt[n][k], At[m][k], acc[ai][bj][m][n], 0, 0, 0); __builtin_amdgcn_s_setprio(0); } while (0)
; #define PG8_WAIT_V(n) asm volatile("s_waitcnt vmcnt(" #n ")" ::: "memory")
; #define PG8_WAIT_L(n) asm volatile("s_waitcnt lgkmcnt(" #n ")" ::: "memory")
; #define PG8_BAR __builtin_amdgcn_s_barrier()
; #define PG8_SCHED __builtin_amdgcn_sched_barrier(0)
; template <class Epi, class Sched, bool ALIGN_EPI = false, bool SP2 = false>
; __device__ __forceinline__ void gemm_phase(PG8_LAS unsigned char* lds, const Gemm g, const Sched& S, const Epi& E) {
;     ...
;             PG8_WAIT_V(8); PG8_WAIT_L(0); PG8_BAR; PG8_MMA(1, 0, At, B0); PG8_MMA(1, 1, At, B1); PG8_BAR; PG8_SCHED;
;             PG8_LDB(B0, 1, 0); PG8_LDB(B1, 1, 1); PG8_SCHED; PG8_LDA(At, 1, 0); PG8_STAGE(PG8_SA(0, 1), a2 + hstep, voffA);
;             PG8_WAIT_V(8); PG8_WAIT_L(0); PG8_BAR; PG8_MMA(0, 0, At, B0); PG8_MMA(0, 1, At, B1); PG8_BAR; PG8_SCHED;
	s_setprio 1
	s_waitcnt lgkmcnt(0)
	v_mfma_f32_16x16x32_bf16 v[102:105], v[150:153], v[182:185], v[102:105]
	v_mfma_f32_16x16x32_bf16 v[98:101], v[158:161], v[182:185], v[98:101]
	v_mfma_f32_16x16x32_bf16 v[78:81], v[150:153], v[192:195], v[78:81]
	v_mfma_f32_16x16x32_bf16 v[70:73], v[158:161], v[192:195], v[70:73]
	v_mfma_f32_16x16x32_bf16 v[38:41], v[150:153], v[200:203], v[38:41]
	v_mfma_f32_16x16x32_bf16 v[34:37], v[158:161], v[200:203], v[34:37]
	v_mfma_f32_16x16x32_bf16 v[14:17], v[150:153], v[208:211], v[14:17]
	v_mfma_f32_16x16x32_bf16 v[10:13], v[158:161], v[208:211], v[10:13]
	v_mfma_f32_16x16x32_bf16 v[102:105], v[154:157], v[188:191], v[102:105]
	v_mfma_f32_16x16x32_bf16 v[98:101], v[162:165], v[188:191], v[98:101]
	v_mfma_f32_16x16x32_bf16 v[78:81], v[154:157], v[196:199], v[78:81]
	v_mfma_f32_16x16x32_bf16 v[70:73], v[162:165], v[196:199], v[70:73]
	v_mfma_f32_16x16x32_bf16 v[38:41], v[154:157], v[204:207], v[38:41]
	v_mfma_f32_16x16x32_bf16 v[34:37], v[162:165], v[204:207], v[34:37]
	v_mfma_f32_16x16x32_bf16 v[14:17], v[154:157], v[212:215], v[14:17]
	v_mfma_f32_16x16x32_bf16 v[10:13], v[162:165], v[212:215], v[10:13]
	v_mfma_f32_16x16x32_bf16 v[90:93], v[166:169], v[182:185], v[90:93]
	v_mfma_f32_16x16x32_bf16 v[82:85], v[174:177], v[182:185], v[82:85]
	v_mfma_f32_16x16x32_bf16 v[62:65], v[166:169], v[192:195], v[62:65]
	v_mfma_f32_16x16x32_bf16 v[58:61], v[174:177], v[192:195], v[58:61]
	v_mfma_f32_16x16x32_bf16 v[26:29], v[166:169], v[200:203], v[26:29]
	v_mfma_f32_16x16x32_bf16 v[22:25], v[174:177], v[200:203], v[22:25]
	v_mfma_f32_16x16x32_bf16 v[6:9], v[166:169], v[208:211], v[6:9]
	v_mfma_f32_16x16x32_bf16 v[2:5], v[174:177], v[208:211], v[2:5]
	v_mfma_f32_16x16x32_bf16 v[90:93], v[170:173], v[188:191], v[90:93]
	v_mfma_f32_16x16x32_bf16 v[82:85], v[178:181], v[188:191], v[82:85]
	v_mfma_f32_16x16x32_bf16 v[62:65], v[170:173], v[196:199], v[62:65]
	v_mfma_f32_16x16x32_bf16 v[58:61], v[178:181], v[196:199], v[58:61]
	v_mfma_f32_16x16x32_bf16 v[26:29], v[170:173], v[204:207], v[26:29]
	v_mfma_f32_16x16x32_bf16 v[22:25], v[178:181], v[204:207], v[22:25]
	v_mfma_f32_16x16x32_bf16 v[6:9], v[170:173], v[212:215], v[6:9]
	v_mfma_f32_16x16x32_bf16 v[2:5], v[178:181], v[212:215], v[2:5]
	s_barrier
	s_setprio 0
	s_add_i32 s60, 0, 0x18000
	s_add_i32 s61, 0, 0x1c000
	v_add_u32_e32 v162, s60, v148
	v_add_u32_e32 v178, s61, v148
	ds_read_b128 v[150:153], v162
	ds_read_b128 v[154:157], v162 offset:1024
	ds_read_b128 v[158:161], v162 offset:2048
	ds_read_b128 v[162:165], v162 offset:3072
	ds_read_b128 v[166:169], v178
	ds_read_b128 v[170:173], v178 offset:1024
	ds_read_b128 v[174:177], v178 offset:2048
	ds_read_b128 v[178:181], v178 offset:3072
	s_add_u32 s30, s30, 0xb0000
	s_addc_u32 s31, s31, 0
	s_mov_b32 m0, s42
	v_lshl_add_u64 v[224:225], s[30:31], 0, v[130:131]
	ds_read_b128 v[182:185], v149 offset:32768
	ds_read_b128 v[188:191], v149 offset:33792
	ds_read_b128 v[192:195], v149 offset:34816
	ds_read_b128 v[196:199], v149 offset:35840
	ds_read_b128 v[200:203], v149 offset:36864
	ds_read_b128 v[204:207], v149 offset:37888
	ds_read_b128 v[208:211], v149 offset:38912
	ds_read_b128 v[212:215], v149 offset:39936
	global_load_lds_dwordx4 v[224:225], off
	v_lshl_add_u64 v[224:225], s[30:31], 0, v[132:133]
	s_mov_b32 m0, s43
	s_nop 0
	global_load_lds_dwordx4 v[224:225], off
	s_waitcnt vmcnt(8)
	s_waitcnt lgkmcnt(0)
	s_barrier
	s_setprio 1
	s_waitcnt lgkmcnt(0)
	v_mfma_f32_16x16x32_bf16 v[106:109], v[150:153], v[182:185], v[106:109]
	v_mfma_f32_16x16x32_bf16 v[66:69], v[158:161], v[182:185], v[66:69]
	v_mfma_f32_16x16x32_bf16 v[114:117], v[150:153], v[192:195], v[114:117]
	v_mfma_f32_16x16x32_bf16 v[86:89], v[158:161], v[192:195], v[86:89]
	v_mfma_f32_16x16x32_bf16 v[126:129], v[150:153], v[200:203], v[126:129]
	v_mfma_f32_16x16x32_bf16 v[110:113], v[158:161], v[200:203], v[110:113]
	v_mfma_f32_16x16x32_bf16 v[122:125], v[150:153], v[208:211], v[122:125]
	v_mfma_f32_16x16x32_bf16 v[118:121], v[158:161], v[208:211], v[118:121]
	v_mfma_f32_16x16x32_bf16 v[106:109], v[154:157], v[188:191], v[106:109]
	v_mfma_f32_16x16x32_bf16 v[66:69], v[162:165], v[188:191], v[66:69]
	v_mfma_f32_16x16x32_bf16 v[114:117], v[154:157], v[196:199], v[114:117]
	v_mfma_f32_16x16x32_bf16 v[86:89], v[162:165], v[196:199], v[86:89]
	v_mfma_f32_16x16x32_bf16 v[126:129], v[154:157], v[204:207], v[126:129]
	v_mfma_f32_16x16x32_bf16 v[110:113], v[162:165], v[204:207], v[110:113]
	v_mfma_f32_16x16x32_bf16 v[122:125], v[154:157], v[212:215], v[122:125]
	v_mfma_f32_16x16x32_bf16 v[118:121], v[162:165], v[212:215], v[118:121]
	v_mfma_f32_16x16x32_bf16 v[42:45], v[166:169], v[182:185], v[42:45]
	v_mfma_f32_16x16x32_bf16 v[18:21], v[174:177], v[182:185], v[18:21]
	v_mfma_f32_16x16x32_bf16 v[50:53], v[166:169], v[192:195], v[50:53]
	v_mfma_f32_16x16x32_bf16 v[30:33], v[174:177], v[192:195], v[30:33]
	v_mfma_f32_16x16x32_bf16 v[74:77], v[166:169], v[200:203], v[74:77]
	v_mfma_f32_16x16x32_bf16 v[46:49], v[174:177], v[200:203], v[46:49]
	v_mfma_f32_16x16x32_bf16 v[94:97], v[166:169], v[208:211], v[94:97]
	v_mfma_f32_16x16x32_bf16 v[54:57], v[174:177], v[208:211], v[54:57]
	v_mfma_f32_16x16x32_bf16 v[42:45], v[170:173], v[188:191], v[42:45]
	v_mfma_f32_16x16x32_bf16 v[18:21], v[178:181], v[188:191], v[18:21]
	v_mfma_f32_16x16x32_bf16 v[50:53], v[170:173], v[196:199], v[50:53]
	v_mfma_f32_16x16x32_bf16 v[30:33], v[178:181], v[196:199], v[30:33]
	v_mfma_f32_16x16x32_bf16 v[74:77], v[170:173], v[204:207], v[74:77]
	v_mfma_f32_16x16x32_bf16 v[46:49], v[178:181], v[204:207], v[46:49]
	v_mfma_f32_16x16x32_bf16 v[94:97], v[170:173], v[212:215], v[94:97]
	v_mfma_f32_16x16x32_bf16 v[54:57], v[178:181], v[212:215], v[54:57]
	s_barrier
; #define PG8_WAIT_V(n) asm volatile("s_waitcnt vmcnt(" #n ")" ::: "memory")
; #define PG8_BAR __builtin_amdgcn_s_barrier()
; template <class Epi, class Sched, bool ALIGN_EPI = false, bool SP2 = false>
; __device__ __forceinline__ void gemm_phase(PG8_LAS unsigned char* lds, const Gemm g, const Sched& S, const Epi& E) {
;     ...
;             PG8_LDA(At, 1, 1); PG8_STAGE(PG8_SB(1, 0), b3, voffB); PG8_STAGE(PG8_SB(1, 1), b3 + hstep, voffB); PG8_STAGE(PG8_SA(1, 0), a3, voffA);
;             PG8_WAIT_V(8); PG8_WAIT_L(0); PG8_BAR; PG8_MMA(1, 0, At, B0); PG8_MMA(1, 1, At, B1); PG8_BAR; PG8_SCHED;
;             } else {
;             PG8_LDB(B0, 0, 0); PG8_SCHED; PG8_LDA(At, 0, 0); PG8_STAGE(PG8_SA(1, 1), a1 + hstep, voffA);
;             PG8_WAIT_L(8); PG8_BAR; PG8_WAIT_L(0); PG8_MMA(0, 0, At, B0); PG8_BAR; PG8_SCHED;
;             PG8_LDB(B1, 0, 1); PG8_STAGE(PG8_SB(0, 0), b2, voffB);
;             PG8_BAR; PG8_WAIT_L(0); PG8_MMA(0, 1, At, B1); PG8_BAR;
;             PG8_LDA(At, 0, 1); PG8_STAGE(PG8_SA(0, 0), a2, voffA);
;             PG8_BAR; PG8_WAIT_L(0); PG8_MMA(1, 0, At, B0); PG8_BAR; PG8_SCHED;
;             PG8_STAGE(PG8_SB(0, 1), b2 + hstep, voffB);
;             PG8_WAIT_V(6); PG8_BAR; PG8_MMA(1, 1, At, B1); PG8_BAR;
;             PG8_LDB(B0, 1, 0); PG8_SCHED; PG8_LDA(At, 1, 0); PG8_STAGE(PG8_SA(0, 1), a2 + hstep, voffA);
;             PG8_WAIT_L(8); PG8_BAR; PG8_WAIT_L(0); PG8_MMA(0, 0, At, B0); PG8_BAR; PG8_SCHED;
;             PG8_LDB(B1, 1, 1); PG8_STAGE(PG8_SB(1, 0), b3, voffB);
;             PG8_BAR; PG8_WAIT_L(0); PG8_MMA(0, 1, At, B1); PG8_BAR;
;             PG8_LDA(At, 1, 1); PG8_STAGE(PG8_SA(1, 0), a3, voffA);
;             PG8_BAR; PG8_WAIT_L(0); PG8_MMA(1, 0, At, B0); PG8_BAR; PG8_SCHED;
;             PG8_STAGE(PG8_SB(1, 1), b3 + hstep, voffB);
;             PG8_WAIT_V(6); PG8_BAR; PG8_MMA(1, 1, At, B1); PG8_BAR;
;             }
;         }
;         if constexpr (ALIGN_EPI) { if (wr == 0) PG8_BAR; }
;         if constexpr (!Epi::AFTER_DRAIN) { E(acc, cur, wr, wc, fr, fq); S.done(cur); }
;         if (!has_next) break;
; #pragma unroll
;         for (int a = 0; a < 2; ++a)
; #pragma unroll
;             for (int b = 0; b < 2; ++b)
; #pragma unroll
;                 for (int m = 0; m < 4; ++m)
; #pragma unroll
;                     for (int n = 0; n < 2; ++n) acc[a][b][m][n] = (f32x4){0.f, 0.f, 0.f, 0.f};
;         cur = nxt; cA = nA; cB = nB; ++ui;
	s_setprio 0
	s_add_i32 s30, s60, s39
	v_lshl_add_u64 v[216:217], v[216:217], 0, s[22:23]
	s_mov_b32 m0, s30
	ds_read_b128 v[182:185], v149 offset:49152
	ds_read_b128 v[188:191], v149 offset:50176
	ds_read_b128 v[192:195], v149 offset:51200
	ds_read_b128 v[196:199], v149 offset:52224
	ds_read_b128 v[200:203], v149 offset:53248
	ds_read_b128 v[204:207], v149 offset:54272
	ds_read_b128 v[208:211], v149 offset:55296
	ds_read_b128 v[212:215], v149 offset:56320
	global_load_lds_dwordx4 v[216:217], off
	s_add_i32 m0, s30, 0x2000
	s_add_u32 s28, s28, 0xb0080
	v_lshl_add_u64 v[216:217], v[218:219], 0, s[22:23]
	s_addc_u32 s29, s29, 0
	s_add_i32 s30, s61, s39
	global_load_lds_dwordx4 v[216:217], off
	v_lshl_add_u64 v[216:217], s[28:29], 0, v[130:131]
	s_mov_b32 m0, s30
	s_nop 0
	global_load_lds_dwordx4 v[216:217], off
	v_lshl_add_u64 v[216:217], s[28:29], 0, v[132:133]
	s_add_i32 m0, s30, 0x2000
	s_nop 0
	global_load_lds_dwordx4 v[216:217], off
	v_lshl_add_u64 v[216:217], v[220:221], 0, s[22:23]
	s_mov_b32 m0, s50
	s_nop 0
	global_load_lds_dwordx4 v[216:217], off
	v_lshl_add_u64 v[216:217], v[222:223], 0, s[22:23]
	s_mov_b32 m0, s51
	s_nop 0
	global_load_lds_dwordx4 v[216:217], off
	s_waitcnt vmcnt(8)
	s_waitcnt lgkmcnt(0)
	s_barrier
	s_setprio 1
	s_waitcnt lgkmcnt(0)
	v_mfma_f32_16x16x32_bf16 v[102:105], v[150:153], v[182:185], v[102:105]
	v_mfma_f32_16x16x32_bf16 v[98:101], v[158:161], v[182:185], v[98:101]
	v_mfma_f32_16x16x32_bf16 v[78:81], v[150:153], v[192:195], v[78:81]
	v_mfma_f32_16x16x32_bf16 v[70:73], v[158:161], v[192:195], v[70:73]
	v_mfma_f32_16x16x32_bf16 v[38:41], v[150:153], v[200:203], v[38:41]
	v_mfma_f32_16x16x32_bf16 v[34:37], v[158:161], v[200:203], v[34:37]
	v_mfma_f32_16x16x32_bf16 v[14:17], v[150:153], v[208:211], v[14:17]
	v_mfma_f32_16x16x32_bf16 v[10:13], v[158:161], v[208:211], v[10:13]
	v_mfma_f32_16x16x32_bf16 v[102:105], v[154:157], v[188:191], v[102:105]
	v_mfma_f32_16x16x32_bf16 v[98:101], v[162:165], v[188:191], v[98:101]
	v_mfma_f32_16x16x32_bf16 v[78:81], v[154:157], v[196:199], v[78:81]
	v_mfma_f32_16x16x32_bf16 v[70:73], v[162:165], v[196:199], v[70:73]
	v_mfma_f32_16x16x32_bf16 v[38:41], v[154:157], v[204:207], v[38:41]
	v_mfma_f32_16x16x32_bf16 v[34:37], v[162:165], v[204:207], v[34:37]
	v_mfma_f32_16x16x32_bf16 v[14:17], v[154:157], v[212:215], v[14:17]
	v_mfma_f32_16x16x32_bf16 v[10:13], v[162:165], v[212:215], v[10:13]
	v_mfma_f32_16x16x32_bf16 v[90:93], v[166:169], v[182:185], v[90:93]
	v_mfma_f32_16x16x32_bf16 v[82:85], v[174:177], v[182:185], v[82:85]
	v_mfma_f32_16x16x32_bf16 v[62:65], v[166:169], v[192:195], v[62:65]
	v_mfma_f32_16x16x32_bf16 v[58:61], v[174:177], v[192:195], v[58:61]
	v_mfma_f32_16x16x32_bf16 v[26:29], v[166:169], v[200:203], v[26:29]
	v_mfma_f32_16x16x32_bf16 v[22:25], v[174:177], v[200:203], v[22:25]
	v_mfma_f32_16x16x32_bf16 v[6:9], v[166:169], v[208:211], v[6:9]
	v_mfma_f32_16x16x32_bf16 v[2:5], v[174:177], v[208:211], v[2:5]
	v_mfma_f32_16x16x32_bf16 v[90:93], v[170:173], v[188:191], v[90:93]
	v_mfma_f32_16x16x32_bf16 v[82:85], v[178:181], v[188:191], v[82:85]
	v_mfma_f32_16x16x32_bf16 v[62:65], v[170:173], v[196:199], v[62:65]
	v_mfma_f32_16x16x32_bf16 v[58:61], v[178:181], v[196:199], v[58:61]
	v_mfma_f32_16x16x32_bf16 v[26:29], v[170:173], v[204:207], v[26:29]
	v_mfma_f32_16x16x32_bf16 v[22:25], v[178:181], v[204:207], v[22:25]
	v_mfma_f32_16x16x32_bf16 v[6:9], v[170:173], v[212:215], v[6:9]
	v_mfma_f32_16x16x32_bf16 v[2:5], v[178:181], v[212:215], v[2:5]
	s_barrier
	s_setprio 0
	s_add_i32 s59, s59, 2
	s_add_u32 s26, s26, 0x100
	s_addc_u32 s27, s27, 0
	s_cmp_gt_u32 s59, 41
	s_cbranch_scc0 .LBB0_252
	s_add_u32 s26, s57, 0xffffff00
	s_addc_u32 s27, s58, -1
	s_and_b64 vcc, exec, s[6:7]
	s_cbranch_vccnz .LBB0_255
	v_mov_b32_e32 v2, 0
	s_mov_b32 s18, s54
	s_mov_b32 s35, s55
	s_mov_b64 s[20:21], s[24:25]
	s_mov_b32 s49, s56
	v_mov_b32_e32 v3, v2
	v_mov_b32_e32 v4, v2
	v_mov_b32_e32 v5, v2
	v_mov_b32_e32 v6, v2
	v_mov_b32_e32 v7, v2
	v_mov_b32_e32 v8, v2
	v_mov_b32_e32 v9, v2
	v_mov_b32_e32 v22, v2
	v_mov_b32_e32 v23, v2
	v_mov_b32_e32 v24, v2
	v_mov_b32_e32 v25, v2
	v_mov_b32_e32 v26, v2
	v_mov_b32_e32 v27, v2
	v_mov_b32_e32 v28, v2
	v_mov_b32_e32 v29, v2
	v_mov_b32_e32 v58, v2
	v_mov_b32_e32 v59, v2
	v_mov_b32_e32 v60, v2
	v_mov_b32_e32 v61, v2
	v_mov_b32_e32 v62, v2
	v_mov_b32_e32 v63, v2
	v_mov_b32_e32 v64, v2
	v_mov_b32_e32 v65, v2
	v_mov_b32_e32 v82, v2
	v_mov_b32_e32 v83, v2
	v_mov_b32_e32 v84, v2
	v_mov_b32_e32 v85, v2
	v_mov_b32_e32 v90, v2
	v_mov_b32_e32 v91, v2
	v_mov_b32_e32 v92, v2
	v_mov_b32_e32 v93, v2
	v_mov_b32_e32 v10, v2
	v_mov_b32_e32 v11, v2
	v_mov_b32_e32 v12, v2
	v_mov_b32_e32 v13, v2
	v_mov_b32_e32 v14, v2
	v_mov_b32_e32 v15, v2
	v_mov_b32_e32 v16, v2
	v_mov_b32_e32 v17, v2
	v_mov_b32_e32 v34, v2
	v_mov_b32_e32 v35, v2
	v_mov_b32_e32 v36, v2
	v_mov_b32_e32 v37, v2
	v_mov_b32_e32 v38, v2
	v_mov_b32_e32 v39, v2
	v_mov_b32_e32 v40, v2
	v_mov_b32_e32 v41, v2
	v_mov_b32_e32 v70, v2
	v_mov_b32_e32 v71, v2
	v_mov_b32_e32 v72, v2
	v_mov_b32_e32 v73, v2
	v_mov_b32_e32 v78, v2
	v_mov_b32_e32 v79, v2
	v_mov_b32_e32 v80, v2
	v_mov_b32_e32 v81, v2
	v_mov_b32_e32 v98, v2
	v_mov_b32_e32 v99, v2
	v_mov_b32_e32 v100, v2
	v_mov_b32_e32 v101, v2
	v_mov_b32_e32 v102, v2
	v_mov_b32_e32 v103, v2
	v_mov_b32_e32 v104, v2
	v_mov_b32_e32 v105, v2
	v_mov_b32_e32 v54, v2
	v_mov_b32_e32 v55, v2
	v_mov_b32_e32 v56, v2
	v_mov_b32_e32 v57, v2
	v_mov_b32_e32 v94, v2
	v_mov_b32_e32 v95, v2
	v_mov_b32_e32 v96, v2
	v_mov_b32_e32 v97, v2
	v_mov_b32_e32 v46, v2
	v_mov_b32_e32 v47, v2
	v_mov_b32_e32 v48, v2
	v_mov_b32_e32 v49, v2
	v_mov_b32_e32 v74, v2
	v_mov_b32_e32 v75, v2
	v_mov_b32_e32 v76, v2
	v_mov_b32_e32 v77, v2
	v_mov_b32_e32 v30, v2
	v_mov_b32_e32 v31, v2
	v_mov_b32_e32 v32, v2
	v_mov_b32_e32 v33, v2
	v_mov_b32_e32 v50, v2
	v_mov_b32_e32 v51, v2
	v_mov_b32_e32 v52, v2
	v_mov_b32_e32 v53, v2
	v_mov_b32_e32 v18, v2
	v_mov_b32_e32 v19, v2
	v_mov_b32_e32 v20, v2
	v_mov_b32_e32 v21, v2
	v_mov_b32_e32 v42, v2
	v_mov_b32_e32 v43, v2
	v_mov_b32_e32 v44, v2
	v_mov_b32_e32 v45, v2
	v_mov_b32_e32 v118, v2
	v_mov_b32_e32 v119, v2
	v_mov_b32_e32 v120, v2
	v_mov_b32_e32 v121, v2
	v_mov_b32_e32 v122, v2
	v_mov_b32_e32 v123, v2
	v_mov_b32_e32 v124, v2
	v_mov_b32_e32 v125, v2
	v_mov_b32_e32 v110, v2
	v_mov_b32_e32 v111, v2
	v_mov_b32_e32 v112, v2
	v_mov_b32_e32 v113, v2
	v_mov_b32_e32 v126, v2
	v_mov_b32_e32 v127, v2
	v_mov_b32_e32 v128, v2
	v_mov_b32_e32 v129, v2
	v_mov_b32_e32 v86, v2
	v_mov_b32_e32 v87, v2
	v_mov_b32_e32 v88, v2
	v_mov_b32_e32 v89, v2
	v_mov_b32_e32 v114, v2
	v_mov_b32_e32 v115, v2
	v_mov_b32_e32 v116, v2
	v_mov_b32_e32 v117, v2
	v_mov_b32_e32 v66, v2
	v_mov_b32_e32 v67, v2
	v_mov_b32_e32 v68, v2
	v_mov_b32_e32 v69, v2
	v_mov_b32_e32 v106, v2
	v_mov_b32_e32 v107, v2
	v_mov_b32_e32 v108, v2
	v_mov_b32_e32 v109, v2
	s_andn2_b64 vcc, exec, s[4:5]
	s_cbranch_vccnz .LBB0_256
	s_branch .LBB0_257

; #define PG8_STAGE(bufoff, gbase, voff) do { _Pragma("unroll") for (int _i = 0; _i < 2; ++_i) \
;         __builtin_amdgcn_global_load_lds((const unsigned*)((const char*)(gbase) + (voff)[_i]), (PG8_LAS unsigned*)(lds + (bufoff) + ldsw + _i * 8192), 16, 0, 0); } while (0)
; #define PG8_LDA(dst, b, h) do { _Pragma("unroll") for (int m = 0; m < 4; ++m) _Pragma("unroll") for (int k = 0; k < 2; ++k) dst[m][k] = *(const PG8_LAS bf16x8*)(lds + PG8_SA(b, h) + aoff + m * 2048 + k * 1024); } while (0)
; #define PG8_LDB(dst, b, h) do { _Pragma("unroll") for (int n = 0; n < 2; ++n) _Pragma("unroll") for (int k = 0; k < 2; ++k) dst[n][k] = *(const PG8_LAS bf16x8*)(lds + PG8_SB(b, h) + boff + n * 2048 + k * 1024); } while (0)
; #define PG8_MMA(ai, bj, At, Bt) do { __builtin_amdgcn_s_setprio(1); _Pragma("unroll") for (int m = 0; m < 4; ++m) _Pragma("unroll") for (int n = 0; n < 2; ++n) _Pragma("unroll") for (int k = 0; k < 2; ++k) \
;         acc[ai][bj][m][n] = __builtin_amdgcn_mfma_f32_16x16x32_bf16(Bt[n][k], At[m][k], acc[ai][bj][m][n], 0, 0, 0); __builtin_amdgcn_s_setprio(0); } while (0)
; #define PG8_WAIT_V(n) asm volatile("s_waitcnt vmcnt(" #n ")" ::: "memory")
; #define PG8_WAIT_L(n) asm volatile("s_waitcnt lgkmcnt(" #n ")" ::: "memory")
; #define PG8_BAR __builtin_amdgcn_s_barrier()
; #define PG8_SCHED __builtin_amdgcn_sched_barrier(0)
; template <class Epi, class Sched, bool ALIGN_EPI = false, bool SP2 = false>
; __device__ __forceinline__ void gemm_phase(PG8_LAS unsigned char* lds, const Gemm g, const Sched& S, const Epi& E) {
;     ...
;             const bool last = (t == nt - 2);
;             const char* a1 = cA + (size_t)(t + 1) * kstep;
;             const char* a2 = last ? nA : cA + (size_t)(t + 2) * kstep; const char* b2 = last ? nB : cB + (size_t)(t + 2) * kstep;
;             const char* a3 = a2 + kstep; const char* b3 = b2 + kstep;
;             if (last && has_next) S.a_ready(nxt);
;             if constexpr (SP2) {
;             PG8_LDB(B0, 0, 0); PG8_LDB(B1, 0, 1); PG8_SCHED; PG8_LDA(At, 0, 0); PG8_STAGE(PG8_SA(1, 1), a1 + hstep, voffA);
;             PG8_WAIT_V(8); PG8_WAIT_L(0); PG8_BAR; PG8_MMA(0, 0, At, B0); PG8_MMA(0, 1, At, B1); PG8_BAR; PG8_SCHED;
;             PG8_LDA(At, 0, 1); PG8_STAGE(PG8_SB(0, 0), b2, voffB); PG8_STAGE(PG8_SB(0, 1), b2 + hstep, voffB); PG8_STAGE(PG8_SA(0, 0), a2, voffA);
.LBB0_319:
	v_add_u32_e32 v162, s52, v148
	v_add_u32_e32 v178, s53, v148
	s_add_u32 s26, s18, s24
	ds_read_b128 v[150:153], v162
	ds_read_b128 v[154:157], v162 offset:1024
	ds_read_b128 v[158:161], v162 offset:2048
	ds_read_b128 v[162:165], v162 offset:3072
	ds_read_b128 v[166:169], v178
	ds_read_b128 v[170:173], v178 offset:1024
	ds_read_b128 v[174:177], v178 offset:2048
	ds_read_b128 v[178:181], v178 offset:3072
	s_addc_u32 s27, s19, s25
	s_add_u32 s26, s26, 0x100
	s_addc_u32 s27, s27, 0
	s_add_u32 s60, s57, s24
	s_addc_u32 s61, s58, s25
	s_cmpk_eq_i32 s24, 0x1500
	s_cselect_b32 s29, s23, s27
	s_cselect_b32 s28, s22, s26
	s_cselect_b32 s27, s9, s61
	s_cselect_b32 s26, s8, s60
	v_lshl_add_u64 v[216:217], v[142:143], 0, s[24:25]
	s_add_i32 m0, s40, 0xc000
	ds_read_b128 v[182:185], v149
	ds_read_b128 v[188:191], v149 offset:1024
	ds_read_b128 v[192:195], v149 offset:2048
	ds_read_b128 v[196:199], v149 offset:3072
	ds_read_b128 v[200:203], v149 offset:4096
	ds_read_b128 v[204:207], v149 offset:5120
	ds_read_b128 v[208:211], v149 offset:6144
	ds_read_b128 v[212:215], v149 offset:7168
	global_load_lds_dwordx4 v[216:217], off
	v_lshl_add_u64 v[216:217], v[144:145], 0, s[24:25]
	s_add_i32 m0, s40, 0xe000
	s_nop 0
	global_load_lds_dwordx4 v[216:217], off
	s_waitcnt vmcnt(8)
	s_waitcnt lgkmcnt(0)
	s_barrier
	s_setprio 1
	s_waitcnt lgkmcnt(0)
	v_mfma_f32_16x16x32_bf16 v[106:109], v[150:153], v[182:185], v[106:109]
	v_mfma_f32_16x16x32_bf16 v[66:69], v[158:161], v[182:185], v[66:69]
	v_mfma_f32_16x16x32_bf16 v[114:117], v[150:153], v[192:195], v[114:117]
	v_mfma_f32_16x16x32_bf16 v[86:89], v[158:161], v[192:195], v[86:89]
	v_mfma_f32_16x16x32_bf16 v[126:129], v[150:153], v[200:203], v[126:129]
	v_mfma_f32_16x16x32_bf16 v[110:113], v[158:161], v[200:203], v[110:113]
	v_mfma_f32_16x16x32_bf16 v[122:125], v[150:153], v[208:211], v[122:125]
	v_mfma_f32_16x16x32_bf16 v[118:121], v[158:161], v[208:211], v[118:121]
	v_mfma_f32_16x16x32_bf16 v[106:109], v[154:157], v[188:191], v[106:109]
	v_mfma_f32_16x16x32_bf16 v[66:69], v[162:165], v[188:191], v[66:69]
	v_mfma_f32_16x16x32_bf16 v[114:117], v[154:157], v[196:199], v[114:117]
	v_mfma_f32_16x16x32_bf16 v[86:89], v[162:165], v[196:199], v[86:89]
	v_mfma_f32_16x16x32_bf16 v[126:129], v[154:157], v[204:207], v[126:129]
	v_mfma_f32_16x16x32_bf16 v[110:113], v[162:165], v[204:207], v[110:113]
	v_mfma_f32_16x16x32_bf16 v[122:125], v[154:157], v[212:215], v[122:125]
	v_mfma_f32_16x16x32_bf16 v[118:121], v[162:165], v[212:215], v[118:121]
	v_mfma_f32_16x16x32_bf16 v[42:45], v[166:169], v[182:185], v[42:45]
	v_mfma_f32_16x16x32_bf16 v[18:21], v[174:177], v[182:185], v[18:21]
	v_mfma_f32_16x16x32_bf16 v[50:53], v[166:169], v[192:195], v[50:53]
	v_mfma_f32_16x16x32_bf16 v[30:33], v[174:177], v[192:195], v[30:33]
	v_mfma_f32_16x16x32_bf16 v[70:73], v[166:169], v[200:203], v[70:73]
	v_mfma_f32_16x16x32_bf16 v[46:49], v[174:177], v[200:203], v[46:49]
	v_mfma_f32_16x16x32_bf16 v[94:97], v[166:169], v[208:211], v[94:97]
	v_mfma_f32_16x16x32_bf16 v[54:57], v[174:177], v[208:211], v[54:57]
	v_mfma_f32_16x16x32_bf16 v[42:45], v[170:173], v[188:191], v[42:45]
	v_mfma_f32_16x16x32_bf16 v[18:21], v[178:181], v[188:191], v[18:21]
	v_mfma_f32_16x16x32_bf16 v[50:53], v[170:173], v[196:199], v[50:53]
	v_mfma_f32_16x16x32_bf16 v[30:33], v[178:181], v[196:199], v[30:33]
	v_mfma_f32_16x16x32_bf16 v[70:73], v[170:173], v[204:207], v[70:73]
	v_mfma_f32_16x16x32_bf16 v[46:49], v[178:181], v[204:207], v[46:49]
	v_mfma_f32_16x16x32_bf16 v[94:97], v[170:173], v[212:215], v[94:97]
	v_mfma_f32_16x16x32_bf16 v[54:57], v[178:181], v[212:215], v[54:57]
	s_barrier
	s_setprio 0
	s_add_i32 s60, s52, s39
	v_lshl_add_u64 v[216:217], s[26:27], 0, v[130:131]
	s_mov_b32 m0, s60
	ds_read_b128 v[182:185], v149 offset:16384
	ds_read_b128 v[188:191], v149 offset:17408
	ds_read_b128 v[192:195], v149 offset:18432
	ds_read_b128 v[196:199], v149 offset:19456
	ds_read_b128 v[200:203], v149 offset:20480
	ds_read_b128 v[204:207], v149 offset:21504
	ds_read_b128 v[208:211], v149 offset:22528
	ds_read_b128 v[212:215], v149 offset:23552
	global_load_lds_dwordx4 v[216:217], off
	s_add_i32 m0, s60, 0x2000
	s_add_u32 s60, s26, 0xb0000
	v_lshl_add_u64 v[218:219], s[26:27], 0, v[132:133]
	s_addc_u32 s61, s27, 0
	s_add_i32 s62, s53, s39
	global_load_lds_dwordx4 v[218:219], off
	v_lshl_add_u64 v[220:221], s[60:61], 0, v[130:131]
	s_mov_b32 m0, s62
	v_lshl_add_u64 v[222:223], s[28:29], 0, v[132:133]
	global_load_lds_dwordx4 v[220:221], off
	v_lshl_add_u64 v[220:221], s[60:61], 0, v[132:133]
	s_add_i32 m0, s62, 0x2000
	s_nop 0
	global_load_lds_dwordx4 v[220:221], off
	v_lshl_add_u64 v[220:221], s[28:29], 0, v[130:131]
	s_mov_b32 m0, s40
	s_nop 0
	global_load_lds_dwordx4 v[220:221], off
	s_mov_b32 m0, s41
	s_nop 0
	global_load_lds_dwordx4 v[222:223], off
	s_waitcnt vmcnt(8)
	s_waitcnt lgkmcnt(0)
	s_barrier
; #define PG8_STAGE(bufoff, gbase, voff) do { _Pragma("unroll") for (int _i = 0; _i < 2; ++_i) \
;         __builtin_amdgcn_global_load_lds((const unsigned*)((const char*)(gbase) + (voff)[_i]), (PG8_LAS unsigned*)(lds + (bufoff) + ldsw + _i * 8192), 16, 0, 0); } while (0)
; #define PG8_LDA(dst, b, h) do { _Pragma("unroll") for (int m = 0; m < 4; ++m) _Pragma("unroll") for (int k = 0; k < 2; ++k) dst[m][k] = *(const PG8_LAS bf16x8*)(lds + PG8_SA(b, h) + aoff + m * 2048 + k * 1024); } while (0)
; #define PG8_LDB(dst, b, h) do { _Pragma("unroll") for (int n = 0; n < 2; ++n) _Pragma("unroll") for (int k = 0; k < 2; ++k) dst[n][k] = *(const PG8_LAS bf16x8*)(lds + PG8_SB(b, h) + boff + n * 2048 + k * 1024); } while (0)
; #define PG8_MMA(ai, bj, At, Bt) do { __builtin_amdgcn_s_setprio(1); _Pragma("unroll") for (int m = 0; m < 4; ++m) _Pragma("unroll") for (int n = 0; n < 2; ++n) _Pragma("unroll") for (int k = 0; k < 2; ++k) \
;         acc[ai][bj][m][n] = __builtin_amdgcn_mfma_f32_16x16x32_bf16(Bt[n][k], At[m][k], acc[ai][bj][m][n], 0, 0, 0); __builtin_amdgcn_s_setprio(0); } while (0)
; #define PG8_WAIT_V(n) asm volatile("s_waitcnt vmcnt(" #n ")" ::: "memory")
; #define PG8_WAIT_L(n) asm volatile("s_waitcnt lgkmcnt(" #n ")" ::: "memory")
; #define PG8_BAR __builtin_amdgcn_s_barrier()
; #define PG8_SCHED __builtin_amdgcn_sched_barrier(0)
; template <class Epi, class Sched, bool ALIGN_EPI = false, bool SP2 = false>
; __device__ __forceinline__ void gemm_phase(PG8_LAS unsigned char* lds, const Gemm g, const Sched& S, const Epi& E) {
;     ...
;             PG8_WAIT_V(8); PG8_WAIT_L(0); PG8_BAR; PG8_MMA(1, 0, At, B0); PG8_MMA(1, 1, At, B1); PG8_BAR; PG8_SCHED;
;             PG8_LDB(B0, 1, 0); PG8_LDB(B1, 1, 1); PG8_SCHED; PG8_LDA(At, 1, 0); PG8_STAGE(PG8_SA(0, 1), a2 + hstep, voffA);
;             PG8_WAIT_V(8); PG8_WAIT_L(0); PG8_BAR; PG8_MMA(0, 0, At, B0); PG8_MMA(0, 1, At, B1); PG8_BAR; PG8_SCHED;
	s_setprio 1
	s_waitcnt lgkmcnt(0)
	v_mfma_f32_16x16x32_bf16 v[102:105], v[150:153], v[182:185], v[102:105]
	v_mfma_f32_16x16x32_bf16 v[98:101], v[158:161], v[182:185], v[98:101]
	v_mfma_f32_16x16x32_bf16 v[78:81], v[150:153], v[192:195], v[78:81]
	v_mfma_f32_16x16x32_bf16 v[74:77], v[158:161], v[192:195], v[74:77]
	v_mfma_f32_16x16x32_bf16 v[38:41], v[150:153], v[200:203], v[38:41]
	v_mfma_f32_16x16x32_bf16 v[34:37], v[158:161], v[200:203], v[34:37]
	v_mfma_f32_16x16x32_bf16 v[14:17], v[150:153], v[208:211], v[14:17]
	v_mfma_f32_16x16x32_bf16 v[10:13], v[158:161], v[208:211], v[10:13]
	v_mfma_f32_16x16x32_bf16 v[102:105], v[154:157], v[188:191], v[102:105]
	v_mfma_f32_16x16x32_bf16 v[98:101], v[162:165], v[188:191], v[98:101]
	v_mfma_f32_16x16x32_bf16 v[78:81], v[154:157], v[196:199], v[78:81]
	v_mfma_f32_16x16x32_bf16 v[74:77], v[162:165], v[196:199], v[74:77]
	v_mfma_f32_16x16x32_bf16 v[38:41], v[154:157], v[204:207], v[38:41]
	v_mfma_f32_16x16x32_bf16 v[34:37], v[162:165], v[204:207], v[34:37]
	v_mfma_f32_16x16x32_bf16 v[14:17], v[154:157], v[212:215], v[14:17]
	v_mfma_f32_16x16x32_bf16 v[10:13], v[162:165], v[212:215], v[10:13]
	v_mfma_f32_16x16x32_bf16 v[90:93], v[166:169], v[182:185], v[90:93]
	v_mfma_f32_16x16x32_bf16 v[82:85], v[174:177], v[182:185], v[82:85]
	v_mfma_f32_16x16x32_bf16 v[62:65], v[166:169], v[192:195], v[62:65]
	v_mfma_f32_16x16x32_bf16 v[58:61], v[174:177], v[192:195], v[58:61]
	v_mfma_f32_16x16x32_bf16 v[26:29], v[166:169], v[200:203], v[26:29]
	v_mfma_f32_16x16x32_bf16 v[22:25], v[174:177], v[200:203], v[22:25]
	v_mfma_f32_16x16x32_bf16 v[6:9], v[166:169], v[208:211], v[6:9]
	v_mfma_f32_16x16x32_bf16 v[2:5], v[174:177], v[208:211], v[2:5]
	v_mfma_f32_16x16x32_bf16 v[90:93], v[170:173], v[188:191], v[90:93]
	v_mfma_f32_16x16x32_bf16 v[82:85], v[178:181], v[188:191], v[82:85]
	v_mfma_f32_16x16x32_bf16 v[62:65], v[170:173], v[196:199], v[62:65]
	v_mfma_f32_16x16x32_bf16 v[58:61], v[178:181], v[196:199], v[58:61]
	v_mfma_f32_16x16x32_bf16 v[26:29], v[170:173], v[204:207], v[26:29]
	v_mfma_f32_16x16x32_bf16 v[22:25], v[178:181], v[204:207], v[22:25]
	v_mfma_f32_16x16x32_bf16 v[6:9], v[170:173], v[212:215], v[6:9]
	v_mfma_f32_16x16x32_bf16 v[2:5], v[178:181], v[212:215], v[2:5]
	s_barrier
	s_setprio 0
	s_add_i32 s60, 0, 0x18000
	s_add_i32 s61, 0, 0x1c000
	v_add_u32_e32 v162, s60, v148
	v_add_u32_e32 v178, s61, v148
	ds_read_b128 v[150:153], v162
	ds_read_b128 v[154:157], v162 offset:1024
	ds_read_b128 v[158:161], v162 offset:2048
	ds_read_b128 v[162:165], v162 offset:3072
	ds_read_b128 v[166:169], v178
	ds_read_b128 v[170:173], v178 offset:1024
	ds_read_b128 v[174:177], v178 offset:2048
	ds_read_b128 v[178:181], v178 offset:3072
	s_add_u32 s28, s28, 0xb0000
	s_addc_u32 s29, s29, 0
	s_mov_b32 m0, s42
	v_lshl_add_u64 v[224:225], s[28:29], 0, v[130:131]
	ds_read_b128 v[182:185], v149 offset:32768
	ds_read_b128 v[188:191], v149 offset:33792
	ds_read_b128 v[192:195], v149 offset:34816
	ds_read_b128 v[196:199], v149 offset:35840
	ds_read_b128 v[200:203], v149 offset:36864
	ds_read_b128 v[204:207], v149 offset:37888
	ds_read_b128 v[208:211], v149 offset:38912
	ds_read_b128 v[212:215], v149 offset:39936
	global_load_lds_dwordx4 v[224:225], off
	v_lshl_add_u64 v[224:225], s[28:29], 0, v[132:133]
	s_mov_b32 m0, s43
	s_nop 0
	global_load_lds_dwordx4 v[224:225], off
	s_waitcnt vmcnt(8)
	s_waitcnt lgkmcnt(0)
	s_barrier
	s_setprio 1
	s_waitcnt lgkmcnt(0)
	v_mfma_f32_16x16x32_bf16 v[106:109], v[150:153], v[182:185], v[106:109]
	v_mfma_f32_16x16x32_bf16 v[66:69], v[158:161], v[182:185], v[66:69]
	v_mfma_f32_16x16x32_bf16 v[114:117], v[150:153], v[192:195], v[114:117]
	v_mfma_f32_16x16x32_bf16 v[86:89], v[158:161], v[192:195], v[86:89]
	v_mfma_f32_16x16x32_bf16 v[126:129], v[150:153], v[200:203], v[126:129]
	v_mfma_f32_16x16x32_bf16 v[110:113], v[158:161], v[200:203], v[110:113]
	v_mfma_f32_16x16x32_bf16 v[122:125], v[150:153], v[208:211], v[122:125]
	v_mfma_f32_16x16x32_bf16 v[118:121], v[158:161], v[208:211], v[118:121]
	v_mfma_f32_16x16x32_bf16 v[106:109], v[154:157], v[188:191], v[106:109]
	v_mfma_f32_16x16x32_bf16 v[66:69], v[162:165], v[188:191], v[66:69]
	v_mfma_f32_16x16x32_bf16 v[114:117], v[154:157], v[196:199], v[114:117]
	v_mfma_f32_16x16x32_bf16 v[86:89], v[162:165], v[196:199], v[86:89]
	v_mfma_f32_16x16x32_bf16 v[126:129], v[154:157], v[204:207], v[126:129]
	v_mfma_f32_16x16x32_bf16 v[110:113], v[162:165], v[204:207], v[110:113]
	v_mfma_f32_16x16x32_bf16 v[122:125], v[154:157], v[212:215], v[122:125]
	v_mfma_f32_16x16x32_bf16 v[118:121], v[162:165], v[212:215], v[118:121]
	v_mfma_f32_16x16x32_bf16 v[42:45], v[166:169], v[182:185], v[42:45]
	v_mfma_f32_16x16x32_bf16 v[18:21], v[174:177], v[182:185], v[18:21]
	v_mfma_f32_16x16x32_bf16 v[50:53], v[166:169], v[192:195], v[50:53]
	v_mfma_f32_16x16x32_bf16 v[30:33], v[174:177], v[192:195], v[30:33]
	v_mfma_f32_16x16x32_bf16 v[70:73], v[166:169], v[200:203], v[70:73]
	v_mfma_f32_16x16x32_bf16 v[46:49], v[174:177], v[200:203], v[46:49]
	v_mfma_f32_16x16x32_bf16 v[94:97], v[166:169], v[208:211], v[94:97]
	v_mfma_f32_16x16x32_bf16 v[54:57], v[174:177], v[208:211], v[54:57]
	v_mfma_f32_16x16x32_bf16 v[42:45], v[170:173], v[188:191], v[42:45]
	v_mfma_f32_16x16x32_bf16 v[18:21], v[178:181], v[188:191], v[18:21]
	v_mfma_f32_16x16x32_bf16 v[50:53], v[170:173], v[196:199], v[50:53]
	v_mfma_f32_16x16x32_bf16 v[30:33], v[178:181], v[196:199], v[30:33]
	v_mfma_f32_16x16x32_bf16 v[70:73], v[170:173], v[204:207], v[70:73]
	v_mfma_f32_16x16x32_bf16 v[46:49], v[178:181], v[204:207], v[46:49]
	v_mfma_f32_16x16x32_bf16 v[94:97], v[170:173], v[212:215], v[94:97]
	v_mfma_f32_16x16x32_bf16 v[54:57], v[178:181], v[212:215], v[54:57]
	s_barrier
; #define PG8_WAIT_V(n) asm volatile("s_waitcnt vmcnt(" #n ")" ::: "memory")
; #define PG8_BAR __builtin_amdgcn_s_barrier()
; template <class Epi, class Sched, bool ALIGN_EPI = false, bool SP2 = false>
; __device__ __forceinline__ void gemm_phase(PG8_LAS unsigned char* lds, const Gemm g, const Sched& S, const Epi& E) {
;     ...
;             PG8_LDA(At, 1, 1); PG8_STAGE(PG8_SB(1, 0), b3, voffB); PG8_STAGE(PG8_SB(1, 1), b3 + hstep, voffB); PG8_STAGE(PG8_SA(1, 0), a3, voffA);
;             PG8_WAIT_V(8); PG8_WAIT_L(0); PG8_BAR; PG8_MMA(1, 0, At, B0); PG8_MMA(1, 1, At, B1); PG8_BAR; PG8_SCHED;
;             } else {
;             PG8_LDB(B0, 0, 0); PG8_SCHED; PG8_LDA(At, 0, 0); PG8_STAGE(PG8_SA(1, 1), a1 + hstep, voffA);
;             PG8_WAIT_L(8); PG8_BAR; PG8_WAIT_L(0); PG8_MMA(0, 0, At, B0); PG8_BAR; PG8_SCHED;
;             PG8_LDB(B1, 0, 1); PG8_STAGE(PG8_SB(0, 0), b2, voffB);
;             PG8_BAR; PG8_WAIT_L(0); PG8_MMA(0, 1, At, B1); PG8_BAR;
;             PG8_LDA(At, 0, 1); PG8_STAGE(PG8_SA(0, 0), a2, voffA);
;             PG8_BAR; PG8_WAIT_L(0); PG8_MMA(1, 0, At, B0); PG8_BAR; PG8_SCHED;
;             PG8_STAGE(PG8_SB(0, 1), b2 + hstep, voffB);
;             PG8_WAIT_V(6); PG8_BAR; PG8_MMA(1, 1, At, B1); PG8_BAR;
;             PG8_LDB(B0, 1, 0); PG8_SCHED; PG8_LDA(At, 1, 0); PG8_STAGE(PG8_SA(0, 1), a2 + hstep, voffA);
;             PG8_WAIT_L(8); PG8_BAR; PG8_WAIT_L(0); PG8_MMA(0, 0, At, B0); PG8_BAR; PG8_SCHED;
;             PG8_LDB(B1, 1, 1); PG8_STAGE(PG8_SB(1, 0), b3, voffB);
;             PG8_BAR; PG8_WAIT_L(0); PG8_MMA(0, 1, At, B1); PG8_BAR;
;             PG8_LDA(At, 1, 1); PG8_STAGE(PG8_SA(1, 0), a3, voffA);
;             PG8_BAR; PG8_WAIT_L(0); PG8_MMA(1, 0, At, B0); PG8_BAR; PG8_SCHED;
;             PG8_STAGE(PG8_SB(1, 1), b3 + hstep, voffB);
;             PG8_WAIT_V(6); PG8_BAR; PG8_MMA(1, 1, At, B1); PG8_BAR;
;             }
;         }
;         if constexpr (ALIGN_EPI) { if (wr == 0) PG8_BAR; }
;         if constexpr (!Epi::AFTER_DRAIN) { E(acc, cur, wr, wc, fr, fq); S.done(cur); }
;         if (!has_next) break;
; #pragma unroll
;         for (int a = 0; a < 2; ++a)
; #pragma unroll
;             for (int b = 0; b < 2; ++b)
; #pragma unroll
;                 for (int m = 0; m < 4; ++m)
; #pragma unroll
;                     for (int n = 0; n < 2; ++n) acc[a][b][m][n] = (f32x4){0.f, 0.f, 0.f, 0.f};
;         cur = nxt; cA = nA; cB = nB; ++ui;
	s_setprio 0
	s_add_i32 s28, s60, s39
	v_lshl_add_u64 v[216:217], v[216:217], 0, s[20:21]
	s_mov_b32 m0, s28
	ds_read_b128 v[182:185], v149 offset:49152
	ds_read_b128 v[188:191], v149 offset:50176
	ds_read_b128 v[192:195], v149 offset:51200
	ds_read_b128 v[196:199], v149 offset:52224
	ds_read_b128 v[200:203], v149 offset:53248
	ds_read_b128 v[204:207], v149 offset:54272
	ds_read_b128 v[208:211], v149 offset:55296
	ds_read_b128 v[212:215], v149 offset:56320
	global_load_lds_dwordx4 v[216:217], off
	s_add_i32 m0, s28, 0x2000
	s_add_u32 s26, s26, 0xb0080
	v_lshl_add_u64 v[216:217], v[218:219], 0, s[20:21]
	s_addc_u32 s27, s27, 0
	s_add_i32 s28, s61, s39
	global_load_lds_dwordx4 v[216:217], off
	v_lshl_add_u64 v[216:217], s[26:27], 0, v[130:131]
	s_mov_b32 m0, s28
	s_nop 0
	global_load_lds_dwordx4 v[216:217], off
	v_lshl_add_u64 v[216:217], s[26:27], 0, v[132:133]
	s_add_i32 m0, s28, 0x2000
	s_nop 0
	global_load_lds_dwordx4 v[216:217], off
	v_lshl_add_u64 v[216:217], v[220:221], 0, s[20:21]
	s_mov_b32 m0, s50
	s_nop 0
	global_load_lds_dwordx4 v[216:217], off
	v_lshl_add_u64 v[216:217], v[222:223], 0, s[20:21]
	s_mov_b32 m0, s51
	s_nop 0
	global_load_lds_dwordx4 v[216:217], off
	s_waitcnt vmcnt(8)
	s_waitcnt lgkmcnt(0)
	s_barrier
	s_setprio 1
	s_waitcnt lgkmcnt(0)
	v_mfma_f32_16x16x32_bf16 v[102:105], v[150:153], v[182:185], v[102:105]
	v_mfma_f32_16x16x32_bf16 v[98:101], v[158:161], v[182:185], v[98:101]
	v_mfma_f32_16x16x32_bf16 v[78:81], v[150:153], v[192:195], v[78:81]
	v_mfma_f32_16x16x32_bf16 v[74:77], v[158:161], v[192:195], v[74:77]
	v_mfma_f32_16x16x32_bf16 v[38:41], v[150:153], v[200:203], v[38:41]
	v_mfma_f32_16x16x32_bf16 v[34:37], v[158:161], v[200:203], v[34:37]
	v_mfma_f32_16x16x32_bf16 v[14:17], v[150:153], v[208:211], v[14:17]
	v_mfma_f32_16x16x32_bf16 v[10:13], v[158:161], v[208:211], v[10:13]
	v_mfma_f32_16x16x32_bf16 v[102:105], v[154:157], v[188:191], v[102:105]
	v_mfma_f32_16x16x32_bf16 v[98:101], v[162:165], v[188:191], v[98:101]
	v_mfma_f32_16x16x32_bf16 v[78:81], v[154:157], v[196:199], v[78:81]
	v_mfma_f32_16x16x32_bf16 v[74:77], v[162:165], v[196:199], v[74:77]
	v_mfma_f32_16x16x32_bf16 v[38:41], v[154:157], v[204:207], v[38:41]
	v_mfma_f32_16x16x32_bf16 v[34:37], v[162:165], v[204:207], v[34:37]
	v_mfma_f32_16x16x32_bf16 v[14:17], v[154:157], v[212:215], v[14:17]
	v_mfma_f32_16x16x32_bf16 v[10:13], v[162:165], v[212:215], v[10:13]
	v_mfma_f32_16x16x32_bf16 v[90:93], v[166:169], v[182:185], v[90:93]
	v_mfma_f32_16x16x32_bf16 v[82:85], v[174:177], v[182:185], v[82:85]
	v_mfma_f32_16x16x32_bf16 v[62:65], v[166:169], v[192:195], v[62:65]
	v_mfma_f32_16x16x32_bf16 v[58:61], v[174:177], v[192:195], v[58:61]
	v_mfma_f32_16x16x32_bf16 v[26:29], v[166:169], v[200:203], v[26:29]
	v_mfma_f32_16x16x32_bf16 v[22:25], v[174:177], v[200:203], v[22:25]
	v_mfma_f32_16x16x32_bf16 v[6:9], v[166:169], v[208:211], v[6:9]
	v_mfma_f32_16x16x32_bf16 v[2:5], v[174:177], v[208:211], v[2:5]
	v_mfma_f32_16x16x32_bf16 v[90:93], v[170:173], v[188:191], v[90:93]
	v_mfma_f32_16x16x32_bf16 v[82:85], v[178:181], v[188:191], v[82:85]
	v_mfma_f32_16x16x32_bf16 v[62:65], v[170:173], v[196:199], v[62:65]
	v_mfma_f32_16x16x32_bf16 v[58:61], v[178:181], v[196:199], v[58:61]
	v_mfma_f32_16x16x32_bf16 v[26:29], v[170:173], v[204:207], v[26:29]
	v_mfma_f32_16x16x32_bf16 v[22:25], v[178:181], v[204:207], v[22:25]
	v_mfma_f32_16x16x32_bf16 v[6:9], v[170:173], v[212:215], v[6:9]
	v_mfma_f32_16x16x32_bf16 v[2:5], v[178:181], v[212:215], v[2:5]
	s_barrier
	s_setprio 0
	s_add_i32 s59, s59, 2
	s_add_u32 s24, s24, 0x100
	s_addc_u32 s25, s25, 0
	s_cmp_gt_u32 s59, 41
	s_cbranch_scc0 .LBB0_319
	s_add_u32 s24, s57, 0xffffff00
	s_addc_u32 s25, s58, -1
	s_and_b64 vcc, exec, s[6:7]
	s_cbranch_vccnz .LBB0_322
	v_mov_b32_e32 v2, 0
	s_mov_b32 s16, s54
	s_mov_b32 s31, s55
	s_mov_b64 s[18:19], s[22:23]
	s_mov_b32 s49, s56
	v_mov_b32_e32 v3, v2
	v_mov_b32_e32 v4, v2
	v_mov_b32_e32 v5, v2
	v_mov_b32_e32 v6, v2
	v_mov_b32_e32 v7, v2
	v_mov_b32_e32 v8, v2
	v_mov_b32_e32 v9, v2
	v_mov_b32_e32 v22, v2
	v_mov_b32_e32 v23, v2
	v_mov_b32_e32 v24, v2
	v_mov_b32_e32 v25, v2
	v_mov_b32_e32 v26, v2
	v_mov_b32_e32 v27, v2
	v_mov_b32_e32 v28, v2
	v_mov_b32_e32 v29, v2
	v_mov_b32_e32 v58, v2
	v_mov_b32_e32 v59, v2
	v_mov_b32_e32 v60, v2
	v_mov_b32_e32 v61, v2
	v_mov_b32_e32 v62, v2
	v_mov_b32_e32 v63, v2
	v_mov_b32_e32 v64, v2
	v_mov_b32_e32 v65, v2
	v_mov_b32_e32 v82, v2
	v_mov_b32_e32 v83, v2
	v_mov_b32_e32 v84, v2
	v_mov_b32_e32 v85, v2
	v_mov_b32_e32 v90, v2
	v_mov_b32_e32 v91, v2
	v_mov_b32_e32 v92, v2
	v_mov_b32_e32 v93, v2
	v_mov_b32_e32 v10, v2
	v_mov_b32_e32 v11, v2
	v_mov_b32_e32 v12, v2
	v_mov_b32_e32 v13, v2
	v_mov_b32_e32 v14, v2
	v_mov_b32_e32 v15, v2
	v_mov_b32_e32 v16, v2
	v_mov_b32_e32 v17, v2
	v_mov_b32_e32 v34, v2
	v_mov_b32_e32 v35, v2
	v_mov_b32_e32 v36, v2
	v_mov_b32_e32 v37, v2
	v_mov_b32_e32 v38, v2
	v_mov_b32_e32 v39, v2
	v_mov_b32_e32 v40, v2
	v_mov_b32_e32 v41, v2
	v_mov_b32_e32 v74, v2
	v_mov_b32_e32 v75, v2
	v_mov_b32_e32 v76, v2
	v_mov_b32_e32 v77, v2
	v_mov_b32_e32 v78, v2
	v_mov_b32_e32 v79, v2
	v_mov_b32_e32 v80, v2
	v_mov_b32_e32 v81, v2
	v_mov_b32_e32 v98, v2
	v_mov_b32_e32 v99, v2
	v_mov_b32_e32 v100, v2
	v_mov_b32_e32 v101, v2
	v_mov_b32_e32 v102, v2
	v_mov_b32_e32 v103, v2
	v_mov_b32_e32 v104, v2
	v_mov_b32_e32 v105, v2
	v_mov_b32_e32 v54, v2
	v_mov_b32_e32 v55, v2
	v_mov_b32_e32 v56, v2
	v_mov_b32_e32 v57, v2
	v_mov_b32_e32 v94, v2
	v_mov_b32_e32 v95, v2
	v_mov_b32_e32 v96, v2
	v_mov_b32_e32 v97, v2
	v_mov_b32_e32 v46, v2
	v_mov_b32_e32 v47, v2
	v_mov_b32_e32 v48, v2
	v_mov_b32_e32 v49, v2
	v_mov_b32_e32 v70, v2
	v_mov_b32_e32 v71, v2
	v_mov_b32_e32 v72, v2
	v_mov_b32_e32 v73, v2
	v_mov_b32_e32 v30, v2
	v_mov_b32_e32 v31, v2
	v_mov_b32_e32 v32, v2
	v_mov_b32_e32 v33, v2
	v_mov_b32_e32 v50, v2
	v_mov_b32_e32 v51, v2
	v_mov_b32_e32 v52, v2
	v_mov_b32_e32 v53, v2
	v_mov_b32_e32 v18, v2
	v_mov_b32_e32 v19, v2
	v_mov_b32_e32 v20, v2
	v_mov_b32_e32 v21, v2
	v_mov_b32_e32 v42, v2
	v_mov_b32_e32 v43, v2
	v_mov_b32_e32 v44, v2
	v_mov_b32_e32 v45, v2
	v_mov_b32_e32 v118, v2
	v_mov_b32_e32 v119, v2
	v_mov_b32_e32 v120, v2
	v_mov_b32_e32 v121, v2
	v_mov_b32_e32 v122, v2
	v_mov_b32_e32 v123, v2
	v_mov_b32_e32 v124, v2
	v_mov_b32_e32 v125, v2
	v_mov_b32_e32 v110, v2
	v_mov_b32_e32 v111, v2
	v_mov_b32_e32 v112, v2
	v_mov_b32_e32 v113, v2
	v_mov_b32_e32 v126, v2
	v_mov_b32_e32 v127, v2
	v_mov_b32_e32 v128, v2
	v_mov_b32_e32 v129, v2
	v_mov_b32_e32 v86, v2
	v_mov_b32_e32 v87, v2
	v_mov_b32_e32 v88, v2
	v_mov_b32_e32 v89, v2
	v_mov_b32_e32 v114, v2
	v_mov_b32_e32 v115, v2
	v_mov_b32_e32 v116, v2
	v_mov_b32_e32 v117, v2
	v_mov_b32_e32 v66, v2
	v_mov_b32_e32 v67, v2
	v_mov_b32_e32 v68, v2
	v_mov_b32_e32 v69, v2
	v_mov_b32_e32 v106, v2
	v_mov_b32_e32 v107, v2
	v_mov_b32_e32 v108, v2
	v_mov_b32_e32 v109, v2
	s_andn2_b64 vcc, exec, s[4:5]
	s_cbranch_vccnz .LBB0_323
	s_branch .LBB0_324

; #define PG8_STAGE(bufoff, gbase, voff) do { _Pragma("unroll") for (int _i = 0; _i < 2; ++_i) \
;         __builtin_amdgcn_global_load_lds((const unsigned*)((const char*)(gbase) + (voff)[_i]), (PG8_LAS unsigned*)(lds + (bufoff) + ldsw + _i * 8192), 16, 0, 0); } while (0)
; #define PG8_LDA(dst, b, h) do { _Pragma("unroll") for (int m = 0; m < 4; ++m) _Pragma("unroll") for (int k = 0; k < 2; ++k) dst[m][k] = *(const PG8_LAS bf16x8*)(lds + PG8_SA(b, h) + aoff + m * 2048 + k * 1024); } while (0)
; #define PG8_LDB(dst, b, h) do { _Pragma("unroll") for (int n = 0; n < 2; ++n) _Pragma("unroll") for (int k = 0; k < 2; ++k) dst[n][k] = *(const PG8_LAS bf16x8*)(lds + PG8_SB(b, h) + boff + n * 2048 + k * 1024); } while (0)
; #define PG8_MMA(ai, bj, At, Bt) do { __builtin_amdgcn_s_setprio(1); _Pragma("unroll") for (int m = 0; m < 4; ++m) _Pragma("unroll") for (int n = 0; n < 2; ++n) _Pragma("unroll") for (int k = 0; k < 2; ++k) \
;         acc[ai][bj][m][n] = __builtin_amdgcn_mfma_f32_16x16x32_bf16(Bt[n][k], At[m][k], acc[ai][bj][m][n], 0, 0, 0); __builtin_amdgcn_s_setprio(0); } while (0)
; #define PG8_WAIT_V(n) asm volatile("s_waitcnt vmcnt(" #n ")" ::: "memory")
; #define PG8_WAIT_L(n) asm volatile("s_waitcnt lgkmcnt(" #n ")" ::: "memory")
; #define PG8_BAR __builtin_amdgcn_s_barrier()
; #define PG8_SCHED __builtin_amdgcn_sched_barrier(0)
; template <class Epi, class Sched, bool ALIGN_EPI = false, bool SP2 = false>
; __device__ __forceinline__ void gemm_phase(PG8_LAS unsigned char* lds, const Gemm g, const Sched& S, const Epi& E) {
;     ...
;             const bool last = (t == nt - 2);
;             const char* a1 = cA + (size_t)(t + 1) * kstep;
;             const char* a2 = last ? nA : cA + (size_t)(t + 2) * kstep; const char* b2 = last ? nB : cB + (size_t)(t + 2) * kstep;
;             const char* a3 = a2 + kstep; const char* b3 = b2 + kstep;
;             if (last && has_next) S.a_ready(nxt);
;             if constexpr (SP2) {
;             PG8_LDB(B0, 0, 0); PG8_LDB(B1, 0, 1); PG8_SCHED; PG8_LDA(At, 0, 0); PG8_STAGE(PG8_SA(1, 1), a1 + hstep, voffA);
;             PG8_WAIT_V(8); PG8_WAIT_L(0); PG8_BAR; PG8_MMA(0, 0, At, B0); PG8_MMA(0, 1, At, B1); PG8_BAR; PG8_SCHED;
;             PG8_LDA(At, 0, 1); PG8_STAGE(PG8_SB(0, 0), b2, voffB); PG8_STAGE(PG8_SB(0, 1), b2 + hstep, voffB); PG8_STAGE(PG8_SA(0, 0), a2, voffA);
.LBB0_457:
	ds_read_b128 v[148:151], v144
	ds_read_b128 v[152:155], v144 offset:1024
	ds_read_b128 v[156:159], v144 offset:2048
	ds_read_b128 v[160:163], v144 offset:3072
	ds_read_b128 v[164:167], v145
	ds_read_b128 v[168:171], v145 offset:1024
	ds_read_b128 v[172:175], v145 offset:2048
	ds_read_b128 v[176:179], v145 offset:3072
	s_add_u32 s24, s22, 0x100
	s_addc_u32 s25, s23, 0
	s_cmp_eq_u32 s53, 12
	s_cselect_b32 s29, s15, s25
	s_cselect_b32 s28, s49, s24
	s_cselect_b32 s27, s13, s52
	s_cselect_b32 s26, s50, s51
	v_lshl_add_u64 v[184:185], s[22:23], 0, v[134:135]
	s_add_i32 m0, s21, 0xc000
	ds_read_b128 v[180:183], v146
	ds_read_b128 v[188:191], v146 offset:1024
	ds_read_b128 v[192:195], v146 offset:2048
	ds_read_b128 v[196:199], v146 offset:3072
	ds_read_b128 v[200:203], v146 offset:4096
	ds_read_b128 v[204:207], v146 offset:5120
	ds_read_b128 v[208:211], v146 offset:6144
	ds_read_b128 v[212:215], v146 offset:7168
	global_load_lds_dwordx4 v[184:185], off
	v_lshl_add_u64 v[184:185], s[22:23], 0, v[136:137]
	s_add_i32 m0, s21, 0xe000
	s_nop 0
	global_load_lds_dwordx4 v[184:185], off
	s_waitcnt vmcnt(8)
	s_waitcnt lgkmcnt(0)
	s_barrier
	s_setprio 1
	s_waitcnt lgkmcnt(0)
	v_mfma_f32_16x16x32_bf16 v[126:129], v[148:151], v[180:183], v[126:129]
	v_mfma_f32_16x16x32_bf16 v[122:125], v[156:159], v[180:183], v[122:125]
	v_mfma_f32_16x16x32_bf16 v[118:121], v[148:151], v[192:195], v[118:121]
	v_mfma_f32_16x16x32_bf16 v[110:113], v[156:159], v[192:195], v[110:113]
	v_mfma_f32_16x16x32_bf16 v[102:105], v[148:151], v[200:203], v[102:105]
	v_mfma_f32_16x16x32_bf16 v[94:97], v[156:159], v[200:203], v[94:97]
	v_mfma_f32_16x16x32_bf16 v[86:89], v[148:151], v[208:211], v[86:89]
	v_mfma_f32_16x16x32_bf16 v[78:81], v[156:159], v[208:211], v[78:81]
	v_mfma_f32_16x16x32_bf16 v[126:129], v[152:155], v[188:191], v[126:129]
	v_mfma_f32_16x16x32_bf16 v[122:125], v[160:163], v[188:191], v[122:125]
	v_mfma_f32_16x16x32_bf16 v[118:121], v[152:155], v[196:199], v[118:121]
	v_mfma_f32_16x16x32_bf16 v[110:113], v[160:163], v[196:199], v[110:113]
	v_mfma_f32_16x16x32_bf16 v[102:105], v[152:155], v[204:207], v[102:105]
	v_mfma_f32_16x16x32_bf16 v[94:97], v[160:163], v[204:207], v[94:97]
	v_mfma_f32_16x16x32_bf16 v[86:89], v[152:155], v[212:215], v[86:89]
	v_mfma_f32_16x16x32_bf16 v[78:81], v[160:163], v[212:215], v[78:81]
	v_mfma_f32_16x16x32_bf16 v[114:117], v[164:167], v[180:183], v[114:117]
	v_mfma_f32_16x16x32_bf16 v[106:109], v[172:175], v[180:183], v[106:109]
	v_mfma_f32_16x16x32_bf16 v[98:101], v[164:167], v[192:195], v[98:101]
	v_mfma_f32_16x16x32_bf16 v[90:93], v[172:175], v[192:195], v[90:93]
	v_mfma_f32_16x16x32_bf16 v[82:85], v[164:167], v[200:203], v[82:85]
	v_mfma_f32_16x16x32_bf16 v[74:77], v[172:175], v[200:203], v[74:77]
	v_mfma_f32_16x16x32_bf16 v[70:73], v[164:167], v[208:211], v[70:73]
	v_mfma_f32_16x16x32_bf16 v[66:69], v[172:175], v[208:211], v[66:69]
	v_mfma_f32_16x16x32_bf16 v[114:117], v[168:171], v[188:191], v[114:117]
	v_mfma_f32_16x16x32_bf16 v[106:109], v[176:179], v[188:191], v[106:109]
	v_mfma_f32_16x16x32_bf16 v[98:101], v[168:171], v[196:199], v[98:101]
	v_mfma_f32_16x16x32_bf16 v[90:93], v[176:179], v[196:199], v[90:93]
	v_mfma_f32_16x16x32_bf16 v[82:85], v[168:171], v[204:207], v[82:85]
	v_mfma_f32_16x16x32_bf16 v[74:77], v[176:179], v[204:207], v[74:77]
	v_mfma_f32_16x16x32_bf16 v[70:73], v[168:171], v[212:215], v[70:73]
	v_mfma_f32_16x16x32_bf16 v[66:69], v[176:179], v[212:215], v[66:69]
	s_barrier
	s_setprio 0
	s_add_i32 s22, s41, s31
	v_lshl_add_u64 v[184:185], s[26:27], 0, v[130:131]
	s_mov_b32 m0, s22
	ds_read_b128 v[180:183], v146 offset:16384
	ds_read_b128 v[188:191], v146 offset:17408
	ds_read_b128 v[192:195], v146 offset:18432
	ds_read_b128 v[196:199], v146 offset:19456
	ds_read_b128 v[200:203], v146 offset:20480
	ds_read_b128 v[204:207], v146 offset:21504
	ds_read_b128 v[208:211], v146 offset:22528
	ds_read_b128 v[212:215], v146 offset:23552
	global_load_lds_dwordx4 v[184:185], off
	s_add_i32 m0, s22, 0x2000
	s_add_u32 s22, s26, 0x40000
	v_lshl_add_u64 v[216:217], s[26:27], 0, v[132:133]
	s_addc_u32 s23, s27, 0
	s_add_i32 s54, s42, s31
	global_load_lds_dwordx4 v[216:217], off
	v_lshl_add_u64 v[218:219], s[22:23], 0, v[130:131]
	s_mov_b32 m0, s54
	v_lshl_add_u64 v[220:221], s[28:29], 0, v[132:133]
	global_load_lds_dwordx4 v[218:219], off
	v_lshl_add_u64 v[218:219], s[22:23], 0, v[132:133]
	s_add_i32 m0, s54, 0x2000
	s_nop 0
	global_load_lds_dwordx4 v[218:219], off
	v_lshl_add_u64 v[218:219], s[28:29], 0, v[130:131]
	s_mov_b32 m0, s21
	s_nop 0
	global_load_lds_dwordx4 v[218:219], off
	s_mov_b32 m0, s34
	s_nop 0
	global_load_lds_dwordx4 v[220:221], off
	s_waitcnt vmcnt(8)
	s_waitcnt lgkmcnt(0)
	s_barrier
; #define PG8_STAGE(bufoff, gbase, voff) do { _Pragma("unroll") for (int _i = 0; _i < 2; ++_i) \
;         __builtin_amdgcn_global_load_lds((const unsigned*)((const char*)(gbase) + (voff)[_i]), (PG8_LAS unsigned*)(lds + (bufoff) + ldsw + _i * 8192), 16, 0, 0); } while (0)
; #define PG8_LDA(dst, b, h) do { _Pragma("unroll") for (int m = 0; m < 4; ++m) _Pragma("unroll") for (int k = 0; k < 2; ++k) dst[m][k] = *(const PG8_LAS bf16x8*)(lds + PG8_SA(b, h) + aoff + m * 2048 + k * 1024); } while (0)
; #define PG8_LDB(dst, b, h) do { _Pragma("unroll") for (int n = 0; n < 2; ++n) _Pragma("unroll") for (int k = 0; k < 2; ++k) dst[n][k] = *(const PG8_LAS bf16x8*)(lds + PG8_SB(b, h) + boff + n * 2048 + k * 1024); } while (0)
; #define PG8_MMA(ai, bj, At, Bt) do { __builtin_amdgcn_s_setprio(1); _Pragma("unroll") for (int m = 0; m < 4; ++m) _Pragma("unroll") for (int n = 0; n < 2; ++n) _Pragma("unroll") for (int k = 0; k < 2; ++k) \
;         acc[ai][bj][m][n] = __builtin_amdgcn_mfma_f32_16x16x32_bf16(Bt[n][k], At[m][k], acc[ai][bj][m][n], 0, 0, 0); __builtin_amdgcn_s_setprio(0); } while (0)
; #define PG8_WAIT_V(n) asm volatile("s_waitcnt vmcnt(" #n ")" ::: "memory")
; #define PG8_WAIT_L(n) asm volatile("s_waitcnt lgkmcnt(" #n ")" ::: "memory")
; #define PG8_BAR __builtin_amdgcn_s_barrier()
; #define PG8_SCHED __builtin_amdgcn_sched_barrier(0)
; template <class Epi, class Sched, bool ALIGN_EPI = false, bool SP2 = false>
; __device__ __forceinline__ void gemm_phase(PG8_LAS unsigned char* lds, const Gemm g, const Sched& S, const Epi& E) {
;     ...
;             PG8_WAIT_V(8); PG8_WAIT_L(0); PG8_BAR; PG8_MMA(1, 0, At, B0); PG8_MMA(1, 1, At, B1); PG8_BAR; PG8_SCHED;
;             PG8_LDB(B0, 1, 0); PG8_LDB(B1, 1, 1); PG8_SCHED; PG8_LDA(At, 1, 0); PG8_STAGE(PG8_SA(0, 1), a2 + hstep, voffA);
;             PG8_WAIT_V(8); PG8_WAIT_L(0); PG8_BAR; PG8_MMA(0, 0, At, B0); PG8_MMA(0, 1, At, B1); PG8_BAR; PG8_SCHED;
	s_setprio 1
	s_waitcnt lgkmcnt(0)
	v_mfma_f32_16x16x32_bf16 v[62:65], v[148:151], v[180:183], v[62:65]
	v_mfma_f32_16x16x32_bf16 v[58:61], v[156:159], v[180:183], v[58:61]
	v_mfma_f32_16x16x32_bf16 v[54:57], v[148:151], v[192:195], v[54:57]
	v_mfma_f32_16x16x32_bf16 v[46:49], v[156:159], v[192:195], v[46:49]
	v_mfma_f32_16x16x32_bf16 v[38:41], v[148:151], v[200:203], v[38:41]
	v_mfma_f32_16x16x32_bf16 v[30:33], v[156:159], v[200:203], v[30:33]
	v_mfma_f32_16x16x32_bf16 v[22:25], v[148:151], v[208:211], v[22:25]
	v_mfma_f32_16x16x32_bf16 v[14:17], v[156:159], v[208:211], v[14:17]
	v_mfma_f32_16x16x32_bf16 v[62:65], v[152:155], v[188:191], v[62:65]
	v_mfma_f32_16x16x32_bf16 v[58:61], v[160:163], v[188:191], v[58:61]
	v_mfma_f32_16x16x32_bf16 v[54:57], v[152:155], v[196:199], v[54:57]
	v_mfma_f32_16x16x32_bf16 v[46:49], v[160:163], v[196:199], v[46:49]
	v_mfma_f32_16x16x32_bf16 v[38:41], v[152:155], v[204:207], v[38:41]
	v_mfma_f32_16x16x32_bf16 v[30:33], v[160:163], v[204:207], v[30:33]
	v_mfma_f32_16x16x32_bf16 v[22:25], v[152:155], v[212:215], v[22:25]
	v_mfma_f32_16x16x32_bf16 v[14:17], v[160:163], v[212:215], v[14:17]
	v_mfma_f32_16x16x32_bf16 v[50:53], v[164:167], v[180:183], v[50:53]
	v_mfma_f32_16x16x32_bf16 v[42:45], v[172:175], v[180:183], v[42:45]
	v_mfma_f32_16x16x32_bf16 v[34:37], v[164:167], v[192:195], v[34:37]
	v_mfma_f32_16x16x32_bf16 v[26:29], v[172:175], v[192:195], v[26:29]
	v_mfma_f32_16x16x32_bf16 v[18:21], v[164:167], v[200:203], v[18:21]
	v_mfma_f32_16x16x32_bf16 v[10:13], v[172:175], v[200:203], v[10:13]
	v_mfma_f32_16x16x32_bf16 v[6:9], v[164:167], v[208:211], v[6:9]
	v_mfma_f32_16x16x32_bf16 v[2:5], v[172:175], v[208:211], v[2:5]
	v_mfma_f32_16x16x32_bf16 v[50:53], v[168:171], v[188:191], v[50:53]
	v_mfma_f32_16x16x32_bf16 v[42:45], v[176:179], v[188:191], v[42:45]
	v_mfma_f32_16x16x32_bf16 v[34:37], v[168:171], v[196:199], v[34:37]
	v_mfma_f32_16x16x32_bf16 v[26:29], v[176:179], v[196:199], v[26:29]
	v_mfma_f32_16x16x32_bf16 v[18:21], v[168:171], v[204:207], v[18:21]
	v_mfma_f32_16x16x32_bf16 v[10:13], v[176:179], v[204:207], v[10:13]
	v_mfma_f32_16x16x32_bf16 v[6:9], v[168:171], v[212:215], v[6:9]
	v_mfma_f32_16x16x32_bf16 v[2:5], v[176:179], v[212:215], v[2:5]
	s_barrier
	s_setprio 0
	s_add_i32 s54, 0, 0x18000
	v_add_u32_e32 v147, s54, v142
	s_add_i32 s55, 0, 0x1c000
	ds_read_b128 v[148:151], v147
	ds_read_b128 v[152:155], v147 offset:1024
	ds_read_b128 v[156:159], v147 offset:2048
	ds_read_b128 v[160:163], v147 offset:3072
	v_add_u32_e32 v147, s55, v142
	ds_read_b128 v[164:167], v147
	ds_read_b128 v[168:171], v147 offset:1024
	ds_read_b128 v[172:175], v147 offset:2048
	ds_read_b128 v[176:179], v147 offset:3072
	s_add_u32 s22, s28, 0x40000
	s_addc_u32 s23, s29, 0
	s_mov_b32 m0, s35
	v_lshl_add_u64 v[222:223], s[22:23], 0, v[130:131]
	ds_read_b128 v[180:183], v146 offset:32768
	ds_read_b128 v[188:191], v146 offset:33792
	ds_read_b128 v[192:195], v146 offset:34816
	ds_read_b128 v[196:199], v146 offset:35840
	ds_read_b128 v[200:203], v146 offset:36864
	ds_read_b128 v[204:207], v146 offset:37888
	ds_read_b128 v[208:211], v146 offset:38912
	ds_read_b128 v[212:215], v146 offset:39936
	global_load_lds_dwordx4 v[222:223], off
	v_lshl_add_u64 v[222:223], s[22:23], 0, v[132:133]
	s_mov_b32 m0, s36
	s_nop 0
	global_load_lds_dwordx4 v[222:223], off
	s_waitcnt vmcnt(8)
	s_waitcnt lgkmcnt(0)
	s_barrier
	s_setprio 1
	s_waitcnt lgkmcnt(0)
	v_mfma_f32_16x16x32_bf16 v[126:129], v[148:151], v[180:183], v[126:129]
	v_mfma_f32_16x16x32_bf16 v[122:125], v[156:159], v[180:183], v[122:125]
	v_mfma_f32_16x16x32_bf16 v[118:121], v[148:151], v[192:195], v[118:121]
	v_mfma_f32_16x16x32_bf16 v[110:113], v[156:159], v[192:195], v[110:113]
	v_mfma_f32_16x16x32_bf16 v[102:105], v[148:151], v[200:203], v[102:105]
	v_mfma_f32_16x16x32_bf16 v[94:97], v[156:159], v[200:203], v[94:97]
	v_mfma_f32_16x16x32_bf16 v[86:89], v[148:151], v[208:211], v[86:89]
	v_mfma_f32_16x16x32_bf16 v[78:81], v[156:159], v[208:211], v[78:81]
	v_mfma_f32_16x16x32_bf16 v[126:129], v[152:155], v[188:191], v[126:129]
	v_mfma_f32_16x16x32_bf16 v[122:125], v[160:163], v[188:191], v[122:125]
	v_mfma_f32_16x16x32_bf16 v[118:121], v[152:155], v[196:199], v[118:121]
	v_mfma_f32_16x16x32_bf16 v[110:113], v[160:163], v[196:199], v[110:113]
	v_mfma_f32_16x16x32_bf16 v[102:105], v[152:155], v[204:207], v[102:105]
	v_mfma_f32_16x16x32_bf16 v[94:97], v[160:163], v[204:207], v[94:97]
	v_mfma_f32_16x16x32_bf16 v[86:89], v[152:155], v[212:215], v[86:89]
	v_mfma_f32_16x16x32_bf16 v[78:81], v[160:163], v[212:215], v[78:81]
	v_mfma_f32_16x16x32_bf16 v[114:117], v[164:167], v[180:183], v[114:117]
	v_mfma_f32_16x16x32_bf16 v[106:109], v[172:175], v[180:183], v[106:109]
	v_mfma_f32_16x16x32_bf16 v[98:101], v[164:167], v[192:195], v[98:101]
	v_mfma_f32_16x16x32_bf16 v[90:93], v[172:175], v[192:195], v[90:93]
	v_mfma_f32_16x16x32_bf16 v[82:85], v[164:167], v[200:203], v[82:85]
	v_mfma_f32_16x16x32_bf16 v[74:77], v[172:175], v[200:203], v[74:77]
	v_mfma_f32_16x16x32_bf16 v[70:73], v[164:167], v[208:211], v[70:73]
	v_mfma_f32_16x16x32_bf16 v[66:69], v[172:175], v[208:211], v[66:69]
	v_mfma_f32_16x16x32_bf16 v[114:117], v[168:171], v[188:191], v[114:117]
	v_mfma_f32_16x16x32_bf16 v[106:109], v[176:179], v[188:191], v[106:109]
	v_mfma_f32_16x16x32_bf16 v[98:101], v[168:171], v[196:199], v[98:101]
	v_mfma_f32_16x16x32_bf16 v[90:93], v[176:179], v[196:199], v[90:93]
	v_mfma_f32_16x16x32_bf16 v[82:85], v[168:171], v[204:207], v[82:85]
	v_mfma_f32_16x16x32_bf16 v[74:77], v[176:179], v[204:207], v[74:77]
	v_mfma_f32_16x16x32_bf16 v[70:73], v[168:171], v[212:215], v[70:73]
	v_mfma_f32_16x16x32_bf16 v[66:69], v[176:179], v[212:215], v[66:69]
	s_barrier
; #define PG8_STAGE(bufoff, gbase, voff) do { _Pragma("unroll") for (int _i = 0; _i < 2; ++_i) \
;         __builtin_amdgcn_global_load_lds((const unsigned*)((const char*)(gbase) + (voff)[_i]), (PG8_LAS unsigned*)(lds + (bufoff) + ldsw + _i * 8192), 16, 0, 0); } while (0)
; #define PG8_LDA(dst, b, h) do { _Pragma("unroll") for (int m = 0; m < 4; ++m) _Pragma("unroll") for (int k = 0; k < 2; ++k) dst[m][k] = *(const PG8_LAS bf16x8*)(lds + PG8_SA(b, h) + aoff + m * 2048 + k * 1024); } while (0)
; #define PG8_WAIT_V(n) asm volatile("s_waitcnt vmcnt(" #n ")" ::: "memory")
; template <class Epi, class Sched, bool ALIGN_EPI = false, bool SP2 = false>
; __device__ __forceinline__ void gemm_phase(PG8_LAS unsigned char* lds, const Gemm g, const Sched& S, const Epi& E) {
;     ...
;             PG8_LDA(At, 1, 1); PG8_STAGE(PG8_SB(1, 0), b3, voffB); PG8_STAGE(PG8_SB(1, 1), b3 + hstep, voffB); PG8_STAGE(PG8_SA(1, 0), a3, voffA);
;             PG8_WAIT_V(8); PG8_WAIT_L(0); PG8_BAR; PG8_MMA(1, 0, At, B0); PG8_MMA(1, 1, At, B1); PG8_BAR; PG8_SCHED;
;             } else {
;             PG8_LDB(B0, 0, 0); PG8_SCHED; PG8_LDA(At, 0, 0); PG8_STAGE(PG8_SA(1, 1), a1 + hstep, voffA);
;             PG8_WAIT_L(8); PG8_BAR; PG8_WAIT_L(0); PG8_MMA(0, 0, At, B0); PG8_BAR; PG8_SCHED;
;             PG8_LDB(B1, 0, 1); PG8_STAGE(PG8_SB(0, 0), b2, voffB);
;             PG8_BAR; PG8_WAIT_L(0); PG8_MMA(0, 1, At, B1); PG8_BAR;
;             PG8_LDA(At, 0, 1); PG8_STAGE(PG8_SA(0, 0), a2, voffA);
;             PG8_BAR; PG8_WAIT_L(0); PG8_MMA(1, 0, At, B0); PG8_BAR; PG8_SCHED;
;             PG8_STAGE(PG8_SB(0, 1), b2 + hstep, voffB);
;             PG8_WAIT_V(6); PG8_BAR; PG8_MMA(1, 1, At, B1); PG8_BAR;
;             PG8_LDB(B0, 1, 0); PG8_SCHED; PG8_LDA(At, 1, 0); PG8_STAGE(PG8_SA(0, 1), a2 + hstep, voffA);
;             PG8_WAIT_L(8); PG8_BAR; PG8_WAIT_L(0); PG8_MMA(0, 0, At, B0); PG8_BAR; PG8_SCHED;
;             PG8_LDB(B1, 1, 1); PG8_STAGE(PG8_SB(1, 0), b3, voffB);
;             PG8_BAR; PG8_WAIT_L(0); PG8_MMA(0, 1, At, B1); PG8_BAR;
;             PG8_LDA(At, 1, 1); PG8_STAGE(PG8_SA(1, 0), a3, voffA);
;             PG8_BAR; PG8_WAIT_L(0); PG8_MMA(1, 0, At, B0); PG8_BAR; PG8_SCHED;
;             PG8_STAGE(PG8_SB(1, 1), b3 + hstep, voffB);
;             PG8_WAIT_V(6); PG8_BAR; PG8_MMA(1, 1, At, B1); PG8_BAR;
;             }
;         }
;         if constexpr (ALIGN_EPI) { if (wr == 0) PG8_BAR; }
	s_setprio 0
	s_add_i32 s22, s54, s31
	v_lshl_add_u64 v[184:185], v[184:185], 0, s[8:9]
	s_mov_b32 m0, s22
	ds_read_b128 v[180:183], v146 offset:49152
	ds_read_b128 v[188:191], v146 offset:50176
	ds_read_b128 v[192:195], v146 offset:51200
	ds_read_b128 v[196:199], v146 offset:52224
	ds_read_b128 v[200:203], v146 offset:53248
	ds_read_b128 v[204:207], v146 offset:54272
	ds_read_b128 v[208:211], v146 offset:55296
	ds_read_b128 v[212:215], v146 offset:56320
	global_load_lds_dwordx4 v[184:185], off
	s_add_i32 m0, s22, 0x2000
	s_add_u32 s22, s26, 0x40080
	v_lshl_add_u64 v[184:185], v[216:217], 0, s[8:9]
	s_addc_u32 s23, s27, 0
	s_add_i32 s26, s55, s31
	global_load_lds_dwordx4 v[184:185], off
	v_lshl_add_u64 v[184:185], s[22:23], 0, v[130:131]
	s_mov_b32 m0, s26
	s_nop 0
	global_load_lds_dwordx4 v[184:185], off
	v_lshl_add_u64 v[184:185], s[22:23], 0, v[132:133]
	s_add_i32 m0, s26, 0x2000
	s_nop 0
	global_load_lds_dwordx4 v[184:185], off
	v_lshl_add_u64 v[184:185], v[218:219], 0, s[8:9]
	s_mov_b32 m0, s38
	s_nop 0
	global_load_lds_dwordx4 v[184:185], off
	v_lshl_add_u64 v[184:185], v[220:221], 0, s[8:9]
	s_mov_b32 m0, s39
	s_nop 0
	global_load_lds_dwordx4 v[184:185], off
	s_waitcnt vmcnt(8)
	s_waitcnt lgkmcnt(0)
	s_barrier
	s_setprio 1
	s_waitcnt lgkmcnt(0)
	v_mfma_f32_16x16x32_bf16 v[62:65], v[148:151], v[180:183], v[62:65]
	v_mfma_f32_16x16x32_bf16 v[58:61], v[156:159], v[180:183], v[58:61]
	v_mfma_f32_16x16x32_bf16 v[54:57], v[148:151], v[192:195], v[54:57]
	v_mfma_f32_16x16x32_bf16 v[46:49], v[156:159], v[192:195], v[46:49]
	v_mfma_f32_16x16x32_bf16 v[38:41], v[148:151], v[200:203], v[38:41]
	v_mfma_f32_16x16x32_bf16 v[30:33], v[156:159], v[200:203], v[30:33]
	v_mfma_f32_16x16x32_bf16 v[22:25], v[148:151], v[208:211], v[22:25]
	v_mfma_f32_16x16x32_bf16 v[14:17], v[156:159], v[208:211], v[14:17]
	v_mfma_f32_16x16x32_bf16 v[62:65], v[152:155], v[188:191], v[62:65]
	v_mfma_f32_16x16x32_bf16 v[58:61], v[160:163], v[188:191], v[58:61]
	v_mfma_f32_16x16x32_bf16 v[54:57], v[152:155], v[196:199], v[54:57]
	v_mfma_f32_16x16x32_bf16 v[46:49], v[160:163], v[196:199], v[46:49]
	v_mfma_f32_16x16x32_bf16 v[38:41], v[152:155], v[204:207], v[38:41]
	v_mfma_f32_16x16x32_bf16 v[30:33], v[160:163], v[204:207], v[30:33]
	v_mfma_f32_16x16x32_bf16 v[22:25], v[152:155], v[212:215], v[22:25]
	v_mfma_f32_16x16x32_bf16 v[14:17], v[160:163], v[212:215], v[14:17]
	v_mfma_f32_16x16x32_bf16 v[50:53], v[164:167], v[180:183], v[50:53]
	v_mfma_f32_16x16x32_bf16 v[42:45], v[172:175], v[180:183], v[42:45]
	v_mfma_f32_16x16x32_bf16 v[34:37], v[164:167], v[192:195], v[34:37]
	v_mfma_f32_16x16x32_bf16 v[26:29], v[172:175], v[192:195], v[26:29]
	v_mfma_f32_16x16x32_bf16 v[18:21], v[164:167], v[200:203], v[18:21]
	v_mfma_f32_16x16x32_bf16 v[10:13], v[172:175], v[200:203], v[10:13]
	v_mfma_f32_16x16x32_bf16 v[6:9], v[164:167], v[208:211], v[6:9]
	v_mfma_f32_16x16x32_bf16 v[2:5], v[172:175], v[208:211], v[2:5]
	v_mfma_f32_16x16x32_bf16 v[50:53], v[168:171], v[188:191], v[50:53]
	v_mfma_f32_16x16x32_bf16 v[42:45], v[176:179], v[188:191], v[42:45]
	v_mfma_f32_16x16x32_bf16 v[34:37], v[168:171], v[196:199], v[34:37]
	v_mfma_f32_16x16x32_bf16 v[26:29], v[176:179], v[196:199], v[26:29]
	v_mfma_f32_16x16x32_bf16 v[18:21], v[168:171], v[204:207], v[18:21]
	v_mfma_f32_16x16x32_bf16 v[10:13], v[176:179], v[204:207], v[10:13]
	v_mfma_f32_16x16x32_bf16 v[6:9], v[168:171], v[212:215], v[6:9]
	v_mfma_f32_16x16x32_bf16 v[2:5], v[176:179], v[212:215], v[2:5]
	s_barrier
	s_setprio 0
	s_add_i32 s53, s53, 2
	s_add_u32 s51, s51, 0x100
	s_addc_u32 s52, s52, 0
	s_cmp_gt_u32 s53, 13
	s_mov_b64 s[22:23], s[24:25]
	s_cbranch_scc0 .LBB0_457
	s_and_b64 vcc, exec, s[10:11]
	s_cbranch_vccz .LBB0_460
	s_barrier

; #define PG8_STAGE(bufoff, gbase, voff) do { _Pragma("unroll") for (int _i = 0; _i < 2; ++_i) \
;         __builtin_amdgcn_global_load_lds((const unsigned*)((const char*)(gbase) + (voff)[_i]), (PG8_LAS unsigned*)(lds + (bufoff) + ldsw + _i * 8192), 16, 0, 0); } while (0)
; #define PG8_LDA(dst, b, h) do { _Pragma("unroll") for (int m = 0; m < 4; ++m) _Pragma("unroll") for (int k = 0; k < 2; ++k) dst[m][k] = *(const PG8_LAS bf16x8*)(lds + PG8_SA(b, h) + aoff + m * 2048 + k * 1024); } while (0)
; #define PG8_LDB(dst, b, h) do { _Pragma("unroll") for (int n = 0; n < 2; ++n) _Pragma("unroll") for (int k = 0; k < 2; ++k) dst[n][k] = *(const PG8_LAS bf16x8*)(lds + PG8_SB(b, h) + boff + n * 2048 + k * 1024); } while (0)
; #define PG8_MMA(ai, bj, At, Bt) do { __builtin_amdgcn_s_setprio(1); _Pragma("unroll") for (int m = 0; m < 4; ++m) _Pragma("unroll") for (int n = 0; n < 2; ++n) _Pragma("unroll") for (int k = 0; k < 2; ++k) \
;         acc[ai][bj][m][n] = __builtin_amdgcn_mfma_f32_16x16x32_bf16(Bt[n][k], At[m][k], acc[ai][bj][m][n], 0, 0, 0); __builtin_amdgcn_s_setprio(0); } while (0)
; #define PG8_WAIT_V(n) asm volatile("s_waitcnt vmcnt(" #n ")" ::: "memory")
; #define PG8_WAIT_L(n) asm volatile("s_waitcnt lgkmcnt(" #n ")" ::: "memory")
; #define PG8_BAR __builtin_amdgcn_s_barrier()
; #define PG8_SCHED __builtin_amdgcn_sched_barrier(0)
; template <class Epi, class Sched, bool ALIGN_EPI = false, bool SP2 = false>
; __device__ __forceinline__ void gemm_phase(PG8_LAS unsigned char* lds, const Gemm g, const Sched& S, const Epi& E) {
;     ...
;             const bool last = (t == nt - 2);
;             const char* a1 = cA + (size_t)(t + 1) * kstep;
;             const char* a2 = last ? nA : cA + (size_t)(t + 2) * kstep; const char* b2 = last ? nB : cB + (size_t)(t + 2) * kstep;
;             const char* a3 = a2 + kstep; const char* b3 = b2 + kstep;
;             if (last && has_next) S.a_ready(nxt);
;             if constexpr (SP2) {
;             PG8_LDB(B0, 0, 0); PG8_LDB(B1, 0, 1); PG8_SCHED; PG8_LDA(At, 0, 0); PG8_STAGE(PG8_SA(1, 1), a1 + hstep, voffA);
;             PG8_WAIT_V(8); PG8_WAIT_L(0); PG8_BAR; PG8_MMA(0, 0, At, B0); PG8_MMA(0, 1, At, B1); PG8_BAR; PG8_SCHED;
;             PG8_LDA(At, 0, 1); PG8_STAGE(PG8_SB(0, 0), b2, voffB); PG8_STAGE(PG8_SB(0, 1), b2 + hstep, voffB); PG8_STAGE(PG8_SA(0, 0), a2, voffA);
.LBB0_713:
	ds_read_b128 v[162:165], v159
	ds_read_b128 v[166:169], v159 offset:1024
	ds_read_b128 v[170:173], v159 offset:2048
	ds_read_b128 v[174:177], v159 offset:3072
	ds_read_b128 v[178:181], v160
	ds_read_b128 v[182:185], v160 offset:1024
	ds_read_b128 v[188:191], v160 offset:2048
	ds_read_b128 v[192:195], v160 offset:3072
	s_add_i32 s66, s36, 2
	s_add_u32 s67, s34, 0x80
	s_addc_u32 s37, s35, 0
	s_cmp_eq_u32 s52, s36
	s_cselect_b32 s36, s4, s67
	s_cselect_b32 s37, s5, s37
	s_cselect_b32 s69, s31, s65
	s_cselect_b32 s68, s30, s63
	v_lshl_add_u64 v[156:157], s[34:35], 0, v[146:147]
	s_add_i32 m0, s42, 0xc000
	ds_read_b128 v[196:199], v161
	ds_read_b128 v[200:203], v161 offset:1024
	ds_read_b128 v[204:207], v161 offset:2048
	ds_read_b128 v[208:211], v161 offset:3072
	ds_read_b128 v[212:215], v161 offset:4096
	ds_read_b128 v[216:219], v161 offset:5120
	ds_read_b128 v[220:223], v161 offset:6144
	ds_read_b128 v[224:227], v161 offset:7168
	global_load_lds_dwordx4 v[156:157], off
	v_lshl_add_u64 v[156:157], s[34:35], 0, v[148:149]
	s_add_i32 m0, s42, 0xe000
	s_nop 0
	global_load_lds_dwordx4 v[156:157], off
	s_waitcnt vmcnt(8)
	s_waitcnt lgkmcnt(0)
	s_barrier
	s_setprio 1
	s_waitcnt lgkmcnt(0)
	v_mfma_f32_16x16x32_bf16 v[126:129], v[162:165], v[196:199], v[126:129]
	v_mfma_f32_16x16x32_bf16 v[122:125], v[170:173], v[196:199], v[122:125]
	v_mfma_f32_16x16x32_bf16 v[110:113], v[162:165], v[204:207], v[110:113]
	v_mfma_f32_16x16x32_bf16 v[106:109], v[170:173], v[204:207], v[106:109]
	v_mfma_f32_16x16x32_bf16 v[94:97], v[162:165], v[212:215], v[94:97]
	v_mfma_f32_16x16x32_bf16 v[90:93], v[170:173], v[212:215], v[90:93]
	v_mfma_f32_16x16x32_bf16 v[78:81], v[162:165], v[220:223], v[78:81]
	v_mfma_f32_16x16x32_bf16 v[74:77], v[170:173], v[220:223], v[74:77]
	v_mfma_f32_16x16x32_bf16 v[126:129], v[166:169], v[200:203], v[126:129]
	v_mfma_f32_16x16x32_bf16 v[122:125], v[174:177], v[200:203], v[122:125]
	v_mfma_f32_16x16x32_bf16 v[110:113], v[166:169], v[208:211], v[110:113]
	v_mfma_f32_16x16x32_bf16 v[106:109], v[174:177], v[208:211], v[106:109]
	v_mfma_f32_16x16x32_bf16 v[94:97], v[166:169], v[216:219], v[94:97]
	v_mfma_f32_16x16x32_bf16 v[90:93], v[174:177], v[216:219], v[90:93]
	v_mfma_f32_16x16x32_bf16 v[78:81], v[166:169], v[224:227], v[78:81]
	v_mfma_f32_16x16x32_bf16 v[74:77], v[174:177], v[224:227], v[74:77]
	v_mfma_f32_16x16x32_bf16 v[118:121], v[178:181], v[196:199], v[118:121]
	v_mfma_f32_16x16x32_bf16 v[114:117], v[188:191], v[196:199], v[114:117]
	v_mfma_f32_16x16x32_bf16 v[102:105], v[178:181], v[204:207], v[102:105]
	v_mfma_f32_16x16x32_bf16 v[98:101], v[188:191], v[204:207], v[98:101]
	v_mfma_f32_16x16x32_bf16 v[86:89], v[178:181], v[212:215], v[86:89]
	v_mfma_f32_16x16x32_bf16 v[82:85], v[188:191], v[212:215], v[82:85]
	v_mfma_f32_16x16x32_bf16 v[70:73], v[178:181], v[220:223], v[70:73]
	v_mfma_f32_16x16x32_bf16 v[66:69], v[188:191], v[220:223], v[66:69]
	v_mfma_f32_16x16x32_bf16 v[118:121], v[182:185], v[200:203], v[118:121]
	v_mfma_f32_16x16x32_bf16 v[114:117], v[192:195], v[200:203], v[114:117]
	v_mfma_f32_16x16x32_bf16 v[102:105], v[182:185], v[208:211], v[102:105]
	v_mfma_f32_16x16x32_bf16 v[98:101], v[192:195], v[208:211], v[98:101]
	v_mfma_f32_16x16x32_bf16 v[86:89], v[182:185], v[216:219], v[86:89]
	v_mfma_f32_16x16x32_bf16 v[82:85], v[192:195], v[216:219], v[82:85]
	v_mfma_f32_16x16x32_bf16 v[70:73], v[182:185], v[224:227], v[70:73]
	v_mfma_f32_16x16x32_bf16 v[66:69], v[192:195], v[224:227], v[66:69]
	s_barrier
	s_setprio 0
	s_add_i32 s67, s55, s40
	v_lshl_add_u64 v[156:157], s[68:69], 0, v[134:135]
	s_mov_b32 m0, s67
	ds_read_b128 v[196:199], v161 offset:16384
	ds_read_b128 v[200:203], v161 offset:17408
	ds_read_b128 v[204:207], v161 offset:18432
	ds_read_b128 v[208:211], v161 offset:19456
	ds_read_b128 v[212:215], v161 offset:20480
	ds_read_b128 v[216:219], v161 offset:21504
	ds_read_b128 v[220:223], v161 offset:22528
	ds_read_b128 v[224:227], v161 offset:23552
	global_load_lds_dwordx4 v[156:157], off
	s_add_i32 m0, s67, 0x2000
	v_lshl_add_u64 v[228:229], s[68:69], 0, v[130:131]
	s_add_u32 s68, s68, s6
	s_addc_u32 s69, s69, s7
	s_add_i32 s67, s56, s40
	global_load_lds_dwordx4 v[228:229], off
	v_lshl_add_u64 v[230:231], s[68:69], 0, v[134:135]
	s_mov_b32 m0, s67
	v_lshl_add_u64 v[232:233], s[68:69], 0, v[130:131]
	global_load_lds_dwordx4 v[230:231], off
	s_add_i32 m0, s67, 0x2000
	v_lshl_add_u64 v[234:235], s[36:37], 0, v[136:137]
	global_load_lds_dwordx4 v[232:233], off
	s_mov_b32 m0, s42
	v_lshl_add_u64 v[236:237], s[36:37], 0, v[132:133]
	global_load_lds_dwordx4 v[234:235], off
	s_mov_b32 m0, s43
	s_nop 0
	global_load_lds_dwordx4 v[236:237], off
	s_waitcnt vmcnt(8)
	s_waitcnt lgkmcnt(0)
	s_barrier
; #define PG8_STAGE(bufoff, gbase, voff) do { _Pragma("unroll") for (int _i = 0; _i < 2; ++_i) \
;         __builtin_amdgcn_global_load_lds((const unsigned*)((const char*)(gbase) + (voff)[_i]), (PG8_LAS unsigned*)(lds + (bufoff) + ldsw + _i * 8192), 16, 0, 0); } while (0)
; #define PG8_LDA(dst, b, h) do { _Pragma("unroll") for (int m = 0; m < 4; ++m) _Pragma("unroll") for (int k = 0; k < 2; ++k) dst[m][k] = *(const PG8_LAS bf16x8*)(lds + PG8_SA(b, h) + aoff + m * 2048 + k * 1024); } while (0)
; #define PG8_LDB(dst, b, h) do { _Pragma("unroll") for (int n = 0; n < 2; ++n) _Pragma("unroll") for (int k = 0; k < 2; ++k) dst[n][k] = *(const PG8_LAS bf16x8*)(lds + PG8_SB(b, h) + boff + n * 2048 + k * 1024); } while (0)
; #define PG8_MMA(ai, bj, At, Bt) do { __builtin_amdgcn_s_setprio(1); _Pragma("unroll") for (int m = 0; m < 4; ++m) _Pragma("unroll") for (int n = 0; n < 2; ++n) _Pragma("unroll") for (int k = 0; k < 2; ++k) \
;         acc[ai][bj][m][n] = __builtin_amdgcn_mfma_f32_16x16x32_bf16(Bt[n][k], At[m][k], acc[ai][bj][m][n], 0, 0, 0); __builtin_amdgcn_s_setprio(0); } while (0)
; #define PG8_WAIT_V(n) asm volatile("s_waitcnt vmcnt(" #n ")" ::: "memory")
; #define PG8_WAIT_L(n) asm volatile("s_waitcnt lgkmcnt(" #n ")" ::: "memory")
; #define PG8_BAR __builtin_amdgcn_s_barrier()
; #define PG8_SCHED __builtin_amdgcn_sched_barrier(0)
; template <class Epi, class Sched, bool ALIGN_EPI = false, bool SP2 = false>
; __device__ __forceinline__ void gemm_phase(PG8_LAS unsigned char* lds, const Gemm g, const Sched& S, const Epi& E) {
;     ...
;             PG8_WAIT_V(8); PG8_WAIT_L(0); PG8_BAR; PG8_MMA(1, 0, At, B0); PG8_MMA(1, 1, At, B1); PG8_BAR; PG8_SCHED;
;             PG8_LDB(B0, 1, 0); PG8_LDB(B1, 1, 1); PG8_SCHED; PG8_LDA(At, 1, 0); PG8_STAGE(PG8_SA(0, 1), a2 + hstep, voffA);
;             PG8_WAIT_V(8); PG8_WAIT_L(0); PG8_BAR; PG8_MMA(0, 0, At, B0); PG8_MMA(0, 1, At, B1); PG8_BAR; PG8_SCHED;
	s_setprio 1
	s_waitcnt lgkmcnt(0)
	v_mfma_f32_16x16x32_bf16 v[62:65], v[162:165], v[196:199], v[62:65]
	v_mfma_f32_16x16x32_bf16 v[58:61], v[170:173], v[196:199], v[58:61]
	v_mfma_f32_16x16x32_bf16 v[46:49], v[162:165], v[204:207], v[46:49]
	v_mfma_f32_16x16x32_bf16 v[42:45], v[170:173], v[204:207], v[42:45]
	v_mfma_f32_16x16x32_bf16 v[30:33], v[162:165], v[212:215], v[30:33]
	v_mfma_f32_16x16x32_bf16 v[26:29], v[170:173], v[212:215], v[26:29]
	v_mfma_f32_16x16x32_bf16 v[14:17], v[162:165], v[220:223], v[14:17]
	v_mfma_f32_16x16x32_bf16 v[10:13], v[170:173], v[220:223], v[10:13]
	v_mfma_f32_16x16x32_bf16 v[62:65], v[166:169], v[200:203], v[62:65]
	v_mfma_f32_16x16x32_bf16 v[58:61], v[174:177], v[200:203], v[58:61]
	v_mfma_f32_16x16x32_bf16 v[46:49], v[166:169], v[208:211], v[46:49]
	v_mfma_f32_16x16x32_bf16 v[42:45], v[174:177], v[208:211], v[42:45]
	v_mfma_f32_16x16x32_bf16 v[30:33], v[166:169], v[216:219], v[30:33]
	v_mfma_f32_16x16x32_bf16 v[26:29], v[174:177], v[216:219], v[26:29]
	v_mfma_f32_16x16x32_bf16 v[14:17], v[166:169], v[224:227], v[14:17]
	v_mfma_f32_16x16x32_bf16 v[10:13], v[174:177], v[224:227], v[10:13]
	v_mfma_f32_16x16x32_bf16 v[54:57], v[178:181], v[196:199], v[54:57]
	v_mfma_f32_16x16x32_bf16 v[50:53], v[188:191], v[196:199], v[50:53]
	v_mfma_f32_16x16x32_bf16 v[38:41], v[178:181], v[204:207], v[38:41]
	v_mfma_f32_16x16x32_bf16 v[34:37], v[188:191], v[204:207], v[34:37]
	v_mfma_f32_16x16x32_bf16 v[22:25], v[178:181], v[212:215], v[22:25]
	v_mfma_f32_16x16x32_bf16 v[18:21], v[188:191], v[212:215], v[18:21]
	v_mfma_f32_16x16x32_bf16 v[6:9], v[178:181], v[220:223], v[6:9]
	v_mfma_f32_16x16x32_bf16 v[2:5], v[188:191], v[220:223], v[2:5]
	v_mfma_f32_16x16x32_bf16 v[54:57], v[182:185], v[200:203], v[54:57]
	v_mfma_f32_16x16x32_bf16 v[50:53], v[192:195], v[200:203], v[50:53]
	v_mfma_f32_16x16x32_bf16 v[38:41], v[182:185], v[208:211], v[38:41]
	v_mfma_f32_16x16x32_bf16 v[34:37], v[192:195], v[208:211], v[34:37]
	v_mfma_f32_16x16x32_bf16 v[22:25], v[182:185], v[216:219], v[22:25]
	v_mfma_f32_16x16x32_bf16 v[18:21], v[192:195], v[216:219], v[18:21]
	v_mfma_f32_16x16x32_bf16 v[6:9], v[182:185], v[224:227], v[6:9]
	v_mfma_f32_16x16x32_bf16 v[2:5], v[192:195], v[224:227], v[2:5]
	s_barrier
	s_setprio 0
	s_add_i32 s67, 0, 0x18000
	v_add_u32_e32 v138, s67, v158
	s_add_i32 s68, 0, 0x1c000
	ds_read_b128 v[162:165], v138
	ds_read_b128 v[166:169], v138 offset:1024
	ds_read_b128 v[170:173], v138 offset:2048
	ds_read_b128 v[174:177], v138 offset:3072
	v_add_u32_e32 v138, s68, v158
	ds_read_b128 v[178:181], v138
	ds_read_b128 v[182:185], v138 offset:1024
	ds_read_b128 v[188:191], v138 offset:2048
	ds_read_b128 v[192:195], v138 offset:3072
	s_add_u32 s36, s36, s6
	s_addc_u32 s37, s37, s7
	s_mov_b32 m0, s48
	v_lshl_add_u64 v[238:239], s[36:37], 0, v[136:137]
	ds_read_b128 v[196:199], v161 offset:32768
	ds_read_b128 v[200:203], v161 offset:33792
	ds_read_b128 v[204:207], v161 offset:34816
	ds_read_b128 v[208:211], v161 offset:35840
	ds_read_b128 v[212:215], v161 offset:36864
	ds_read_b128 v[216:219], v161 offset:37888
	ds_read_b128 v[220:223], v161 offset:38912
	ds_read_b128 v[224:227], v161 offset:39936
	global_load_lds_dwordx4 v[238:239], off
	v_lshl_add_u64 v[238:239], s[36:37], 0, v[132:133]
	s_mov_b32 m0, s49
	s_nop 0
	global_load_lds_dwordx4 v[238:239], off
	s_waitcnt vmcnt(8)
	s_waitcnt lgkmcnt(0)
	s_barrier
	s_setprio 1
	s_waitcnt lgkmcnt(0)
	v_mfma_f32_16x16x32_bf16 v[126:129], v[162:165], v[196:199], v[126:129]
	v_mfma_f32_16x16x32_bf16 v[122:125], v[170:173], v[196:199], v[122:125]
	v_mfma_f32_16x16x32_bf16 v[110:113], v[162:165], v[204:207], v[110:113]
	v_mfma_f32_16x16x32_bf16 v[106:109], v[170:173], v[204:207], v[106:109]
	v_mfma_f32_16x16x32_bf16 v[94:97], v[162:165], v[212:215], v[94:97]
	v_mfma_f32_16x16x32_bf16 v[90:93], v[170:173], v[212:215], v[90:93]
	v_mfma_f32_16x16x32_bf16 v[78:81], v[162:165], v[220:223], v[78:81]
	v_mfma_f32_16x16x32_bf16 v[74:77], v[170:173], v[220:223], v[74:77]
	v_mfma_f32_16x16x32_bf16 v[126:129], v[166:169], v[200:203], v[126:129]
	v_mfma_f32_16x16x32_bf16 v[122:125], v[174:177], v[200:203], v[122:125]
	v_mfma_f32_16x16x32_bf16 v[110:113], v[166:169], v[208:211], v[110:113]
	v_mfma_f32_16x16x32_bf16 v[106:109], v[174:177], v[208:211], v[106:109]
	v_mfma_f32_16x16x32_bf16 v[94:97], v[166:169], v[216:219], v[94:97]
	v_mfma_f32_16x16x32_bf16 v[90:93], v[174:177], v[216:219], v[90:93]
	v_mfma_f32_16x16x32_bf16 v[78:81], v[166:169], v[224:227], v[78:81]
	v_mfma_f32_16x16x32_bf16 v[74:77], v[174:177], v[224:227], v[74:77]
	v_mfma_f32_16x16x32_bf16 v[118:121], v[178:181], v[196:199], v[118:121]
	v_mfma_f32_16x16x32_bf16 v[114:117], v[188:191], v[196:199], v[114:117]
	v_mfma_f32_16x16x32_bf16 v[102:105], v[178:181], v[204:207], v[102:105]
	v_mfma_f32_16x16x32_bf16 v[98:101], v[188:191], v[204:207], v[98:101]
	v_mfma_f32_16x16x32_bf16 v[86:89], v[178:181], v[212:215], v[86:89]
	v_mfma_f32_16x16x32_bf16 v[82:85], v[188:191], v[212:215], v[82:85]
	v_mfma_f32_16x16x32_bf16 v[70:73], v[178:181], v[220:223], v[70:73]
	v_mfma_f32_16x16x32_bf16 v[66:69], v[188:191], v[220:223], v[66:69]
	v_mfma_f32_16x16x32_bf16 v[118:121], v[182:185], v[200:203], v[118:121]
	v_mfma_f32_16x16x32_bf16 v[114:117], v[192:195], v[200:203], v[114:117]
	v_mfma_f32_16x16x32_bf16 v[102:105], v[182:185], v[208:211], v[102:105]
	v_mfma_f32_16x16x32_bf16 v[98:101], v[192:195], v[208:211], v[98:101]
	v_mfma_f32_16x16x32_bf16 v[86:89], v[182:185], v[216:219], v[86:89]
	v_mfma_f32_16x16x32_bf16 v[82:85], v[192:195], v[216:219], v[82:85]
	v_mfma_f32_16x16x32_bf16 v[70:73], v[182:185], v[224:227], v[70:73]
	v_mfma_f32_16x16x32_bf16 v[66:69], v[192:195], v[224:227], v[66:69]
	s_barrier
; #define PG8_STAGE(bufoff, gbase, voff) do { _Pragma("unroll") for (int _i = 0; _i < 2; ++_i) \
;         __builtin_amdgcn_global_load_lds((const unsigned*)((const char*)(gbase) + (voff)[_i]), (PG8_LAS unsigned*)(lds + (bufoff) + ldsw + _i * 8192), 16, 0, 0); } while (0)
; #define PG8_LDA(dst, b, h) do { _Pragma("unroll") for (int m = 0; m < 4; ++m) _Pragma("unroll") for (int k = 0; k < 2; ++k) dst[m][k] = *(const PG8_LAS bf16x8*)(lds + PG8_SA(b, h) + aoff + m * 2048 + k * 1024); } while (0)
; #define PG8_WAIT_V(n) asm volatile("s_waitcnt vmcnt(" #n ")" ::: "memory")
; #define PG8_BAR __builtin_amdgcn_s_barrier()
; template <class Epi, class Sched, bool ALIGN_EPI = false, bool SP2 = false>
; __device__ __forceinline__ void gemm_phase(PG8_LAS unsigned char* lds, const Gemm g, const Sched& S, const Epi& E) {
;     ...
;             PG8_LDA(At, 1, 1); PG8_STAGE(PG8_SB(1, 0), b3, voffB); PG8_STAGE(PG8_SB(1, 1), b3 + hstep, voffB); PG8_STAGE(PG8_SA(1, 0), a3, voffA);
;             PG8_WAIT_V(8); PG8_WAIT_L(0); PG8_BAR; PG8_MMA(1, 0, At, B0); PG8_MMA(1, 1, At, B1); PG8_BAR; PG8_SCHED;
;             } else {
;             PG8_LDB(B0, 0, 0); PG8_SCHED; PG8_LDA(At, 0, 0); PG8_STAGE(PG8_SA(1, 1), a1 + hstep, voffA);
;             PG8_WAIT_L(8); PG8_BAR; PG8_WAIT_L(0); PG8_MMA(0, 0, At, B0); PG8_BAR; PG8_SCHED;
;             PG8_LDB(B1, 0, 1); PG8_STAGE(PG8_SB(0, 0), b2, voffB);
;             PG8_BAR; PG8_WAIT_L(0); PG8_MMA(0, 1, At, B1); PG8_BAR;
;             PG8_LDA(At, 0, 1); PG8_STAGE(PG8_SA(0, 0), a2, voffA);
;             PG8_BAR; PG8_WAIT_L(0); PG8_MMA(1, 0, At, B0); PG8_BAR; PG8_SCHED;
;             PG8_STAGE(PG8_SB(0, 1), b2 + hstep, voffB);
;             PG8_WAIT_V(6); PG8_BAR; PG8_MMA(1, 1, At, B1); PG8_BAR;
;             PG8_LDB(B0, 1, 0); PG8_SCHED; PG8_LDA(At, 1, 0); PG8_STAGE(PG8_SA(0, 1), a2 + hstep, voffA);
;             PG8_WAIT_L(8); PG8_BAR; PG8_WAIT_L(0); PG8_MMA(0, 0, At, B0); PG8_BAR; PG8_SCHED;
;             PG8_LDB(B1, 1, 1); PG8_STAGE(PG8_SB(1, 0), b3, voffB);
;             PG8_BAR; PG8_WAIT_L(0); PG8_MMA(0, 1, At, B1); PG8_BAR;
;             PG8_LDA(At, 1, 1); PG8_STAGE(PG8_SA(1, 0), a3, voffA);
;             PG8_BAR; PG8_WAIT_L(0); PG8_MMA(1, 0, At, B0); PG8_BAR; PG8_SCHED;
;             PG8_STAGE(PG8_SB(1, 1), b3 + hstep, voffB);
;             PG8_WAIT_V(6); PG8_BAR; PG8_MMA(1, 1, At, B1); PG8_BAR;
;             }
;         }
	s_setprio 0
	s_add_i32 s36, s67, s40
	v_lshl_add_u64 v[156:157], v[156:157], 0, s[22:23]
	s_mov_b32 m0, s36
	ds_read_b128 v[196:199], v161 offset:49152
	ds_read_b128 v[200:203], v161 offset:50176
	ds_read_b128 v[204:207], v161 offset:51200
	ds_read_b128 v[208:211], v161 offset:52224
	ds_read_b128 v[212:215], v161 offset:53248
	ds_read_b128 v[216:219], v161 offset:54272
	ds_read_b128 v[220:223], v161 offset:55296
	ds_read_b128 v[224:227], v161 offset:56320
	global_load_lds_dwordx4 v[156:157], off
	v_lshl_add_u64 v[156:157], v[228:229], 0, s[22:23]
	s_add_i32 m0, s36, 0x2000
	s_add_i32 s36, s68, s40
	global_load_lds_dwordx4 v[156:157], off
	v_lshl_add_u64 v[156:157], v[230:231], 0, s[22:23]
	s_mov_b32 m0, s36
	s_nop 0
	global_load_lds_dwordx4 v[156:157], off
	v_lshl_add_u64 v[156:157], v[232:233], 0, s[22:23]
	s_add_i32 m0, s36, 0x2000
	s_nop 0
	global_load_lds_dwordx4 v[156:157], off
	v_lshl_add_u64 v[156:157], v[234:235], 0, s[22:23]
	s_mov_b32 m0, s50
	s_nop 0
	global_load_lds_dwordx4 v[156:157], off
	v_lshl_add_u64 v[156:157], v[236:237], 0, s[22:23]
	s_mov_b32 m0, s51
	s_nop 0
	global_load_lds_dwordx4 v[156:157], off
	s_waitcnt vmcnt(8)
	s_waitcnt lgkmcnt(0)
	s_barrier
	s_setprio 1
	s_waitcnt lgkmcnt(0)
	v_mfma_f32_16x16x32_bf16 v[62:65], v[162:165], v[196:199], v[62:65]
	v_mfma_f32_16x16x32_bf16 v[58:61], v[170:173], v[196:199], v[58:61]
	v_mfma_f32_16x16x32_bf16 v[46:49], v[162:165], v[204:207], v[46:49]
	v_mfma_f32_16x16x32_bf16 v[42:45], v[170:173], v[204:207], v[42:45]
	v_mfma_f32_16x16x32_bf16 v[30:33], v[162:165], v[212:215], v[30:33]
	v_mfma_f32_16x16x32_bf16 v[26:29], v[170:173], v[212:215], v[26:29]
	v_mfma_f32_16x16x32_bf16 v[14:17], v[162:165], v[220:223], v[14:17]
	v_mfma_f32_16x16x32_bf16 v[10:13], v[170:173], v[220:223], v[10:13]
	v_mfma_f32_16x16x32_bf16 v[62:65], v[166:169], v[200:203], v[62:65]
	v_mfma_f32_16x16x32_bf16 v[58:61], v[174:177], v[200:203], v[58:61]
	v_mfma_f32_16x16x32_bf16 v[46:49], v[166:169], v[208:211], v[46:49]
	v_mfma_f32_16x16x32_bf16 v[42:45], v[174:177], v[208:211], v[42:45]
	v_mfma_f32_16x16x32_bf16 v[30:33], v[166:169], v[216:219], v[30:33]
	v_mfma_f32_16x16x32_bf16 v[26:29], v[174:177], v[216:219], v[26:29]
	v_mfma_f32_16x16x32_bf16 v[14:17], v[166:169], v[224:227], v[14:17]
	v_mfma_f32_16x16x32_bf16 v[10:13], v[174:177], v[224:227], v[10:13]
	v_mfma_f32_16x16x32_bf16 v[54:57], v[178:181], v[196:199], v[54:57]
	v_mfma_f32_16x16x32_bf16 v[50:53], v[188:191], v[196:199], v[50:53]
	v_mfma_f32_16x16x32_bf16 v[38:41], v[178:181], v[204:207], v[38:41]
	v_mfma_f32_16x16x32_bf16 v[34:37], v[188:191], v[204:207], v[34:37]
	v_mfma_f32_16x16x32_bf16 v[22:25], v[178:181], v[212:215], v[22:25]
	v_mfma_f32_16x16x32_bf16 v[18:21], v[188:191], v[212:215], v[18:21]
	v_mfma_f32_16x16x32_bf16 v[6:9], v[178:181], v[220:223], v[6:9]
	v_mfma_f32_16x16x32_bf16 v[2:5], v[188:191], v[220:223], v[2:5]
	v_mfma_f32_16x16x32_bf16 v[54:57], v[182:185], v[200:203], v[54:57]
	v_mfma_f32_16x16x32_bf16 v[50:53], v[192:195], v[200:203], v[50:53]
	v_mfma_f32_16x16x32_bf16 v[38:41], v[182:185], v[208:211], v[38:41]
	v_mfma_f32_16x16x32_bf16 v[34:37], v[192:195], v[208:211], v[34:37]
	v_mfma_f32_16x16x32_bf16 v[22:25], v[182:185], v[216:219], v[22:25]
	v_mfma_f32_16x16x32_bf16 v[18:21], v[192:195], v[216:219], v[18:21]
	v_mfma_f32_16x16x32_bf16 v[6:9], v[182:185], v[224:227], v[6:9]
	v_mfma_f32_16x16x32_bf16 v[2:5], v[192:195], v[224:227], v[2:5]
	s_barrier
	s_setprio 0
	s_add_u32 s34, s34, 0x100
	s_addc_u32 s35, s35, 0
	s_add_u32 s63, s63, 0x100
	s_addc_u32 s65, s65, 0
	s_cmp_ge_i32 s66, s0
	s_mov_b32 s36, s66
	s_cbranch_scc0 .LBB0_713

; #define PG8_STAGE(bufoff, gbase, voff) do { _Pragma("unroll") for (int _i = 0; _i < 2; ++_i) \
;         __builtin_amdgcn_global_load_lds((const unsigned*)((const char*)(gbase) + (voff)[_i]), (PG8_LAS unsigned*)(lds + (bufoff) + ldsw + _i * 8192), 16, 0, 0); } while (0)
; #define PG8_LDA(dst, b, h) do { _Pragma("unroll") for (int m = 0; m < 4; ++m) _Pragma("unroll") for (int k = 0; k < 2; ++k) dst[m][k] = *(const PG8_LAS bf16x8*)(lds + PG8_SA(b, h) + aoff + m * 2048 + k * 1024); } while (0)
; #define PG8_LDB(dst, b, h) do { _Pragma("unroll") for (int n = 0; n < 2; ++n) _Pragma("unroll") for (int k = 0; k < 2; ++k) dst[n][k] = *(const PG8_LAS bf16x8*)(lds + PG8_SB(b, h) + boff + n * 2048 + k * 1024); } while (0)
; #define PG8_MMA(ai, bj, At, Bt) do { __builtin_amdgcn_s_setprio(1); _Pragma("unroll") for (int m = 0; m < 4; ++m) _Pragma("unroll") for (int n = 0; n < 2; ++n) _Pragma("unroll") for (int k = 0; k < 2; ++k) \
;         acc[ai][bj][m][n] = __builtin_amdgcn_mfma_f32_16x16x32_bf16(Bt[n][k], At[m][k], acc[ai][bj][m][n], 0, 0, 0); __builtin_amdgcn_s_setprio(0); } while (0)
; #define PG8_WAIT_V(n) asm volatile("s_waitcnt vmcnt(" #n ")" ::: "memory")
; #define PG8_WAIT_L(n) asm volatile("s_waitcnt lgkmcnt(" #n ")" ::: "memory")
; #define PG8_BAR __builtin_amdgcn_s_barrier()
; #define PG8_SCHED __builtin_amdgcn_sched_barrier(0)
; template <class Epi, class Sched, bool ALIGN_EPI = false, bool SP2 = false>
; __device__ __forceinline__ void gemm_phase(PG8_LAS unsigned char* lds, const Gemm g, const Sched& S, const Epi& E) {
;     ...
;             const bool last = (t == nt - 2);
;             const char* a1 = cA + (size_t)(t + 1) * kstep;
;             const char* a2 = last ? nA : cA + (size_t)(t + 2) * kstep; const char* b2 = last ? nB : cB + (size_t)(t + 2) * kstep;
;             const char* a3 = a2 + kstep; const char* b3 = b2 + kstep;
;             if (last && has_next) S.a_ready(nxt);
;             if constexpr (SP2) {
;             PG8_LDB(B0, 0, 0); PG8_LDB(B1, 0, 1); PG8_SCHED; PG8_LDA(At, 0, 0); PG8_STAGE(PG8_SA(1, 1), a1 + hstep, voffA);
;             PG8_WAIT_V(8); PG8_WAIT_L(0); PG8_BAR; PG8_MMA(0, 0, At, B0); PG8_MMA(0, 1, At, B1); PG8_BAR; PG8_SCHED;
;             PG8_LDA(At, 0, 1); PG8_STAGE(PG8_SB(0, 0), b2, voffB); PG8_STAGE(PG8_SB(0, 1), b2 + hstep, voffB); PG8_STAGE(PG8_SA(0, 0), a2, voffA);
.LBB0_738:
	ds_read_b128 v[160:163], v156
	ds_read_b128 v[164:167], v156 offset:1024
	ds_read_b128 v[168:171], v156 offset:2048
	ds_read_b128 v[172:175], v156 offset:3072
	ds_read_b128 v[176:179], v157
	ds_read_b128 v[180:183], v157 offset:1024
	ds_read_b128 v[188:191], v157 offset:2048
	ds_read_b128 v[192:195], v157 offset:3072
	s_add_i32 s71, s36, 2
	s_add_u32 s72, s34, 0x80
	s_addc_u32 s37, s35, 0
	s_cmp_eq_u32 s52, s36
	s_cselect_b32 s36, s14, s72
	s_cselect_b32 s37, s15, s37
	s_cselect_b32 s73, s31, s70
	s_cselect_b32 s72, s30, s69
	v_lshl_add_u64 v[152:153], s[34:35], 0, v[146:147]
	s_add_i32 m0, s42, 0xc000
	ds_read_b128 v[196:199], v158
	ds_read_b128 v[200:203], v158 offset:1024
	ds_read_b128 v[204:207], v158 offset:2048
	ds_read_b128 v[208:211], v158 offset:3072
	ds_read_b128 v[212:215], v158 offset:4096
	ds_read_b128 v[216:219], v158 offset:5120
	ds_read_b128 v[220:223], v158 offset:6144
	ds_read_b128 v[224:227], v158 offset:7168
	global_load_lds_dwordx4 v[152:153], off
	v_lshl_add_u64 v[152:153], s[34:35], 0, v[148:149]
	s_add_i32 m0, s42, 0xe000
	s_nop 0
	global_load_lds_dwordx4 v[152:153], off
	s_waitcnt vmcnt(8)
	s_waitcnt lgkmcnt(0)
	s_barrier
	s_setprio 1
	s_waitcnt lgkmcnt(0)
	v_mfma_f32_16x16x32_bf16 v[126:129], v[160:163], v[196:199], v[126:129]
	v_mfma_f32_16x16x32_bf16 v[122:125], v[168:171], v[196:199], v[122:125]
	v_mfma_f32_16x16x32_bf16 v[110:113], v[160:163], v[204:207], v[110:113]
	v_mfma_f32_16x16x32_bf16 v[106:109], v[168:171], v[204:207], v[106:109]
	v_mfma_f32_16x16x32_bf16 v[94:97], v[160:163], v[212:215], v[94:97]
	v_mfma_f32_16x16x32_bf16 v[90:93], v[168:171], v[212:215], v[90:93]
	v_mfma_f32_16x16x32_bf16 v[78:81], v[160:163], v[220:223], v[78:81]
	v_mfma_f32_16x16x32_bf16 v[74:77], v[168:171], v[220:223], v[74:77]
	v_mfma_f32_16x16x32_bf16 v[126:129], v[164:167], v[200:203], v[126:129]
	v_mfma_f32_16x16x32_bf16 v[122:125], v[172:175], v[200:203], v[122:125]
	v_mfma_f32_16x16x32_bf16 v[110:113], v[164:167], v[208:211], v[110:113]
	v_mfma_f32_16x16x32_bf16 v[106:109], v[172:175], v[208:211], v[106:109]
	v_mfma_f32_16x16x32_bf16 v[94:97], v[164:167], v[216:219], v[94:97]
	v_mfma_f32_16x16x32_bf16 v[90:93], v[172:175], v[216:219], v[90:93]
	v_mfma_f32_16x16x32_bf16 v[78:81], v[164:167], v[224:227], v[78:81]
	v_mfma_f32_16x16x32_bf16 v[74:77], v[172:175], v[224:227], v[74:77]
	v_mfma_f32_16x16x32_bf16 v[118:121], v[176:179], v[196:199], v[118:121]
	v_mfma_f32_16x16x32_bf16 v[114:117], v[188:191], v[196:199], v[114:117]
	v_mfma_f32_16x16x32_bf16 v[102:105], v[176:179], v[204:207], v[102:105]
	v_mfma_f32_16x16x32_bf16 v[98:101], v[188:191], v[204:207], v[98:101]
	v_mfma_f32_16x16x32_bf16 v[86:89], v[176:179], v[212:215], v[86:89]
	v_mfma_f32_16x16x32_bf16 v[82:85], v[188:191], v[212:215], v[82:85]
	v_mfma_f32_16x16x32_bf16 v[70:73], v[176:179], v[220:223], v[70:73]
	v_mfma_f32_16x16x32_bf16 v[66:69], v[188:191], v[220:223], v[66:69]
	v_mfma_f32_16x16x32_bf16 v[118:121], v[180:183], v[200:203], v[118:121]
	v_mfma_f32_16x16x32_bf16 v[114:117], v[192:195], v[200:203], v[114:117]
	v_mfma_f32_16x16x32_bf16 v[102:105], v[180:183], v[208:211], v[102:105]
	v_mfma_f32_16x16x32_bf16 v[98:101], v[192:195], v[208:211], v[98:101]
	v_mfma_f32_16x16x32_bf16 v[86:89], v[180:183], v[216:219], v[86:89]
	v_mfma_f32_16x16x32_bf16 v[82:85], v[192:195], v[216:219], v[82:85]
	v_mfma_f32_16x16x32_bf16 v[70:73], v[180:183], v[224:227], v[70:73]
	v_mfma_f32_16x16x32_bf16 v[66:69], v[192:195], v[224:227], v[66:69]
	s_barrier
	s_setprio 0
	s_add_i32 s74, s13, s41
	v_lshl_add_u64 v[152:153], s[72:73], 0, v[134:135]
	s_mov_b32 m0, s74
	ds_read_b128 v[196:199], v158 offset:16384
	ds_read_b128 v[200:203], v158 offset:17408
	ds_read_b128 v[204:207], v158 offset:18432
	ds_read_b128 v[208:211], v158 offset:19456
	ds_read_b128 v[212:215], v158 offset:20480
	ds_read_b128 v[216:219], v158 offset:21504
	ds_read_b128 v[220:223], v158 offset:22528
	ds_read_b128 v[224:227], v158 offset:23552
	global_load_lds_dwordx4 v[152:153], off
	s_add_i32 m0, s74, 0x2000
	v_lshl_add_u64 v[184:185], s[72:73], 0, v[130:131]
	s_add_u32 s72, s72, s6
	s_addc_u32 s73, s73, s7
	s_add_i32 s74, s53, s41
	global_load_lds_dwordx4 v[184:185], off
	v_lshl_add_u64 v[228:229], s[72:73], 0, v[134:135]
	s_mov_b32 m0, s74
	v_lshl_add_u64 v[230:231], s[72:73], 0, v[130:131]
	global_load_lds_dwordx4 v[228:229], off
	s_add_i32 m0, s74, 0x2000
	v_lshl_add_u64 v[232:233], s[36:37], 0, v[136:137]
	global_load_lds_dwordx4 v[230:231], off
	s_mov_b32 m0, s42
	v_lshl_add_u64 v[234:235], s[36:37], 0, v[132:133]
	global_load_lds_dwordx4 v[232:233], off
	s_mov_b32 m0, s43
	s_nop 0
	global_load_lds_dwordx4 v[234:235], off
	s_waitcnt vmcnt(8)
	s_waitcnt lgkmcnt(0)
	s_barrier
; #define PG8_STAGE(bufoff, gbase, voff) do { _Pragma("unroll") for (int _i = 0; _i < 2; ++_i) \
;         __builtin_amdgcn_global_load_lds((const unsigned*)((const char*)(gbase) + (voff)[_i]), (PG8_LAS unsigned*)(lds + (bufoff) + ldsw + _i * 8192), 16, 0, 0); } while (0)
; #define PG8_LDA(dst, b, h) do { _Pragma("unroll") for (int m = 0; m < 4; ++m) _Pragma("unroll") for (int k = 0; k < 2; ++k) dst[m][k] = *(const PG8_LAS bf16x8*)(lds + PG8_SA(b, h) + aoff + m * 2048 + k * 1024); } while (0)
; #define PG8_LDB(dst, b, h) do { _Pragma("unroll") for (int n = 0; n < 2; ++n) _Pragma("unroll") for (int k = 0; k < 2; ++k) dst[n][k] = *(const PG8_LAS bf16x8*)(lds + PG8_SB(b, h) + boff + n * 2048 + k * 1024); } while (0)
; #define PG8_MMA(ai, bj, At, Bt) do { __builtin_amdgcn_s_setprio(1); _Pragma("unroll") for (int m = 0; m < 4; ++m) _Pragma("unroll") for (int n = 0; n < 2; ++n) _Pragma("unroll") for (int k = 0; k < 2; ++k) \
;         acc[ai][bj][m][n] = __builtin_amdgcn_mfma_f32_16x16x32_bf16(Bt[n][k], At[m][k], acc[ai][bj][m][n], 0, 0, 0); __builtin_amdgcn_s_setprio(0); } while (0)
; #define PG8_WAIT_V(n) asm volatile("s_waitcnt vmcnt(" #n ")" ::: "memory")
; #define PG8_WAIT_L(n) asm volatile("s_waitcnt lgkmcnt(" #n ")" ::: "memory")
; #define PG8_BAR __builtin_amdgcn_s_barrier()
; #define PG8_SCHED __builtin_amdgcn_sched_barrier(0)
; template <class Epi, class Sched, bool ALIGN_EPI = false, bool SP2 = false>
; __device__ __forceinline__ void gemm_phase(PG8_LAS unsigned char* lds, const Gemm g, const Sched& S, const Epi& E) {
;     ...
;             PG8_WAIT_V(8); PG8_WAIT_L(0); PG8_BAR; PG8_MMA(1, 0, At, B0); PG8_MMA(1, 1, At, B1); PG8_BAR; PG8_SCHED;
;             PG8_LDB(B0, 1, 0); PG8_LDB(B1, 1, 1); PG8_SCHED; PG8_LDA(At, 1, 0); PG8_STAGE(PG8_SA(0, 1), a2 + hstep, voffA);
;             PG8_WAIT_V(8); PG8_WAIT_L(0); PG8_BAR; PG8_MMA(0, 0, At, B0); PG8_MMA(0, 1, At, B1); PG8_BAR; PG8_SCHED;
	s_setprio 1
	s_waitcnt lgkmcnt(0)
	v_mfma_f32_16x16x32_bf16 v[62:65], v[160:163], v[196:199], v[62:65]
	v_mfma_f32_16x16x32_bf16 v[58:61], v[168:171], v[196:199], v[58:61]
	v_mfma_f32_16x16x32_bf16 v[46:49], v[160:163], v[204:207], v[46:49]
	v_mfma_f32_16x16x32_bf16 v[42:45], v[168:171], v[204:207], v[42:45]
	v_mfma_f32_16x16x32_bf16 v[30:33], v[160:163], v[212:215], v[30:33]
	v_mfma_f32_16x16x32_bf16 v[26:29], v[168:171], v[212:215], v[26:29]
	v_mfma_f32_16x16x32_bf16 v[14:17], v[160:163], v[220:223], v[14:17]
	v_mfma_f32_16x16x32_bf16 v[10:13], v[168:171], v[220:223], v[10:13]
	v_mfma_f32_16x16x32_bf16 v[62:65], v[164:167], v[200:203], v[62:65]
	v_mfma_f32_16x16x32_bf16 v[58:61], v[172:175], v[200:203], v[58:61]
	v_mfma_f32_16x16x32_bf16 v[46:49], v[164:167], v[208:211], v[46:49]
	v_mfma_f32_16x16x32_bf16 v[42:45], v[172:175], v[208:211], v[42:45]
	v_mfma_f32_16x16x32_bf16 v[30:33], v[164:167], v[216:219], v[30:33]
	v_mfma_f32_16x16x32_bf16 v[26:29], v[172:175], v[216:219], v[26:29]
	v_mfma_f32_16x16x32_bf16 v[14:17], v[164:167], v[224:227], v[14:17]
	v_mfma_f32_16x16x32_bf16 v[10:13], v[172:175], v[224:227], v[10:13]
	v_mfma_f32_16x16x32_bf16 v[54:57], v[176:179], v[196:199], v[54:57]
	v_mfma_f32_16x16x32_bf16 v[50:53], v[188:191], v[196:199], v[50:53]
	v_mfma_f32_16x16x32_bf16 v[38:41], v[176:179], v[204:207], v[38:41]
	v_mfma_f32_16x16x32_bf16 v[34:37], v[188:191], v[204:207], v[34:37]
	v_mfma_f32_16x16x32_bf16 v[22:25], v[176:179], v[212:215], v[22:25]
	v_mfma_f32_16x16x32_bf16 v[18:21], v[188:191], v[212:215], v[18:21]
	v_mfma_f32_16x16x32_bf16 v[6:9], v[176:179], v[220:223], v[6:9]
	v_mfma_f32_16x16x32_bf16 v[2:5], v[188:191], v[220:223], v[2:5]
	v_mfma_f32_16x16x32_bf16 v[54:57], v[180:183], v[200:203], v[54:57]
	v_mfma_f32_16x16x32_bf16 v[50:53], v[192:195], v[200:203], v[50:53]
	v_mfma_f32_16x16x32_bf16 v[38:41], v[180:183], v[208:211], v[38:41]
	v_mfma_f32_16x16x32_bf16 v[34:37], v[192:195], v[208:211], v[34:37]
	v_mfma_f32_16x16x32_bf16 v[22:25], v[180:183], v[216:219], v[22:25]
	v_mfma_f32_16x16x32_bf16 v[18:21], v[192:195], v[216:219], v[18:21]
	v_mfma_f32_16x16x32_bf16 v[6:9], v[180:183], v[224:227], v[6:9]
	v_mfma_f32_16x16x32_bf16 v[2:5], v[192:195], v[224:227], v[2:5]
	s_barrier
	s_setprio 0
	s_add_i32 s72, 0, 0x18000
	v_add_u32_e32 v138, s72, v154
	s_add_i32 s73, 0, 0x1c000
	ds_read_b128 v[160:163], v138
	ds_read_b128 v[164:167], v138 offset:1024
	ds_read_b128 v[168:171], v138 offset:2048
	ds_read_b128 v[172:175], v138 offset:3072
	v_add_u32_e32 v138, s73, v154
	ds_read_b128 v[176:179], v138
	ds_read_b128 v[180:183], v138 offset:1024
	ds_read_b128 v[188:191], v138 offset:2048
	ds_read_b128 v[192:195], v138 offset:3072
	s_add_u32 s36, s36, s6
	s_addc_u32 s37, s37, s7
	s_mov_b32 m0, s48
	v_lshl_add_u64 v[236:237], s[36:37], 0, v[136:137]
	ds_read_b128 v[196:199], v158 offset:32768
	ds_read_b128 v[200:203], v158 offset:33792
	ds_read_b128 v[204:207], v158 offset:34816
	ds_read_b128 v[208:211], v158 offset:35840
	ds_read_b128 v[212:215], v158 offset:36864
	ds_read_b128 v[216:219], v158 offset:37888
	ds_read_b128 v[220:223], v158 offset:38912
	ds_read_b128 v[224:227], v158 offset:39936
	global_load_lds_dwordx4 v[236:237], off
	v_lshl_add_u64 v[236:237], s[36:37], 0, v[132:133]
	s_mov_b32 m0, s49
	s_nop 0
	global_load_lds_dwordx4 v[236:237], off
	s_waitcnt vmcnt(8)
	s_waitcnt lgkmcnt(0)
	s_barrier
	s_setprio 1
	s_waitcnt lgkmcnt(0)
	v_mfma_f32_16x16x32_bf16 v[126:129], v[160:163], v[196:199], v[126:129]
	v_mfma_f32_16x16x32_bf16 v[122:125], v[168:171], v[196:199], v[122:125]
	v_mfma_f32_16x16x32_bf16 v[110:113], v[160:163], v[204:207], v[110:113]
	v_mfma_f32_16x16x32_bf16 v[106:109], v[168:171], v[204:207], v[106:109]
	v_mfma_f32_16x16x32_bf16 v[94:97], v[160:163], v[212:215], v[94:97]
	v_mfma_f32_16x16x32_bf16 v[90:93], v[168:171], v[212:215], v[90:93]
	v_mfma_f32_16x16x32_bf16 v[78:81], v[160:163], v[220:223], v[78:81]
	v_mfma_f32_16x16x32_bf16 v[74:77], v[168:171], v[220:223], v[74:77]
	v_mfma_f32_16x16x32_bf16 v[126:129], v[164:167], v[200:203], v[126:129]
	v_mfma_f32_16x16x32_bf16 v[122:125], v[172:175], v[200:203], v[122:125]
	v_mfma_f32_16x16x32_bf16 v[110:113], v[164:167], v[208:211], v[110:113]
	v_mfma_f32_16x16x32_bf16 v[106:109], v[172:175], v[208:211], v[106:109]
	v_mfma_f32_16x16x32_bf16 v[94:97], v[164:167], v[216:219], v[94:97]
	v_mfma_f32_16x16x32_bf16 v[90:93], v[172:175], v[216:219], v[90:93]
	v_mfma_f32_16x16x32_bf16 v[78:81], v[164:167], v[224:227], v[78:81]
	v_mfma_f32_16x16x32_bf16 v[74:77], v[172:175], v[224:227], v[74:77]
	v_mfma_f32_16x16x32_bf16 v[118:121], v[176:179], v[196:199], v[118:121]
	v_mfma_f32_16x16x32_bf16 v[114:117], v[188:191], v[196:199], v[114:117]
	v_mfma_f32_16x16x32_bf16 v[102:105], v[176:179], v[204:207], v[102:105]
	v_mfma_f32_16x16x32_bf16 v[98:101], v[188:191], v[204:207], v[98:101]
	v_mfma_f32_16x16x32_bf16 v[86:89], v[176:179], v[212:215], v[86:89]
	v_mfma_f32_16x16x32_bf16 v[82:85], v[188:191], v[212:215], v[82:85]
	v_mfma_f32_16x16x32_bf16 v[70:73], v[176:179], v[220:223], v[70:73]
	v_mfma_f32_16x16x32_bf16 v[66:69], v[188:191], v[220:223], v[66:69]
	v_mfma_f32_16x16x32_bf16 v[118:121], v[180:183], v[200:203], v[118:121]
	v_mfma_f32_16x16x32_bf16 v[114:117], v[192:195], v[200:203], v[114:117]
	v_mfma_f32_16x16x32_bf16 v[102:105], v[180:183], v[208:211], v[102:105]
	v_mfma_f32_16x16x32_bf16 v[98:101], v[192:195], v[208:211], v[98:101]
	v_mfma_f32_16x16x32_bf16 v[86:89], v[180:183], v[216:219], v[86:89]
	v_mfma_f32_16x16x32_bf16 v[82:85], v[192:195], v[216:219], v[82:85]
	v_mfma_f32_16x16x32_bf16 v[70:73], v[180:183], v[224:227], v[70:73]
	v_mfma_f32_16x16x32_bf16 v[66:69], v[192:195], v[224:227], v[66:69]
	s_barrier
; #define PG8_STAGE(bufoff, gbase, voff) do { _Pragma("unroll") for (int _i = 0; _i < 2; ++_i) \
;         __builtin_amdgcn_global_load_lds((const unsigned*)((const char*)(gbase) + (voff)[_i]), (PG8_LAS unsigned*)(lds + (bufoff) + ldsw + _i * 8192), 16, 0, 0); } while (0)
; #define PG8_LDA(dst, b, h) do { _Pragma("unroll") for (int m = 0; m < 4; ++m) _Pragma("unroll") for (int k = 0; k < 2; ++k) dst[m][k] = *(const PG8_LAS bf16x8*)(lds + PG8_SA(b, h) + aoff + m * 2048 + k * 1024); } while (0)
; #define PG8_WAIT_V(n) asm volatile("s_waitcnt vmcnt(" #n ")" ::: "memory")
; #define PG8_BAR __builtin_amdgcn_s_barrier()
; template <class Epi, class Sched, bool ALIGN_EPI = false, bool SP2 = false>
; __device__ __forceinline__ void gemm_phase(PG8_LAS unsigned char* lds, const Gemm g, const Sched& S, const Epi& E) {
;     ...
;             PG8_LDA(At, 1, 1); PG8_STAGE(PG8_SB(1, 0), b3, voffB); PG8_STAGE(PG8_SB(1, 1), b3 + hstep, voffB); PG8_STAGE(PG8_SA(1, 0), a3, voffA);
;             PG8_WAIT_V(8); PG8_WAIT_L(0); PG8_BAR; PG8_MMA(1, 0, At, B0); PG8_MMA(1, 1, At, B1); PG8_BAR; PG8_SCHED;
;             } else {
;             PG8_LDB(B0, 0, 0); PG8_SCHED; PG8_LDA(At, 0, 0); PG8_STAGE(PG8_SA(1, 1), a1 + hstep, voffA);
;             PG8_WAIT_L(8); PG8_BAR; PG8_WAIT_L(0); PG8_MMA(0, 0, At, B0); PG8_BAR; PG8_SCHED;
;             PG8_LDB(B1, 0, 1); PG8_STAGE(PG8_SB(0, 0), b2, voffB);
;             PG8_BAR; PG8_WAIT_L(0); PG8_MMA(0, 1, At, B1); PG8_BAR;
;             PG8_LDA(At, 0, 1); PG8_STAGE(PG8_SA(0, 0), a2, voffA);
;             PG8_BAR; PG8_WAIT_L(0); PG8_MMA(1, 0, At, B0); PG8_BAR; PG8_SCHED;
;             PG8_STAGE(PG8_SB(0, 1), b2 + hstep, voffB);
;             PG8_WAIT_V(6); PG8_BAR; PG8_MMA(1, 1, At, B1); PG8_BAR;
;             PG8_LDB(B0, 1, 0); PG8_SCHED; PG8_LDA(At, 1, 0); PG8_STAGE(PG8_SA(0, 1), a2 + hstep, voffA);
;             PG8_WAIT_L(8); PG8_BAR; PG8_WAIT_L(0); PG8_MMA(0, 0, At, B0); PG8_BAR; PG8_SCHED;
;             PG8_LDB(B1, 1, 1); PG8_STAGE(PG8_SB(1, 0), b3, voffB);
;             PG8_BAR; PG8_WAIT_L(0); PG8_MMA(0, 1, At, B1); PG8_BAR;
;             PG8_LDA(At, 1, 1); PG8_STAGE(PG8_SA(1, 0), a3, voffA);
;             PG8_BAR; PG8_WAIT_L(0); PG8_MMA(1, 0, At, B0); PG8_BAR; PG8_SCHED;
;             PG8_STAGE(PG8_SB(1, 1), b3 + hstep, voffB);
;             PG8_WAIT_V(6); PG8_BAR; PG8_MMA(1, 1, At, B1); PG8_BAR;
;             }
;         }
	s_setprio 0
	s_add_i32 s36, s72, s41
	v_lshl_add_u64 v[152:153], v[152:153], 0, s[24:25]
	s_mov_b32 m0, s36
	ds_read_b128 v[196:199], v158 offset:49152
	ds_read_b128 v[200:203], v158 offset:50176
	ds_read_b128 v[204:207], v158 offset:51200
	ds_read_b128 v[208:211], v158 offset:52224
	ds_read_b128 v[212:215], v158 offset:53248
	ds_read_b128 v[216:219], v158 offset:54272
	ds_read_b128 v[220:223], v158 offset:55296
	ds_read_b128 v[224:227], v158 offset:56320
	global_load_lds_dwordx4 v[152:153], off
	v_lshl_add_u64 v[152:153], v[184:185], 0, s[24:25]
	s_add_i32 m0, s36, 0x2000
	s_add_i32 s36, s73, s41
	global_load_lds_dwordx4 v[152:153], off
	v_lshl_add_u64 v[152:153], v[228:229], 0, s[24:25]
	s_mov_b32 m0, s36
	s_nop 0
	global_load_lds_dwordx4 v[152:153], off
	v_lshl_add_u64 v[152:153], v[230:231], 0, s[24:25]
	s_add_i32 m0, s36, 0x2000
	s_nop 0
	global_load_lds_dwordx4 v[152:153], off
	v_lshl_add_u64 v[152:153], v[232:233], 0, s[24:25]
	s_mov_b32 m0, s11
	s_nop 0
	global_load_lds_dwordx4 v[152:153], off
	v_lshl_add_u64 v[152:153], v[234:235], 0, s[24:25]
	s_mov_b32 m0, s50
	s_nop 0
	global_load_lds_dwordx4 v[152:153], off
	s_waitcnt vmcnt(8)
	s_waitcnt lgkmcnt(0)
	s_barrier
	s_setprio 1
	s_waitcnt lgkmcnt(0)
	v_mfma_f32_16x16x32_bf16 v[62:65], v[160:163], v[196:199], v[62:65]
	v_mfma_f32_16x16x32_bf16 v[58:61], v[168:171], v[196:199], v[58:61]
	v_mfma_f32_16x16x32_bf16 v[46:49], v[160:163], v[204:207], v[46:49]
	v_mfma_f32_16x16x32_bf16 v[42:45], v[168:171], v[204:207], v[42:45]
	v_mfma_f32_16x16x32_bf16 v[30:33], v[160:163], v[212:215], v[30:33]
	v_mfma_f32_16x16x32_bf16 v[26:29], v[168:171], v[212:215], v[26:29]
	v_mfma_f32_16x16x32_bf16 v[14:17], v[160:163], v[220:223], v[14:17]
	v_mfma_f32_16x16x32_bf16 v[10:13], v[168:171], v[220:223], v[10:13]
	v_mfma_f32_16x16x32_bf16 v[62:65], v[164:167], v[200:203], v[62:65]
	v_mfma_f32_16x16x32_bf16 v[58:61], v[172:175], v[200:203], v[58:61]
	v_mfma_f32_16x16x32_bf16 v[46:49], v[164:167], v[208:211], v[46:49]
	v_mfma_f32_16x16x32_bf16 v[42:45], v[172:175], v[208:211], v[42:45]
	v_mfma_f32_16x16x32_bf16 v[30:33], v[164:167], v[216:219], v[30:33]
	v_mfma_f32_16x16x32_bf16 v[26:29], v[172:175], v[216:219], v[26:29]
	v_mfma_f32_16x16x32_bf16 v[14:17], v[164:167], v[224:227], v[14:17]
	v_mfma_f32_16x16x32_bf16 v[10:13], v[172:175], v[224:227], v[10:13]
	v_mfma_f32_16x16x32_bf16 v[54:57], v[176:179], v[196:199], v[54:57]
	v_mfma_f32_16x16x32_bf16 v[50:53], v[188:191], v[196:199], v[50:53]
	v_mfma_f32_16x16x32_bf16 v[38:41], v[176:179], v[204:207], v[38:41]
	v_mfma_f32_16x16x32_bf16 v[34:37], v[188:191], v[204:207], v[34:37]
	v_mfma_f32_16x16x32_bf16 v[22:25], v[176:179], v[212:215], v[22:25]
	v_mfma_f32_16x16x32_bf16 v[18:21], v[188:191], v[212:215], v[18:21]
	v_mfma_f32_16x16x32_bf16 v[6:9], v[176:179], v[220:223], v[6:9]
	v_mfma_f32_16x16x32_bf16 v[2:5], v[188:191], v[220:223], v[2:5]
	v_mfma_f32_16x16x32_bf16 v[54:57], v[180:183], v[200:203], v[54:57]
	v_mfma_f32_16x16x32_bf16 v[50:53], v[192:195], v[200:203], v[50:53]
	v_mfma_f32_16x16x32_bf16 v[38:41], v[180:183], v[208:211], v[38:41]
	v_mfma_f32_16x16x32_bf16 v[34:37], v[192:195], v[208:211], v[34:37]
	v_mfma_f32_16x16x32_bf16 v[22:25], v[180:183], v[216:219], v[22:25]
	v_mfma_f32_16x16x32_bf16 v[18:21], v[192:195], v[216:219], v[18:21]
	v_mfma_f32_16x16x32_bf16 v[6:9], v[180:183], v[224:227], v[6:9]
	v_mfma_f32_16x16x32_bf16 v[2:5], v[192:195], v[224:227], v[2:5]
	s_barrier
	s_setprio 0
	s_add_u32 s34, s34, 0x100
	s_addc_u32 s35, s35, 0
	s_add_u32 s69, s69, 0x100
	s_addc_u32 s70, s70, 0
	s_cmp_ge_i32 s71, s0
	s_mov_b32 s36, s71
	s_cbranch_scc0 .LBB0_738

; #define PG8_STAGE(bufoff, gbase, voff) do { _Pragma("unroll") for (int _i = 0; _i < 2; ++_i) \
;         __builtin_amdgcn_global_load_lds((const unsigned*)((const char*)(gbase) + (voff)[_i]), (PG8_LAS unsigned*)(lds + (bufoff) + ldsw + _i * 8192), 16, 0, 0); } while (0)
; #define PG8_LDA(dst, b, h) do { _Pragma("unroll") for (int m = 0; m < 4; ++m) _Pragma("unroll") for (int k = 0; k < 2; ++k) dst[m][k] = *(const PG8_LAS bf16x8*)(lds + PG8_SA(b, h) + aoff + m * 2048 + k * 1024); } while (0)
; #define PG8_LDB(dst, b, h) do { _Pragma("unroll") for (int n = 0; n < 2; ++n) _Pragma("unroll") for (int k = 0; k < 2; ++k) dst[n][k] = *(const PG8_LAS bf16x8*)(lds + PG8_SB(b, h) + boff + n * 2048 + k * 1024); } while (0)
; #define PG8_MMA(ai, bj, At, Bt) do { __builtin_amdgcn_s_setprio(1); _Pragma("unroll") for (int m = 0; m < 4; ++m) _Pragma("unroll") for (int n = 0; n < 2; ++n) _Pragma("unroll") for (int k = 0; k < 2; ++k) \
;         acc[ai][bj][m][n] = __builtin_amdgcn_mfma_f32_16x16x32_bf16(Bt[n][k], At[m][k], acc[ai][bj][m][n], 0, 0, 0); __builtin_amdgcn_s_setprio(0); } while (0)
; #define PG8_WAIT_V(n) asm volatile("s_waitcnt vmcnt(" #n ")" ::: "memory")
; #define PG8_WAIT_L(n) asm volatile("s_waitcnt lgkmcnt(" #n ")" ::: "memory")
; #define PG8_BAR __builtin_amdgcn_s_barrier()
; #define PG8_SCHED __builtin_amdgcn_sched_barrier(0)
; template <class Epi, class Sched, bool ALIGN_EPI = false, bool SP2 = false>
; __device__ __forceinline__ void gemm_phase(PG8_LAS unsigned char* lds, const Gemm g, const Sched& S, const Epi& E) {
;     ...
;             const bool last = (t == nt - 2);
;             const char* a1 = cA + (size_t)(t + 1) * kstep;
;             const char* a2 = last ? nA : cA + (size_t)(t + 2) * kstep; const char* b2 = last ? nB : cB + (size_t)(t + 2) * kstep;
;             const char* a3 = a2 + kstep; const char* b3 = b2 + kstep;
;             if (last && has_next) S.a_ready(nxt);
;             if constexpr (SP2) {
;             PG8_LDB(B0, 0, 0); PG8_LDB(B1, 0, 1); PG8_SCHED; PG8_LDA(At, 0, 0); PG8_STAGE(PG8_SA(1, 1), a1 + hstep, voffA);
;             PG8_WAIT_V(8); PG8_WAIT_L(0); PG8_BAR; PG8_MMA(0, 0, At, B0); PG8_MMA(0, 1, At, B1); PG8_BAR; PG8_SCHED;
;             PG8_LDA(At, 0, 1); PG8_STAGE(PG8_SB(0, 0), b2, voffB); PG8_STAGE(PG8_SB(0, 1), b2 + hstep, voffB); PG8_STAGE(PG8_SA(0, 0), a2, voffA);
.LBB0_771:
	ds_read_b128 v[156:159], v152
	ds_read_b128 v[160:163], v152 offset:1024
	ds_read_b128 v[164:167], v152 offset:2048
	ds_read_b128 v[168:171], v152 offset:3072
	ds_read_b128 v[172:175], v153
	ds_read_b128 v[176:179], v153 offset:1024
	ds_read_b128 v[180:183], v153 offset:2048
	ds_read_b128 v[188:191], v153 offset:3072
	s_add_i32 s65, s34, 2
	s_add_u32 s66, s30, 0x80
	s_addc_u32 s35, s31, 0
	s_cmp_eq_u32 s52, s34
	s_cselect_b32 s34, s4, s66
	s_cselect_b32 s35, s5, s35
	s_cselect_b32 s67, s29, s63
	s_cselect_b32 s66, s28, s62
	v_lshl_add_u64 v[184:185], s[30:31], 0, v[142:143]
	s_add_i32 m0, s40, 0xc000
	ds_read_b128 v[192:195], v154
	ds_read_b128 v[196:199], v154 offset:1024
	ds_read_b128 v[200:203], v154 offset:2048
	ds_read_b128 v[204:207], v154 offset:3072
	ds_read_b128 v[208:211], v154 offset:4096
	ds_read_b128 v[212:215], v154 offset:5120
	ds_read_b128 v[216:219], v154 offset:6144
	ds_read_b128 v[220:223], v154 offset:7168
	global_load_lds_dwordx4 v[184:185], off
	v_lshl_add_u64 v[184:185], s[30:31], 0, v[144:145]
	s_add_i32 m0, s40, 0xe000
	s_nop 0
	global_load_lds_dwordx4 v[184:185], off
	s_waitcnt vmcnt(8)
	s_waitcnt lgkmcnt(0)
	s_barrier
	s_setprio 1
	s_waitcnt lgkmcnt(0)
	v_mfma_f32_16x16x32_bf16 v[122:125], v[156:159], v[192:195], v[122:125]
	v_mfma_f32_16x16x32_bf16 v[126:129], v[164:167], v[192:195], v[126:129]
	v_mfma_f32_16x16x32_bf16 v[110:113], v[156:159], v[200:203], v[110:113]
	v_mfma_f32_16x16x32_bf16 v[106:109], v[164:167], v[200:203], v[106:109]
	v_mfma_f32_16x16x32_bf16 v[94:97], v[156:159], v[208:211], v[94:97]
	v_mfma_f32_16x16x32_bf16 v[90:93], v[164:167], v[208:211], v[90:93]
	v_mfma_f32_16x16x32_bf16 v[78:81], v[156:159], v[216:219], v[78:81]
	v_mfma_f32_16x16x32_bf16 v[74:77], v[164:167], v[216:219], v[74:77]
	v_mfma_f32_16x16x32_bf16 v[122:125], v[160:163], v[196:199], v[122:125]
	v_mfma_f32_16x16x32_bf16 v[126:129], v[168:171], v[196:199], v[126:129]
	v_mfma_f32_16x16x32_bf16 v[110:113], v[160:163], v[204:207], v[110:113]
	v_mfma_f32_16x16x32_bf16 v[106:109], v[168:171], v[204:207], v[106:109]
	v_mfma_f32_16x16x32_bf16 v[94:97], v[160:163], v[212:215], v[94:97]
	v_mfma_f32_16x16x32_bf16 v[90:93], v[168:171], v[212:215], v[90:93]
	v_mfma_f32_16x16x32_bf16 v[78:81], v[160:163], v[220:223], v[78:81]
	v_mfma_f32_16x16x32_bf16 v[74:77], v[168:171], v[220:223], v[74:77]
	v_mfma_f32_16x16x32_bf16 v[118:121], v[172:175], v[192:195], v[118:121]
	v_mfma_f32_16x16x32_bf16 v[114:117], v[180:183], v[192:195], v[114:117]
	v_mfma_f32_16x16x32_bf16 v[102:105], v[172:175], v[200:203], v[102:105]
	v_mfma_f32_16x16x32_bf16 v[98:101], v[180:183], v[200:203], v[98:101]
	v_mfma_f32_16x16x32_bf16 v[86:89], v[172:175], v[208:211], v[86:89]
	v_mfma_f32_16x16x32_bf16 v[82:85], v[180:183], v[208:211], v[82:85]
	v_mfma_f32_16x16x32_bf16 v[70:73], v[172:175], v[216:219], v[70:73]
	v_mfma_f32_16x16x32_bf16 v[66:69], v[180:183], v[216:219], v[66:69]
	v_mfma_f32_16x16x32_bf16 v[118:121], v[176:179], v[196:199], v[118:121]
	v_mfma_f32_16x16x32_bf16 v[114:117], v[188:191], v[196:199], v[114:117]
	v_mfma_f32_16x16x32_bf16 v[102:105], v[176:179], v[204:207], v[102:105]
	v_mfma_f32_16x16x32_bf16 v[98:101], v[188:191], v[204:207], v[98:101]
	v_mfma_f32_16x16x32_bf16 v[86:89], v[176:179], v[212:215], v[86:89]
	v_mfma_f32_16x16x32_bf16 v[82:85], v[188:191], v[212:215], v[82:85]
	v_mfma_f32_16x16x32_bf16 v[70:73], v[176:179], v[220:223], v[70:73]
	v_mfma_f32_16x16x32_bf16 v[66:69], v[188:191], v[220:223], v[66:69]
	s_barrier
	s_setprio 0
	s_add_i32 s68, s55, s39
	v_lshl_add_u64 v[184:185], s[66:67], 0, v[132:133]
	s_mov_b32 m0, s68
	ds_read_b128 v[192:195], v154 offset:16384
	ds_read_b128 v[196:199], v154 offset:17408
	ds_read_b128 v[200:203], v154 offset:18432
	ds_read_b128 v[204:207], v154 offset:19456
	ds_read_b128 v[208:211], v154 offset:20480
	ds_read_b128 v[212:215], v154 offset:21504
	ds_read_b128 v[216:219], v154 offset:22528
	ds_read_b128 v[220:223], v154 offset:23552
	global_load_lds_dwordx4 v[184:185], off
	s_add_i32 m0, s68, 0x2000
	v_lshl_add_u64 v[224:225], s[66:67], 0, v[136:137]
	s_add_u32 s66, s66, s12
	s_addc_u32 s67, s67, s13
	s_add_i32 s68, s56, s39
	global_load_lds_dwordx4 v[224:225], off
	v_lshl_add_u64 v[226:227], s[66:67], 0, v[132:133]
	s_mov_b32 m0, s68
	v_lshl_add_u64 v[228:229], s[66:67], 0, v[136:137]
	global_load_lds_dwordx4 v[226:227], off
	s_add_i32 m0, s68, 0x2000
	v_lshl_add_u64 v[230:231], s[34:35], 0, v[130:131]
	global_load_lds_dwordx4 v[228:229], off
	s_mov_b32 m0, s40
	v_lshl_add_u64 v[232:233], s[34:35], 0, v[134:135]
	global_load_lds_dwordx4 v[230:231], off
	s_mov_b32 m0, s41
	s_nop 0
	global_load_lds_dwordx4 v[232:233], off
	s_waitcnt vmcnt(8)
	s_waitcnt lgkmcnt(0)
	s_barrier
; #define PG8_STAGE(bufoff, gbase, voff) do { _Pragma("unroll") for (int _i = 0; _i < 2; ++_i) \
;         __builtin_amdgcn_global_load_lds((const unsigned*)((const char*)(gbase) + (voff)[_i]), (PG8_LAS unsigned*)(lds + (bufoff) + ldsw + _i * 8192), 16, 0, 0); } while (0)
; #define PG8_LDA(dst, b, h) do { _Pragma("unroll") for (int m = 0; m < 4; ++m) _Pragma("unroll") for (int k = 0; k < 2; ++k) dst[m][k] = *(const PG8_LAS bf16x8*)(lds + PG8_SA(b, h) + aoff + m * 2048 + k * 1024); } while (0)
; #define PG8_LDB(dst, b, h) do { _Pragma("unroll") for (int n = 0; n < 2; ++n) _Pragma("unroll") for (int k = 0; k < 2; ++k) dst[n][k] = *(const PG8_LAS bf16x8*)(lds + PG8_SB(b, h) + boff + n * 2048 + k * 1024); } while (0)
; #define PG8_MMA(ai, bj, At, Bt) do { __builtin_amdgcn_s_setprio(1); _Pragma("unroll") for (int m = 0; m < 4; ++m) _Pragma("unroll") for (int n = 0; n < 2; ++n) _Pragma("unroll") for (int k = 0; k < 2; ++k) \
;         acc[ai][bj][m][n] = __builtin_amdgcn_mfma_f32_16x16x32_bf16(Bt[n][k], At[m][k], acc[ai][bj][m][n], 0, 0, 0); __builtin_amdgcn_s_setprio(0); } while (0)
; #define PG8_WAIT_V(n) asm volatile("s_waitcnt vmcnt(" #n ")" ::: "memory")
; #define PG8_WAIT_L(n) asm volatile("s_waitcnt lgkmcnt(" #n ")" ::: "memory")
; #define PG8_BAR __builtin_amdgcn_s_barrier()
; #define PG8_SCHED __builtin_amdgcn_sched_barrier(0)
; template <class Epi, class Sched, bool ALIGN_EPI = false, bool SP2 = false>
; __device__ __forceinline__ void gemm_phase(PG8_LAS unsigned char* lds, const Gemm g, const Sched& S, const Epi& E) {
;     ...
;             PG8_WAIT_V(8); PG8_WAIT_L(0); PG8_BAR; PG8_MMA(1, 0, At, B0); PG8_MMA(1, 1, At, B1); PG8_BAR; PG8_SCHED;
;             PG8_LDB(B0, 1, 0); PG8_LDB(B1, 1, 1); PG8_SCHED; PG8_LDA(At, 1, 0); PG8_STAGE(PG8_SA(0, 1), a2 + hstep, voffA);
;             PG8_WAIT_V(8); PG8_WAIT_L(0); PG8_BAR; PG8_MMA(0, 0, At, B0); PG8_MMA(0, 1, At, B1); PG8_BAR; PG8_SCHED;
	s_setprio 1
	s_waitcnt lgkmcnt(0)
	v_mfma_f32_16x16x32_bf16 v[62:65], v[156:159], v[192:195], v[62:65]
	v_mfma_f32_16x16x32_bf16 v[58:61], v[164:167], v[192:195], v[58:61]
	v_mfma_f32_16x16x32_bf16 v[46:49], v[156:159], v[200:203], v[46:49]
	v_mfma_f32_16x16x32_bf16 v[42:45], v[164:167], v[200:203], v[42:45]
	v_mfma_f32_16x16x32_bf16 v[30:33], v[156:159], v[208:211], v[30:33]
	v_mfma_f32_16x16x32_bf16 v[26:29], v[164:167], v[208:211], v[26:29]
	v_mfma_f32_16x16x32_bf16 v[14:17], v[156:159], v[216:219], v[14:17]
	v_mfma_f32_16x16x32_bf16 v[10:13], v[164:167], v[216:219], v[10:13]
	v_mfma_f32_16x16x32_bf16 v[62:65], v[160:163], v[196:199], v[62:65]
	v_mfma_f32_16x16x32_bf16 v[58:61], v[168:171], v[196:199], v[58:61]
	v_mfma_f32_16x16x32_bf16 v[46:49], v[160:163], v[204:207], v[46:49]
	v_mfma_f32_16x16x32_bf16 v[42:45], v[168:171], v[204:207], v[42:45]
	v_mfma_f32_16x16x32_bf16 v[30:33], v[160:163], v[212:215], v[30:33]
	v_mfma_f32_16x16x32_bf16 v[26:29], v[168:171], v[212:215], v[26:29]
	v_mfma_f32_16x16x32_bf16 v[14:17], v[160:163], v[220:223], v[14:17]
	v_mfma_f32_16x16x32_bf16 v[10:13], v[168:171], v[220:223], v[10:13]
	v_mfma_f32_16x16x32_bf16 v[54:57], v[172:175], v[192:195], v[54:57]
	v_mfma_f32_16x16x32_bf16 v[50:53], v[180:183], v[192:195], v[50:53]
	v_mfma_f32_16x16x32_bf16 v[38:41], v[172:175], v[200:203], v[38:41]
	v_mfma_f32_16x16x32_bf16 v[34:37], v[180:183], v[200:203], v[34:37]
	v_mfma_f32_16x16x32_bf16 v[22:25], v[172:175], v[208:211], v[22:25]
	v_mfma_f32_16x16x32_bf16 v[18:21], v[180:183], v[208:211], v[18:21]
	v_mfma_f32_16x16x32_bf16 v[6:9], v[172:175], v[216:219], v[6:9]
	v_mfma_f32_16x16x32_bf16 v[2:5], v[180:183], v[216:219], v[2:5]
	v_mfma_f32_16x16x32_bf16 v[54:57], v[176:179], v[196:199], v[54:57]
	v_mfma_f32_16x16x32_bf16 v[50:53], v[188:191], v[196:199], v[50:53]
	v_mfma_f32_16x16x32_bf16 v[38:41], v[176:179], v[204:207], v[38:41]
	v_mfma_f32_16x16x32_bf16 v[34:37], v[188:191], v[204:207], v[34:37]
	v_mfma_f32_16x16x32_bf16 v[22:25], v[176:179], v[212:215], v[22:25]
	v_mfma_f32_16x16x32_bf16 v[18:21], v[188:191], v[212:215], v[18:21]
	v_mfma_f32_16x16x32_bf16 v[6:9], v[176:179], v[220:223], v[6:9]
	v_mfma_f32_16x16x32_bf16 v[2:5], v[188:191], v[220:223], v[2:5]
	s_barrier
	s_setprio 0
	s_add_i32 s66, 0, 0x18000
	v_add_u32_e32 v138, s66, v150
	s_add_i32 s67, 0, 0x1c000
	ds_read_b128 v[156:159], v138
	ds_read_b128 v[160:163], v138 offset:1024
	ds_read_b128 v[164:167], v138 offset:2048
	ds_read_b128 v[168:171], v138 offset:3072
	v_add_u32_e32 v138, s67, v150
	ds_read_b128 v[172:175], v138
	ds_read_b128 v[176:179], v138 offset:1024
	ds_read_b128 v[180:183], v138 offset:2048
	ds_read_b128 v[188:191], v138 offset:3072
	s_add_u32 s34, s34, s12
	s_addc_u32 s35, s35, s13
	s_mov_b32 m0, s42
	v_lshl_add_u64 v[234:235], s[34:35], 0, v[130:131]
	ds_read_b128 v[192:195], v154 offset:32768
	ds_read_b128 v[196:199], v154 offset:33792
	ds_read_b128 v[200:203], v154 offset:34816
	ds_read_b128 v[204:207], v154 offset:35840
	ds_read_b128 v[208:211], v154 offset:36864
	ds_read_b128 v[212:215], v154 offset:37888
	ds_read_b128 v[216:219], v154 offset:38912
	ds_read_b128 v[220:223], v154 offset:39936
	global_load_lds_dwordx4 v[234:235], off
	v_lshl_add_u64 v[234:235], s[34:35], 0, v[134:135]
	s_mov_b32 m0, s43
	s_nop 0
	global_load_lds_dwordx4 v[234:235], off
	s_waitcnt vmcnt(8)
	s_waitcnt lgkmcnt(0)
	s_barrier
	s_setprio 1
	s_waitcnt lgkmcnt(0)
	v_mfma_f32_16x16x32_bf16 v[122:125], v[156:159], v[192:195], v[122:125]
	v_mfma_f32_16x16x32_bf16 v[126:129], v[164:167], v[192:195], v[126:129]
	v_mfma_f32_16x16x32_bf16 v[110:113], v[156:159], v[200:203], v[110:113]
	v_mfma_f32_16x16x32_bf16 v[106:109], v[164:167], v[200:203], v[106:109]
	v_mfma_f32_16x16x32_bf16 v[94:97], v[156:159], v[208:211], v[94:97]
	v_mfma_f32_16x16x32_bf16 v[90:93], v[164:167], v[208:211], v[90:93]
	v_mfma_f32_16x16x32_bf16 v[78:81], v[156:159], v[216:219], v[78:81]
	v_mfma_f32_16x16x32_bf16 v[74:77], v[164:167], v[216:219], v[74:77]
	v_mfma_f32_16x16x32_bf16 v[122:125], v[160:163], v[196:199], v[122:125]
	v_mfma_f32_16x16x32_bf16 v[126:129], v[168:171], v[196:199], v[126:129]
	v_mfma_f32_16x16x32_bf16 v[110:113], v[160:163], v[204:207], v[110:113]
	v_mfma_f32_16x16x32_bf16 v[106:109], v[168:171], v[204:207], v[106:109]
	v_mfma_f32_16x16x32_bf16 v[94:97], v[160:163], v[212:215], v[94:97]
	v_mfma_f32_16x16x32_bf16 v[90:93], v[168:171], v[212:215], v[90:93]
	v_mfma_f32_16x16x32_bf16 v[78:81], v[160:163], v[220:223], v[78:81]
	v_mfma_f32_16x16x32_bf16 v[74:77], v[168:171], v[220:223], v[74:77]
	v_mfma_f32_16x16x32_bf16 v[118:121], v[172:175], v[192:195], v[118:121]
	v_mfma_f32_16x16x32_bf16 v[114:117], v[180:183], v[192:195], v[114:117]
	v_mfma_f32_16x16x32_bf16 v[102:105], v[172:175], v[200:203], v[102:105]
	v_mfma_f32_16x16x32_bf16 v[98:101], v[180:183], v[200:203], v[98:101]
	v_mfma_f32_16x16x32_bf16 v[86:89], v[172:175], v[208:211], v[86:89]
	v_mfma_f32_16x16x32_bf16 v[82:85], v[180:183], v[208:211], v[82:85]
	v_mfma_f32_16x16x32_bf16 v[70:73], v[172:175], v[216:219], v[70:73]
	v_mfma_f32_16x16x32_bf16 v[66:69], v[180:183], v[216:219], v[66:69]
	v_mfma_f32_16x16x32_bf16 v[118:121], v[176:179], v[196:199], v[118:121]
	v_mfma_f32_16x16x32_bf16 v[114:117], v[188:191], v[196:199], v[114:117]
	v_mfma_f32_16x16x32_bf16 v[102:105], v[176:179], v[204:207], v[102:105]
	v_mfma_f32_16x16x32_bf16 v[98:101], v[188:191], v[204:207], v[98:101]
	v_mfma_f32_16x16x32_bf16 v[86:89], v[176:179], v[212:215], v[86:89]
	v_mfma_f32_16x16x32_bf16 v[82:85], v[188:191], v[212:215], v[82:85]
	v_mfma_f32_16x16x32_bf16 v[70:73], v[176:179], v[220:223], v[70:73]
	v_mfma_f32_16x16x32_bf16 v[66:69], v[188:191], v[220:223], v[66:69]
	s_barrier
; #define PG8_STAGE(bufoff, gbase, voff) do { _Pragma("unroll") for (int _i = 0; _i < 2; ++_i) \
;         __builtin_amdgcn_global_load_lds((const unsigned*)((const char*)(gbase) + (voff)[_i]), (PG8_LAS unsigned*)(lds + (bufoff) + ldsw + _i * 8192), 16, 0, 0); } while (0)
; #define PG8_LDA(dst, b, h) do { _Pragma("unroll") for (int m = 0; m < 4; ++m) _Pragma("unroll") for (int k = 0; k < 2; ++k) dst[m][k] = *(const PG8_LAS bf16x8*)(lds + PG8_SA(b, h) + aoff + m * 2048 + k * 1024); } while (0)
; #define PG8_MMA(ai, bj, At, Bt) do { __builtin_amdgcn_s_setprio(1); _Pragma("unroll") for (int m = 0; m < 4; ++m) _Pragma("unroll") for (int n = 0; n < 2; ++n) _Pragma("unroll") for (int k = 0; k < 2; ++k) \
;         acc[ai][bj][m][n] = __builtin_amdgcn_mfma_f32_16x16x32_bf16(Bt[n][k], At[m][k], acc[ai][bj][m][n], 0, 0, 0); __builtin_amdgcn_s_setprio(0); } while (0)
; #define PG8_WAIT_V(n) asm volatile("s_waitcnt vmcnt(" #n ")" ::: "memory")
; #define PG8_WAIT_L(n) asm volatile("s_waitcnt lgkmcnt(" #n ")" ::: "memory")
; #define PG8_BAR __builtin_amdgcn_s_barrier()
; #define PG8_SCHED __builtin_amdgcn_sched_barrier(0)
; template <class Epi, class Sched, bool ALIGN_EPI = false, bool SP2 = false>
; __device__ __forceinline__ void gemm_phase(PG8_LAS unsigned char* lds, const Gemm g, const Sched& S, const Epi& E) {
;     ...
;             PG8_LDA(At, 1, 1); PG8_STAGE(PG8_SB(1, 0), b3, voffB); PG8_STAGE(PG8_SB(1, 1), b3 + hstep, voffB); PG8_STAGE(PG8_SA(1, 0), a3, voffA);
;             PG8_WAIT_V(8); PG8_WAIT_L(0); PG8_BAR; PG8_MMA(1, 0, At, B0); PG8_MMA(1, 1, At, B1); PG8_BAR; PG8_SCHED;
	s_setprio 0
	s_add_i32 s34, s66, s39
	v_lshl_add_u64 v[184:185], v[184:185], 0, s[22:23]
	s_mov_b32 m0, s34
	ds_read_b128 v[192:195], v154 offset:49152
	ds_read_b128 v[196:199], v154 offset:50176
	ds_read_b128 v[200:203], v154 offset:51200
	ds_read_b128 v[204:207], v154 offset:52224
	ds_read_b128 v[208:211], v154 offset:53248
	ds_read_b128 v[212:215], v154 offset:54272
	ds_read_b128 v[216:219], v154 offset:55296
	ds_read_b128 v[220:223], v154 offset:56320
	global_load_lds_dwordx4 v[184:185], off
	v_lshl_add_u64 v[184:185], v[224:225], 0, s[22:23]
	s_add_i32 m0, s34, 0x2000
	s_add_i32 s34, s67, s39
	global_load_lds_dwordx4 v[184:185], off
	v_lshl_add_u64 v[184:185], v[226:227], 0, s[22:23]
	s_mov_b32 m0, s34
	s_nop 0
	global_load_lds_dwordx4 v[184:185], off
	v_lshl_add_u64 v[184:185], v[228:229], 0, s[22:23]
	s_add_i32 m0, s34, 0x2000
	s_nop 0
	global_load_lds_dwordx4 v[184:185], off
	v_lshl_add_u64 v[184:185], v[230:231], 0, s[22:23]
	s_mov_b32 m0, s48
	s_nop 0
	global_load_lds_dwordx4 v[184:185], off
	v_lshl_add_u64 v[184:185], v[232:233], 0, s[22:23]
	s_mov_b32 m0, s49
	s_nop 0
	global_load_lds_dwordx4 v[184:185], off
	s_waitcnt vmcnt(8)
	s_waitcnt lgkmcnt(0)
	s_barrier
	s_setprio 1
	s_waitcnt lgkmcnt(0)
	v_mfma_f32_16x16x32_bf16 v[62:65], v[156:159], v[192:195], v[62:65]
	v_mfma_f32_16x16x32_bf16 v[58:61], v[164:167], v[192:195], v[58:61]
	v_mfma_f32_16x16x32_bf16 v[46:49], v[156:159], v[200:203], v[46:49]
	v_mfma_f32_16x16x32_bf16 v[42:45], v[164:167], v[200:203], v[42:45]
	v_mfma_f32_16x16x32_bf16 v[30:33], v[156:159], v[208:211], v[30:33]
	v_mfma_f32_16x16x32_bf16 v[26:29], v[164:167], v[208:211], v[26:29]
	v_mfma_f32_16x16x32_bf16 v[14:17], v[156:159], v[216:219], v[14:17]
	v_mfma_f32_16x16x32_bf16 v[10:13], v[164:167], v[216:219], v[10:13]
	v_mfma_f32_16x16x32_bf16 v[62:65], v[160:163], v[196:199], v[62:65]
	v_mfma_f32_16x16x32_bf16 v[58:61], v[168:171], v[196:199], v[58:61]
	v_mfma_f32_16x16x32_bf16 v[46:49], v[160:163], v[204:207], v[46:49]
	v_mfma_f32_16x16x32_bf16 v[42:45], v[168:171], v[204:207], v[42:45]
	v_mfma_f32_16x16x32_bf16 v[30:33], v[160:163], v[212:215], v[30:33]
	v_mfma_f32_16x16x32_bf16 v[26:29], v[168:171], v[212:215], v[26:29]
	v_mfma_f32_16x16x32_bf16 v[14:17], v[160:163], v[220:223], v[14:17]
	v_mfma_f32_16x16x32_bf16 v[10:13], v[168:171], v[220:223], v[10:13]
	v_mfma_f32_16x16x32_bf16 v[54:57], v[172:175], v[192:195], v[54:57]
	v_mfma_f32_16x16x32_bf16 v[50:53], v[180:183], v[192:195], v[50:53]
	v_mfma_f32_16x16x32_bf16 v[38:41], v[172:175], v[200:203], v[38:41]
	v_mfma_f32_16x16x32_bf16 v[34:37], v[180:183], v[200:203], v[34:37]
	v_mfma_f32_16x16x32_bf16 v[22:25], v[172:175], v[208:211], v[22:25]
	v_mfma_f32_16x16x32_bf16 v[18:21], v[180:183], v[208:211], v[18:21]
	v_mfma_f32_16x16x32_bf16 v[6:9], v[172:175], v[216:219], v[6:9]
	v_mfma_f32_16x16x32_bf16 v[2:5], v[180:183], v[216:219], v[2:5]
	v_mfma_f32_16x16x32_bf16 v[54:57], v[176:179], v[196:199], v[54:57]
	v_mfma_f32_16x16x32_bf16 v[50:53], v[188:191], v[196:199], v[50:53]
	v_mfma_f32_16x16x32_bf16 v[38:41], v[176:179], v[204:207], v[38:41]
	v_mfma_f32_16x16x32_bf16 v[34:37], v[188:191], v[204:207], v[34:37]
	v_mfma_f32_16x16x32_bf16 v[22:25], v[176:179], v[212:215], v[22:25]
	v_mfma_f32_16x16x32_bf16 v[18:21], v[188:191], v[212:215], v[18:21]
	v_mfma_f32_16x16x32_bf16 v[6:9], v[176:179], v[220:223], v[6:9]
	v_mfma_f32_16x16x32_bf16 v[2:5], v[188:191], v[220:223], v[2:5]
	s_barrier
	s_setprio 0
	s_add_u32 s30, s30, 0x100
	s_addc_u32 s31, s31, 0
	s_add_u32 s62, s62, 0x100
	s_addc_u32 s63, s63, 0
	s_cmp_ge_i32 s65, s50
	s_mov_b32 s34, s65
	s_cbranch_scc0 .LBB0_771

; #define PG8_STAGE(bufoff, gbase, voff) do { _Pragma("unroll") for (int _i = 0; _i < 2; ++_i) \
;         __builtin_amdgcn_global_load_lds((const unsigned*)((const char*)(gbase) + (voff)[_i]), (PG8_LAS unsigned*)(lds + (bufoff) + ldsw + _i * 8192), 16, 0, 0); } while (0)
; #define PG8_LDA(dst, b, h) do { _Pragma("unroll") for (int m = 0; m < 4; ++m) _Pragma("unroll") for (int k = 0; k < 2; ++k) dst[m][k] = *(const PG8_LAS bf16x8*)(lds + PG8_SA(b, h) + aoff + m * 2048 + k * 1024); } while (0)
; #define PG8_LDB(dst, b, h) do { _Pragma("unroll") for (int n = 0; n < 2; ++n) _Pragma("unroll") for (int k = 0; k < 2; ++k) dst[n][k] = *(const PG8_LAS bf16x8*)(lds + PG8_SB(b, h) + boff + n * 2048 + k * 1024); } while (0)
; #define PG8_MMA(ai, bj, At, Bt) do { __builtin_amdgcn_s_setprio(1); _Pragma("unroll") for (int m = 0; m < 4; ++m) _Pragma("unroll") for (int n = 0; n < 2; ++n) _Pragma("unroll") for (int k = 0; k < 2; ++k) \
;         acc[ai][bj][m][n] = __builtin_amdgcn_mfma_f32_16x16x32_bf16(Bt[n][k], At[m][k], acc[ai][bj][m][n], 0, 0, 0); __builtin_amdgcn_s_setprio(0); } while (0)
; #define PG8_WAIT_V(n) asm volatile("s_waitcnt vmcnt(" #n ")" ::: "memory")
; #define PG8_WAIT_L(n) asm volatile("s_waitcnt lgkmcnt(" #n ")" ::: "memory")
; #define PG8_BAR __builtin_amdgcn_s_barrier()
; #define PG8_SCHED __builtin_amdgcn_sched_barrier(0)
; template <class Epi, class Sched, bool ALIGN_EPI = false, bool SP2 = false>
; __device__ __forceinline__ void gemm_phase(PG8_LAS unsigned char* lds, const Gemm g, const Sched& S, const Epi& E) {
;     ...
;         for (int t = 0; t < nt; t += 2) {
;             const bool last = (t == nt - 2);
;             const char* a1 = cA + (size_t)(t + 1) * kstep;
;             const char* a2 = last ? nA : cA + (size_t)(t + 2) * kstep; const char* b2 = last ? nB : cB + (size_t)(t + 2) * kstep;
;             const char* a3 = a2 + kstep; const char* b3 = b2 + kstep;
;             if (last && has_next) S.a_ready(nxt);
;             if constexpr (SP2) {
;             PG8_LDB(B0, 0, 0); PG8_LDB(B1, 0, 1); PG8_SCHED; PG8_LDA(At, 0, 0); PG8_STAGE(PG8_SA(1, 1), a1 + hstep, voffA);
;             PG8_WAIT_V(8); PG8_WAIT_L(0); PG8_BAR; PG8_MMA(0, 0, At, B0); PG8_MMA(0, 1, At, B1); PG8_BAR; PG8_SCHED;
;             PG8_LDA(At, 0, 1); PG8_STAGE(PG8_SB(0, 0), b2, voffB); PG8_STAGE(PG8_SB(0, 1), b2 + hstep, voffB); PG8_STAGE(PG8_SA(0, 0), a2, voffA);
.LBB0_791:
	ds_read_b128 v[148:151], v144
	ds_read_b128 v[152:155], v144 offset:1024
	ds_read_b128 v[156:159], v144 offset:2048
	ds_read_b128 v[160:163], v144 offset:3072
	ds_read_b128 v[164:167], v145
	ds_read_b128 v[168:171], v145 offset:1024
	ds_read_b128 v[172:175], v145 offset:2048
	ds_read_b128 v[176:179], v145 offset:3072
	s_add_i32 s56, s24, 2
	s_add_u32 s57, s22, 0x80
	s_addc_u32 s25, s23, 0
	s_cmp_eq_u32 s40, s24
	s_cselect_b32 s24, s4, s57
	s_cselect_b32 s25, s5, s25
	s_cselect_b32 s59, s21, s55
	s_cselect_b32 s58, s20, s54
	v_lshl_add_u64 v[184:185], s[22:23], 0, v[134:135]
	s_add_i32 m0, s30, 0xc000
	ds_read_b128 v[180:183], v146
	ds_read_b128 v[188:191], v146 offset:1024
	ds_read_b128 v[192:195], v146 offset:2048
	ds_read_b128 v[196:199], v146 offset:3072
	ds_read_b128 v[200:203], v146 offset:4096
	ds_read_b128 v[204:207], v146 offset:5120
	ds_read_b128 v[208:211], v146 offset:6144
	ds_read_b128 v[212:215], v146 offset:7168
	global_load_lds_dwordx4 v[184:185], off
	v_lshl_add_u64 v[184:185], s[22:23], 0, v[136:137]
	s_add_i32 m0, s30, 0xe000
	s_nop 0
	global_load_lds_dwordx4 v[184:185], off
	s_waitcnt vmcnt(8)
	s_waitcnt lgkmcnt(0)
	s_barrier
	s_setprio 1
	s_waitcnt lgkmcnt(0)
	v_mfma_f32_16x16x32_bf16 v[126:129], v[148:151], v[180:183], v[126:129]
	v_mfma_f32_16x16x32_bf16 v[122:125], v[156:159], v[180:183], v[122:125]
	v_mfma_f32_16x16x32_bf16 v[110:113], v[148:151], v[192:195], v[110:113]
	v_mfma_f32_16x16x32_bf16 v[106:109], v[156:159], v[192:195], v[106:109]
	v_mfma_f32_16x16x32_bf16 v[94:97], v[148:151], v[200:203], v[94:97]
	v_mfma_f32_16x16x32_bf16 v[90:93], v[156:159], v[200:203], v[90:93]
	v_mfma_f32_16x16x32_bf16 v[78:81], v[148:151], v[208:211], v[78:81]
	v_mfma_f32_16x16x32_bf16 v[74:77], v[156:159], v[208:211], v[74:77]
	v_mfma_f32_16x16x32_bf16 v[126:129], v[152:155], v[188:191], v[126:129]
	v_mfma_f32_16x16x32_bf16 v[122:125], v[160:163], v[188:191], v[122:125]
	v_mfma_f32_16x16x32_bf16 v[110:113], v[152:155], v[196:199], v[110:113]
	v_mfma_f32_16x16x32_bf16 v[106:109], v[160:163], v[196:199], v[106:109]
	v_mfma_f32_16x16x32_bf16 v[94:97], v[152:155], v[204:207], v[94:97]
	v_mfma_f32_16x16x32_bf16 v[90:93], v[160:163], v[204:207], v[90:93]
	v_mfma_f32_16x16x32_bf16 v[78:81], v[152:155], v[212:215], v[78:81]
	v_mfma_f32_16x16x32_bf16 v[74:77], v[160:163], v[212:215], v[74:77]
	v_mfma_f32_16x16x32_bf16 v[118:121], v[164:167], v[180:183], v[118:121]
	v_mfma_f32_16x16x32_bf16 v[114:117], v[172:175], v[180:183], v[114:117]
	v_mfma_f32_16x16x32_bf16 v[102:105], v[164:167], v[192:195], v[102:105]
	v_mfma_f32_16x16x32_bf16 v[98:101], v[172:175], v[192:195], v[98:101]
	v_mfma_f32_16x16x32_bf16 v[86:89], v[164:167], v[200:203], v[86:89]
	v_mfma_f32_16x16x32_bf16 v[82:85], v[172:175], v[200:203], v[82:85]
	v_mfma_f32_16x16x32_bf16 v[70:73], v[164:167], v[208:211], v[70:73]
	v_mfma_f32_16x16x32_bf16 v[66:69], v[172:175], v[208:211], v[66:69]
	v_mfma_f32_16x16x32_bf16 v[118:121], v[168:171], v[188:191], v[118:121]
	v_mfma_f32_16x16x32_bf16 v[114:117], v[176:179], v[188:191], v[114:117]
	v_mfma_f32_16x16x32_bf16 v[102:105], v[168:171], v[196:199], v[102:105]
	v_mfma_f32_16x16x32_bf16 v[98:101], v[176:179], v[196:199], v[98:101]
	v_mfma_f32_16x16x32_bf16 v[86:89], v[168:171], v[204:207], v[86:89]
	v_mfma_f32_16x16x32_bf16 v[82:85], v[176:179], v[204:207], v[82:85]
	v_mfma_f32_16x16x32_bf16 v[70:73], v[168:171], v[212:215], v[70:73]
	v_mfma_f32_16x16x32_bf16 v[66:69], v[176:179], v[212:215], v[66:69]
	s_barrier
	s_setprio 0
	s_add_i32 s57, s43, s29
	v_lshl_add_u64 v[184:185], s[58:59], 0, v[130:131]
	s_mov_b32 m0, s57
	ds_read_b128 v[180:183], v146 offset:16384
	ds_read_b128 v[188:191], v146 offset:17408
	ds_read_b128 v[192:195], v146 offset:18432
	ds_read_b128 v[196:199], v146 offset:19456
	ds_read_b128 v[200:203], v146 offset:20480
	ds_read_b128 v[204:207], v146 offset:21504
	ds_read_b128 v[208:211], v146 offset:22528
	ds_read_b128 v[212:215], v146 offset:23552
	global_load_lds_dwordx4 v[184:185], off
	s_add_i32 m0, s57, 0x2000
	v_lshl_add_u64 v[216:217], s[58:59], 0, v[132:133]
	s_add_u32 s58, s58, s6
	s_addc_u32 s59, s59, s7
	s_add_i32 s57, s48, s29
	global_load_lds_dwordx4 v[216:217], off
	v_lshl_add_u64 v[218:219], s[58:59], 0, v[130:131]
	s_mov_b32 m0, s57
	v_lshl_add_u64 v[220:221], s[58:59], 0, v[132:133]
	global_load_lds_dwordx4 v[218:219], off
	s_add_i32 m0, s57, 0x2000
	v_lshl_add_u64 v[222:223], s[24:25], 0, v[130:131]
	global_load_lds_dwordx4 v[220:221], off
	s_mov_b32 m0, s30
	v_lshl_add_u64 v[224:225], s[24:25], 0, v[132:133]
	global_load_lds_dwordx4 v[222:223], off
	s_mov_b32 m0, s31
	s_nop 0
	global_load_lds_dwordx4 v[224:225], off
	s_waitcnt vmcnt(8)
	s_waitcnt lgkmcnt(0)
	s_barrier
; #define PG8_STAGE(bufoff, gbase, voff) do { _Pragma("unroll") for (int _i = 0; _i < 2; ++_i) \
;         __builtin_amdgcn_global_load_lds((const unsigned*)((const char*)(gbase) + (voff)[_i]), (PG8_LAS unsigned*)(lds + (bufoff) + ldsw + _i * 8192), 16, 0, 0); } while (0)
; #define PG8_LDA(dst, b, h) do { _Pragma("unroll") for (int m = 0; m < 4; ++m) _Pragma("unroll") for (int k = 0; k < 2; ++k) dst[m][k] = *(const PG8_LAS bf16x8*)(lds + PG8_SA(b, h) + aoff + m * 2048 + k * 1024); } while (0)
; #define PG8_LDB(dst, b, h) do { _Pragma("unroll") for (int n = 0; n < 2; ++n) _Pragma("unroll") for (int k = 0; k < 2; ++k) dst[n][k] = *(const PG8_LAS bf16x8*)(lds + PG8_SB(b, h) + boff + n * 2048 + k * 1024); } while (0)
; #define PG8_MMA(ai, bj, At, Bt) do { __builtin_amdgcn_s_setprio(1); _Pragma("unroll") for (int m = 0; m < 4; ++m) _Pragma("unroll") for (int n = 0; n < 2; ++n) _Pragma("unroll") for (int k = 0; k < 2; ++k) \
;         acc[ai][bj][m][n] = __builtin_amdgcn_mfma_f32_16x16x32_bf16(Bt[n][k], At[m][k], acc[ai][bj][m][n], 0, 0, 0); __builtin_amdgcn_s_setprio(0); } while (0)
; #define PG8_WAIT_V(n) asm volatile("s_waitcnt vmcnt(" #n ")" ::: "memory")
; #define PG8_WAIT_L(n) asm volatile("s_waitcnt lgkmcnt(" #n ")" ::: "memory")
; #define PG8_BAR __builtin_amdgcn_s_barrier()
; #define PG8_SCHED __builtin_amdgcn_sched_barrier(0)
; template <class Epi, class Sched, bool ALIGN_EPI = false, bool SP2 = false>
; __device__ __forceinline__ void gemm_phase(PG8_LAS unsigned char* lds, const Gemm g, const Sched& S, const Epi& E) {
;     ...
;             PG8_WAIT_V(8); PG8_WAIT_L(0); PG8_BAR; PG8_MMA(1, 0, At, B0); PG8_MMA(1, 1, At, B1); PG8_BAR; PG8_SCHED;
;             PG8_LDB(B0, 1, 0); PG8_LDB(B1, 1, 1); PG8_SCHED; PG8_LDA(At, 1, 0); PG8_STAGE(PG8_SA(0, 1), a2 + hstep, voffA);
;             PG8_WAIT_V(8); PG8_WAIT_L(0); PG8_BAR; PG8_MMA(0, 0, At, B0); PG8_MMA(0, 1, At, B1); PG8_BAR; PG8_SCHED;
	s_setprio 1
	s_waitcnt lgkmcnt(0)
	v_mfma_f32_16x16x32_bf16 v[62:65], v[148:151], v[180:183], v[62:65]
	v_mfma_f32_16x16x32_bf16 v[58:61], v[156:159], v[180:183], v[58:61]
	v_mfma_f32_16x16x32_bf16 v[46:49], v[148:151], v[192:195], v[46:49]
	v_mfma_f32_16x16x32_bf16 v[42:45], v[156:159], v[192:195], v[42:45]
	v_mfma_f32_16x16x32_bf16 v[30:33], v[148:151], v[200:203], v[30:33]
	v_mfma_f32_16x16x32_bf16 v[26:29], v[156:159], v[200:203], v[26:29]
	v_mfma_f32_16x16x32_bf16 v[14:17], v[148:151], v[208:211], v[14:17]
	v_mfma_f32_16x16x32_bf16 v[10:13], v[156:159], v[208:211], v[10:13]
	v_mfma_f32_16x16x32_bf16 v[62:65], v[152:155], v[188:191], v[62:65]
	v_mfma_f32_16x16x32_bf16 v[58:61], v[160:163], v[188:191], v[58:61]
	v_mfma_f32_16x16x32_bf16 v[46:49], v[152:155], v[196:199], v[46:49]
	v_mfma_f32_16x16x32_bf16 v[42:45], v[160:163], v[196:199], v[42:45]
	v_mfma_f32_16x16x32_bf16 v[30:33], v[152:155], v[204:207], v[30:33]
	v_mfma_f32_16x16x32_bf16 v[26:29], v[160:163], v[204:207], v[26:29]
	v_mfma_f32_16x16x32_bf16 v[14:17], v[152:155], v[212:215], v[14:17]
	v_mfma_f32_16x16x32_bf16 v[10:13], v[160:163], v[212:215], v[10:13]
	v_mfma_f32_16x16x32_bf16 v[54:57], v[164:167], v[180:183], v[54:57]
	v_mfma_f32_16x16x32_bf16 v[50:53], v[172:175], v[180:183], v[50:53]
	v_mfma_f32_16x16x32_bf16 v[38:41], v[164:167], v[192:195], v[38:41]
	v_mfma_f32_16x16x32_bf16 v[34:37], v[172:175], v[192:195], v[34:37]
	v_mfma_f32_16x16x32_bf16 v[22:25], v[164:167], v[200:203], v[22:25]
	v_mfma_f32_16x16x32_bf16 v[18:21], v[172:175], v[200:203], v[18:21]
	v_mfma_f32_16x16x32_bf16 v[6:9], v[164:167], v[208:211], v[6:9]
	v_mfma_f32_16x16x32_bf16 v[2:5], v[172:175], v[208:211], v[2:5]
	v_mfma_f32_16x16x32_bf16 v[54:57], v[168:171], v[188:191], v[54:57]
	v_mfma_f32_16x16x32_bf16 v[50:53], v[176:179], v[188:191], v[50:53]
	v_mfma_f32_16x16x32_bf16 v[38:41], v[168:171], v[196:199], v[38:41]
	v_mfma_f32_16x16x32_bf16 v[34:37], v[176:179], v[196:199], v[34:37]
	v_mfma_f32_16x16x32_bf16 v[22:25], v[168:171], v[204:207], v[22:25]
	v_mfma_f32_16x16x32_bf16 v[18:21], v[176:179], v[204:207], v[18:21]
	v_mfma_f32_16x16x32_bf16 v[6:9], v[168:171], v[212:215], v[6:9]
	v_mfma_f32_16x16x32_bf16 v[2:5], v[176:179], v[212:215], v[2:5]
	s_barrier
	s_setprio 0
	s_add_i32 s57, 0, 0x18000
	v_add_u32_e32 v147, s57, v142
	s_add_i32 s58, 0, 0x1c000
	ds_read_b128 v[148:151], v147
	ds_read_b128 v[152:155], v147 offset:1024
	ds_read_b128 v[156:159], v147 offset:2048
	ds_read_b128 v[160:163], v147 offset:3072
	v_add_u32_e32 v147, s58, v142
	ds_read_b128 v[164:167], v147
	ds_read_b128 v[168:171], v147 offset:1024
	ds_read_b128 v[172:175], v147 offset:2048
	ds_read_b128 v[176:179], v147 offset:3072
	s_add_u32 s24, s24, s6
	s_addc_u32 s25, s25, s7
	s_mov_b32 m0, s34
	v_lshl_add_u64 v[226:227], s[24:25], 0, v[130:131]
	ds_read_b128 v[180:183], v146 offset:32768
	ds_read_b128 v[188:191], v146 offset:33792
	ds_read_b128 v[192:195], v146 offset:34816
	ds_read_b128 v[196:199], v146 offset:35840
	ds_read_b128 v[200:203], v146 offset:36864
	ds_read_b128 v[204:207], v146 offset:37888
	ds_read_b128 v[208:211], v146 offset:38912
	ds_read_b128 v[212:215], v146 offset:39936
	global_load_lds_dwordx4 v[226:227], off
	v_lshl_add_u64 v[226:227], s[24:25], 0, v[132:133]
	s_mov_b32 m0, s35
	s_nop 0
	global_load_lds_dwordx4 v[226:227], off
	s_waitcnt vmcnt(8)
	s_waitcnt lgkmcnt(0)
	s_barrier
	s_setprio 1
	s_waitcnt lgkmcnt(0)
	v_mfma_f32_16x16x32_bf16 v[126:129], v[148:151], v[180:183], v[126:129]
	v_mfma_f32_16x16x32_bf16 v[122:125], v[156:159], v[180:183], v[122:125]
	v_mfma_f32_16x16x32_bf16 v[110:113], v[148:151], v[192:195], v[110:113]
	v_mfma_f32_16x16x32_bf16 v[106:109], v[156:159], v[192:195], v[106:109]
	v_mfma_f32_16x16x32_bf16 v[94:97], v[148:151], v[200:203], v[94:97]
	v_mfma_f32_16x16x32_bf16 v[90:93], v[156:159], v[200:203], v[90:93]
	v_mfma_f32_16x16x32_bf16 v[78:81], v[148:151], v[208:211], v[78:81]
	v_mfma_f32_16x16x32_bf16 v[74:77], v[156:159], v[208:211], v[74:77]
	v_mfma_f32_16x16x32_bf16 v[126:129], v[152:155], v[188:191], v[126:129]
	v_mfma_f32_16x16x32_bf16 v[122:125], v[160:163], v[188:191], v[122:125]
	v_mfma_f32_16x16x32_bf16 v[110:113], v[152:155], v[196:199], v[110:113]
	v_mfma_f32_16x16x32_bf16 v[106:109], v[160:163], v[196:199], v[106:109]
	v_mfma_f32_16x16x32_bf16 v[94:97], v[152:155], v[204:207], v[94:97]
	v_mfma_f32_16x16x32_bf16 v[90:93], v[160:163], v[204:207], v[90:93]
	v_mfma_f32_16x16x32_bf16 v[78:81], v[152:155], v[212:215], v[78:81]
	v_mfma_f32_16x16x32_bf16 v[74:77], v[160:163], v[212:215], v[74:77]
	v_mfma_f32_16x16x32_bf16 v[118:121], v[164:167], v[180:183], v[118:121]
	v_mfma_f32_16x16x32_bf16 v[114:117], v[172:175], v[180:183], v[114:117]
	v_mfma_f32_16x16x32_bf16 v[102:105], v[164:167], v[192:195], v[102:105]
	v_mfma_f32_16x16x32_bf16 v[98:101], v[172:175], v[192:195], v[98:101]
	v_mfma_f32_16x16x32_bf16 v[86:89], v[164:167], v[200:203], v[86:89]
	v_mfma_f32_16x16x32_bf16 v[82:85], v[172:175], v[200:203], v[82:85]
	v_mfma_f32_16x16x32_bf16 v[70:73], v[164:167], v[208:211], v[70:73]
	v_mfma_f32_16x16x32_bf16 v[66:69], v[172:175], v[208:211], v[66:69]
	v_mfma_f32_16x16x32_bf16 v[118:121], v[168:171], v[188:191], v[118:121]
	v_mfma_f32_16x16x32_bf16 v[114:117], v[176:179], v[188:191], v[114:117]
	v_mfma_f32_16x16x32_bf16 v[102:105], v[168:171], v[196:199], v[102:105]
	v_mfma_f32_16x16x32_bf16 v[98:101], v[176:179], v[196:199], v[98:101]
	v_mfma_f32_16x16x32_bf16 v[86:89], v[168:171], v[204:207], v[86:89]
	v_mfma_f32_16x16x32_bf16 v[82:85], v[176:179], v[204:207], v[82:85]
	v_mfma_f32_16x16x32_bf16 v[70:73], v[168:171], v[212:215], v[70:73]
	v_mfma_f32_16x16x32_bf16 v[66:69], v[176:179], v[212:215], v[66:69]
	s_barrier
; #define PG8_STAGE(bufoff, gbase, voff) do { _Pragma("unroll") for (int _i = 0; _i < 2; ++_i) \
;         __builtin_amdgcn_global_load_lds((const unsigned*)((const char*)(gbase) + (voff)[_i]), (PG8_LAS unsigned*)(lds + (bufoff) + ldsw + _i * 8192), 16, 0, 0); } while (0)
; #define PG8_LDA(dst, b, h) do { _Pragma("unroll") for (int m = 0; m < 4; ++m) _Pragma("unroll") for (int k = 0; k < 2; ++k) dst[m][k] = *(const PG8_LAS bf16x8*)(lds + PG8_SA(b, h) + aoff + m * 2048 + k * 1024); } while (0)
; #define PG8_MMA(ai, bj, At, Bt) do { __builtin_amdgcn_s_setprio(1); _Pragma("unroll") for (int m = 0; m < 4; ++m) _Pragma("unroll") for (int n = 0; n < 2; ++n) _Pragma("unroll") for (int k = 0; k < 2; ++k) \
;         acc[ai][bj][m][n] = __builtin_amdgcn_mfma_f32_16x16x32_bf16(Bt[n][k], At[m][k], acc[ai][bj][m][n], 0, 0, 0); __builtin_amdgcn_s_setprio(0); } while (0)
; #define PG8_WAIT_V(n) asm volatile("s_waitcnt vmcnt(" #n ")" ::: "memory")
; #define PG8_WAIT_L(n) asm volatile("s_waitcnt lgkmcnt(" #n ")" ::: "memory")
; #define PG8_BAR __builtin_amdgcn_s_barrier()
; #define PG8_SCHED __builtin_amdgcn_sched_barrier(0)
; template <class Epi, class Sched, bool ALIGN_EPI = false, bool SP2 = false>
; __device__ __forceinline__ void gemm_phase(PG8_LAS unsigned char* lds, const Gemm g, const Sched& S, const Epi& E) {
;     ...
;             PG8_LDA(At, 1, 1); PG8_STAGE(PG8_SB(1, 0), b3, voffB); PG8_STAGE(PG8_SB(1, 1), b3 + hstep, voffB); PG8_STAGE(PG8_SA(1, 0), a3, voffA);
;             PG8_WAIT_V(8); PG8_WAIT_L(0); PG8_BAR; PG8_MMA(1, 0, At, B0); PG8_MMA(1, 1, At, B1); PG8_BAR; PG8_SCHED;
	s_setprio 0
	s_add_i32 s24, s57, s29
	v_lshl_add_u64 v[184:185], v[184:185], 0, s[16:17]
	s_mov_b32 m0, s24
	ds_read_b128 v[180:183], v146 offset:49152
	ds_read_b128 v[188:191], v146 offset:50176
	ds_read_b128 v[192:195], v146 offset:51200
	ds_read_b128 v[196:199], v146 offset:52224
	ds_read_b128 v[200:203], v146 offset:53248
	ds_read_b128 v[204:207], v146 offset:54272
	ds_read_b128 v[208:211], v146 offset:55296
	ds_read_b128 v[212:215], v146 offset:56320
	global_load_lds_dwordx4 v[184:185], off
	v_lshl_add_u64 v[184:185], v[216:217], 0, s[16:17]
	s_add_i32 m0, s24, 0x2000
	s_add_i32 s24, s58, s29
	global_load_lds_dwordx4 v[184:185], off
	v_lshl_add_u64 v[184:185], v[218:219], 0, s[16:17]
	s_mov_b32 m0, s24
	s_nop 0
	global_load_lds_dwordx4 v[184:185], off
	v_lshl_add_u64 v[184:185], v[220:221], 0, s[16:17]
	s_add_i32 m0, s24, 0x2000
	s_nop 0
	global_load_lds_dwordx4 v[184:185], off
	v_lshl_add_u64 v[184:185], v[222:223], 0, s[16:17]
	s_mov_b32 m0, s38
	s_nop 0
	global_load_lds_dwordx4 v[184:185], off
	v_lshl_add_u64 v[184:185], v[224:225], 0, s[16:17]
	s_mov_b32 m0, s39
	s_nop 0
	global_load_lds_dwordx4 v[184:185], off
	s_waitcnt vmcnt(8)
	s_waitcnt lgkmcnt(0)
	s_barrier
	s_setprio 1
	s_waitcnt lgkmcnt(0)
	v_mfma_f32_16x16x32_bf16 v[62:65], v[148:151], v[180:183], v[62:65]
	v_mfma_f32_16x16x32_bf16 v[58:61], v[156:159], v[180:183], v[58:61]
	v_mfma_f32_16x16x32_bf16 v[46:49], v[148:151], v[192:195], v[46:49]
	v_mfma_f32_16x16x32_bf16 v[42:45], v[156:159], v[192:195], v[42:45]
	v_mfma_f32_16x16x32_bf16 v[30:33], v[148:151], v[200:203], v[30:33]
	v_mfma_f32_16x16x32_bf16 v[26:29], v[156:159], v[200:203], v[26:29]
	v_mfma_f32_16x16x32_bf16 v[14:17], v[148:151], v[208:211], v[14:17]
	v_mfma_f32_16x16x32_bf16 v[10:13], v[156:159], v[208:211], v[10:13]
	v_mfma_f32_16x16x32_bf16 v[62:65], v[152:155], v[188:191], v[62:65]
	v_mfma_f32_16x16x32_bf16 v[58:61], v[160:163], v[188:191], v[58:61]
	v_mfma_f32_16x16x32_bf16 v[46:49], v[152:155], v[196:199], v[46:49]
	v_mfma_f32_16x16x32_bf16 v[42:45], v[160:163], v[196:199], v[42:45]
	v_mfma_f32_16x16x32_bf16 v[30:33], v[152:155], v[204:207], v[30:33]
	v_mfma_f32_16x16x32_bf16 v[26:29], v[160:163], v[204:207], v[26:29]
	v_mfma_f32_16x16x32_bf16 v[14:17], v[152:155], v[212:215], v[14:17]
	v_mfma_f32_16x16x32_bf16 v[10:13], v[160:163], v[212:215], v[10:13]
	v_mfma_f32_16x16x32_bf16 v[54:57], v[164:167], v[180:183], v[54:57]
	v_mfma_f32_16x16x32_bf16 v[50:53], v[172:175], v[180:183], v[50:53]
	v_mfma_f32_16x16x32_bf16 v[38:41], v[164:167], v[192:195], v[38:41]
	v_mfma_f32_16x16x32_bf16 v[34:37], v[172:175], v[192:195], v[34:37]
	v_mfma_f32_16x16x32_bf16 v[22:25], v[164:167], v[200:203], v[22:25]
	v_mfma_f32_16x16x32_bf16 v[18:21], v[172:175], v[200:203], v[18:21]
	v_mfma_f32_16x16x32_bf16 v[6:9], v[164:167], v[208:211], v[6:9]
	v_mfma_f32_16x16x32_bf16 v[2:5], v[172:175], v[208:211], v[2:5]
	v_mfma_f32_16x16x32_bf16 v[54:57], v[168:171], v[188:191], v[54:57]
	v_mfma_f32_16x16x32_bf16 v[50:53], v[176:179], v[188:191], v[50:53]
	v_mfma_f32_16x16x32_bf16 v[38:41], v[168:171], v[196:199], v[38:41]
	v_mfma_f32_16x16x32_bf16 v[34:37], v[176:179], v[196:199], v[34:37]
	v_mfma_f32_16x16x32_bf16 v[22:25], v[168:171], v[204:207], v[22:25]
	v_mfma_f32_16x16x32_bf16 v[18:21], v[176:179], v[204:207], v[18:21]
	v_mfma_f32_16x16x32_bf16 v[6:9], v[168:171], v[212:215], v[6:9]
	v_mfma_f32_16x16x32_bf16 v[2:5], v[176:179], v[212:215], v[2:5]
	s_barrier
	s_setprio 0
	s_add_u32 s22, s22, 0x100
	s_addc_u32 s23, s23, 0
	s_add_u32 s54, s54, 0x100
	s_addc_u32 s55, s55, 0
	s_cmp_ge_i32 s56, 2
	s_mov_b32 s24, s56
	s_cbranch_scc0 .LBB0_791

; #define PG8_STAGE(bufoff, gbase, voff) do { _Pragma("unroll") for (int _i = 0; _i < 2; ++_i) \
;         __builtin_amdgcn_global_load_lds((const unsigned*)((const char*)(gbase) + (voff)[_i]), (PG8_LAS unsigned*)(lds + (bufoff) + ldsw + _i * 8192), 16, 0, 0); } while (0)
; #define PG8_LDA(dst, b, h) do { _Pragma("unroll") for (int m = 0; m < 4; ++m) _Pragma("unroll") for (int k = 0; k < 2; ++k) dst[m][k] = *(const PG8_LAS bf16x8*)(lds + PG8_SA(b, h) + aoff + m * 2048 + k * 1024); } while (0)
; #define PG8_LDB(dst, b, h) do { _Pragma("unroll") for (int n = 0; n < 2; ++n) _Pragma("unroll") for (int k = 0; k < 2; ++k) dst[n][k] = *(const PG8_LAS bf16x8*)(lds + PG8_SB(b, h) + boff + n * 2048 + k * 1024); } while (0)
; #define PG8_MMA(ai, bj, At, Bt) do { __builtin_amdgcn_s_setprio(1); _Pragma("unroll") for (int m = 0; m < 4; ++m) _Pragma("unroll") for (int n = 0; n < 2; ++n) _Pragma("unroll") for (int k = 0; k < 2; ++k) \
;         acc[ai][bj][m][n] = __builtin_amdgcn_mfma_f32_16x16x32_bf16(Bt[n][k], At[m][k], acc[ai][bj][m][n], 0, 0, 0); __builtin_amdgcn_s_setprio(0); } while (0)
; #define PG8_WAIT_V(n) asm volatile("s_waitcnt vmcnt(" #n ")" ::: "memory")
; #define PG8_WAIT_L(n) asm volatile("s_waitcnt lgkmcnt(" #n ")" ::: "memory")
; #define PG8_BAR __builtin_amdgcn_s_barrier()
; #define PG8_SCHED __builtin_amdgcn_sched_barrier(0)
; template <class Epi, class Sched, bool ALIGN_EPI = false, bool SP2 = false>
; __device__ __forceinline__ void gemm_phase(PG8_LAS unsigned char* lds, const Gemm g, const Sched& S, const Epi& E) {
;     ...
;         for (int t = 0; t < nt; t += 2) {
;             const bool last = (t == nt - 2);
;             const char* a1 = cA + (size_t)(t + 1) * kstep;
;             const char* a2 = last ? nA : cA + (size_t)(t + 2) * kstep; const char* b2 = last ? nB : cB + (size_t)(t + 2) * kstep;
;             const char* a3 = a2 + kstep; const char* b3 = b2 + kstep;
;             if (last && has_next) S.a_ready(nxt);
;             if constexpr (SP2) {
;             PG8_LDB(B0, 0, 0); PG8_LDB(B1, 0, 1); PG8_SCHED; PG8_LDA(At, 0, 0); PG8_STAGE(PG8_SA(1, 1), a1 + hstep, voffA);
;             PG8_WAIT_V(8); PG8_WAIT_L(0); PG8_BAR; PG8_MMA(0, 0, At, B0); PG8_MMA(0, 1, At, B1); PG8_BAR; PG8_SCHED;
;             PG8_LDA(At, 0, 1); PG8_STAGE(PG8_SB(0, 0), b2, voffB); PG8_STAGE(PG8_SB(0, 1), b2 + hstep, voffB); PG8_STAGE(PG8_SA(0, 0), a2, voffA);
.LBB0_1405:
	v_add_u32_e32 v162, s56, v148
	v_add_u32_e32 v178, s57, v148
	s_add_u32 s34, s18, s30
	ds_read_b128 v[150:153], v162
	ds_read_b128 v[154:157], v162 offset:1024
	ds_read_b128 v[158:161], v162 offset:2048
	ds_read_b128 v[162:165], v162 offset:3072
	ds_read_b128 v[166:169], v178
	ds_read_b128 v[170:173], v178 offset:1024
	ds_read_b128 v[174:177], v178 offset:2048
	ds_read_b128 v[178:181], v178 offset:3072
	s_addc_u32 s35, s19, s31
	s_add_u32 s34, s34, 0x100
	s_addc_u32 s35, s35, 0
	s_add_u32 s65, s59, s30
	s_addc_u32 s66, s60, s31
	s_cmpk_eq_i32 s30, 0x700
	s_cselect_b32 s37, s25, s35
	s_cselect_b32 s36, s61, s34
	s_cselect_b32 s35, s23, s66
	s_cselect_b32 s34, s62, s65
	v_lshl_add_u64 v[216:217], v[142:143], 0, s[30:31]
	s_add_i32 m0, s42, 0xc000
	ds_read_b128 v[182:185], v149
	ds_read_b128 v[188:191], v149 offset:1024
	ds_read_b128 v[192:195], v149 offset:2048
	ds_read_b128 v[196:199], v149 offset:3072
	ds_read_b128 v[200:203], v149 offset:4096
	ds_read_b128 v[204:207], v149 offset:5120
	ds_read_b128 v[208:211], v149 offset:6144
	ds_read_b128 v[212:215], v149 offset:7168
	global_load_lds_dwordx4 v[216:217], off
	v_lshl_add_u64 v[216:217], v[144:145], 0, s[30:31]
	s_add_i32 m0, s42, 0xe000
	s_nop 0
	global_load_lds_dwordx4 v[216:217], off
	s_waitcnt vmcnt(8)
	s_waitcnt lgkmcnt(0)
	s_barrier
	s_setprio 1
	s_waitcnt lgkmcnt(0)
	v_mfma_f32_16x16x32_bf16 v[110:113], v[150:153], v[182:185], v[110:113]
	v_mfma_f32_16x16x32_bf16 v[74:77], v[158:161], v[182:185], v[74:77]
	v_mfma_f32_16x16x32_bf16 v[118:121], v[150:153], v[192:195], v[118:121]
	v_mfma_f32_16x16x32_bf16 v[94:97], v[158:161], v[192:195], v[94:97]
	v_mfma_f32_16x16x32_bf16 v[126:129], v[150:153], v[200:203], v[126:129]
	v_mfma_f32_16x16x32_bf16 v[106:109], v[158:161], v[200:203], v[106:109]
	v_mfma_f32_16x16x32_bf16 v[122:125], v[150:153], v[208:211], v[122:125]
	v_mfma_f32_16x16x32_bf16 v[114:117], v[158:161], v[208:211], v[114:117]
	v_mfma_f32_16x16x32_bf16 v[110:113], v[154:157], v[188:191], v[110:113]
	v_mfma_f32_16x16x32_bf16 v[74:77], v[162:165], v[188:191], v[74:77]
	v_mfma_f32_16x16x32_bf16 v[118:121], v[154:157], v[196:199], v[118:121]
	v_mfma_f32_16x16x32_bf16 v[94:97], v[162:165], v[196:199], v[94:97]
	v_mfma_f32_16x16x32_bf16 v[126:129], v[154:157], v[204:207], v[126:129]
	v_mfma_f32_16x16x32_bf16 v[106:109], v[162:165], v[204:207], v[106:109]
	v_mfma_f32_16x16x32_bf16 v[122:125], v[154:157], v[212:215], v[122:125]
	v_mfma_f32_16x16x32_bf16 v[114:117], v[162:165], v[212:215], v[114:117]
	v_mfma_f32_16x16x32_bf16 v[46:49], v[166:169], v[182:185], v[46:49]
	v_mfma_f32_16x16x32_bf16 v[14:17], v[174:177], v[182:185], v[14:17]
	v_mfma_f32_16x16x32_bf16 v[54:57], v[166:169], v[192:195], v[54:57]
	v_mfma_f32_16x16x32_bf16 v[30:33], v[174:177], v[192:195], v[30:33]
	v_mfma_f32_16x16x32_bf16 v[70:73], v[166:169], v[200:203], v[70:73]
	v_mfma_f32_16x16x32_bf16 v[42:45], v[174:177], v[200:203], v[42:45]
	v_mfma_f32_16x16x32_bf16 v[86:89], v[166:169], v[208:211], v[86:89]
	v_mfma_f32_16x16x32_bf16 v[50:53], v[174:177], v[208:211], v[50:53]
	v_mfma_f32_16x16x32_bf16 v[46:49], v[170:173], v[188:191], v[46:49]
	v_mfma_f32_16x16x32_bf16 v[14:17], v[178:181], v[188:191], v[14:17]
	v_mfma_f32_16x16x32_bf16 v[54:57], v[170:173], v[196:199], v[54:57]
	v_mfma_f32_16x16x32_bf16 v[30:33], v[178:181], v[196:199], v[30:33]
	v_mfma_f32_16x16x32_bf16 v[70:73], v[170:173], v[204:207], v[70:73]
	v_mfma_f32_16x16x32_bf16 v[42:45], v[178:181], v[204:207], v[42:45]
	v_mfma_f32_16x16x32_bf16 v[86:89], v[170:173], v[212:215], v[86:89]
	v_mfma_f32_16x16x32_bf16 v[50:53], v[178:181], v[212:215], v[50:53]
	s_barrier
	s_setprio 0
	s_add_i32 s65, s56, s41
	v_lshl_add_u64 v[216:217], s[34:35], 0, v[130:131]
	s_mov_b32 m0, s65
	ds_read_b128 v[182:185], v149 offset:16384
	ds_read_b128 v[188:191], v149 offset:17408
	ds_read_b128 v[192:195], v149 offset:18432
	ds_read_b128 v[196:199], v149 offset:19456
	ds_read_b128 v[200:203], v149 offset:20480
	ds_read_b128 v[204:207], v149 offset:21504
	ds_read_b128 v[208:211], v149 offset:22528
	ds_read_b128 v[212:215], v149 offset:23552
	global_load_lds_dwordx4 v[216:217], off
	s_add_i32 m0, s65, 0x2000
	s_add_u32 s66, s34, 0x40000
	v_lshl_add_u64 v[218:219], s[34:35], 0, v[132:133]
	s_addc_u32 s67, s35, 0
	s_add_i32 s65, s57, s41
	global_load_lds_dwordx4 v[218:219], off
	v_lshl_add_u64 v[220:221], s[66:67], 0, v[130:131]
	s_mov_b32 m0, s65
	v_lshl_add_u64 v[222:223], s[36:37], 0, v[132:133]
	global_load_lds_dwordx4 v[220:221], off
	v_lshl_add_u64 v[220:221], s[66:67], 0, v[132:133]
	s_add_i32 m0, s65, 0x2000
	s_nop 0
	global_load_lds_dwordx4 v[220:221], off
	v_lshl_add_u64 v[220:221], s[36:37], 0, v[130:131]
	s_mov_b32 m0, s42
	s_nop 0
	global_load_lds_dwordx4 v[220:221], off
	s_mov_b32 m0, s48
	s_nop 0
	global_load_lds_dwordx4 v[222:223], off
	s_waitcnt vmcnt(8)
	s_waitcnt lgkmcnt(0)
	s_barrier
; #define PG8_STAGE(bufoff, gbase, voff) do { _Pragma("unroll") for (int _i = 0; _i < 2; ++_i) \
;         __builtin_amdgcn_global_load_lds((const unsigned*)((const char*)(gbase) + (voff)[_i]), (PG8_LAS unsigned*)(lds + (bufoff) + ldsw + _i * 8192), 16, 0, 0); } while (0)
; #define PG8_LDA(dst, b, h) do { _Pragma("unroll") for (int m = 0; m < 4; ++m) _Pragma("unroll") for (int k = 0; k < 2; ++k) dst[m][k] = *(const PG8_LAS bf16x8*)(lds + PG8_SA(b, h) + aoff + m * 2048 + k * 1024); } while (0)
; #define PG8_LDB(dst, b, h) do { _Pragma("unroll") for (int n = 0; n < 2; ++n) _Pragma("unroll") for (int k = 0; k < 2; ++k) dst[n][k] = *(const PG8_LAS bf16x8*)(lds + PG8_SB(b, h) + boff + n * 2048 + k * 1024); } while (0)
; #define PG8_MMA(ai, bj, At, Bt) do { __builtin_amdgcn_s_setprio(1); _Pragma("unroll") for (int m = 0; m < 4; ++m) _Pragma("unroll") for (int n = 0; n < 2; ++n) _Pragma("unroll") for (int k = 0; k < 2; ++k) \
;         acc[ai][bj][m][n] = __builtin_amdgcn_mfma_f32_16x16x32_bf16(Bt[n][k], At[m][k], acc[ai][bj][m][n], 0, 0, 0); __builtin_amdgcn_s_setprio(0); } while (0)
; #define PG8_WAIT_V(n) asm volatile("s_waitcnt vmcnt(" #n ")" ::: "memory")
; #define PG8_WAIT_L(n) asm volatile("s_waitcnt lgkmcnt(" #n ")" ::: "memory")
; #define PG8_BAR __builtin_amdgcn_s_barrier()
; #define PG8_SCHED __builtin_amdgcn_sched_barrier(0)
; template <class Epi, class Sched, bool ALIGN_EPI = false, bool SP2 = false>
; __device__ __forceinline__ void gemm_phase(PG8_LAS unsigned char* lds, const Gemm g, const Sched& S, const Epi& E) {
;     ...
;             PG8_WAIT_V(8); PG8_WAIT_L(0); PG8_BAR; PG8_MMA(1, 0, At, B0); PG8_MMA(1, 1, At, B1); PG8_BAR; PG8_SCHED;
;             PG8_LDB(B0, 1, 0); PG8_LDB(B1, 1, 1); PG8_SCHED; PG8_LDA(At, 1, 0); PG8_STAGE(PG8_SA(0, 1), a2 + hstep, voffA);
;             PG8_WAIT_V(8); PG8_WAIT_L(0); PG8_BAR; PG8_MMA(0, 0, At, B0); PG8_MMA(0, 1, At, B1); PG8_BAR; PG8_SCHED;
	s_setprio 1
	s_waitcnt lgkmcnt(0)
	v_mfma_f32_16x16x32_bf16 v[102:105], v[150:153], v[182:185], v[102:105]
	v_mfma_f32_16x16x32_bf16 v[98:101], v[158:161], v[182:185], v[98:101]
	v_mfma_f32_16x16x32_bf16 v[82:85], v[150:153], v[192:195], v[82:85]
	v_mfma_f32_16x16x32_bf16 v[78:81], v[158:161], v[192:195], v[78:81]
	v_mfma_f32_16x16x32_bf16 v[38:41], v[150:153], v[200:203], v[38:41]
	v_mfma_f32_16x16x32_bf16 v[34:37], v[158:161], v[200:203], v[34:37]
	v_mfma_f32_16x16x32_bf16 v[18:21], v[150:153], v[208:211], v[18:21]
	v_mfma_f32_16x16x32_bf16 v[10:13], v[158:161], v[208:211], v[10:13]
	v_mfma_f32_16x16x32_bf16 v[102:105], v[154:157], v[188:191], v[102:105]
	v_mfma_f32_16x16x32_bf16 v[98:101], v[162:165], v[188:191], v[98:101]
	v_mfma_f32_16x16x32_bf16 v[82:85], v[154:157], v[196:199], v[82:85]
	v_mfma_f32_16x16x32_bf16 v[78:81], v[162:165], v[196:199], v[78:81]
	v_mfma_f32_16x16x32_bf16 v[38:41], v[154:157], v[204:207], v[38:41]
	v_mfma_f32_16x16x32_bf16 v[34:37], v[162:165], v[204:207], v[34:37]
	v_mfma_f32_16x16x32_bf16 v[18:21], v[154:157], v[212:215], v[18:21]
	v_mfma_f32_16x16x32_bf16 v[10:13], v[162:165], v[212:215], v[10:13]
	v_mfma_f32_16x16x32_bf16 v[90:93], v[166:169], v[182:185], v[90:93]
	v_mfma_f32_16x16x32_bf16 v[66:69], v[174:177], v[182:185], v[66:69]
	v_mfma_f32_16x16x32_bf16 v[62:65], v[166:169], v[192:195], v[62:65]
	v_mfma_f32_16x16x32_bf16 v[58:61], v[174:177], v[192:195], v[58:61]
	v_mfma_f32_16x16x32_bf16 v[26:29], v[166:169], v[200:203], v[26:29]
	v_mfma_f32_16x16x32_bf16 v[22:25], v[174:177], v[200:203], v[22:25]
	v_mfma_f32_16x16x32_bf16 v[6:9], v[166:169], v[208:211], v[6:9]
	v_mfma_f32_16x16x32_bf16 v[2:5], v[174:177], v[208:211], v[2:5]
	v_mfma_f32_16x16x32_bf16 v[90:93], v[170:173], v[188:191], v[90:93]
	v_mfma_f32_16x16x32_bf16 v[66:69], v[178:181], v[188:191], v[66:69]
	v_mfma_f32_16x16x32_bf16 v[62:65], v[170:173], v[196:199], v[62:65]
	v_mfma_f32_16x16x32_bf16 v[58:61], v[178:181], v[196:199], v[58:61]
	v_mfma_f32_16x16x32_bf16 v[26:29], v[170:173], v[204:207], v[26:29]
	v_mfma_f32_16x16x32_bf16 v[22:25], v[178:181], v[204:207], v[22:25]
	v_mfma_f32_16x16x32_bf16 v[6:9], v[170:173], v[212:215], v[6:9]
	v_mfma_f32_16x16x32_bf16 v[2:5], v[178:181], v[212:215], v[2:5]
	s_barrier
	s_setprio 0
	s_add_i32 s65, 0, 0x18000
	s_add_i32 s66, 0, 0x1c000
	v_add_u32_e32 v162, s65, v148
	v_add_u32_e32 v178, s66, v148
	ds_read_b128 v[150:153], v162
	ds_read_b128 v[154:157], v162 offset:1024
	ds_read_b128 v[158:161], v162 offset:2048
	ds_read_b128 v[162:165], v162 offset:3072
	ds_read_b128 v[166:169], v178
	ds_read_b128 v[170:173], v178 offset:1024
	ds_read_b128 v[174:177], v178 offset:2048
	ds_read_b128 v[178:181], v178 offset:3072
	s_add_u32 s36, s36, 0x40000
	s_addc_u32 s37, s37, 0
	s_mov_b32 m0, s49
	v_lshl_add_u64 v[224:225], s[36:37], 0, v[130:131]
	ds_read_b128 v[182:185], v149 offset:32768
	ds_read_b128 v[188:191], v149 offset:33792
	ds_read_b128 v[192:195], v149 offset:34816
	ds_read_b128 v[196:199], v149 offset:35840
	ds_read_b128 v[200:203], v149 offset:36864
	ds_read_b128 v[204:207], v149 offset:37888
	ds_read_b128 v[208:211], v149 offset:38912
	ds_read_b128 v[212:215], v149 offset:39936
	global_load_lds_dwordx4 v[224:225], off
	v_lshl_add_u64 v[224:225], s[36:37], 0, v[132:133]
	s_mov_b32 m0, s51
	s_nop 0
	global_load_lds_dwordx4 v[224:225], off
	s_waitcnt vmcnt(8)
	s_waitcnt lgkmcnt(0)
	s_barrier
	s_setprio 1
	s_waitcnt lgkmcnt(0)
	v_mfma_f32_16x16x32_bf16 v[110:113], v[150:153], v[182:185], v[110:113]
	v_mfma_f32_16x16x32_bf16 v[74:77], v[158:161], v[182:185], v[74:77]
	v_mfma_f32_16x16x32_bf16 v[118:121], v[150:153], v[192:195], v[118:121]
	v_mfma_f32_16x16x32_bf16 v[94:97], v[158:161], v[192:195], v[94:97]
	v_mfma_f32_16x16x32_bf16 v[126:129], v[150:153], v[200:203], v[126:129]
	v_mfma_f32_16x16x32_bf16 v[106:109], v[158:161], v[200:203], v[106:109]
	v_mfma_f32_16x16x32_bf16 v[122:125], v[150:153], v[208:211], v[122:125]
	v_mfma_f32_16x16x32_bf16 v[114:117], v[158:161], v[208:211], v[114:117]
	v_mfma_f32_16x16x32_bf16 v[110:113], v[154:157], v[188:191], v[110:113]
	v_mfma_f32_16x16x32_bf16 v[74:77], v[162:165], v[188:191], v[74:77]
	v_mfma_f32_16x16x32_bf16 v[118:121], v[154:157], v[196:199], v[118:121]
	v_mfma_f32_16x16x32_bf16 v[94:97], v[162:165], v[196:199], v[94:97]
	v_mfma_f32_16x16x32_bf16 v[126:129], v[154:157], v[204:207], v[126:129]
	v_mfma_f32_16x16x32_bf16 v[106:109], v[162:165], v[204:207], v[106:109]
	v_mfma_f32_16x16x32_bf16 v[122:125], v[154:157], v[212:215], v[122:125]
	v_mfma_f32_16x16x32_bf16 v[114:117], v[162:165], v[212:215], v[114:117]
	v_mfma_f32_16x16x32_bf16 v[46:49], v[166:169], v[182:185], v[46:49]
	v_mfma_f32_16x16x32_bf16 v[14:17], v[174:177], v[182:185], v[14:17]
	v_mfma_f32_16x16x32_bf16 v[54:57], v[166:169], v[192:195], v[54:57]
	v_mfma_f32_16x16x32_bf16 v[30:33], v[174:177], v[192:195], v[30:33]
	v_mfma_f32_16x16x32_bf16 v[70:73], v[166:169], v[200:203], v[70:73]
	v_mfma_f32_16x16x32_bf16 v[42:45], v[174:177], v[200:203], v[42:45]
	v_mfma_f32_16x16x32_bf16 v[86:89], v[166:169], v[208:211], v[86:89]
	v_mfma_f32_16x16x32_bf16 v[50:53], v[174:177], v[208:211], v[50:53]
	v_mfma_f32_16x16x32_bf16 v[46:49], v[170:173], v[188:191], v[46:49]
	v_mfma_f32_16x16x32_bf16 v[14:17], v[178:181], v[188:191], v[14:17]
	v_mfma_f32_16x16x32_bf16 v[54:57], v[170:173], v[196:199], v[54:57]
	v_mfma_f32_16x16x32_bf16 v[30:33], v[178:181], v[196:199], v[30:33]
	v_mfma_f32_16x16x32_bf16 v[70:73], v[170:173], v[204:207], v[70:73]
	v_mfma_f32_16x16x32_bf16 v[42:45], v[178:181], v[204:207], v[42:45]
	v_mfma_f32_16x16x32_bf16 v[86:89], v[170:173], v[212:215], v[86:89]
	v_mfma_f32_16x16x32_bf16 v[50:53], v[178:181], v[212:215], v[50:53]
	s_barrier
; #define PG8_STAGE(bufoff, gbase, voff) do { _Pragma("unroll") for (int _i = 0; _i < 2; ++_i) \
;         __builtin_amdgcn_global_load_lds((const unsigned*)((const char*)(gbase) + (voff)[_i]), (PG8_LAS unsigned*)(lds + (bufoff) + ldsw + _i * 8192), 16, 0, 0); } while (0)
; #define PG8_LDA(dst, b, h) do { _Pragma("unroll") for (int m = 0; m < 4; ++m) _Pragma("unroll") for (int k = 0; k < 2; ++k) dst[m][k] = *(const PG8_LAS bf16x8*)(lds + PG8_SA(b, h) + aoff + m * 2048 + k * 1024); } while (0)
; #define PG8_MMA(ai, bj, At, Bt) do { __builtin_amdgcn_s_setprio(1); _Pragma("unroll") for (int m = 0; m < 4; ++m) _Pragma("unroll") for (int n = 0; n < 2; ++n) _Pragma("unroll") for (int k = 0; k < 2; ++k) \
;         acc[ai][bj][m][n] = __builtin_amdgcn_mfma_f32_16x16x32_bf16(Bt[n][k], At[m][k], acc[ai][bj][m][n], 0, 0, 0); __builtin_amdgcn_s_setprio(0); } while (0)
; #define PG8_WAIT_V(n) asm volatile("s_waitcnt vmcnt(" #n ")" ::: "memory")
; #define PG8_WAIT_L(n) asm volatile("s_waitcnt lgkmcnt(" #n ")" ::: "memory")
; #define PG8_BAR __builtin_amdgcn_s_barrier()
; #define PG8_SCHED __builtin_amdgcn_sched_barrier(0)
; template <class Epi, class Sched, bool ALIGN_EPI = false, bool SP2 = false>
; __device__ __forceinline__ void gemm_phase(PG8_LAS unsigned char* lds, const Gemm g, const Sched& S, const Epi& E) {
;     ...
;             PG8_LDA(At, 1, 1); PG8_STAGE(PG8_SB(1, 0), b3, voffB); PG8_STAGE(PG8_SB(1, 1), b3 + hstep, voffB); PG8_STAGE(PG8_SA(1, 0), a3, voffA);
;             PG8_WAIT_V(8); PG8_WAIT_L(0); PG8_BAR; PG8_MMA(1, 0, At, B0); PG8_MMA(1, 1, At, B1); PG8_BAR; PG8_SCHED;
;     ...
;         if (!has_next) break;
; #pragma unroll
;         for (int a = 0; a < 2; ++a)
; #pragma unroll
;             for (int b = 0; b < 2; ++b)
; #pragma unroll
;                 for (int m = 0; m < 4; ++m)
; #pragma unroll
;                     for (int n = 0; n < 2; ++n) acc[a][b][m][n] = (f32x4){0.f, 0.f, 0.f, 0.f};
	s_setprio 0
	s_add_i32 s36, s65, s41
	v_lshl_add_u64 v[216:217], v[216:217], 0, s[20:21]
	s_mov_b32 m0, s36
	ds_read_b128 v[182:185], v149 offset:49152
	ds_read_b128 v[188:191], v149 offset:50176
	ds_read_b128 v[192:195], v149 offset:51200
	ds_read_b128 v[196:199], v149 offset:52224
	ds_read_b128 v[200:203], v149 offset:53248
	ds_read_b128 v[204:207], v149 offset:54272
	ds_read_b128 v[208:211], v149 offset:55296
	ds_read_b128 v[212:215], v149 offset:56320
	global_load_lds_dwordx4 v[216:217], off
	s_add_i32 m0, s36, 0x2000
	s_add_u32 s34, s34, 0x40080
	v_lshl_add_u64 v[216:217], v[218:219], 0, s[20:21]
	s_addc_u32 s35, s35, 0
	s_add_i32 s36, s66, s41
	global_load_lds_dwordx4 v[216:217], off
	v_lshl_add_u64 v[216:217], s[34:35], 0, v[130:131]
	s_mov_b32 m0, s36
	s_nop 0
	global_load_lds_dwordx4 v[216:217], off
	v_lshl_add_u64 v[216:217], s[34:35], 0, v[132:133]
	s_add_i32 m0, s36, 0x2000
	s_nop 0
	global_load_lds_dwordx4 v[216:217], off
	v_lshl_add_u64 v[216:217], v[220:221], 0, s[20:21]
	s_mov_b32 m0, s54
	s_nop 0
	global_load_lds_dwordx4 v[216:217], off
	v_lshl_add_u64 v[216:217], v[222:223], 0, s[20:21]
	s_mov_b32 m0, s55
	s_nop 0
	global_load_lds_dwordx4 v[216:217], off
	s_waitcnt vmcnt(8)
	s_waitcnt lgkmcnt(0)
	s_barrier
	s_setprio 1
	s_waitcnt lgkmcnt(0)
	v_mfma_f32_16x16x32_bf16 v[102:105], v[150:153], v[182:185], v[102:105]
	v_mfma_f32_16x16x32_bf16 v[98:101], v[158:161], v[182:185], v[98:101]
	v_mfma_f32_16x16x32_bf16 v[82:85], v[150:153], v[192:195], v[82:85]
	v_mfma_f32_16x16x32_bf16 v[78:81], v[158:161], v[192:195], v[78:81]
	v_mfma_f32_16x16x32_bf16 v[38:41], v[150:153], v[200:203], v[38:41]
	v_mfma_f32_16x16x32_bf16 v[34:37], v[158:161], v[200:203], v[34:37]
	v_mfma_f32_16x16x32_bf16 v[18:21], v[150:153], v[208:211], v[18:21]
	v_mfma_f32_16x16x32_bf16 v[10:13], v[158:161], v[208:211], v[10:13]
	v_mfma_f32_16x16x32_bf16 v[102:105], v[154:157], v[188:191], v[102:105]
	v_mfma_f32_16x16x32_bf16 v[98:101], v[162:165], v[188:191], v[98:101]
	v_mfma_f32_16x16x32_bf16 v[82:85], v[154:157], v[196:199], v[82:85]
	v_mfma_f32_16x16x32_bf16 v[78:81], v[162:165], v[196:199], v[78:81]
	v_mfma_f32_16x16x32_bf16 v[38:41], v[154:157], v[204:207], v[38:41]
	v_mfma_f32_16x16x32_bf16 v[34:37], v[162:165], v[204:207], v[34:37]
	v_mfma_f32_16x16x32_bf16 v[18:21], v[154:157], v[212:215], v[18:21]
	v_mfma_f32_16x16x32_bf16 v[10:13], v[162:165], v[212:215], v[10:13]
	v_mfma_f32_16x16x32_bf16 v[90:93], v[166:169], v[182:185], v[90:93]
	v_mfma_f32_16x16x32_bf16 v[66:69], v[174:177], v[182:185], v[66:69]
	v_mfma_f32_16x16x32_bf16 v[62:65], v[166:169], v[192:195], v[62:65]
	v_mfma_f32_16x16x32_bf16 v[58:61], v[174:177], v[192:195], v[58:61]
	v_mfma_f32_16x16x32_bf16 v[26:29], v[166:169], v[200:203], v[26:29]
	v_mfma_f32_16x16x32_bf16 v[22:25], v[174:177], v[200:203], v[22:25]
	v_mfma_f32_16x16x32_bf16 v[6:9], v[166:169], v[208:211], v[6:9]
	v_mfma_f32_16x16x32_bf16 v[2:5], v[174:177], v[208:211], v[2:5]
	v_mfma_f32_16x16x32_bf16 v[90:93], v[170:173], v[188:191], v[90:93]
	v_mfma_f32_16x16x32_bf16 v[66:69], v[178:181], v[188:191], v[66:69]
	v_mfma_f32_16x16x32_bf16 v[62:65], v[170:173], v[196:199], v[62:65]
	v_mfma_f32_16x16x32_bf16 v[58:61], v[178:181], v[196:199], v[58:61]
	v_mfma_f32_16x16x32_bf16 v[26:29], v[170:173], v[204:207], v[26:29]
	v_mfma_f32_16x16x32_bf16 v[22:25], v[178:181], v[204:207], v[22:25]
	v_mfma_f32_16x16x32_bf16 v[6:9], v[170:173], v[212:215], v[6:9]
	v_mfma_f32_16x16x32_bf16 v[2:5], v[178:181], v[212:215], v[2:5]
	s_barrier
	s_setprio 0
	s_add_i32 s63, s63, 2
	s_add_u32 s30, s30, 0x100
	s_addc_u32 s31, s31, 0
	s_cmp_gt_u32 s63, 13
	s_cbranch_scc0 .LBB0_1405
	s_add_u32 s30, s59, 0xffffff00
	s_addc_u32 s31, s60, -1
	s_andn2_b64 vcc, exec, s[6:7]
	s_cbranch_vccnz .LBB0_1408
	v_mov_b32_e32 v2, 0
	s_mov_b32 s8, s22
	s_mov_b32 s16, s24
	s_mov_b64 s[18:19], s[28:29]
	s_mov_b32 s53, s58
	v_mov_b32_e32 v3, v2
	v_mov_b32_e32 v4, v2
	v_mov_b32_e32 v5, v2
	v_mov_b32_e32 v6, v2
	v_mov_b32_e32 v7, v2
	v_mov_b32_e32 v8, v2
	v_mov_b32_e32 v9, v2
	v_mov_b32_e32 v22, v2
	v_mov_b32_e32 v23, v2
	v_mov_b32_e32 v24, v2
	v_mov_b32_e32 v25, v2
	v_mov_b32_e32 v26, v2
	v_mov_b32_e32 v27, v2
	v_mov_b32_e32 v28, v2
	v_mov_b32_e32 v29, v2
	v_mov_b32_e32 v58, v2
	v_mov_b32_e32 v59, v2
	v_mov_b32_e32 v60, v2
	v_mov_b32_e32 v61, v2
	v_mov_b32_e32 v62, v2
	v_mov_b32_e32 v63, v2
	v_mov_b32_e32 v64, v2
	v_mov_b32_e32 v65, v2
	v_mov_b32_e32 v66, v2
	v_mov_b32_e32 v67, v2
	v_mov_b32_e32 v68, v2
	v_mov_b32_e32 v69, v2
	v_mov_b32_e32 v90, v2
	v_mov_b32_e32 v91, v2
	v_mov_b32_e32 v92, v2
	v_mov_b32_e32 v93, v2
	v_mov_b32_e32 v10, v2
	v_mov_b32_e32 v11, v2
	v_mov_b32_e32 v12, v2
	v_mov_b32_e32 v13, v2
	v_mov_b32_e32 v18, v2
	v_mov_b32_e32 v19, v2
	v_mov_b32_e32 v20, v2
	v_mov_b32_e32 v21, v2
	v_mov_b32_e32 v34, v2
	v_mov_b32_e32 v35, v2
	v_mov_b32_e32 v36, v2
	v_mov_b32_e32 v37, v2
	v_mov_b32_e32 v38, v2
	v_mov_b32_e32 v39, v2
	v_mov_b32_e32 v40, v2
	v_mov_b32_e32 v41, v2
	v_mov_b32_e32 v78, v2
	v_mov_b32_e32 v79, v2
	v_mov_b32_e32 v80, v2
	v_mov_b32_e32 v81, v2
	v_mov_b32_e32 v82, v2
	v_mov_b32_e32 v83, v2
	v_mov_b32_e32 v84, v2
	v_mov_b32_e32 v85, v2
	v_mov_b32_e32 v98, v2
	v_mov_b32_e32 v99, v2
	v_mov_b32_e32 v100, v2
	v_mov_b32_e32 v101, v2
	v_mov_b32_e32 v102, v2
	v_mov_b32_e32 v103, v2
	v_mov_b32_e32 v104, v2
	v_mov_b32_e32 v105, v2
	v_mov_b32_e32 v50, v2
	v_mov_b32_e32 v51, v2
	v_mov_b32_e32 v52, v2
	v_mov_b32_e32 v53, v2
	v_mov_b32_e32 v86, v2
	v_mov_b32_e32 v87, v2
	v_mov_b32_e32 v88, v2
	v_mov_b32_e32 v89, v2
	v_mov_b32_e32 v42, v2
	v_mov_b32_e32 v43, v2
	v_mov_b32_e32 v44, v2
	v_mov_b32_e32 v45, v2
	v_mov_b32_e32 v70, v2
	v_mov_b32_e32 v71, v2
	v_mov_b32_e32 v72, v2
	v_mov_b32_e32 v73, v2
	v_mov_b32_e32 v30, v2
	v_mov_b32_e32 v31, v2
	v_mov_b32_e32 v32, v2
	v_mov_b32_e32 v33, v2
	v_mov_b32_e32 v54, v2
	v_mov_b32_e32 v55, v2
	v_mov_b32_e32 v56, v2
	v_mov_b32_e32 v57, v2
	v_mov_b32_e32 v14, v2
	v_mov_b32_e32 v15, v2
	v_mov_b32_e32 v16, v2
	v_mov_b32_e32 v17, v2
	v_mov_b32_e32 v46, v2
	v_mov_b32_e32 v47, v2
	v_mov_b32_e32 v48, v2
	v_mov_b32_e32 v49, v2
	v_mov_b32_e32 v114, v2
	v_mov_b32_e32 v115, v2
	v_mov_b32_e32 v116, v2
	v_mov_b32_e32 v117, v2
	v_mov_b32_e32 v122, v2
	v_mov_b32_e32 v123, v2
	v_mov_b32_e32 v124, v2
	v_mov_b32_e32 v125, v2
	v_mov_b32_e32 v106, v2
	v_mov_b32_e32 v107, v2
	v_mov_b32_e32 v108, v2
	v_mov_b32_e32 v109, v2
	v_mov_b32_e32 v126, v2
	v_mov_b32_e32 v127, v2
	v_mov_b32_e32 v128, v2
	v_mov_b32_e32 v129, v2
	v_mov_b32_e32 v94, v2
	v_mov_b32_e32 v95, v2
	v_mov_b32_e32 v96, v2
	v_mov_b32_e32 v97, v2
	v_mov_b32_e32 v118, v2
	v_mov_b32_e32 v119, v2
	v_mov_b32_e32 v120, v2
	v_mov_b32_e32 v121, v2
	v_mov_b32_e32 v74, v2
	v_mov_b32_e32 v75, v2
	v_mov_b32_e32 v76, v2
	v_mov_b32_e32 v77, v2
	v_mov_b32_e32 v110, v2
	v_mov_b32_e32 v111, v2
	v_mov_b32_e32 v112, v2
	v_mov_b32_e32 v113, v2
	s_andn2_b64 vcc, exec, s[4:5]
	s_cbranch_vccnz .LBB0_1409
	s_branch .LBB0_1410

; #define PG8_STAGE(bufoff, gbase, voff) do { _Pragma("unroll") for (int _i = 0; _i < 2; ++_i) \
;         __builtin_amdgcn_global_load_lds((const unsigned*)((const char*)(gbase) + (voff)[_i]), (PG8_LAS unsigned*)(lds + (bufoff) + ldsw + _i * 8192), 16, 0, 0); } while (0)
; #define PG8_LDA(dst, b, h) do { _Pragma("unroll") for (int m = 0; m < 4; ++m) _Pragma("unroll") for (int k = 0; k < 2; ++k) dst[m][k] = *(const PG8_LAS bf16x8*)(lds + PG8_SA(b, h) + aoff + m * 2048 + k * 1024); } while (0)
; #define PG8_LDB(dst, b, h) do { _Pragma("unroll") for (int n = 0; n < 2; ++n) _Pragma("unroll") for (int k = 0; k < 2; ++k) dst[n][k] = *(const PG8_LAS bf16x8*)(lds + PG8_SB(b, h) + boff + n * 2048 + k * 1024); } while (0)
; #define PG8_MMA(ai, bj, At, Bt) do { __builtin_amdgcn_s_setprio(1); _Pragma("unroll") for (int m = 0; m < 4; ++m) _Pragma("unroll") for (int n = 0; n < 2; ++n) _Pragma("unroll") for (int k = 0; k < 2; ++k) \
;         acc[ai][bj][m][n] = __builtin_amdgcn_mfma_f32_16x16x32_bf16(Bt[n][k], At[m][k], acc[ai][bj][m][n], 0, 0, 0); __builtin_amdgcn_s_setprio(0); } while (0)
; #define PG8_WAIT_V(n) asm volatile("s_waitcnt vmcnt(" #n ")" ::: "memory")
; #define PG8_WAIT_L(n) asm volatile("s_waitcnt lgkmcnt(" #n ")" ::: "memory")
; #define PG8_BAR __builtin_amdgcn_s_barrier()
; #define PG8_SCHED __builtin_amdgcn_sched_barrier(0)
; template <class Epi, class Sched, bool ALIGN_EPI = false, bool SP2 = false>
; __device__ __forceinline__ void gemm_phase(PG8_LAS unsigned char* lds, const Gemm g, const Sched& S, const Epi& E) {
;     ...
;         for (int t = 0; t < nt; t += 2) {
;             const bool last = (t == nt - 2);
;             const char* a1 = cA + (size_t)(t + 1) * kstep;
;             const char* a2 = last ? nA : cA + (size_t)(t + 2) * kstep; const char* b2 = last ? nB : cB + (size_t)(t + 2) * kstep;
;             const char* a3 = a2 + kstep; const char* b3 = b2 + kstep;
;             if (last && has_next) S.a_ready(nxt);
;             if constexpr (SP2) {
;             PG8_LDB(B0, 0, 0); PG8_LDB(B1, 0, 1); PG8_SCHED; PG8_LDA(At, 0, 0); PG8_STAGE(PG8_SA(1, 1), a1 + hstep, voffA);
;             PG8_WAIT_V(8); PG8_WAIT_L(0); PG8_BAR; PG8_MMA(0, 0, At, B0); PG8_MMA(0, 1, At, B1); PG8_BAR; PG8_SCHED;
;             PG8_LDA(At, 0, 1); PG8_STAGE(PG8_SB(0, 0), b2, voffB); PG8_STAGE(PG8_SB(0, 1), b2 + hstep, voffB); PG8_STAGE(PG8_SA(0, 0), a2, voffA);
.LBB0_1482:
	ds_read_b128 v[144:147], v140
	ds_read_b128 v[148:151], v140 offset:1024
	ds_read_b128 v[152:155], v140 offset:2048
	ds_read_b128 v[156:159], v140 offset:3072
	ds_read_b128 v[160:163], v141
	ds_read_b128 v[164:167], v141 offset:1024
	ds_read_b128 v[168:171], v141 offset:2048
	ds_read_b128 v[172:175], v141 offset:3072
	s_add_i32 s75, s40, 2
	s_add_u32 s38, s36, 0x100
	s_addc_u32 s39, s37, 0
	s_cmp_eq_u32 s61, s40
	s_cselect_b32 s40, s34, s73
	s_cselect_b32 s49, s31, s39
	s_cselect_b32 s48, s30, s38
	s_cselect_b32 s41, s35, s74
	v_lshl_add_u64 v[184:185], s[36:37], 0, v[134:135]
	s_add_i32 m0, s53, 0xc000
	ds_read_b128 v[176:179], v142
	ds_read_b128 v[180:183], v142 offset:1024
	ds_read_b128 v[188:191], v142 offset:2048
	ds_read_b128 v[192:195], v142 offset:3072
	ds_read_b128 v[196:199], v142 offset:4096
	ds_read_b128 v[200:203], v142 offset:5120
	ds_read_b128 v[204:207], v142 offset:6144
	ds_read_b128 v[208:211], v142 offset:7168
	global_load_lds_dwordx4 v[184:185], off
	v_lshl_add_u64 v[184:185], s[36:37], 0, v[136:137]
	s_add_i32 m0, s53, 0xe000
	s_nop 0
	global_load_lds_dwordx4 v[184:185], off
	s_waitcnt vmcnt(8)
	s_waitcnt lgkmcnt(0)
	s_barrier
	s_setprio 1
	s_waitcnt lgkmcnt(0)
	v_mfma_f32_16x16x32_bf16 v[126:129], v[144:147], v[176:179], v[126:129]
	v_mfma_f32_16x16x32_bf16 v[122:125], v[152:155], v[176:179], v[122:125]
	v_mfma_f32_16x16x32_bf16 v[110:113], v[144:147], v[188:191], v[110:113]
	v_mfma_f32_16x16x32_bf16 v[106:109], v[152:155], v[188:191], v[106:109]
	v_mfma_f32_16x16x32_bf16 v[94:97], v[144:147], v[196:199], v[94:97]
	v_mfma_f32_16x16x32_bf16 v[90:93], v[152:155], v[196:199], v[90:93]
	v_mfma_f32_16x16x32_bf16 v[78:81], v[144:147], v[204:207], v[78:81]
	v_mfma_f32_16x16x32_bf16 v[74:77], v[152:155], v[204:207], v[74:77]
	v_mfma_f32_16x16x32_bf16 v[126:129], v[148:151], v[180:183], v[126:129]
	v_mfma_f32_16x16x32_bf16 v[122:125], v[156:159], v[180:183], v[122:125]
	v_mfma_f32_16x16x32_bf16 v[110:113], v[148:151], v[192:195], v[110:113]
	v_mfma_f32_16x16x32_bf16 v[106:109], v[156:159], v[192:195], v[106:109]
	v_mfma_f32_16x16x32_bf16 v[94:97], v[148:151], v[200:203], v[94:97]
	v_mfma_f32_16x16x32_bf16 v[90:93], v[156:159], v[200:203], v[90:93]
	v_mfma_f32_16x16x32_bf16 v[78:81], v[148:151], v[208:211], v[78:81]
	v_mfma_f32_16x16x32_bf16 v[74:77], v[156:159], v[208:211], v[74:77]
	v_mfma_f32_16x16x32_bf16 v[118:121], v[160:163], v[176:179], v[118:121]
	v_mfma_f32_16x16x32_bf16 v[114:117], v[168:171], v[176:179], v[114:117]
	v_mfma_f32_16x16x32_bf16 v[102:105], v[160:163], v[188:191], v[102:105]
	v_mfma_f32_16x16x32_bf16 v[98:101], v[168:171], v[188:191], v[98:101]
	v_mfma_f32_16x16x32_bf16 v[86:89], v[160:163], v[196:199], v[86:89]
	v_mfma_f32_16x16x32_bf16 v[82:85], v[168:171], v[196:199], v[82:85]
	v_mfma_f32_16x16x32_bf16 v[70:73], v[160:163], v[204:207], v[70:73]
	v_mfma_f32_16x16x32_bf16 v[66:69], v[168:171], v[204:207], v[66:69]
	v_mfma_f32_16x16x32_bf16 v[118:121], v[164:167], v[180:183], v[118:121]
	v_mfma_f32_16x16x32_bf16 v[114:117], v[172:175], v[180:183], v[114:117]
	v_mfma_f32_16x16x32_bf16 v[102:105], v[164:167], v[192:195], v[102:105]
	v_mfma_f32_16x16x32_bf16 v[98:101], v[172:175], v[192:195], v[98:101]
	v_mfma_f32_16x16x32_bf16 v[86:89], v[164:167], v[200:203], v[86:89]
	v_mfma_f32_16x16x32_bf16 v[82:85], v[172:175], v[200:203], v[82:85]
	v_mfma_f32_16x16x32_bf16 v[70:73], v[164:167], v[208:211], v[70:73]
	v_mfma_f32_16x16x32_bf16 v[66:69], v[172:175], v[208:211], v[66:69]
	s_barrier
	s_setprio 0
	s_add_i32 s36, s62, s52
	v_lshl_add_u64 v[184:185], s[40:41], 0, v[132:133]
	s_mov_b32 m0, s36
	ds_read_b128 v[176:179], v142 offset:16384
	ds_read_b128 v[180:183], v142 offset:17408
	ds_read_b128 v[188:191], v142 offset:18432
	ds_read_b128 v[192:195], v142 offset:19456
	ds_read_b128 v[196:199], v142 offset:20480
	ds_read_b128 v[200:203], v142 offset:21504
	ds_read_b128 v[204:207], v142 offset:22528
	ds_read_b128 v[208:211], v142 offset:23552
	global_load_lds_dwordx4 v[184:185], off
	s_add_i32 m0, s36, 0x2000
	s_add_u32 s36, s40, 0x60000
	v_lshl_add_u64 v[212:213], s[40:41], 0, v[130:131]
	s_addc_u32 s37, s41, 0
	s_add_i32 s76, s63, s52
	global_load_lds_dwordx4 v[212:213], off
	v_lshl_add_u64 v[214:215], s[36:37], 0, v[132:133]
	s_mov_b32 m0, s76
	v_lshl_add_u64 v[216:217], s[48:49], 0, v[130:131]
	global_load_lds_dwordx4 v[214:215], off
	v_lshl_add_u64 v[214:215], s[36:37], 0, v[130:131]
	s_add_i32 m0, s76, 0x2000
	s_nop 0
	global_load_lds_dwordx4 v[214:215], off
	v_lshl_add_u64 v[214:215], s[48:49], 0, v[132:133]
	s_mov_b32 m0, s53
	s_nop 0
	global_load_lds_dwordx4 v[214:215], off
	s_mov_b32 m0, s54
	s_nop 0
	global_load_lds_dwordx4 v[216:217], off
	s_waitcnt vmcnt(8)
	s_waitcnt lgkmcnt(0)
	s_barrier
; #define PG8_STAGE(bufoff, gbase, voff) do { _Pragma("unroll") for (int _i = 0; _i < 2; ++_i) \
;         __builtin_amdgcn_global_load_lds((const unsigned*)((const char*)(gbase) + (voff)[_i]), (PG8_LAS unsigned*)(lds + (bufoff) + ldsw + _i * 8192), 16, 0, 0); } while (0)
; #define PG8_LDA(dst, b, h) do { _Pragma("unroll") for (int m = 0; m < 4; ++m) _Pragma("unroll") for (int k = 0; k < 2; ++k) dst[m][k] = *(const PG8_LAS bf16x8*)(lds + PG8_SA(b, h) + aoff + m * 2048 + k * 1024); } while (0)
; #define PG8_LDB(dst, b, h) do { _Pragma("unroll") for (int n = 0; n < 2; ++n) _Pragma("unroll") for (int k = 0; k < 2; ++k) dst[n][k] = *(const PG8_LAS bf16x8*)(lds + PG8_SB(b, h) + boff + n * 2048 + k * 1024); } while (0)
; #define PG8_MMA(ai, bj, At, Bt) do { __builtin_amdgcn_s_setprio(1); _Pragma("unroll") for (int m = 0; m < 4; ++m) _Pragma("unroll") for (int n = 0; n < 2; ++n) _Pragma("unroll") for (int k = 0; k < 2; ++k) \
;         acc[ai][bj][m][n] = __builtin_amdgcn_mfma_f32_16x16x32_bf16(Bt[n][k], At[m][k], acc[ai][bj][m][n], 0, 0, 0); __builtin_amdgcn_s_setprio(0); } while (0)
; #define PG8_WAIT_V(n) asm volatile("s_waitcnt vmcnt(" #n ")" ::: "memory")
; #define PG8_WAIT_L(n) asm volatile("s_waitcnt lgkmcnt(" #n ")" ::: "memory")
; #define PG8_BAR __builtin_amdgcn_s_barrier()
; #define PG8_SCHED __builtin_amdgcn_sched_barrier(0)
; template <class Epi, class Sched, bool ALIGN_EPI = false, bool SP2 = false>
; __device__ __forceinline__ void gemm_phase(PG8_LAS unsigned char* lds, const Gemm g, const Sched& S, const Epi& E) {
;     ...
;             PG8_WAIT_V(8); PG8_WAIT_L(0); PG8_BAR; PG8_MMA(1, 0, At, B0); PG8_MMA(1, 1, At, B1); PG8_BAR; PG8_SCHED;
;             PG8_LDB(B0, 1, 0); PG8_LDB(B1, 1, 1); PG8_SCHED; PG8_LDA(At, 1, 0); PG8_STAGE(PG8_SA(0, 1), a2 + hstep, voffA);
;             PG8_WAIT_V(8); PG8_WAIT_L(0); PG8_BAR; PG8_MMA(0, 0, At, B0); PG8_MMA(0, 1, At, B1); PG8_BAR; PG8_SCHED;
	s_setprio 1
	s_waitcnt lgkmcnt(0)
	v_mfma_f32_16x16x32_bf16 v[62:65], v[144:147], v[176:179], v[62:65]
	v_mfma_f32_16x16x32_bf16 v[58:61], v[152:155], v[176:179], v[58:61]
	v_mfma_f32_16x16x32_bf16 v[46:49], v[144:147], v[188:191], v[46:49]
	v_mfma_f32_16x16x32_bf16 v[42:45], v[152:155], v[188:191], v[42:45]
	v_mfma_f32_16x16x32_bf16 v[30:33], v[144:147], v[196:199], v[30:33]
	v_mfma_f32_16x16x32_bf16 v[26:29], v[152:155], v[196:199], v[26:29]
	v_mfma_f32_16x16x32_bf16 v[14:17], v[144:147], v[204:207], v[14:17]
	v_mfma_f32_16x16x32_bf16 v[10:13], v[152:155], v[204:207], v[10:13]
	v_mfma_f32_16x16x32_bf16 v[62:65], v[148:151], v[180:183], v[62:65]
	v_mfma_f32_16x16x32_bf16 v[58:61], v[156:159], v[180:183], v[58:61]
	v_mfma_f32_16x16x32_bf16 v[46:49], v[148:151], v[192:195], v[46:49]
	v_mfma_f32_16x16x32_bf16 v[42:45], v[156:159], v[192:195], v[42:45]
	v_mfma_f32_16x16x32_bf16 v[30:33], v[148:151], v[200:203], v[30:33]
	v_mfma_f32_16x16x32_bf16 v[26:29], v[156:159], v[200:203], v[26:29]
	v_mfma_f32_16x16x32_bf16 v[14:17], v[148:151], v[208:211], v[14:17]
	v_mfma_f32_16x16x32_bf16 v[10:13], v[156:159], v[208:211], v[10:13]
	v_mfma_f32_16x16x32_bf16 v[54:57], v[160:163], v[176:179], v[54:57]
	v_mfma_f32_16x16x32_bf16 v[50:53], v[168:171], v[176:179], v[50:53]
	v_mfma_f32_16x16x32_bf16 v[38:41], v[160:163], v[188:191], v[38:41]
	v_mfma_f32_16x16x32_bf16 v[34:37], v[168:171], v[188:191], v[34:37]
	v_mfma_f32_16x16x32_bf16 v[22:25], v[160:163], v[196:199], v[22:25]
	v_mfma_f32_16x16x32_bf16 v[18:21], v[168:171], v[196:199], v[18:21]
	v_mfma_f32_16x16x32_bf16 v[6:9], v[160:163], v[204:207], v[6:9]
	v_mfma_f32_16x16x32_bf16 v[2:5], v[168:171], v[204:207], v[2:5]
	v_mfma_f32_16x16x32_bf16 v[54:57], v[164:167], v[180:183], v[54:57]
	v_mfma_f32_16x16x32_bf16 v[50:53], v[172:175], v[180:183], v[50:53]
	v_mfma_f32_16x16x32_bf16 v[38:41], v[164:167], v[192:195], v[38:41]
	v_mfma_f32_16x16x32_bf16 v[34:37], v[172:175], v[192:195], v[34:37]
	v_mfma_f32_16x16x32_bf16 v[22:25], v[164:167], v[200:203], v[22:25]
	v_mfma_f32_16x16x32_bf16 v[18:21], v[172:175], v[200:203], v[18:21]
	v_mfma_f32_16x16x32_bf16 v[6:9], v[164:167], v[208:211], v[6:9]
	v_mfma_f32_16x16x32_bf16 v[2:5], v[172:175], v[208:211], v[2:5]
	s_barrier
	s_setprio 0
	s_add_i32 s76, 0, 0x18000
	v_add_u32_e32 v143, s76, v1
	s_add_i32 s77, 0, 0x1c000
	ds_read_b128 v[144:147], v143
	ds_read_b128 v[148:151], v143 offset:1024
	ds_read_b128 v[152:155], v143 offset:2048
	ds_read_b128 v[156:159], v143 offset:3072
	v_add_u32_e32 v143, s77, v1
	ds_read_b128 v[160:163], v143
	ds_read_b128 v[164:167], v143 offset:1024
	ds_read_b128 v[168:171], v143 offset:2048
	ds_read_b128 v[172:175], v143 offset:3072
	s_add_u32 s36, s48, 0x60000
	s_addc_u32 s37, s49, 0
	s_mov_b32 m0, s55
	v_lshl_add_u64 v[218:219], s[36:37], 0, v[132:133]
	ds_read_b128 v[176:179], v142 offset:32768
	ds_read_b128 v[180:183], v142 offset:33792
	ds_read_b128 v[188:191], v142 offset:34816
	ds_read_b128 v[192:195], v142 offset:35840
	ds_read_b128 v[196:199], v142 offset:36864
	ds_read_b128 v[200:203], v142 offset:37888
	ds_read_b128 v[204:207], v142 offset:38912
	ds_read_b128 v[208:211], v142 offset:39936
	global_load_lds_dwordx4 v[218:219], off
	v_lshl_add_u64 v[218:219], s[36:37], 0, v[130:131]
	s_mov_b32 m0, s56
	s_nop 0
	global_load_lds_dwordx4 v[218:219], off
	s_waitcnt vmcnt(8)
	s_waitcnt lgkmcnt(0)
	s_barrier
	s_setprio 1
	s_waitcnt lgkmcnt(0)
	v_mfma_f32_16x16x32_bf16 v[126:129], v[144:147], v[176:179], v[126:129]
	v_mfma_f32_16x16x32_bf16 v[122:125], v[152:155], v[176:179], v[122:125]
	v_mfma_f32_16x16x32_bf16 v[110:113], v[144:147], v[188:191], v[110:113]
	v_mfma_f32_16x16x32_bf16 v[106:109], v[152:155], v[188:191], v[106:109]
	v_mfma_f32_16x16x32_bf16 v[94:97], v[144:147], v[196:199], v[94:97]
	v_mfma_f32_16x16x32_bf16 v[90:93], v[152:155], v[196:199], v[90:93]
	v_mfma_f32_16x16x32_bf16 v[78:81], v[144:147], v[204:207], v[78:81]
	v_mfma_f32_16x16x32_bf16 v[74:77], v[152:155], v[204:207], v[74:77]
	v_mfma_f32_16x16x32_bf16 v[126:129], v[148:151], v[180:183], v[126:129]
	v_mfma_f32_16x16x32_bf16 v[122:125], v[156:159], v[180:183], v[122:125]
	v_mfma_f32_16x16x32_bf16 v[110:113], v[148:151], v[192:195], v[110:113]
	v_mfma_f32_16x16x32_bf16 v[106:109], v[156:159], v[192:195], v[106:109]
	v_mfma_f32_16x16x32_bf16 v[94:97], v[148:151], v[200:203], v[94:97]
	v_mfma_f32_16x16x32_bf16 v[90:93], v[156:159], v[200:203], v[90:93]
	v_mfma_f32_16x16x32_bf16 v[78:81], v[148:151], v[208:211], v[78:81]
	v_mfma_f32_16x16x32_bf16 v[74:77], v[156:159], v[208:211], v[74:77]
	v_mfma_f32_16x16x32_bf16 v[118:121], v[160:163], v[176:179], v[118:121]
	v_mfma_f32_16x16x32_bf16 v[114:117], v[168:171], v[176:179], v[114:117]
	v_mfma_f32_16x16x32_bf16 v[102:105], v[160:163], v[188:191], v[102:105]
	v_mfma_f32_16x16x32_bf16 v[98:101], v[168:171], v[188:191], v[98:101]
	v_mfma_f32_16x16x32_bf16 v[86:89], v[160:163], v[196:199], v[86:89]
	v_mfma_f32_16x16x32_bf16 v[82:85], v[168:171], v[196:199], v[82:85]
	v_mfma_f32_16x16x32_bf16 v[70:73], v[160:163], v[204:207], v[70:73]
	v_mfma_f32_16x16x32_bf16 v[66:69], v[168:171], v[204:207], v[66:69]
	v_mfma_f32_16x16x32_bf16 v[118:121], v[164:167], v[180:183], v[118:121]
	v_mfma_f32_16x16x32_bf16 v[114:117], v[172:175], v[180:183], v[114:117]
	v_mfma_f32_16x16x32_bf16 v[102:105], v[164:167], v[192:195], v[102:105]
	v_mfma_f32_16x16x32_bf16 v[98:101], v[172:175], v[192:195], v[98:101]
	v_mfma_f32_16x16x32_bf16 v[86:89], v[164:167], v[200:203], v[86:89]
	v_mfma_f32_16x16x32_bf16 v[82:85], v[172:175], v[200:203], v[82:85]
	v_mfma_f32_16x16x32_bf16 v[70:73], v[164:167], v[208:211], v[70:73]
	v_mfma_f32_16x16x32_bf16 v[66:69], v[172:175], v[208:211], v[66:69]
	s_barrier
; #define PG8_STAGE(bufoff, gbase, voff) do { _Pragma("unroll") for (int _i = 0; _i < 2; ++_i) \
;         __builtin_amdgcn_global_load_lds((const unsigned*)((const char*)(gbase) + (voff)[_i]), (PG8_LAS unsigned*)(lds + (bufoff) + ldsw + _i * 8192), 16, 0, 0); } while (0)
; #define PG8_LDA(dst, b, h) do { _Pragma("unroll") for (int m = 0; m < 4; ++m) _Pragma("unroll") for (int k = 0; k < 2; ++k) dst[m][k] = *(const PG8_LAS bf16x8*)(lds + PG8_SA(b, h) + aoff + m * 2048 + k * 1024); } while (0)
; #define PG8_MMA(ai, bj, At, Bt) do { __builtin_amdgcn_s_setprio(1); _Pragma("unroll") for (int m = 0; m < 4; ++m) _Pragma("unroll") for (int n = 0; n < 2; ++n) _Pragma("unroll") for (int k = 0; k < 2; ++k) \
;         acc[ai][bj][m][n] = __builtin_amdgcn_mfma_f32_16x16x32_bf16(Bt[n][k], At[m][k], acc[ai][bj][m][n], 0, 0, 0); __builtin_amdgcn_s_setprio(0); } while (0)
; #define PG8_WAIT_V(n) asm volatile("s_waitcnt vmcnt(" #n ")" ::: "memory")
; #define PG8_WAIT_L(n) asm volatile("s_waitcnt lgkmcnt(" #n ")" ::: "memory")
; #define PG8_BAR __builtin_amdgcn_s_barrier()
; #define PG8_SCHED __builtin_amdgcn_sched_barrier(0)
; template <class Epi, class Sched, bool ALIGN_EPI = false, bool SP2 = false>
; __device__ __forceinline__ void gemm_phase(PG8_LAS unsigned char* lds, const Gemm g, const Sched& S, const Epi& E) {
;     ...
;             PG8_LDA(At, 1, 1); PG8_STAGE(PG8_SB(1, 0), b3, voffB); PG8_STAGE(PG8_SB(1, 1), b3 + hstep, voffB); PG8_STAGE(PG8_SA(1, 0), a3, voffA);
;             PG8_WAIT_V(8); PG8_WAIT_L(0); PG8_BAR; PG8_MMA(1, 0, At, B0); PG8_MMA(1, 1, At, B1); PG8_BAR; PG8_SCHED;
	s_setprio 0
	s_add_i32 s36, s76, s52
	v_lshl_add_u64 v[184:185], v[184:185], 0, s[16:17]
	s_mov_b32 m0, s36
	ds_read_b128 v[176:179], v142 offset:49152
	ds_read_b128 v[180:183], v142 offset:50176
	ds_read_b128 v[188:191], v142 offset:51200
	ds_read_b128 v[192:195], v142 offset:52224
	ds_read_b128 v[196:199], v142 offset:53248
	ds_read_b128 v[200:203], v142 offset:54272
	ds_read_b128 v[204:207], v142 offset:55296
	ds_read_b128 v[208:211], v142 offset:56320
	global_load_lds_dwordx4 v[184:185], off
	s_add_i32 m0, s36, 0x2000
	s_add_u32 s36, s40, 0x60080
	v_lshl_add_u64 v[184:185], v[212:213], 0, s[16:17]
	s_addc_u32 s37, s41, 0
	s_add_i32 s40, s77, s52
	global_load_lds_dwordx4 v[184:185], off
	v_lshl_add_u64 v[184:185], s[36:37], 0, v[132:133]
	s_mov_b32 m0, s40
	s_nop 0
	global_load_lds_dwordx4 v[184:185], off
	v_lshl_add_u64 v[184:185], s[36:37], 0, v[130:131]
	s_add_i32 m0, s40, 0x2000
	s_nop 0
	global_load_lds_dwordx4 v[184:185], off
	v_lshl_add_u64 v[184:185], v[214:215], 0, s[16:17]
	s_mov_b32 m0, s59
	s_nop 0
	global_load_lds_dwordx4 v[184:185], off
	v_lshl_add_u64 v[184:185], v[216:217], 0, s[16:17]
	s_mov_b32 m0, s60
	s_nop 0
	global_load_lds_dwordx4 v[184:185], off
	s_waitcnt vmcnt(8)
	s_waitcnt lgkmcnt(0)
	s_barrier
	s_setprio 1
	s_waitcnt lgkmcnt(0)
	v_mfma_f32_16x16x32_bf16 v[62:65], v[144:147], v[176:179], v[62:65]
	v_mfma_f32_16x16x32_bf16 v[58:61], v[152:155], v[176:179], v[58:61]
	v_mfma_f32_16x16x32_bf16 v[46:49], v[144:147], v[188:191], v[46:49]
	v_mfma_f32_16x16x32_bf16 v[42:45], v[152:155], v[188:191], v[42:45]
	v_mfma_f32_16x16x32_bf16 v[30:33], v[144:147], v[196:199], v[30:33]
	v_mfma_f32_16x16x32_bf16 v[26:29], v[152:155], v[196:199], v[26:29]
	v_mfma_f32_16x16x32_bf16 v[14:17], v[144:147], v[204:207], v[14:17]
	v_mfma_f32_16x16x32_bf16 v[10:13], v[152:155], v[204:207], v[10:13]
	v_mfma_f32_16x16x32_bf16 v[62:65], v[148:151], v[180:183], v[62:65]
	v_mfma_f32_16x16x32_bf16 v[58:61], v[156:159], v[180:183], v[58:61]
	v_mfma_f32_16x16x32_bf16 v[46:49], v[148:151], v[192:195], v[46:49]
	v_mfma_f32_16x16x32_bf16 v[42:45], v[156:159], v[192:195], v[42:45]
	v_mfma_f32_16x16x32_bf16 v[30:33], v[148:151], v[200:203], v[30:33]
	v_mfma_f32_16x16x32_bf16 v[26:29], v[156:159], v[200:203], v[26:29]
	v_mfma_f32_16x16x32_bf16 v[14:17], v[148:151], v[208:211], v[14:17]
	v_mfma_f32_16x16x32_bf16 v[10:13], v[156:159], v[208:211], v[10:13]
	v_mfma_f32_16x16x32_bf16 v[54:57], v[160:163], v[176:179], v[54:57]
	v_mfma_f32_16x16x32_bf16 v[50:53], v[168:171], v[176:179], v[50:53]
	v_mfma_f32_16x16x32_bf16 v[38:41], v[160:163], v[188:191], v[38:41]
	v_mfma_f32_16x16x32_bf16 v[34:37], v[168:171], v[188:191], v[34:37]
	v_mfma_f32_16x16x32_bf16 v[22:25], v[160:163], v[196:199], v[22:25]
	v_mfma_f32_16x16x32_bf16 v[18:21], v[168:171], v[196:199], v[18:21]
	v_mfma_f32_16x16x32_bf16 v[6:9], v[160:163], v[204:207], v[6:9]
	v_mfma_f32_16x16x32_bf16 v[2:5], v[168:171], v[204:207], v[2:5]
	v_mfma_f32_16x16x32_bf16 v[54:57], v[164:167], v[180:183], v[54:57]
	v_mfma_f32_16x16x32_bf16 v[50:53], v[172:175], v[180:183], v[50:53]
	v_mfma_f32_16x16x32_bf16 v[38:41], v[164:167], v[192:195], v[38:41]
	v_mfma_f32_16x16x32_bf16 v[34:37], v[172:175], v[192:195], v[34:37]
	v_mfma_f32_16x16x32_bf16 v[22:25], v[164:167], v[200:203], v[22:25]
	v_mfma_f32_16x16x32_bf16 v[18:21], v[172:175], v[200:203], v[18:21]
	v_mfma_f32_16x16x32_bf16 v[6:9], v[164:167], v[208:211], v[6:9]
	v_mfma_f32_16x16x32_bf16 v[2:5], v[172:175], v[208:211], v[2:5]
	s_barrier
	s_setprio 0
	s_add_u32 s73, s73, 0x100
	s_addc_u32 s74, s74, 0
	s_cmp_ge_i32 s75, s58
	s_mov_b64 s[36:37], s[38:39]
	s_mov_b32 s40, s75
	s_cbranch_scc0 .LBB0_1482

; #define PG8_STAGE(bufoff, gbase, voff) do { _Pragma("unroll") for (int _i = 0; _i < 2; ++_i) \
;         __builtin_amdgcn_global_load_lds((const unsigned*)((const char*)(gbase) + (voff)[_i]), (PG8_LAS unsigned*)(lds + (bufoff) + ldsw + _i * 8192), 16, 0, 0); } while (0)
; #define PG8_LDA(dst, b, h) do { _Pragma("unroll") for (int m = 0; m < 4; ++m) _Pragma("unroll") for (int k = 0; k < 2; ++k) dst[m][k] = *(const PG8_LAS bf16x8*)(lds + PG8_SA(b, h) + aoff + m * 2048 + k * 1024); } while (0)
; #define PG8_LDB(dst, b, h) do { _Pragma("unroll") for (int n = 0; n < 2; ++n) _Pragma("unroll") for (int k = 0; k < 2; ++k) dst[n][k] = *(const PG8_LAS bf16x8*)(lds + PG8_SB(b, h) + boff + n * 2048 + k * 1024); } while (0)
; #define PG8_MMA(ai, bj, At, Bt) do { __builtin_amdgcn_s_setprio(1); _Pragma("unroll") for (int m = 0; m < 4; ++m) _Pragma("unroll") for (int n = 0; n < 2; ++n) _Pragma("unroll") for (int k = 0; k < 2; ++k) \
;         acc[ai][bj][m][n] = __builtin_amdgcn_mfma_f32_16x16x32_bf16(Bt[n][k], At[m][k], acc[ai][bj][m][n], 0, 0, 0); __builtin_amdgcn_s_setprio(0); } while (0)
; #define PG8_WAIT_V(n) asm volatile("s_waitcnt vmcnt(" #n ")" ::: "memory")
; #define PG8_WAIT_L(n) asm volatile("s_waitcnt lgkmcnt(" #n ")" ::: "memory")
; #define PG8_BAR __builtin_amdgcn_s_barrier()
; #define PG8_SCHED __builtin_amdgcn_sched_barrier(0)
; template <class Epi, class Sched, bool ALIGN_EPI = false, bool SP2 = false>
; __device__ __forceinline__ void gemm_phase(PG8_LAS unsigned char* lds, const Gemm g, const Sched& S, const Epi& E) {
;     ...
;         for (int t = 0; t < nt; t += 2) {
;             const bool last = (t == nt - 2);
;             const char* a1 = cA + (size_t)(t + 1) * kstep;
;             const char* a2 = last ? nA : cA + (size_t)(t + 2) * kstep; const char* b2 = last ? nB : cB + (size_t)(t + 2) * kstep;
;             const char* a3 = a2 + kstep; const char* b3 = b2 + kstep;
;             if (last && has_next) S.a_ready(nxt);
;             if constexpr (SP2) {
;             PG8_LDB(B0, 0, 0); PG8_LDB(B1, 0, 1); PG8_SCHED; PG8_LDA(At, 0, 0); PG8_STAGE(PG8_SA(1, 1), a1 + hstep, voffA);
;             PG8_WAIT_V(8); PG8_WAIT_L(0); PG8_BAR; PG8_MMA(0, 0, At, B0); PG8_MMA(0, 1, At, B1); PG8_BAR; PG8_SCHED;
;             PG8_LDA(At, 0, 1); PG8_STAGE(PG8_SB(0, 0), b2, voffB); PG8_STAGE(PG8_SB(0, 1), b2 + hstep, voffB); PG8_STAGE(PG8_SA(0, 0), a2, voffA);
.LBB0_1523:
	v_add_u32_e32 v162, s56, v148
	v_add_u32_e32 v178, s57, v148
	s_add_u32 s34, s18, s30
	ds_read_b128 v[150:153], v162
	ds_read_b128 v[154:157], v162 offset:1024
	ds_read_b128 v[158:161], v162 offset:2048
	ds_read_b128 v[162:165], v162 offset:3072
	ds_read_b128 v[166:169], v178
	ds_read_b128 v[170:173], v178 offset:1024
	ds_read_b128 v[174:177], v178 offset:2048
	ds_read_b128 v[178:181], v178 offset:3072
	s_addc_u32 s35, s19, s31
	s_add_u32 s34, s34, 0x100
	s_addc_u32 s35, s35, 0
	s_add_u32 s65, s59, s30
	s_addc_u32 s66, s60, s31
	s_cmpk_eq_i32 s30, 0x700
	s_cselect_b32 s37, s25, s35
	s_cselect_b32 s36, s61, s34
	s_cselect_b32 s35, s23, s66
	s_cselect_b32 s34, s62, s65
	v_lshl_add_u64 v[216:217], v[142:143], 0, s[30:31]
	s_add_i32 m0, s48, 0xc000
	ds_read_b128 v[182:185], v149
	ds_read_b128 v[188:191], v149 offset:1024
	ds_read_b128 v[192:195], v149 offset:2048
	ds_read_b128 v[196:199], v149 offset:3072
	ds_read_b128 v[200:203], v149 offset:4096
	ds_read_b128 v[204:207], v149 offset:5120
	ds_read_b128 v[208:211], v149 offset:6144
	ds_read_b128 v[212:215], v149 offset:7168
	global_load_lds_dwordx4 v[216:217], off
	v_lshl_add_u64 v[216:217], v[144:145], 0, s[30:31]
	s_add_i32 m0, s48, 0xe000
	s_nop 0
	global_load_lds_dwordx4 v[216:217], off
	s_waitcnt vmcnt(8)
	s_waitcnt lgkmcnt(0)
	s_barrier
	s_setprio 1
	s_waitcnt lgkmcnt(0)
	v_mfma_f32_16x16x32_bf16 v[110:113], v[150:153], v[182:185], v[110:113]
	v_mfma_f32_16x16x32_bf16 v[74:77], v[158:161], v[182:185], v[74:77]
	v_mfma_f32_16x16x32_bf16 v[118:121], v[150:153], v[192:195], v[118:121]
	v_mfma_f32_16x16x32_bf16 v[94:97], v[158:161], v[192:195], v[94:97]
	v_mfma_f32_16x16x32_bf16 v[126:129], v[150:153], v[200:203], v[126:129]
	v_mfma_f32_16x16x32_bf16 v[106:109], v[158:161], v[200:203], v[106:109]
	v_mfma_f32_16x16x32_bf16 v[122:125], v[150:153], v[208:211], v[122:125]
	v_mfma_f32_16x16x32_bf16 v[114:117], v[158:161], v[208:211], v[114:117]
	v_mfma_f32_16x16x32_bf16 v[110:113], v[154:157], v[188:191], v[110:113]
	v_mfma_f32_16x16x32_bf16 v[74:77], v[162:165], v[188:191], v[74:77]
	v_mfma_f32_16x16x32_bf16 v[118:121], v[154:157], v[196:199], v[118:121]
	v_mfma_f32_16x16x32_bf16 v[94:97], v[162:165], v[196:199], v[94:97]
	v_mfma_f32_16x16x32_bf16 v[126:129], v[154:157], v[204:207], v[126:129]
	v_mfma_f32_16x16x32_bf16 v[106:109], v[162:165], v[204:207], v[106:109]
	v_mfma_f32_16x16x32_bf16 v[122:125], v[154:157], v[212:215], v[122:125]
	v_mfma_f32_16x16x32_bf16 v[114:117], v[162:165], v[212:215], v[114:117]
	v_mfma_f32_16x16x32_bf16 v[46:49], v[166:169], v[182:185], v[46:49]
	v_mfma_f32_16x16x32_bf16 v[14:17], v[174:177], v[182:185], v[14:17]
	v_mfma_f32_16x16x32_bf16 v[54:57], v[166:169], v[192:195], v[54:57]
	v_mfma_f32_16x16x32_bf16 v[30:33], v[174:177], v[192:195], v[30:33]
	v_mfma_f32_16x16x32_bf16 v[70:73], v[166:169], v[200:203], v[70:73]
	v_mfma_f32_16x16x32_bf16 v[42:45], v[174:177], v[200:203], v[42:45]
	v_mfma_f32_16x16x32_bf16 v[86:89], v[166:169], v[208:211], v[86:89]
	v_mfma_f32_16x16x32_bf16 v[50:53], v[174:177], v[208:211], v[50:53]
	v_mfma_f32_16x16x32_bf16 v[46:49], v[170:173], v[188:191], v[46:49]
	v_mfma_f32_16x16x32_bf16 v[14:17], v[178:181], v[188:191], v[14:17]
	v_mfma_f32_16x16x32_bf16 v[54:57], v[170:173], v[196:199], v[54:57]
	v_mfma_f32_16x16x32_bf16 v[30:33], v[178:181], v[196:199], v[30:33]
	v_mfma_f32_16x16x32_bf16 v[70:73], v[170:173], v[204:207], v[70:73]
	v_mfma_f32_16x16x32_bf16 v[42:45], v[178:181], v[204:207], v[42:45]
	v_mfma_f32_16x16x32_bf16 v[86:89], v[170:173], v[212:215], v[86:89]
	v_mfma_f32_16x16x32_bf16 v[50:53], v[178:181], v[212:215], v[50:53]
	s_barrier
	s_setprio 0
	s_add_i32 s65, s56, s43
	v_lshl_add_u64 v[216:217], s[34:35], 0, v[130:131]
	s_mov_b32 m0, s65
	ds_read_b128 v[182:185], v149 offset:16384
	ds_read_b128 v[188:191], v149 offset:17408
	ds_read_b128 v[192:195], v149 offset:18432
	ds_read_b128 v[196:199], v149 offset:19456
	ds_read_b128 v[200:203], v149 offset:20480
	ds_read_b128 v[204:207], v149 offset:21504
	ds_read_b128 v[208:211], v149 offset:22528
	ds_read_b128 v[212:215], v149 offset:23552
	global_load_lds_dwordx4 v[216:217], off
	s_add_i32 m0, s65, 0x2000
	s_add_u32 s66, s34, 0x40000
	v_lshl_add_u64 v[218:219], s[34:35], 0, v[132:133]
	s_addc_u32 s67, s35, 0
	s_add_i32 s65, s57, s43
	global_load_lds_dwordx4 v[218:219], off
	v_lshl_add_u64 v[220:221], s[66:67], 0, v[130:131]
	s_mov_b32 m0, s65
	v_lshl_add_u64 v[222:223], s[36:37], 0, v[132:133]
	global_load_lds_dwordx4 v[220:221], off
	v_lshl_add_u64 v[220:221], s[66:67], 0, v[132:133]
	s_add_i32 m0, s65, 0x2000
	s_nop 0
	global_load_lds_dwordx4 v[220:221], off
	v_lshl_add_u64 v[220:221], s[36:37], 0, v[130:131]
	s_mov_b32 m0, s48
	s_nop 0
	global_load_lds_dwordx4 v[220:221], off
	s_mov_b32 m0, s49
	s_nop 0
	global_load_lds_dwordx4 v[222:223], off
	s_waitcnt vmcnt(8)
	s_waitcnt lgkmcnt(0)
	s_barrier
; #define PG8_STAGE(bufoff, gbase, voff) do { _Pragma("unroll") for (int _i = 0; _i < 2; ++_i) \
;         __builtin_amdgcn_global_load_lds((const unsigned*)((const char*)(gbase) + (voff)[_i]), (PG8_LAS unsigned*)(lds + (bufoff) + ldsw + _i * 8192), 16, 0, 0); } while (0)
; #define PG8_LDA(dst, b, h) do { _Pragma("unroll") for (int m = 0; m < 4; ++m) _Pragma("unroll") for (int k = 0; k < 2; ++k) dst[m][k] = *(const PG8_LAS bf16x8*)(lds + PG8_SA(b, h) + aoff + m * 2048 + k * 1024); } while (0)
; #define PG8_LDB(dst, b, h) do { _Pragma("unroll") for (int n = 0; n < 2; ++n) _Pragma("unroll") for (int k = 0; k < 2; ++k) dst[n][k] = *(const PG8_LAS bf16x8*)(lds + PG8_SB(b, h) + boff + n * 2048 + k * 1024); } while (0)
; #define PG8_MMA(ai, bj, At, Bt) do { __builtin_amdgcn_s_setprio(1); _Pragma("unroll") for (int m = 0; m < 4; ++m) _Pragma("unroll") for (int n = 0; n < 2; ++n) _Pragma("unroll") for (int k = 0; k < 2; ++k) \
;         acc[ai][bj][m][n] = __builtin_amdgcn_mfma_f32_16x16x32_bf16(Bt[n][k], At[m][k], acc[ai][bj][m][n], 0, 0, 0); __builtin_amdgcn_s_setprio(0); } while (0)
; #define PG8_WAIT_V(n) asm volatile("s_waitcnt vmcnt(" #n ")" ::: "memory")
; #define PG8_WAIT_L(n) asm volatile("s_waitcnt lgkmcnt(" #n ")" ::: "memory")
; #define PG8_BAR __builtin_amdgcn_s_barrier()
; #define PG8_SCHED __builtin_amdgcn_sched_barrier(0)
; template <class Epi, class Sched, bool ALIGN_EPI = false, bool SP2 = false>
; __device__ __forceinline__ void gemm_phase(PG8_LAS unsigned char* lds, const Gemm g, const Sched& S, const Epi& E) {
;     ...
;             PG8_WAIT_V(8); PG8_WAIT_L(0); PG8_BAR; PG8_MMA(1, 0, At, B0); PG8_MMA(1, 1, At, B1); PG8_BAR; PG8_SCHED;
;             PG8_LDB(B0, 1, 0); PG8_LDB(B1, 1, 1); PG8_SCHED; PG8_LDA(At, 1, 0); PG8_STAGE(PG8_SA(0, 1), a2 + hstep, voffA);
;             PG8_WAIT_V(8); PG8_WAIT_L(0); PG8_BAR; PG8_MMA(0, 0, At, B0); PG8_MMA(0, 1, At, B1); PG8_BAR; PG8_SCHED;
	s_setprio 1
	s_waitcnt lgkmcnt(0)
	v_mfma_f32_16x16x32_bf16 v[102:105], v[150:153], v[182:185], v[102:105]
	v_mfma_f32_16x16x32_bf16 v[98:101], v[158:161], v[182:185], v[98:101]
	v_mfma_f32_16x16x32_bf16 v[82:85], v[150:153], v[192:195], v[82:85]
	v_mfma_f32_16x16x32_bf16 v[78:81], v[158:161], v[192:195], v[78:81]
	v_mfma_f32_16x16x32_bf16 v[38:41], v[150:153], v[200:203], v[38:41]
	v_mfma_f32_16x16x32_bf16 v[34:37], v[158:161], v[200:203], v[34:37]
	v_mfma_f32_16x16x32_bf16 v[18:21], v[150:153], v[208:211], v[18:21]
	v_mfma_f32_16x16x32_bf16 v[10:13], v[158:161], v[208:211], v[10:13]
	v_mfma_f32_16x16x32_bf16 v[102:105], v[154:157], v[188:191], v[102:105]
	v_mfma_f32_16x16x32_bf16 v[98:101], v[162:165], v[188:191], v[98:101]
	v_mfma_f32_16x16x32_bf16 v[82:85], v[154:157], v[196:199], v[82:85]
	v_mfma_f32_16x16x32_bf16 v[78:81], v[162:165], v[196:199], v[78:81]
	v_mfma_f32_16x16x32_bf16 v[38:41], v[154:157], v[204:207], v[38:41]
	v_mfma_f32_16x16x32_bf16 v[34:37], v[162:165], v[204:207], v[34:37]
	v_mfma_f32_16x16x32_bf16 v[18:21], v[154:157], v[212:215], v[18:21]
	v_mfma_f32_16x16x32_bf16 v[10:13], v[162:165], v[212:215], v[10:13]
	v_mfma_f32_16x16x32_bf16 v[90:93], v[166:169], v[182:185], v[90:93]
	v_mfma_f32_16x16x32_bf16 v[66:69], v[174:177], v[182:185], v[66:69]
	v_mfma_f32_16x16x32_bf16 v[62:65], v[166:169], v[192:195], v[62:65]
	v_mfma_f32_16x16x32_bf16 v[58:61], v[174:177], v[192:195], v[58:61]
	v_mfma_f32_16x16x32_bf16 v[26:29], v[166:169], v[200:203], v[26:29]
	v_mfma_f32_16x16x32_bf16 v[22:25], v[174:177], v[200:203], v[22:25]
	v_mfma_f32_16x16x32_bf16 v[6:9], v[166:169], v[208:211], v[6:9]
	v_mfma_f32_16x16x32_bf16 v[2:5], v[174:177], v[208:211], v[2:5]
	v_mfma_f32_16x16x32_bf16 v[90:93], v[170:173], v[188:191], v[90:93]
	v_mfma_f32_16x16x32_bf16 v[66:69], v[178:181], v[188:191], v[66:69]
	v_mfma_f32_16x16x32_bf16 v[62:65], v[170:173], v[196:199], v[62:65]
	v_mfma_f32_16x16x32_bf16 v[58:61], v[178:181], v[196:199], v[58:61]
	v_mfma_f32_16x16x32_bf16 v[26:29], v[170:173], v[204:207], v[26:29]
	v_mfma_f32_16x16x32_bf16 v[22:25], v[178:181], v[204:207], v[22:25]
	v_mfma_f32_16x16x32_bf16 v[6:9], v[170:173], v[212:215], v[6:9]
	v_mfma_f32_16x16x32_bf16 v[2:5], v[178:181], v[212:215], v[2:5]
	s_barrier
	s_setprio 0
	s_add_i32 s65, 0, 0x18000
	s_add_i32 s66, 0, 0x1c000
	v_add_u32_e32 v162, s65, v148
	v_add_u32_e32 v178, s66, v148
	ds_read_b128 v[150:153], v162
	ds_read_b128 v[154:157], v162 offset:1024
	ds_read_b128 v[158:161], v162 offset:2048
	ds_read_b128 v[162:165], v162 offset:3072
	ds_read_b128 v[166:169], v178
	ds_read_b128 v[170:173], v178 offset:1024
	ds_read_b128 v[174:177], v178 offset:2048
	ds_read_b128 v[178:181], v178 offset:3072
	s_add_u32 s36, s36, 0x40000
	s_addc_u32 s37, s37, 0
	s_mov_b32 m0, s50
	v_lshl_add_u64 v[224:225], s[36:37], 0, v[130:131]
	ds_read_b128 v[182:185], v149 offset:32768
	ds_read_b128 v[188:191], v149 offset:33792
	ds_read_b128 v[192:195], v149 offset:34816
	ds_read_b128 v[196:199], v149 offset:35840
	ds_read_b128 v[200:203], v149 offset:36864
	ds_read_b128 v[204:207], v149 offset:37888
	ds_read_b128 v[208:211], v149 offset:38912
	ds_read_b128 v[212:215], v149 offset:39936
	global_load_lds_dwordx4 v[224:225], off
	v_lshl_add_u64 v[224:225], s[36:37], 0, v[132:133]
	s_mov_b32 m0, s51
	s_nop 0
	global_load_lds_dwordx4 v[224:225], off
	s_waitcnt vmcnt(8)
	s_waitcnt lgkmcnt(0)
	s_barrier
	s_setprio 1
	s_waitcnt lgkmcnt(0)
	v_mfma_f32_16x16x32_bf16 v[110:113], v[150:153], v[182:185], v[110:113]
	v_mfma_f32_16x16x32_bf16 v[74:77], v[158:161], v[182:185], v[74:77]
	v_mfma_f32_16x16x32_bf16 v[118:121], v[150:153], v[192:195], v[118:121]
	v_mfma_f32_16x16x32_bf16 v[94:97], v[158:161], v[192:195], v[94:97]
	v_mfma_f32_16x16x32_bf16 v[126:129], v[150:153], v[200:203], v[126:129]
	v_mfma_f32_16x16x32_bf16 v[106:109], v[158:161], v[200:203], v[106:109]
	v_mfma_f32_16x16x32_bf16 v[122:125], v[150:153], v[208:211], v[122:125]
	v_mfma_f32_16x16x32_bf16 v[114:117], v[158:161], v[208:211], v[114:117]
	v_mfma_f32_16x16x32_bf16 v[110:113], v[154:157], v[188:191], v[110:113]
	v_mfma_f32_16x16x32_bf16 v[74:77], v[162:165], v[188:191], v[74:77]
	v_mfma_f32_16x16x32_bf16 v[118:121], v[154:157], v[196:199], v[118:121]
	v_mfma_f32_16x16x32_bf16 v[94:97], v[162:165], v[196:199], v[94:97]
	v_mfma_f32_16x16x32_bf16 v[126:129], v[154:157], v[204:207], v[126:129]
	v_mfma_f32_16x16x32_bf16 v[106:109], v[162:165], v[204:207], v[106:109]
	v_mfma_f32_16x16x32_bf16 v[122:125], v[154:157], v[212:215], v[122:125]
	v_mfma_f32_16x16x32_bf16 v[114:117], v[162:165], v[212:215], v[114:117]
	v_mfma_f32_16x16x32_bf16 v[46:49], v[166:169], v[182:185], v[46:49]
	v_mfma_f32_16x16x32_bf16 v[14:17], v[174:177], v[182:185], v[14:17]
	v_mfma_f32_16x16x32_bf16 v[54:57], v[166:169], v[192:195], v[54:57]
	v_mfma_f32_16x16x32_bf16 v[30:33], v[174:177], v[192:195], v[30:33]
	v_mfma_f32_16x16x32_bf16 v[70:73], v[166:169], v[200:203], v[70:73]
	v_mfma_f32_16x16x32_bf16 v[42:45], v[174:177], v[200:203], v[42:45]
	v_mfma_f32_16x16x32_bf16 v[86:89], v[166:169], v[208:211], v[86:89]
	v_mfma_f32_16x16x32_bf16 v[50:53], v[174:177], v[208:211], v[50:53]
	v_mfma_f32_16x16x32_bf16 v[46:49], v[170:173], v[188:191], v[46:49]
	v_mfma_f32_16x16x32_bf16 v[14:17], v[178:181], v[188:191], v[14:17]
	v_mfma_f32_16x16x32_bf16 v[54:57], v[170:173], v[196:199], v[54:57]
	v_mfma_f32_16x16x32_bf16 v[30:33], v[178:181], v[196:199], v[30:33]
	v_mfma_f32_16x16x32_bf16 v[70:73], v[170:173], v[204:207], v[70:73]
	v_mfma_f32_16x16x32_bf16 v[42:45], v[178:181], v[204:207], v[42:45]
	v_mfma_f32_16x16x32_bf16 v[86:89], v[170:173], v[212:215], v[86:89]
	v_mfma_f32_16x16x32_bf16 v[50:53], v[178:181], v[212:215], v[50:53]
	s_barrier
; #define PG8_STAGE(bufoff, gbase, voff) do { _Pragma("unroll") for (int _i = 0; _i < 2; ++_i) \
;         __builtin_amdgcn_global_load_lds((const unsigned*)((const char*)(gbase) + (voff)[_i]), (PG8_LAS unsigned*)(lds + (bufoff) + ldsw + _i * 8192), 16, 0, 0); } while (0)
; #define PG8_LDA(dst, b, h) do { _Pragma("unroll") for (int m = 0; m < 4; ++m) _Pragma("unroll") for (int k = 0; k < 2; ++k) dst[m][k] = *(const PG8_LAS bf16x8*)(lds + PG8_SA(b, h) + aoff + m * 2048 + k * 1024); } while (0)
; #define PG8_MMA(ai, bj, At, Bt) do { __builtin_amdgcn_s_setprio(1); _Pragma("unroll") for (int m = 0; m < 4; ++m) _Pragma("unroll") for (int n = 0; n < 2; ++n) _Pragma("unroll") for (int k = 0; k < 2; ++k) \
;         acc[ai][bj][m][n] = __builtin_amdgcn_mfma_f32_16x16x32_bf16(Bt[n][k], At[m][k], acc[ai][bj][m][n], 0, 0, 0); __builtin_amdgcn_s_setprio(0); } while (0)
; #define PG8_WAIT_V(n) asm volatile("s_waitcnt vmcnt(" #n ")" ::: "memory")
; #define PG8_WAIT_L(n) asm volatile("s_waitcnt lgkmcnt(" #n ")" ::: "memory")
; #define PG8_BAR __builtin_amdgcn_s_barrier()
; #define PG8_SCHED __builtin_amdgcn_sched_barrier(0)
; template <class Epi, class Sched, bool ALIGN_EPI = false, bool SP2 = false>
; __device__ __forceinline__ void gemm_phase(PG8_LAS unsigned char* lds, const Gemm g, const Sched& S, const Epi& E) {
;     ...
;             PG8_LDA(At, 1, 1); PG8_STAGE(PG8_SB(1, 0), b3, voffB); PG8_STAGE(PG8_SB(1, 1), b3 + hstep, voffB); PG8_STAGE(PG8_SA(1, 0), a3, voffA);
;             PG8_WAIT_V(8); PG8_WAIT_L(0); PG8_BAR; PG8_MMA(1, 0, At, B0); PG8_MMA(1, 1, At, B1); PG8_BAR; PG8_SCHED;
;     ...
;         if (!has_next) break;
; #pragma unroll
;         for (int a = 0; a < 2; ++a)
; #pragma unroll
;             for (int b = 0; b < 2; ++b)
; #pragma unroll
;                 for (int m = 0; m < 4; ++m)
; #pragma unroll
;                     for (int n = 0; n < 2; ++n) acc[a][b][m][n] = (f32x4){0.f, 0.f, 0.f, 0.f};
	s_setprio 0
	s_add_i32 s36, s65, s43
	v_lshl_add_u64 v[216:217], v[216:217], 0, s[20:21]
	s_mov_b32 m0, s36
	ds_read_b128 v[182:185], v149 offset:49152
	ds_read_b128 v[188:191], v149 offset:50176
	ds_read_b128 v[192:195], v149 offset:51200
	ds_read_b128 v[196:199], v149 offset:52224
	ds_read_b128 v[200:203], v149 offset:53248
	ds_read_b128 v[204:207], v149 offset:54272
	ds_read_b128 v[208:211], v149 offset:55296
	ds_read_b128 v[212:215], v149 offset:56320
	global_load_lds_dwordx4 v[216:217], off
	s_add_i32 m0, s36, 0x2000
	s_add_u32 s34, s34, 0x40080
	v_lshl_add_u64 v[216:217], v[218:219], 0, s[20:21]
	s_addc_u32 s35, s35, 0
	s_add_i32 s36, s66, s43
	global_load_lds_dwordx4 v[216:217], off
	v_lshl_add_u64 v[216:217], s[34:35], 0, v[130:131]
	s_mov_b32 m0, s36
	s_nop 0
	global_load_lds_dwordx4 v[216:217], off
	v_lshl_add_u64 v[216:217], s[34:35], 0, v[132:133]
	s_add_i32 m0, s36, 0x2000
	s_nop 0
	global_load_lds_dwordx4 v[216:217], off
	v_lshl_add_u64 v[216:217], v[220:221], 0, s[20:21]
	s_mov_b32 m0, s54
	s_nop 0
	global_load_lds_dwordx4 v[216:217], off
	v_lshl_add_u64 v[216:217], v[222:223], 0, s[20:21]
	s_mov_b32 m0, s55
	s_nop 0
	global_load_lds_dwordx4 v[216:217], off
	s_waitcnt vmcnt(8)
	s_waitcnt lgkmcnt(0)
	s_barrier
	s_setprio 1
	s_waitcnt lgkmcnt(0)
	v_mfma_f32_16x16x32_bf16 v[102:105], v[150:153], v[182:185], v[102:105]
	v_mfma_f32_16x16x32_bf16 v[98:101], v[158:161], v[182:185], v[98:101]
	v_mfma_f32_16x16x32_bf16 v[82:85], v[150:153], v[192:195], v[82:85]
	v_mfma_f32_16x16x32_bf16 v[78:81], v[158:161], v[192:195], v[78:81]
	v_mfma_f32_16x16x32_bf16 v[38:41], v[150:153], v[200:203], v[38:41]
	v_mfma_f32_16x16x32_bf16 v[34:37], v[158:161], v[200:203], v[34:37]
	v_mfma_f32_16x16x32_bf16 v[18:21], v[150:153], v[208:211], v[18:21]
	v_mfma_f32_16x16x32_bf16 v[10:13], v[158:161], v[208:211], v[10:13]
	v_mfma_f32_16x16x32_bf16 v[102:105], v[154:157], v[188:191], v[102:105]
	v_mfma_f32_16x16x32_bf16 v[98:101], v[162:165], v[188:191], v[98:101]
	v_mfma_f32_16x16x32_bf16 v[82:85], v[154:157], v[196:199], v[82:85]
	v_mfma_f32_16x16x32_bf16 v[78:81], v[162:165], v[196:199], v[78:81]
	v_mfma_f32_16x16x32_bf16 v[38:41], v[154:157], v[204:207], v[38:41]
	v_mfma_f32_16x16x32_bf16 v[34:37], v[162:165], v[204:207], v[34:37]
	v_mfma_f32_16x16x32_bf16 v[18:21], v[154:157], v[212:215], v[18:21]
	v_mfma_f32_16x16x32_bf16 v[10:13], v[162:165], v[212:215], v[10:13]
	v_mfma_f32_16x16x32_bf16 v[90:93], v[166:169], v[182:185], v[90:93]
	v_mfma_f32_16x16x32_bf16 v[66:69], v[174:177], v[182:185], v[66:69]
	v_mfma_f32_16x16x32_bf16 v[62:65], v[166:169], v[192:195], v[62:65]
	v_mfma_f32_16x16x32_bf16 v[58:61], v[174:177], v[192:195], v[58:61]
	v_mfma_f32_16x16x32_bf16 v[26:29], v[166:169], v[200:203], v[26:29]
	v_mfma_f32_16x16x32_bf16 v[22:25], v[174:177], v[200:203], v[22:25]
	v_mfma_f32_16x16x32_bf16 v[6:9], v[166:169], v[208:211], v[6:9]
	v_mfma_f32_16x16x32_bf16 v[2:5], v[174:177], v[208:211], v[2:5]
	v_mfma_f32_16x16x32_bf16 v[90:93], v[170:173], v[188:191], v[90:93]
	v_mfma_f32_16x16x32_bf16 v[66:69], v[178:181], v[188:191], v[66:69]
	v_mfma_f32_16x16x32_bf16 v[62:65], v[170:173], v[196:199], v[62:65]
	v_mfma_f32_16x16x32_bf16 v[58:61], v[178:181], v[196:199], v[58:61]
	v_mfma_f32_16x16x32_bf16 v[26:29], v[170:173], v[204:207], v[26:29]
	v_mfma_f32_16x16x32_bf16 v[22:25], v[178:181], v[204:207], v[22:25]
	v_mfma_f32_16x16x32_bf16 v[6:9], v[170:173], v[212:215], v[6:9]
	v_mfma_f32_16x16x32_bf16 v[2:5], v[178:181], v[212:215], v[2:5]
	s_barrier
	s_setprio 0
	s_add_i32 s63, s63, 2
	s_add_u32 s30, s30, 0x100
	s_addc_u32 s31, s31, 0
	s_cmp_gt_u32 s63, 13
	s_cbranch_scc0 .LBB0_1523
	s_add_u32 s30, s59, 0xffffff00
	s_addc_u32 s31, s60, -1
	s_andn2_b64 vcc, exec, s[6:7]
	s_cbranch_vccnz .LBB0_1526
	v_mov_b32_e32 v2, 0
	s_mov_b32 s8, s22
	s_mov_b32 s16, s24
	s_mov_b64 s[18:19], s[28:29]
	s_mov_b32 s53, s58
	v_mov_b32_e32 v3, v2
	v_mov_b32_e32 v4, v2
	v_mov_b32_e32 v5, v2
	v_mov_b32_e32 v6, v2
	v_mov_b32_e32 v7, v2
	v_mov_b32_e32 v8, v2
	v_mov_b32_e32 v9, v2
	v_mov_b32_e32 v22, v2
	v_mov_b32_e32 v23, v2
	v_mov_b32_e32 v24, v2
	v_mov_b32_e32 v25, v2
	v_mov_b32_e32 v26, v2
	v_mov_b32_e32 v27, v2
	v_mov_b32_e32 v28, v2
	v_mov_b32_e32 v29, v2
	v_mov_b32_e32 v58, v2
	v_mov_b32_e32 v59, v2
	v_mov_b32_e32 v60, v2
	v_mov_b32_e32 v61, v2
	v_mov_b32_e32 v62, v2
	v_mov_b32_e32 v63, v2
	v_mov_b32_e32 v64, v2
	v_mov_b32_e32 v65, v2
	v_mov_b32_e32 v66, v2
	v_mov_b32_e32 v67, v2
	v_mov_b32_e32 v68, v2
	v_mov_b32_e32 v69, v2
	v_mov_b32_e32 v90, v2
	v_mov_b32_e32 v91, v2
	v_mov_b32_e32 v92, v2
	v_mov_b32_e32 v93, v2
	v_mov_b32_e32 v10, v2
	v_mov_b32_e32 v11, v2
	v_mov_b32_e32 v12, v2
	v_mov_b32_e32 v13, v2
	v_mov_b32_e32 v18, v2
	v_mov_b32_e32 v19, v2
	v_mov_b32_e32 v20, v2
	v_mov_b32_e32 v21, v2
	v_mov_b32_e32 v34, v2
	v_mov_b32_e32 v35, v2
	v_mov_b32_e32 v36, v2
	v_mov_b32_e32 v37, v2
	v_mov_b32_e32 v38, v2
	v_mov_b32_e32 v39, v2
	v_mov_b32_e32 v40, v2
	v_mov_b32_e32 v41, v2
	v_mov_b32_e32 v78, v2
	v_mov_b32_e32 v79, v2
	v_mov_b32_e32 v80, v2
	v_mov_b32_e32 v81, v2
	v_mov_b32_e32 v82, v2
	v_mov_b32_e32 v83, v2
	v_mov_b32_e32 v84, v2
	v_mov_b32_e32 v85, v2
	v_mov_b32_e32 v98, v2
	v_mov_b32_e32 v99, v2
	v_mov_b32_e32 v100, v2
	v_mov_b32_e32 v101, v2
	v_mov_b32_e32 v102, v2
	v_mov_b32_e32 v103, v2
	v_mov_b32_e32 v104, v2
	v_mov_b32_e32 v105, v2
	v_mov_b32_e32 v50, v2
	v_mov_b32_e32 v51, v2
	v_mov_b32_e32 v52, v2
	v_mov_b32_e32 v53, v2
	v_mov_b32_e32 v86, v2
	v_mov_b32_e32 v87, v2
	v_mov_b32_e32 v88, v2
	v_mov_b32_e32 v89, v2
	v_mov_b32_e32 v42, v2
	v_mov_b32_e32 v43, v2
	v_mov_b32_e32 v44, v2
	v_mov_b32_e32 v45, v2
	v_mov_b32_e32 v70, v2
	v_mov_b32_e32 v71, v2
	v_mov_b32_e32 v72, v2
	v_mov_b32_e32 v73, v2
	v_mov_b32_e32 v30, v2
	v_mov_b32_e32 v31, v2
	v_mov_b32_e32 v32, v2
	v_mov_b32_e32 v33, v2
	v_mov_b32_e32 v54, v2
	v_mov_b32_e32 v55, v2
	v_mov_b32_e32 v56, v2
	v_mov_b32_e32 v57, v2
	v_mov_b32_e32 v14, v2
	v_mov_b32_e32 v15, v2
	v_mov_b32_e32 v16, v2
	v_mov_b32_e32 v17, v2
	v_mov_b32_e32 v46, v2
	v_mov_b32_e32 v47, v2
	v_mov_b32_e32 v48, v2
	v_mov_b32_e32 v49, v2
	v_mov_b32_e32 v114, v2
	v_mov_b32_e32 v115, v2
	v_mov_b32_e32 v116, v2
	v_mov_b32_e32 v117, v2
	v_mov_b32_e32 v122, v2
	v_mov_b32_e32 v123, v2
	v_mov_b32_e32 v124, v2
	v_mov_b32_e32 v125, v2
	v_mov_b32_e32 v106, v2
	v_mov_b32_e32 v107, v2
	v_mov_b32_e32 v108, v2
	v_mov_b32_e32 v109, v2
	v_mov_b32_e32 v126, v2
	v_mov_b32_e32 v127, v2
	v_mov_b32_e32 v128, v2
	v_mov_b32_e32 v129, v2
	v_mov_b32_e32 v94, v2
	v_mov_b32_e32 v95, v2
	v_mov_b32_e32 v96, v2
	v_mov_b32_e32 v97, v2
	v_mov_b32_e32 v118, v2
	v_mov_b32_e32 v119, v2
	v_mov_b32_e32 v120, v2
	v_mov_b32_e32 v121, v2
	v_mov_b32_e32 v74, v2
	v_mov_b32_e32 v75, v2
	v_mov_b32_e32 v76, v2
	v_mov_b32_e32 v77, v2
	v_mov_b32_e32 v110, v2
	v_mov_b32_e32 v111, v2
	v_mov_b32_e32 v112, v2
	v_mov_b32_e32 v113, v2
	s_andn2_b64 vcc, exec, s[4:5]
	s_cbranch_vccnz .LBB0_1527
	s_branch .LBB0_1528

; #define PG8_STAGE(bufoff, gbase, voff) do { _Pragma("unroll") for (int _i = 0; _i < 2; ++_i) \
;         __builtin_amdgcn_global_load_lds((const unsigned*)((const char*)(gbase) + (voff)[_i]), (PG8_LAS unsigned*)(lds + (bufoff) + ldsw + _i * 8192), 16, 0, 0); } while (0)
; #define PG8_LDA(dst, b, h) do { _Pragma("unroll") for (int m = 0; m < 4; ++m) _Pragma("unroll") for (int k = 0; k < 2; ++k) dst[m][k] = *(const PG8_LAS bf16x8*)(lds + PG8_SA(b, h) + aoff + m * 2048 + k * 1024); } while (0)
; #define PG8_LDB(dst, b, h) do { _Pragma("unroll") for (int n = 0; n < 2; ++n) _Pragma("unroll") for (int k = 0; k < 2; ++k) dst[n][k] = *(const PG8_LAS bf16x8*)(lds + PG8_SB(b, h) + boff + n * 2048 + k * 1024); } while (0)
; #define PG8_MMA(ai, bj, At, Bt) do { __builtin_amdgcn_s_setprio(1); _Pragma("unroll") for (int m = 0; m < 4; ++m) _Pragma("unroll") for (int n = 0; n < 2; ++n) _Pragma("unroll") for (int k = 0; k < 2; ++k) \
;         acc[ai][bj][m][n] = __builtin_amdgcn_mfma_f32_16x16x32_bf16(Bt[n][k], At[m][k], acc[ai][bj][m][n], 0, 0, 0); __builtin_amdgcn_s_setprio(0); } while (0)
; #define PG8_WAIT_V(n) asm volatile("s_waitcnt vmcnt(" #n ")" ::: "memory")
; #define PG8_WAIT_L(n) asm volatile("s_waitcnt lgkmcnt(" #n ")" ::: "memory")
; #define PG8_BAR __builtin_amdgcn_s_barrier()
; #define PG8_SCHED __builtin_amdgcn_sched_barrier(0)
; template <class Epi, class Sched, bool ALIGN_EPI = false, bool SP2 = false>
; __device__ __forceinline__ void gemm_phase(PG8_LAS unsigned char* lds, const Gemm g, const Sched& S, const Epi& E) {
;     ...
;         for (int t = 0; t < nt; t += 2) {
;             const bool last = (t == nt - 2);
;             const char* a1 = cA + (size_t)(t + 1) * kstep;
;             const char* a2 = last ? nA : cA + (size_t)(t + 2) * kstep; const char* b2 = last ? nB : cB + (size_t)(t + 2) * kstep;
;             const char* a3 = a2 + kstep; const char* b3 = b2 + kstep;
;             if (last && has_next) S.a_ready(nxt);
;             if constexpr (SP2) {
;             PG8_LDB(B0, 0, 0); PG8_LDB(B1, 0, 1); PG8_SCHED; PG8_LDA(At, 0, 0); PG8_STAGE(PG8_SA(1, 1), a1 + hstep, voffA);
;             PG8_WAIT_V(8); PG8_WAIT_L(0); PG8_BAR; PG8_MMA(0, 0, At, B0); PG8_MMA(0, 1, At, B1); PG8_BAR; PG8_SCHED;
;             PG8_LDA(At, 0, 1); PG8_STAGE(PG8_SB(0, 0), b2, voffB); PG8_STAGE(PG8_SB(0, 1), b2 + hstep, voffB); PG8_STAGE(PG8_SA(0, 0), a2, voffA);
.LBB0_1733:
	ds_read_b128 v[144:147], v140
	ds_read_b128 v[148:151], v140 offset:1024
	ds_read_b128 v[152:155], v140 offset:2048
	ds_read_b128 v[156:159], v140 offset:3072
	ds_read_b128 v[160:163], v141
	ds_read_b128 v[164:167], v141 offset:1024
	ds_read_b128 v[168:171], v141 offset:2048
	ds_read_b128 v[172:175], v141 offset:3072
	s_add_i32 s66, s36, 2
	s_add_u32 s34, s30, 0x100
	s_addc_u32 s35, s31, 0
	s_cmp_eq_u32 s50, s36
	s_cselect_b32 s36, s28, s63
	s_cselect_b32 s39, s27, s35
	s_cselect_b32 s38, s26, s34
	s_cselect_b32 s37, s29, s65
	s_mov_b32 m0, s58
	v_lshl_add_u64 v[184:185], s[30:31], 0, v[134:135]
	ds_read_b128 v[176:179], v142
	ds_read_b128 v[180:183], v142 offset:1024
	ds_read_b128 v[188:191], v142 offset:2048
	ds_read_b128 v[192:195], v142 offset:3072
	ds_read_b128 v[196:199], v142 offset:4096
	ds_read_b128 v[200:203], v142 offset:5120
	ds_read_b128 v[204:207], v142 offset:6144
	ds_read_b128 v[208:211], v142 offset:7168
	global_load_lds_dwordx4 v[184:185], off
	v_lshl_add_u64 v[184:185], s[30:31], 0, v[136:137]
	s_add_i32 m0, s1, 0xe000
	s_nop 0
	global_load_lds_dwordx4 v[184:185], off
	s_waitcnt vmcnt(8)
	s_waitcnt lgkmcnt(0)
	s_barrier
	s_setprio 1
	s_waitcnt lgkmcnt(0)
	v_mfma_f32_16x16x32_bf16 v[126:129], v[144:147], v[176:179], v[126:129]
	v_mfma_f32_16x16x32_bf16 v[122:125], v[152:155], v[176:179], v[122:125]
	v_mfma_f32_16x16x32_bf16 v[110:113], v[144:147], v[188:191], v[110:113]
	v_mfma_f32_16x16x32_bf16 v[106:109], v[152:155], v[188:191], v[106:109]
	v_mfma_f32_16x16x32_bf16 v[94:97], v[144:147], v[196:199], v[94:97]
	v_mfma_f32_16x16x32_bf16 v[90:93], v[152:155], v[196:199], v[90:93]
	v_mfma_f32_16x16x32_bf16 v[78:81], v[144:147], v[204:207], v[78:81]
	v_mfma_f32_16x16x32_bf16 v[74:77], v[152:155], v[204:207], v[74:77]
	v_mfma_f32_16x16x32_bf16 v[126:129], v[148:151], v[180:183], v[126:129]
	v_mfma_f32_16x16x32_bf16 v[122:125], v[156:159], v[180:183], v[122:125]
	v_mfma_f32_16x16x32_bf16 v[110:113], v[148:151], v[192:195], v[110:113]
	v_mfma_f32_16x16x32_bf16 v[106:109], v[156:159], v[192:195], v[106:109]
	v_mfma_f32_16x16x32_bf16 v[94:97], v[148:151], v[200:203], v[94:97]
	v_mfma_f32_16x16x32_bf16 v[90:93], v[156:159], v[200:203], v[90:93]
	v_mfma_f32_16x16x32_bf16 v[78:81], v[148:151], v[208:211], v[78:81]
	v_mfma_f32_16x16x32_bf16 v[74:77], v[156:159], v[208:211], v[74:77]
	v_mfma_f32_16x16x32_bf16 v[118:121], v[160:163], v[176:179], v[118:121]
	v_mfma_f32_16x16x32_bf16 v[114:117], v[168:171], v[176:179], v[114:117]
	v_mfma_f32_16x16x32_bf16 v[102:105], v[160:163], v[188:191], v[102:105]
	v_mfma_f32_16x16x32_bf16 v[98:101], v[168:171], v[188:191], v[98:101]
	v_mfma_f32_16x16x32_bf16 v[86:89], v[160:163], v[196:199], v[86:89]
	v_mfma_f32_16x16x32_bf16 v[82:85], v[168:171], v[196:199], v[82:85]
	v_mfma_f32_16x16x32_bf16 v[70:73], v[160:163], v[204:207], v[70:73]
	v_mfma_f32_16x16x32_bf16 v[66:69], v[168:171], v[204:207], v[66:69]
	v_mfma_f32_16x16x32_bf16 v[118:121], v[164:167], v[180:183], v[118:121]
	v_mfma_f32_16x16x32_bf16 v[114:117], v[172:175], v[180:183], v[114:117]
	v_mfma_f32_16x16x32_bf16 v[102:105], v[164:167], v[192:195], v[102:105]
	v_mfma_f32_16x16x32_bf16 v[98:101], v[172:175], v[192:195], v[98:101]
	v_mfma_f32_16x16x32_bf16 v[86:89], v[164:167], v[200:203], v[86:89]
	v_mfma_f32_16x16x32_bf16 v[82:85], v[172:175], v[200:203], v[82:85]
	v_mfma_f32_16x16x32_bf16 v[70:73], v[164:167], v[208:211], v[70:73]
	v_mfma_f32_16x16x32_bf16 v[66:69], v[172:175], v[208:211], v[66:69]
	s_barrier
	s_setprio 0
	s_add_i32 s30, s51, s0
	v_lshl_add_u64 v[184:185], s[36:37], 0, v[132:133]
	s_mov_b32 m0, s30
	ds_read_b128 v[176:179], v142 offset:16384
	ds_read_b128 v[180:183], v142 offset:17408
	ds_read_b128 v[188:191], v142 offset:18432
	ds_read_b128 v[192:195], v142 offset:19456
	ds_read_b128 v[196:199], v142 offset:20480
	ds_read_b128 v[200:203], v142 offset:21504
	ds_read_b128 v[204:207], v142 offset:22528
	ds_read_b128 v[208:211], v142 offset:23552
	global_load_lds_dwordx4 v[184:185], off
	s_add_i32 m0, s30, 0x2000
	s_add_u32 s30, s36, 0xb0000
	v_lshl_add_u64 v[212:213], s[36:37], 0, v[130:131]
	s_addc_u32 s31, s37, 0
	s_add_i32 s67, s52, s0
	global_load_lds_dwordx4 v[212:213], off
	v_lshl_add_u64 v[214:215], s[30:31], 0, v[132:133]
	s_mov_b32 m0, s67
	v_lshl_add_u64 v[216:217], s[38:39], 0, v[130:131]
	global_load_lds_dwordx4 v[214:215], off
	v_lshl_add_u64 v[214:215], s[30:31], 0, v[130:131]
	s_add_i32 m0, s67, 0x2000
	s_nop 0
	global_load_lds_dwordx4 v[214:215], off
	v_lshl_add_u64 v[214:215], s[38:39], 0, v[132:133]
	s_mov_b32 m0, s1
	s_nop 0
	global_load_lds_dwordx4 v[214:215], off
	s_mov_b32 m0, s40
	s_nop 0
	global_load_lds_dwordx4 v[216:217], off
	s_waitcnt vmcnt(8)
	s_waitcnt lgkmcnt(0)
	s_barrier
; #define PG8_STAGE(bufoff, gbase, voff) do { _Pragma("unroll") for (int _i = 0; _i < 2; ++_i) \
;         __builtin_amdgcn_global_load_lds((const unsigned*)((const char*)(gbase) + (voff)[_i]), (PG8_LAS unsigned*)(lds + (bufoff) + ldsw + _i * 8192), 16, 0, 0); } while (0)
; #define PG8_LDA(dst, b, h) do { _Pragma("unroll") for (int m = 0; m < 4; ++m) _Pragma("unroll") for (int k = 0; k < 2; ++k) dst[m][k] = *(const PG8_LAS bf16x8*)(lds + PG8_SA(b, h) + aoff + m * 2048 + k * 1024); } while (0)
; #define PG8_LDB(dst, b, h) do { _Pragma("unroll") for (int n = 0; n < 2; ++n) _Pragma("unroll") for (int k = 0; k < 2; ++k) dst[n][k] = *(const PG8_LAS bf16x8*)(lds + PG8_SB(b, h) + boff + n * 2048 + k * 1024); } while (0)
; #define PG8_MMA(ai, bj, At, Bt) do { __builtin_amdgcn_s_setprio(1); _Pragma("unroll") for (int m = 0; m < 4; ++m) _Pragma("unroll") for (int n = 0; n < 2; ++n) _Pragma("unroll") for (int k = 0; k < 2; ++k) \
;         acc[ai][bj][m][n] = __builtin_amdgcn_mfma_f32_16x16x32_bf16(Bt[n][k], At[m][k], acc[ai][bj][m][n], 0, 0, 0); __builtin_amdgcn_s_setprio(0); } while (0)
; #define PG8_WAIT_V(n) asm volatile("s_waitcnt vmcnt(" #n ")" ::: "memory")
; #define PG8_WAIT_L(n) asm volatile("s_waitcnt lgkmcnt(" #n ")" ::: "memory")
; #define PG8_BAR __builtin_amdgcn_s_barrier()
; #define PG8_SCHED __builtin_amdgcn_sched_barrier(0)
; template <class Epi, class Sched, bool ALIGN_EPI = false, bool SP2 = false>
; __device__ __forceinline__ void gemm_phase(PG8_LAS unsigned char* lds, const Gemm g, const Sched& S, const Epi& E) {
;     ...
;             PG8_WAIT_V(8); PG8_WAIT_L(0); PG8_BAR; PG8_MMA(1, 0, At, B0); PG8_MMA(1, 1, At, B1); PG8_BAR; PG8_SCHED;
;             PG8_LDB(B0, 1, 0); PG8_LDB(B1, 1, 1); PG8_SCHED; PG8_LDA(At, 1, 0); PG8_STAGE(PG8_SA(0, 1), a2 + hstep, voffA);
;             PG8_WAIT_V(8); PG8_WAIT_L(0); PG8_BAR; PG8_MMA(0, 0, At, B0); PG8_MMA(0, 1, At, B1); PG8_BAR; PG8_SCHED;
	s_setprio 1
	s_waitcnt lgkmcnt(0)
	v_mfma_f32_16x16x32_bf16 v[62:65], v[144:147], v[176:179], v[62:65]
	v_mfma_f32_16x16x32_bf16 v[58:61], v[152:155], v[176:179], v[58:61]
	v_mfma_f32_16x16x32_bf16 v[46:49], v[144:147], v[188:191], v[46:49]
	v_mfma_f32_16x16x32_bf16 v[42:45], v[152:155], v[188:191], v[42:45]
	v_mfma_f32_16x16x32_bf16 v[30:33], v[144:147], v[196:199], v[30:33]
	v_mfma_f32_16x16x32_bf16 v[26:29], v[152:155], v[196:199], v[26:29]
	v_mfma_f32_16x16x32_bf16 v[14:17], v[144:147], v[204:207], v[14:17]
	v_mfma_f32_16x16x32_bf16 v[10:13], v[152:155], v[204:207], v[10:13]
	v_mfma_f32_16x16x32_bf16 v[62:65], v[148:151], v[180:183], v[62:65]
	v_mfma_f32_16x16x32_bf16 v[58:61], v[156:159], v[180:183], v[58:61]
	v_mfma_f32_16x16x32_bf16 v[46:49], v[148:151], v[192:195], v[46:49]
	v_mfma_f32_16x16x32_bf16 v[42:45], v[156:159], v[192:195], v[42:45]
	v_mfma_f32_16x16x32_bf16 v[30:33], v[148:151], v[200:203], v[30:33]
	v_mfma_f32_16x16x32_bf16 v[26:29], v[156:159], v[200:203], v[26:29]
	v_mfma_f32_16x16x32_bf16 v[14:17], v[148:151], v[208:211], v[14:17]
	v_mfma_f32_16x16x32_bf16 v[10:13], v[156:159], v[208:211], v[10:13]
	v_mfma_f32_16x16x32_bf16 v[54:57], v[160:163], v[176:179], v[54:57]
	v_mfma_f32_16x16x32_bf16 v[50:53], v[168:171], v[176:179], v[50:53]
	v_mfma_f32_16x16x32_bf16 v[38:41], v[160:163], v[188:191], v[38:41]
	v_mfma_f32_16x16x32_bf16 v[34:37], v[168:171], v[188:191], v[34:37]
	v_mfma_f32_16x16x32_bf16 v[22:25], v[160:163], v[196:199], v[22:25]
	v_mfma_f32_16x16x32_bf16 v[18:21], v[168:171], v[196:199], v[18:21]
	v_mfma_f32_16x16x32_bf16 v[6:9], v[160:163], v[204:207], v[6:9]
	v_mfma_f32_16x16x32_bf16 v[2:5], v[168:171], v[204:207], v[2:5]
	v_mfma_f32_16x16x32_bf16 v[54:57], v[164:167], v[180:183], v[54:57]
	v_mfma_f32_16x16x32_bf16 v[50:53], v[172:175], v[180:183], v[50:53]
	v_mfma_f32_16x16x32_bf16 v[38:41], v[164:167], v[192:195], v[38:41]
	v_mfma_f32_16x16x32_bf16 v[34:37], v[172:175], v[192:195], v[34:37]
	v_mfma_f32_16x16x32_bf16 v[22:25], v[164:167], v[200:203], v[22:25]
	v_mfma_f32_16x16x32_bf16 v[18:21], v[172:175], v[200:203], v[18:21]
	v_mfma_f32_16x16x32_bf16 v[6:9], v[164:167], v[208:211], v[6:9]
	v_mfma_f32_16x16x32_bf16 v[2:5], v[172:175], v[208:211], v[2:5]
	s_barrier
	s_setprio 0
	s_add_i32 s67, 0, 0x18000
	v_add_u32_e32 v143, s67, v1
	s_add_i32 s68, 0, 0x1c000
	ds_read_b128 v[144:147], v143
	ds_read_b128 v[148:151], v143 offset:1024
	ds_read_b128 v[152:155], v143 offset:2048
	ds_read_b128 v[156:159], v143 offset:3072
	v_add_u32_e32 v143, s68, v1
	ds_read_b128 v[160:163], v143
	ds_read_b128 v[164:167], v143 offset:1024
	ds_read_b128 v[168:171], v143 offset:2048
	ds_read_b128 v[172:175], v143 offset:3072
	s_add_u32 s30, s38, 0xb0000
	s_addc_u32 s31, s39, 0
	s_mov_b32 m0, s41
	v_lshl_add_u64 v[218:219], s[30:31], 0, v[132:133]
	ds_read_b128 v[176:179], v142 offset:32768
	ds_read_b128 v[180:183], v142 offset:33792
	ds_read_b128 v[188:191], v142 offset:34816
	ds_read_b128 v[192:195], v142 offset:35840
	ds_read_b128 v[196:199], v142 offset:36864
	ds_read_b128 v[200:203], v142 offset:37888
	ds_read_b128 v[204:207], v142 offset:38912
	ds_read_b128 v[208:211], v142 offset:39936
	global_load_lds_dwordx4 v[218:219], off
	v_lshl_add_u64 v[218:219], s[30:31], 0, v[130:131]
	s_mov_b32 m0, s42
	s_nop 0
	global_load_lds_dwordx4 v[218:219], off
	s_waitcnt vmcnt(8)
	s_waitcnt lgkmcnt(0)
	s_barrier
	s_setprio 1
	s_waitcnt lgkmcnt(0)
	v_mfma_f32_16x16x32_bf16 v[126:129], v[144:147], v[176:179], v[126:129]
	v_mfma_f32_16x16x32_bf16 v[122:125], v[152:155], v[176:179], v[122:125]
	v_mfma_f32_16x16x32_bf16 v[110:113], v[144:147], v[188:191], v[110:113]
	v_mfma_f32_16x16x32_bf16 v[106:109], v[152:155], v[188:191], v[106:109]
	v_mfma_f32_16x16x32_bf16 v[94:97], v[144:147], v[196:199], v[94:97]
	v_mfma_f32_16x16x32_bf16 v[90:93], v[152:155], v[196:199], v[90:93]
	v_mfma_f32_16x16x32_bf16 v[78:81], v[144:147], v[204:207], v[78:81]
	v_mfma_f32_16x16x32_bf16 v[74:77], v[152:155], v[204:207], v[74:77]
	v_mfma_f32_16x16x32_bf16 v[126:129], v[148:151], v[180:183], v[126:129]
	v_mfma_f32_16x16x32_bf16 v[122:125], v[156:159], v[180:183], v[122:125]
	v_mfma_f32_16x16x32_bf16 v[110:113], v[148:151], v[192:195], v[110:113]
	v_mfma_f32_16x16x32_bf16 v[106:109], v[156:159], v[192:195], v[106:109]
	v_mfma_f32_16x16x32_bf16 v[94:97], v[148:151], v[200:203], v[94:97]
	v_mfma_f32_16x16x32_bf16 v[90:93], v[156:159], v[200:203], v[90:93]
	v_mfma_f32_16x16x32_bf16 v[78:81], v[148:151], v[208:211], v[78:81]
	v_mfma_f32_16x16x32_bf16 v[74:77], v[156:159], v[208:211], v[74:77]
	v_mfma_f32_16x16x32_bf16 v[118:121], v[160:163], v[176:179], v[118:121]
	v_mfma_f32_16x16x32_bf16 v[114:117], v[168:171], v[176:179], v[114:117]
	v_mfma_f32_16x16x32_bf16 v[102:105], v[160:163], v[188:191], v[102:105]
	v_mfma_f32_16x16x32_bf16 v[98:101], v[168:171], v[188:191], v[98:101]
	v_mfma_f32_16x16x32_bf16 v[86:89], v[160:163], v[196:199], v[86:89]
	v_mfma_f32_16x16x32_bf16 v[82:85], v[168:171], v[196:199], v[82:85]
	v_mfma_f32_16x16x32_bf16 v[70:73], v[160:163], v[204:207], v[70:73]
	v_mfma_f32_16x16x32_bf16 v[66:69], v[168:171], v[204:207], v[66:69]
	v_mfma_f32_16x16x32_bf16 v[118:121], v[164:167], v[180:183], v[118:121]
	v_mfma_f32_16x16x32_bf16 v[114:117], v[172:175], v[180:183], v[114:117]
	v_mfma_f32_16x16x32_bf16 v[102:105], v[164:167], v[192:195], v[102:105]
	v_mfma_f32_16x16x32_bf16 v[98:101], v[172:175], v[192:195], v[98:101]
	v_mfma_f32_16x16x32_bf16 v[86:89], v[164:167], v[200:203], v[86:89]
	v_mfma_f32_16x16x32_bf16 v[82:85], v[172:175], v[200:203], v[82:85]
	v_mfma_f32_16x16x32_bf16 v[70:73], v[164:167], v[208:211], v[70:73]
	v_mfma_f32_16x16x32_bf16 v[66:69], v[172:175], v[208:211], v[66:69]
	s_barrier
; #define PG8_STAGE(bufoff, gbase, voff) do { _Pragma("unroll") for (int _i = 0; _i < 2; ++_i) \
;         __builtin_amdgcn_global_load_lds((const unsigned*)((const char*)(gbase) + (voff)[_i]), (PG8_LAS unsigned*)(lds + (bufoff) + ldsw + _i * 8192), 16, 0, 0); } while (0)
; #define PG8_LDA(dst, b, h) do { _Pragma("unroll") for (int m = 0; m < 4; ++m) _Pragma("unroll") for (int k = 0; k < 2; ++k) dst[m][k] = *(const PG8_LAS bf16x8*)(lds + PG8_SA(b, h) + aoff + m * 2048 + k * 1024); } while (0)
; #define PG8_MMA(ai, bj, At, Bt) do { __builtin_amdgcn_s_setprio(1); _Pragma("unroll") for (int m = 0; m < 4; ++m) _Pragma("unroll") for (int n = 0; n < 2; ++n) _Pragma("unroll") for (int k = 0; k < 2; ++k) \
;         acc[ai][bj][m][n] = __builtin_amdgcn_mfma_f32_16x16x32_bf16(Bt[n][k], At[m][k], acc[ai][bj][m][n], 0, 0, 0); __builtin_amdgcn_s_setprio(0); } while (0)
; #define PG8_WAIT_V(n) asm volatile("s_waitcnt vmcnt(" #n ")" ::: "memory")
; #define PG8_WAIT_L(n) asm volatile("s_waitcnt lgkmcnt(" #n ")" ::: "memory")
; #define PG8_BAR __builtin_amdgcn_s_barrier()
; #define PG8_SCHED __builtin_amdgcn_sched_barrier(0)
; template <class Epi, class Sched, bool ALIGN_EPI = false, bool SP2 = false>
; __device__ __forceinline__ void gemm_phase(PG8_LAS unsigned char* lds, const Gemm g, const Sched& S, const Epi& E) {
;     ...
;             PG8_LDA(At, 1, 1); PG8_STAGE(PG8_SB(1, 0), b3, voffB); PG8_STAGE(PG8_SB(1, 1), b3 + hstep, voffB); PG8_STAGE(PG8_SA(1, 0), a3, voffA);
;             PG8_WAIT_V(8); PG8_WAIT_L(0); PG8_BAR; PG8_MMA(1, 0, At, B0); PG8_MMA(1, 1, At, B1); PG8_BAR; PG8_SCHED;
	s_setprio 0
	s_add_i32 s30, s67, s0
	v_lshl_add_u64 v[184:185], v[184:185], 0, s[14:15]
	s_mov_b32 m0, s30
	ds_read_b128 v[176:179], v142 offset:49152
	ds_read_b128 v[180:183], v142 offset:50176
	ds_read_b128 v[188:191], v142 offset:51200
	ds_read_b128 v[192:195], v142 offset:52224
	ds_read_b128 v[196:199], v142 offset:53248
	ds_read_b128 v[200:203], v142 offset:54272
	ds_read_b128 v[204:207], v142 offset:55296
	ds_read_b128 v[208:211], v142 offset:56320
	global_load_lds_dwordx4 v[184:185], off
	s_add_i32 m0, s30, 0x2000
	s_add_u32 s30, s36, 0xb0080
	v_lshl_add_u64 v[184:185], v[212:213], 0, s[14:15]
	s_addc_u32 s31, s37, 0
	s_add_i32 s36, s68, s0
	global_load_lds_dwordx4 v[184:185], off
	v_lshl_add_u64 v[184:185], s[30:31], 0, v[132:133]
	s_mov_b32 m0, s36
	s_nop 0
	global_load_lds_dwordx4 v[184:185], off
	v_lshl_add_u64 v[184:185], s[30:31], 0, v[130:131]
	s_add_i32 m0, s36, 0x2000
	s_nop 0
	global_load_lds_dwordx4 v[184:185], off
	v_lshl_add_u64 v[184:185], v[214:215], 0, s[14:15]
	s_mov_b32 m0, s48
	s_nop 0
	global_load_lds_dwordx4 v[184:185], off
	v_lshl_add_u64 v[184:185], v[216:217], 0, s[14:15]
	s_mov_b32 m0, s49
	s_nop 0
	global_load_lds_dwordx4 v[184:185], off
	s_waitcnt vmcnt(8)
	s_waitcnt lgkmcnt(0)
	s_barrier
	s_setprio 1
	s_waitcnt lgkmcnt(0)
	v_mfma_f32_16x16x32_bf16 v[62:65], v[144:147], v[176:179], v[62:65]
	v_mfma_f32_16x16x32_bf16 v[58:61], v[152:155], v[176:179], v[58:61]
	v_mfma_f32_16x16x32_bf16 v[46:49], v[144:147], v[188:191], v[46:49]
	v_mfma_f32_16x16x32_bf16 v[42:45], v[152:155], v[188:191], v[42:45]
	v_mfma_f32_16x16x32_bf16 v[30:33], v[144:147], v[196:199], v[30:33]
	v_mfma_f32_16x16x32_bf16 v[26:29], v[152:155], v[196:199], v[26:29]
	v_mfma_f32_16x16x32_bf16 v[14:17], v[144:147], v[204:207], v[14:17]
	v_mfma_f32_16x16x32_bf16 v[10:13], v[152:155], v[204:207], v[10:13]
	v_mfma_f32_16x16x32_bf16 v[62:65], v[148:151], v[180:183], v[62:65]
	v_mfma_f32_16x16x32_bf16 v[58:61], v[156:159], v[180:183], v[58:61]
	v_mfma_f32_16x16x32_bf16 v[46:49], v[148:151], v[192:195], v[46:49]
	v_mfma_f32_16x16x32_bf16 v[42:45], v[156:159], v[192:195], v[42:45]
	v_mfma_f32_16x16x32_bf16 v[30:33], v[148:151], v[200:203], v[30:33]
	v_mfma_f32_16x16x32_bf16 v[26:29], v[156:159], v[200:203], v[26:29]
	v_mfma_f32_16x16x32_bf16 v[14:17], v[148:151], v[208:211], v[14:17]
	v_mfma_f32_16x16x32_bf16 v[10:13], v[156:159], v[208:211], v[10:13]
	v_mfma_f32_16x16x32_bf16 v[54:57], v[160:163], v[176:179], v[54:57]
	v_mfma_f32_16x16x32_bf16 v[50:53], v[168:171], v[176:179], v[50:53]
	v_mfma_f32_16x16x32_bf16 v[38:41], v[160:163], v[188:191], v[38:41]
	v_mfma_f32_16x16x32_bf16 v[34:37], v[168:171], v[188:191], v[34:37]
	v_mfma_f32_16x16x32_bf16 v[22:25], v[160:163], v[196:199], v[22:25]
	v_mfma_f32_16x16x32_bf16 v[18:21], v[168:171], v[196:199], v[18:21]
	v_mfma_f32_16x16x32_bf16 v[6:9], v[160:163], v[204:207], v[6:9]
	v_mfma_f32_16x16x32_bf16 v[2:5], v[168:171], v[204:207], v[2:5]
	v_mfma_f32_16x16x32_bf16 v[54:57], v[164:167], v[180:183], v[54:57]
	v_mfma_f32_16x16x32_bf16 v[50:53], v[172:175], v[180:183], v[50:53]
	v_mfma_f32_16x16x32_bf16 v[38:41], v[164:167], v[192:195], v[38:41]
	v_mfma_f32_16x16x32_bf16 v[34:37], v[172:175], v[192:195], v[34:37]
	v_mfma_f32_16x16x32_bf16 v[22:25], v[164:167], v[200:203], v[22:25]
	v_mfma_f32_16x16x32_bf16 v[18:21], v[172:175], v[200:203], v[18:21]
	v_mfma_f32_16x16x32_bf16 v[6:9], v[164:167], v[208:211], v[6:9]
	v_mfma_f32_16x16x32_bf16 v[2:5], v[172:175], v[208:211], v[2:5]
	s_barrier
	s_setprio 0
	s_add_u32 s63, s63, 0x100
	s_addc_u32 s65, s65, 0
	s_cmp_ge_i32 s66, s47
	s_mov_b64 s[30:31], s[34:35]
	s_mov_b32 s36, s66
	s_cbranch_scc0 .LBB0_1733

; #define PG8_STAGE(bufoff, gbase, voff) do { _Pragma("unroll") for (int _i = 0; _i < 2; ++_i) \
;         __builtin_amdgcn_global_load_lds((const unsigned*)((const char*)(gbase) + (voff)[_i]), (PG8_LAS unsigned*)(lds + (bufoff) + ldsw + _i * 8192), 16, 0, 0); } while (0)
; #define PG8_LDA(dst, b, h) do { _Pragma("unroll") for (int m = 0; m < 4; ++m) _Pragma("unroll") for (int k = 0; k < 2; ++k) dst[m][k] = *(const PG8_LAS bf16x8*)(lds + PG8_SA(b, h) + aoff + m * 2048 + k * 1024); } while (0)
; #define PG8_LDB(dst, b, h) do { _Pragma("unroll") for (int n = 0; n < 2; ++n) _Pragma("unroll") for (int k = 0; k < 2; ++k) dst[n][k] = *(const PG8_LAS bf16x8*)(lds + PG8_SB(b, h) + boff + n * 2048 + k * 1024); } while (0)
; #define PG8_MMA(ai, bj, At, Bt) do { __builtin_amdgcn_s_setprio(1); _Pragma("unroll") for (int m = 0; m < 4; ++m) _Pragma("unroll") for (int n = 0; n < 2; ++n) _Pragma("unroll") for (int k = 0; k < 2; ++k) \
;         acc[ai][bj][m][n] = __builtin_amdgcn_mfma_f32_16x16x32_bf16(Bt[n][k], At[m][k], acc[ai][bj][m][n], 0, 0, 0); __builtin_amdgcn_s_setprio(0); } while (0)
; #define PG8_WAIT_V(n) asm volatile("s_waitcnt vmcnt(" #n ")" ::: "memory")
; #define PG8_WAIT_L(n) asm volatile("s_waitcnt lgkmcnt(" #n ")" ::: "memory")
; #define PG8_BAR __builtin_amdgcn_s_barrier()
; #define PG8_SCHED __builtin_amdgcn_sched_barrier(0)
; template <class Epi, class Sched, bool ALIGN_EPI = false, bool SP2 = false>
; __device__ __forceinline__ void gemm_phase(PG8_LAS unsigned char* lds, const Gemm g, const Sched& S, const Epi& E) {
;     ...
;         for (int t = 0; t < nt; t += 2) {
;             const bool last = (t == nt - 2);
;             const char* a1 = cA + (size_t)(t + 1) * kstep;
;             const char* a2 = last ? nA : cA + (size_t)(t + 2) * kstep; const char* b2 = last ? nB : cB + (size_t)(t + 2) * kstep;
;             const char* a3 = a2 + kstep; const char* b3 = b2 + kstep;
;             if (last && has_next) S.a_ready(nxt);
;             if constexpr (SP2) {
;             PG8_LDB(B0, 0, 0); PG8_LDB(B1, 0, 1); PG8_SCHED; PG8_LDA(At, 0, 0); PG8_STAGE(PG8_SA(1, 1), a1 + hstep, voffA);
;             PG8_WAIT_V(8); PG8_WAIT_L(0); PG8_BAR; PG8_MMA(0, 0, At, B0); PG8_MMA(0, 1, At, B1); PG8_BAR; PG8_SCHED;
;             PG8_LDA(At, 0, 1); PG8_STAGE(PG8_SB(0, 0), b2, voffB); PG8_STAGE(PG8_SB(0, 1), b2 + hstep, voffB); PG8_STAGE(PG8_SA(0, 0), a2, voffA);
.LBB0_1778:
	v_add_u32_e32 v162, s51, v148
	v_add_u32_e32 v178, s52, v148
	s_add_u32 s30, s22, s28
	ds_read_b128 v[150:153], v162
	ds_read_b128 v[154:157], v162 offset:1024
	ds_read_b128 v[158:161], v162 offset:2048
	ds_read_b128 v[162:165], v162 offset:3072
	ds_read_b128 v[166:169], v178
	ds_read_b128 v[170:173], v178 offset:1024
	ds_read_b128 v[174:177], v178 offset:2048
	ds_read_b128 v[178:181], v178 offset:3072
	s_addc_u32 s31, s23, s29
	s_add_u32 s30, s30, 0x100
	s_addc_u32 s31, s31, 0
	s_add_u32 s60, s57, s28
	s_addc_u32 s61, s58, s29
	s_cmpk_eq_i32 s28, 0x1500
	s_cselect_b32 s35, s27, s31
	s_cselect_b32 s34, s26, s30
	s_cselect_b32 s31, s9, s61
	s_cselect_b32 s30, s8, s60
	v_lshl_add_u64 v[216:217], v[142:143], 0, s[28:29]
	s_add_i32 m0, s40, 0xc000
	ds_read_b128 v[182:185], v149
	ds_read_b128 v[188:191], v149 offset:1024
	ds_read_b128 v[192:195], v149 offset:2048
	ds_read_b128 v[196:199], v149 offset:3072
	ds_read_b128 v[200:203], v149 offset:4096
	ds_read_b128 v[204:207], v149 offset:5120
	ds_read_b128 v[208:211], v149 offset:6144
	ds_read_b128 v[212:215], v149 offset:7168
	global_load_lds_dwordx4 v[216:217], off
	v_lshl_add_u64 v[216:217], v[144:145], 0, s[28:29]
	s_add_i32 m0, s40, 0xe000
	s_nop 0
	global_load_lds_dwordx4 v[216:217], off
	s_waitcnt vmcnt(8)
	s_waitcnt lgkmcnt(0)
	s_barrier
	s_setprio 1
	s_waitcnt lgkmcnt(0)
	v_mfma_f32_16x16x32_bf16 v[114:117], v[150:153], v[182:185], v[114:117]
	v_mfma_f32_16x16x32_bf16 v[82:85], v[158:161], v[182:185], v[82:85]
	v_mfma_f32_16x16x32_bf16 v[122:125], v[150:153], v[192:195], v[122:125]
	v_mfma_f32_16x16x32_bf16 v[86:89], v[158:161], v[192:195], v[86:89]
	v_mfma_f32_16x16x32_bf16 v[126:129], v[150:153], v[200:203], v[126:129]
	v_mfma_f32_16x16x32_bf16 v[90:93], v[158:161], v[200:203], v[90:93]
	v_mfma_f32_16x16x32_bf16 v[118:121], v[150:153], v[208:211], v[118:121]
	v_mfma_f32_16x16x32_bf16 v[102:105], v[158:161], v[208:211], v[102:105]
	v_mfma_f32_16x16x32_bf16 v[114:117], v[154:157], v[188:191], v[114:117]
	v_mfma_f32_16x16x32_bf16 v[82:85], v[162:165], v[188:191], v[82:85]
	v_mfma_f32_16x16x32_bf16 v[122:125], v[154:157], v[196:199], v[122:125]
	v_mfma_f32_16x16x32_bf16 v[86:89], v[162:165], v[196:199], v[86:89]
	v_mfma_f32_16x16x32_bf16 v[126:129], v[154:157], v[204:207], v[126:129]
	v_mfma_f32_16x16x32_bf16 v[90:93], v[162:165], v[204:207], v[90:93]
	v_mfma_f32_16x16x32_bf16 v[118:121], v[154:157], v[212:215], v[118:121]
	v_mfma_f32_16x16x32_bf16 v[102:105], v[162:165], v[212:215], v[102:105]
	v_mfma_f32_16x16x32_bf16 v[26:29], v[166:169], v[182:185], v[26:29]
	v_mfma_f32_16x16x32_bf16 v[2:5], v[174:177], v[182:185], v[2:5]
	v_mfma_f32_16x16x32_bf16 v[30:33], v[166:169], v[192:195], v[30:33]
	v_mfma_f32_16x16x32_bf16 v[6:9], v[174:177], v[192:195], v[6:9]
	v_mfma_f32_16x16x32_bf16 v[42:45], v[166:169], v[200:203], v[42:45]
	v_mfma_f32_16x16x32_bf16 v[10:13], v[174:177], v[200:203], v[10:13]
	v_mfma_f32_16x16x32_bf16 v[58:61], v[166:169], v[208:211], v[58:61]
	v_mfma_f32_16x16x32_bf16 v[14:17], v[174:177], v[208:211], v[14:17]
	v_mfma_f32_16x16x32_bf16 v[26:29], v[170:173], v[188:191], v[26:29]
	v_mfma_f32_16x16x32_bf16 v[2:5], v[178:181], v[188:191], v[2:5]
	v_mfma_f32_16x16x32_bf16 v[30:33], v[170:173], v[196:199], v[30:33]
	v_mfma_f32_16x16x32_bf16 v[6:9], v[178:181], v[196:199], v[6:9]
	v_mfma_f32_16x16x32_bf16 v[42:45], v[170:173], v[204:207], v[42:45]
	v_mfma_f32_16x16x32_bf16 v[10:13], v[178:181], v[204:207], v[10:13]
	v_mfma_f32_16x16x32_bf16 v[58:61], v[170:173], v[212:215], v[58:61]
	v_mfma_f32_16x16x32_bf16 v[14:17], v[178:181], v[212:215], v[14:17]
	s_barrier
	s_setprio 0
	s_add_i32 s60, s51, s39
	v_lshl_add_u64 v[216:217], s[30:31], 0, v[130:131]
	s_mov_b32 m0, s60
	ds_read_b128 v[182:185], v149 offset:16384
	ds_read_b128 v[188:191], v149 offset:17408
	ds_read_b128 v[192:195], v149 offset:18432
	ds_read_b128 v[196:199], v149 offset:19456
	ds_read_b128 v[200:203], v149 offset:20480
	ds_read_b128 v[204:207], v149 offset:21504
	ds_read_b128 v[208:211], v149 offset:22528
	ds_read_b128 v[212:215], v149 offset:23552
	global_load_lds_dwordx4 v[216:217], off
	s_add_i32 m0, s60, 0x2000
	s_add_u32 s60, s30, 0xb0000
	v_lshl_add_u64 v[218:219], s[30:31], 0, v[132:133]
	s_addc_u32 s61, s31, 0
	s_add_i32 s62, s52, s39
	global_load_lds_dwordx4 v[218:219], off
	v_lshl_add_u64 v[220:221], s[60:61], 0, v[130:131]
	s_mov_b32 m0, s62
	v_lshl_add_u64 v[222:223], s[34:35], 0, v[132:133]
	global_load_lds_dwordx4 v[220:221], off
	v_lshl_add_u64 v[220:221], s[60:61], 0, v[132:133]
	s_add_i32 m0, s62, 0x2000
	s_nop 0
	global_load_lds_dwordx4 v[220:221], off
	v_lshl_add_u64 v[220:221], s[34:35], 0, v[130:131]
	s_mov_b32 m0, s40
	s_nop 0
	global_load_lds_dwordx4 v[220:221], off
	s_mov_b32 m0, s41
	s_nop 0
	global_load_lds_dwordx4 v[222:223], off
	s_waitcnt vmcnt(8)
	s_waitcnt lgkmcnt(0)
	s_barrier
; #define PG8_STAGE(bufoff, gbase, voff) do { _Pragma("unroll") for (int _i = 0; _i < 2; ++_i) \
;         __builtin_amdgcn_global_load_lds((const unsigned*)((const char*)(gbase) + (voff)[_i]), (PG8_LAS unsigned*)(lds + (bufoff) + ldsw + _i * 8192), 16, 0, 0); } while (0)
; #define PG8_LDA(dst, b, h) do { _Pragma("unroll") for (int m = 0; m < 4; ++m) _Pragma("unroll") for (int k = 0; k < 2; ++k) dst[m][k] = *(const PG8_LAS bf16x8*)(lds + PG8_SA(b, h) + aoff + m * 2048 + k * 1024); } while (0)
; #define PG8_LDB(dst, b, h) do { _Pragma("unroll") for (int n = 0; n < 2; ++n) _Pragma("unroll") for (int k = 0; k < 2; ++k) dst[n][k] = *(const PG8_LAS bf16x8*)(lds + PG8_SB(b, h) + boff + n * 2048 + k * 1024); } while (0)
; #define PG8_MMA(ai, bj, At, Bt) do { __builtin_amdgcn_s_setprio(1); _Pragma("unroll") for (int m = 0; m < 4; ++m) _Pragma("unroll") for (int n = 0; n < 2; ++n) _Pragma("unroll") for (int k = 0; k < 2; ++k) \
;         acc[ai][bj][m][n] = __builtin_amdgcn_mfma_f32_16x16x32_bf16(Bt[n][k], At[m][k], acc[ai][bj][m][n], 0, 0, 0); __builtin_amdgcn_s_setprio(0); } while (0)
; #define PG8_WAIT_V(n) asm volatile("s_waitcnt vmcnt(" #n ")" ::: "memory")
; #define PG8_WAIT_L(n) asm volatile("s_waitcnt lgkmcnt(" #n ")" ::: "memory")
; #define PG8_BAR __builtin_amdgcn_s_barrier()
; #define PG8_SCHED __builtin_amdgcn_sched_barrier(0)
; template <class Epi, class Sched, bool ALIGN_EPI = false, bool SP2 = false>
; __device__ __forceinline__ void gemm_phase(PG8_LAS unsigned char* lds, const Gemm g, const Sched& S, const Epi& E) {
;     ...
;             PG8_WAIT_V(8); PG8_WAIT_L(0); PG8_BAR; PG8_MMA(1, 0, At, B0); PG8_MMA(1, 1, At, B1); PG8_BAR; PG8_SCHED;
;             PG8_LDB(B0, 1, 0); PG8_LDB(B1, 1, 1); PG8_SCHED; PG8_LDA(At, 1, 0); PG8_STAGE(PG8_SA(0, 1), a2 + hstep, voffA);
;             PG8_WAIT_V(8); PG8_WAIT_L(0); PG8_BAR; PG8_MMA(0, 0, At, B0); PG8_MMA(0, 1, At, B1); PG8_BAR; PG8_SCHED;
	s_setprio 1
	s_waitcnt lgkmcnt(0)
	v_mfma_f32_16x16x32_bf16 v[110:113], v[150:153], v[182:185], v[110:113]
	v_mfma_f32_16x16x32_bf16 v[106:109], v[158:161], v[182:185], v[106:109]
	v_mfma_f32_16x16x32_bf16 v[98:101], v[150:153], v[192:195], v[98:101]
	v_mfma_f32_16x16x32_bf16 v[94:97], v[158:161], v[192:195], v[94:97]
	v_mfma_f32_16x16x32_bf16 v[74:77], v[150:153], v[200:203], v[74:77]
	v_mfma_f32_16x16x32_bf16 v[70:73], v[158:161], v[200:203], v[70:73]
	v_mfma_f32_16x16x32_bf16 v[54:57], v[150:153], v[208:211], v[54:57]
	v_mfma_f32_16x16x32_bf16 v[50:53], v[158:161], v[208:211], v[50:53]
	v_mfma_f32_16x16x32_bf16 v[110:113], v[154:157], v[188:191], v[110:113]
	v_mfma_f32_16x16x32_bf16 v[106:109], v[162:165], v[188:191], v[106:109]
	v_mfma_f32_16x16x32_bf16 v[98:101], v[154:157], v[196:199], v[98:101]
	v_mfma_f32_16x16x32_bf16 v[94:97], v[162:165], v[196:199], v[94:97]
	v_mfma_f32_16x16x32_bf16 v[74:77], v[154:157], v[204:207], v[74:77]
	v_mfma_f32_16x16x32_bf16 v[70:73], v[162:165], v[204:207], v[70:73]
	v_mfma_f32_16x16x32_bf16 v[54:57], v[154:157], v[212:215], v[54:57]
	v_mfma_f32_16x16x32_bf16 v[50:53], v[162:165], v[212:215], v[50:53]
	v_mfma_f32_16x16x32_bf16 v[66:69], v[166:169], v[182:185], v[66:69]
	v_mfma_f32_16x16x32_bf16 v[18:21], v[174:177], v[182:185], v[18:21]
	v_mfma_f32_16x16x32_bf16 v[78:81], v[166:169], v[192:195], v[78:81]
	v_mfma_f32_16x16x32_bf16 v[22:25], v[174:177], v[192:195], v[22:25]
	v_mfma_f32_16x16x32_bf16 v[62:65], v[166:169], v[200:203], v[62:65]
	v_mfma_f32_16x16x32_bf16 v[46:49], v[174:177], v[200:203], v[46:49]
	v_mfma_f32_16x16x32_bf16 v[38:41], v[166:169], v[208:211], v[38:41]
	v_mfma_f32_16x16x32_bf16 v[34:37], v[174:177], v[208:211], v[34:37]
	v_mfma_f32_16x16x32_bf16 v[66:69], v[170:173], v[188:191], v[66:69]
	v_mfma_f32_16x16x32_bf16 v[18:21], v[178:181], v[188:191], v[18:21]
	v_mfma_f32_16x16x32_bf16 v[78:81], v[170:173], v[196:199], v[78:81]
	v_mfma_f32_16x16x32_bf16 v[22:25], v[178:181], v[196:199], v[22:25]
	v_mfma_f32_16x16x32_bf16 v[62:65], v[170:173], v[204:207], v[62:65]
	v_mfma_f32_16x16x32_bf16 v[46:49], v[178:181], v[204:207], v[46:49]
	v_mfma_f32_16x16x32_bf16 v[38:41], v[170:173], v[212:215], v[38:41]
	v_mfma_f32_16x16x32_bf16 v[34:37], v[178:181], v[212:215], v[34:37]
	s_barrier
	s_setprio 0
	s_add_i32 s60, 0, 0x18000
	s_add_i32 s61, 0, 0x1c000
	v_add_u32_e32 v162, s60, v148
	v_add_u32_e32 v178, s61, v148
	ds_read_b128 v[150:153], v162
	ds_read_b128 v[154:157], v162 offset:1024
	ds_read_b128 v[158:161], v162 offset:2048
	ds_read_b128 v[162:165], v162 offset:3072
	ds_read_b128 v[166:169], v178
	ds_read_b128 v[170:173], v178 offset:1024
	ds_read_b128 v[174:177], v178 offset:2048
	ds_read_b128 v[178:181], v178 offset:3072
	s_add_u32 s34, s34, 0xb0000
	s_addc_u32 s35, s35, 0
	s_mov_b32 m0, s42
	v_lshl_add_u64 v[224:225], s[34:35], 0, v[130:131]
	ds_read_b128 v[182:185], v149 offset:32768
	ds_read_b128 v[188:191], v149 offset:33792
	ds_read_b128 v[192:195], v149 offset:34816
	ds_read_b128 v[196:199], v149 offset:35840
	ds_read_b128 v[200:203], v149 offset:36864
	ds_read_b128 v[204:207], v149 offset:37888
	ds_read_b128 v[208:211], v149 offset:38912
	ds_read_b128 v[212:215], v149 offset:39936
	global_load_lds_dwordx4 v[224:225], off
	v_lshl_add_u64 v[224:225], s[34:35], 0, v[132:133]
	s_mov_b32 m0, s46
	s_nop 0
	global_load_lds_dwordx4 v[224:225], off
	s_waitcnt vmcnt(8)
	s_waitcnt lgkmcnt(0)
	s_barrier
	s_setprio 1
	s_waitcnt lgkmcnt(0)
	v_mfma_f32_16x16x32_bf16 v[114:117], v[150:153], v[182:185], v[114:117]
	v_mfma_f32_16x16x32_bf16 v[82:85], v[158:161], v[182:185], v[82:85]
	v_mfma_f32_16x16x32_bf16 v[122:125], v[150:153], v[192:195], v[122:125]
	v_mfma_f32_16x16x32_bf16 v[86:89], v[158:161], v[192:195], v[86:89]
	v_mfma_f32_16x16x32_bf16 v[126:129], v[150:153], v[200:203], v[126:129]
	v_mfma_f32_16x16x32_bf16 v[90:93], v[158:161], v[200:203], v[90:93]
	v_mfma_f32_16x16x32_bf16 v[118:121], v[150:153], v[208:211], v[118:121]
	v_mfma_f32_16x16x32_bf16 v[102:105], v[158:161], v[208:211], v[102:105]
	v_mfma_f32_16x16x32_bf16 v[114:117], v[154:157], v[188:191], v[114:117]
	v_mfma_f32_16x16x32_bf16 v[82:85], v[162:165], v[188:191], v[82:85]
	v_mfma_f32_16x16x32_bf16 v[122:125], v[154:157], v[196:199], v[122:125]
	v_mfma_f32_16x16x32_bf16 v[86:89], v[162:165], v[196:199], v[86:89]
	v_mfma_f32_16x16x32_bf16 v[126:129], v[154:157], v[204:207], v[126:129]
	v_mfma_f32_16x16x32_bf16 v[90:93], v[162:165], v[204:207], v[90:93]
	v_mfma_f32_16x16x32_bf16 v[118:121], v[154:157], v[212:215], v[118:121]
	v_mfma_f32_16x16x32_bf16 v[102:105], v[162:165], v[212:215], v[102:105]
	v_mfma_f32_16x16x32_bf16 v[26:29], v[166:169], v[182:185], v[26:29]
	v_mfma_f32_16x16x32_bf16 v[2:5], v[174:177], v[182:185], v[2:5]
	v_mfma_f32_16x16x32_bf16 v[30:33], v[166:169], v[192:195], v[30:33]
	v_mfma_f32_16x16x32_bf16 v[6:9], v[174:177], v[192:195], v[6:9]
	v_mfma_f32_16x16x32_bf16 v[42:45], v[166:169], v[200:203], v[42:45]
	v_mfma_f32_16x16x32_bf16 v[10:13], v[174:177], v[200:203], v[10:13]
	v_mfma_f32_16x16x32_bf16 v[58:61], v[166:169], v[208:211], v[58:61]
	v_mfma_f32_16x16x32_bf16 v[14:17], v[174:177], v[208:211], v[14:17]
	v_mfma_f32_16x16x32_bf16 v[26:29], v[170:173], v[188:191], v[26:29]
	v_mfma_f32_16x16x32_bf16 v[2:5], v[178:181], v[188:191], v[2:5]
	v_mfma_f32_16x16x32_bf16 v[30:33], v[170:173], v[196:199], v[30:33]
	v_mfma_f32_16x16x32_bf16 v[6:9], v[178:181], v[196:199], v[6:9]
	v_mfma_f32_16x16x32_bf16 v[42:45], v[170:173], v[204:207], v[42:45]
	v_mfma_f32_16x16x32_bf16 v[10:13], v[178:181], v[204:207], v[10:13]
	v_mfma_f32_16x16x32_bf16 v[58:61], v[170:173], v[212:215], v[58:61]
	v_mfma_f32_16x16x32_bf16 v[14:17], v[178:181], v[212:215], v[14:17]
	s_barrier
; #define PG8_STAGE(bufoff, gbase, voff) do { _Pragma("unroll") for (int _i = 0; _i < 2; ++_i) \
;         __builtin_amdgcn_global_load_lds((const unsigned*)((const char*)(gbase) + (voff)[_i]), (PG8_LAS unsigned*)(lds + (bufoff) + ldsw + _i * 8192), 16, 0, 0); } while (0)
; #define PG8_LDA(dst, b, h) do { _Pragma("unroll") for (int m = 0; m < 4; ++m) _Pragma("unroll") for (int k = 0; k < 2; ++k) dst[m][k] = *(const PG8_LAS bf16x8*)(lds + PG8_SA(b, h) + aoff + m * 2048 + k * 1024); } while (0)
; #define PG8_MMA(ai, bj, At, Bt) do { __builtin_amdgcn_s_setprio(1); _Pragma("unroll") for (int m = 0; m < 4; ++m) _Pragma("unroll") for (int n = 0; n < 2; ++n) _Pragma("unroll") for (int k = 0; k < 2; ++k) \
;         acc[ai][bj][m][n] = __builtin_amdgcn_mfma_f32_16x16x32_bf16(Bt[n][k], At[m][k], acc[ai][bj][m][n], 0, 0, 0); __builtin_amdgcn_s_setprio(0); } while (0)
; #define PG8_WAIT_V(n) asm volatile("s_waitcnt vmcnt(" #n ")" ::: "memory")
; #define PG8_WAIT_L(n) asm volatile("s_waitcnt lgkmcnt(" #n ")" ::: "memory")
; #define PG8_BAR __builtin_amdgcn_s_barrier()
; #define PG8_SCHED __builtin_amdgcn_sched_barrier(0)
; template <class Epi, class Sched, bool ALIGN_EPI = false, bool SP2 = false>
; __device__ __forceinline__ void gemm_phase(PG8_LAS unsigned char* lds, const Gemm g, const Sched& S, const Epi& E) {
;     ...
;             PG8_LDA(At, 1, 1); PG8_STAGE(PG8_SB(1, 0), b3, voffB); PG8_STAGE(PG8_SB(1, 1), b3 + hstep, voffB); PG8_STAGE(PG8_SA(1, 0), a3, voffA);
;             PG8_WAIT_V(8); PG8_WAIT_L(0); PG8_BAR; PG8_MMA(1, 0, At, B0); PG8_MMA(1, 1, At, B1); PG8_BAR; PG8_SCHED;
;     ...
;         if (!has_next) break;
; #pragma unroll
;         for (int a = 0; a < 2; ++a)
; #pragma unroll
;             for (int b = 0; b < 2; ++b)
; #pragma unroll
;                 for (int m = 0; m < 4; ++m)
; #pragma unroll
;                     for (int n = 0; n < 2; ++n) acc[a][b][m][n] = (f32x4){0.f, 0.f, 0.f, 0.f};
	s_setprio 0
	s_add_i32 s34, s60, s39
	v_lshl_add_u64 v[216:217], v[216:217], 0, s[24:25]
	s_mov_b32 m0, s34
	ds_read_b128 v[182:185], v149 offset:49152
	ds_read_b128 v[188:191], v149 offset:50176
	ds_read_b128 v[192:195], v149 offset:51200
	ds_read_b128 v[196:199], v149 offset:52224
	ds_read_b128 v[200:203], v149 offset:53248
	ds_read_b128 v[204:207], v149 offset:54272
	ds_read_b128 v[208:211], v149 offset:55296
	ds_read_b128 v[212:215], v149 offset:56320
	global_load_lds_dwordx4 v[216:217], off
	s_add_i32 m0, s34, 0x2000
	s_add_u32 s30, s30, 0xb0080
	v_lshl_add_u64 v[216:217], v[218:219], 0, s[24:25]
	s_addc_u32 s31, s31, 0
	s_add_i32 s34, s61, s39
	global_load_lds_dwordx4 v[216:217], off
	v_lshl_add_u64 v[216:217], s[30:31], 0, v[130:131]
	s_mov_b32 m0, s34
	s_nop 0
	global_load_lds_dwordx4 v[216:217], off
	v_lshl_add_u64 v[216:217], s[30:31], 0, v[132:133]
	s_add_i32 m0, s34, 0x2000
	s_nop 0
	global_load_lds_dwordx4 v[216:217], off
	v_lshl_add_u64 v[216:217], v[220:221], 0, s[24:25]
	s_mov_b32 m0, s49
	s_nop 0
	global_load_lds_dwordx4 v[216:217], off
	v_lshl_add_u64 v[216:217], v[222:223], 0, s[24:25]
	s_mov_b32 m0, s50
	s_nop 0
	global_load_lds_dwordx4 v[216:217], off
	s_waitcnt vmcnt(8)
	s_waitcnt lgkmcnt(0)
	s_barrier
	s_setprio 1
	s_waitcnt lgkmcnt(0)
	v_mfma_f32_16x16x32_bf16 v[110:113], v[150:153], v[182:185], v[110:113]
	v_mfma_f32_16x16x32_bf16 v[106:109], v[158:161], v[182:185], v[106:109]
	v_mfma_f32_16x16x32_bf16 v[98:101], v[150:153], v[192:195], v[98:101]
	v_mfma_f32_16x16x32_bf16 v[94:97], v[158:161], v[192:195], v[94:97]
	v_mfma_f32_16x16x32_bf16 v[74:77], v[150:153], v[200:203], v[74:77]
	v_mfma_f32_16x16x32_bf16 v[70:73], v[158:161], v[200:203], v[70:73]
	v_mfma_f32_16x16x32_bf16 v[54:57], v[150:153], v[208:211], v[54:57]
	v_mfma_f32_16x16x32_bf16 v[50:53], v[158:161], v[208:211], v[50:53]
	v_mfma_f32_16x16x32_bf16 v[110:113], v[154:157], v[188:191], v[110:113]
	v_mfma_f32_16x16x32_bf16 v[106:109], v[162:165], v[188:191], v[106:109]
	v_mfma_f32_16x16x32_bf16 v[98:101], v[154:157], v[196:199], v[98:101]
	v_mfma_f32_16x16x32_bf16 v[94:97], v[162:165], v[196:199], v[94:97]
	v_mfma_f32_16x16x32_bf16 v[74:77], v[154:157], v[204:207], v[74:77]
	v_mfma_f32_16x16x32_bf16 v[70:73], v[162:165], v[204:207], v[70:73]
	v_mfma_f32_16x16x32_bf16 v[54:57], v[154:157], v[212:215], v[54:57]
	v_mfma_f32_16x16x32_bf16 v[50:53], v[162:165], v[212:215], v[50:53]
	v_mfma_f32_16x16x32_bf16 v[66:69], v[166:169], v[182:185], v[66:69]
	v_mfma_f32_16x16x32_bf16 v[18:21], v[174:177], v[182:185], v[18:21]
	v_mfma_f32_16x16x32_bf16 v[78:81], v[166:169], v[192:195], v[78:81]
	v_mfma_f32_16x16x32_bf16 v[22:25], v[174:177], v[192:195], v[22:25]
	v_mfma_f32_16x16x32_bf16 v[62:65], v[166:169], v[200:203], v[62:65]
	v_mfma_f32_16x16x32_bf16 v[46:49], v[174:177], v[200:203], v[46:49]
	v_mfma_f32_16x16x32_bf16 v[38:41], v[166:169], v[208:211], v[38:41]
	v_mfma_f32_16x16x32_bf16 v[34:37], v[174:177], v[208:211], v[34:37]
	v_mfma_f32_16x16x32_bf16 v[66:69], v[170:173], v[188:191], v[66:69]
	v_mfma_f32_16x16x32_bf16 v[18:21], v[178:181], v[188:191], v[18:21]
	v_mfma_f32_16x16x32_bf16 v[78:81], v[170:173], v[196:199], v[78:81]
	v_mfma_f32_16x16x32_bf16 v[22:25], v[178:181], v[196:199], v[22:25]
	v_mfma_f32_16x16x32_bf16 v[62:65], v[170:173], v[204:207], v[62:65]
	v_mfma_f32_16x16x32_bf16 v[46:49], v[178:181], v[204:207], v[46:49]
	v_mfma_f32_16x16x32_bf16 v[38:41], v[170:173], v[212:215], v[38:41]
	v_mfma_f32_16x16x32_bf16 v[34:37], v[178:181], v[212:215], v[34:37]
	s_barrier
	s_setprio 0
	s_add_i32 s59, s59, 2
	s_add_u32 s28, s28, 0x100
	s_addc_u32 s29, s29, 0
	s_cmp_gt_u32 s59, 41
	s_cbranch_scc0 .LBB0_1778
	s_add_u32 s28, s57, 0xffffff00
	s_addc_u32 s29, s58, -1
	s_and_b64 vcc, exec, s[6:7]
	s_cbranch_vccnz .LBB0_1781
	v_mov_b32_e32 v34, 0
	s_mov_b32 s20, s54
	s_mov_b32 s37, s55
	s_mov_b64 s[22:23], s[26:27]
	s_mov_b32 s48, s56
	v_mov_b32_e32 v35, v34
	v_mov_b32_e32 v36, v34
	v_mov_b32_e32 v37, v34
	v_mov_b32_e32 v38, v34
	v_mov_b32_e32 v39, v34
	v_mov_b32_e32 v40, v34
	v_mov_b32_e32 v41, v34
	v_mov_b32_e32 v46, v34
	v_mov_b32_e32 v47, v34
	v_mov_b32_e32 v48, v34
	v_mov_b32_e32 v49, v34
	v_mov_b32_e32 v62, v34
	v_mov_b32_e32 v63, v34
	v_mov_b32_e32 v64, v34
	v_mov_b32_e32 v65, v34
	v_mov_b32_e32 v22, v34
	v_mov_b32_e32 v23, v34
	v_mov_b32_e32 v24, v34
	v_mov_b32_e32 v25, v34
	v_mov_b32_e32 v78, v34
	v_mov_b32_e32 v79, v34
	v_mov_b32_e32 v80, v34
	v_mov_b32_e32 v81, v34
	v_mov_b32_e32 v18, v34
	v_mov_b32_e32 v19, v34
	v_mov_b32_e32 v20, v34
	v_mov_b32_e32 v21, v34
	v_mov_b32_e32 v66, v34
	v_mov_b32_e32 v67, v34
	v_mov_b32_e32 v68, v34
	v_mov_b32_e32 v69, v34
	v_mov_b32_e32 v50, v34
	v_mov_b32_e32 v51, v34
	v_mov_b32_e32 v52, v34
	v_mov_b32_e32 v53, v34
	v_mov_b32_e32 v54, v34
	v_mov_b32_e32 v55, v34
	v_mov_b32_e32 v56, v34
	v_mov_b32_e32 v57, v34
	v_mov_b32_e32 v70, v34
	v_mov_b32_e32 v71, v34
	v_mov_b32_e32 v72, v34
	v_mov_b32_e32 v73, v34
	v_mov_b32_e32 v74, v34
	v_mov_b32_e32 v75, v34
	v_mov_b32_e32 v76, v34
	v_mov_b32_e32 v77, v34
	v_mov_b32_e32 v94, v34
	v_mov_b32_e32 v95, v34
	v_mov_b32_e32 v96, v34
	v_mov_b32_e32 v97, v34
	v_mov_b32_e32 v98, v34
	v_mov_b32_e32 v99, v34
	v_mov_b32_e32 v100, v34
	v_mov_b32_e32 v101, v34
	v_mov_b32_e32 v106, v34
	v_mov_b32_e32 v107, v34
	v_mov_b32_e32 v108, v34
	v_mov_b32_e32 v109, v34
	v_mov_b32_e32 v110, v34
	v_mov_b32_e32 v111, v34
	v_mov_b32_e32 v112, v34
	v_mov_b32_e32 v113, v34
	v_mov_b32_e32 v14, v34
	v_mov_b32_e32 v15, v34
	v_mov_b32_e32 v16, v34
	v_mov_b32_e32 v17, v34
	v_mov_b32_e32 v58, v34
	v_mov_b32_e32 v59, v34
	v_mov_b32_e32 v60, v34
	v_mov_b32_e32 v61, v34
	v_mov_b32_e32 v10, v34
	v_mov_b32_e32 v11, v34
	v_mov_b32_e32 v12, v34
	v_mov_b32_e32 v13, v34
	v_mov_b32_e32 v42, v34
	v_mov_b32_e32 v43, v34
	v_mov_b32_e32 v44, v34
	v_mov_b32_e32 v45, v34
	v_mov_b32_e32 v6, v34
	v_mov_b32_e32 v7, v34
	v_mov_b32_e32 v8, v34
	v_mov_b32_e32 v9, v34
	v_mov_b32_e32 v30, v34
	v_mov_b32_e32 v31, v34
	v_mov_b32_e32 v32, v34
	v_mov_b32_e32 v33, v34
	v_mov_b32_e32 v2, v34
	v_mov_b32_e32 v3, v34
	v_mov_b32_e32 v4, v34
	v_mov_b32_e32 v5, v34
	v_mov_b32_e32 v26, v34
	v_mov_b32_e32 v27, v34
	v_mov_b32_e32 v28, v34
	v_mov_b32_e32 v29, v34
	v_mov_b32_e32 v102, v34
	v_mov_b32_e32 v103, v34
	v_mov_b32_e32 v104, v34
	v_mov_b32_e32 v105, v34
	v_mov_b32_e32 v118, v34
	v_mov_b32_e32 v119, v34
	v_mov_b32_e32 v120, v34
	v_mov_b32_e32 v121, v34
	v_mov_b32_e32 v90, v34
	v_mov_b32_e32 v91, v34
	v_mov_b32_e32 v92, v34
	v_mov_b32_e32 v93, v34
	v_mov_b32_e32 v126, v34
	v_mov_b32_e32 v127, v34
	v_mov_b32_e32 v128, v34
	v_mov_b32_e32 v129, v34
	v_mov_b32_e32 v86, v34
	v_mov_b32_e32 v87, v34
	v_mov_b32_e32 v88, v34
	v_mov_b32_e32 v89, v34
	v_mov_b32_e32 v122, v34
	v_mov_b32_e32 v123, v34
	v_mov_b32_e32 v124, v34
	v_mov_b32_e32 v125, v34
	v_mov_b32_e32 v82, v34
	v_mov_b32_e32 v83, v34
	v_mov_b32_e32 v84, v34
	v_mov_b32_e32 v85, v34
	v_mov_b32_e32 v114, v34
	v_mov_b32_e32 v115, v34
	v_mov_b32_e32 v116, v34
	v_mov_b32_e32 v117, v34
	s_andn2_b64 vcc, exec, s[4:5]
	s_cbranch_vccnz .LBB0_1782
	s_branch .LBB0_1783

; #define PG8_STAGE(bufoff, gbase, voff) do { _Pragma("unroll") for (int _i = 0; _i < 2; ++_i) \
;         __builtin_amdgcn_global_load_lds((const unsigned*)((const char*)(gbase) + (voff)[_i]), (PG8_LAS unsigned*)(lds + (bufoff) + ldsw + _i * 8192), 16, 0, 0); } while (0)
; #define PG8_LDA(dst, b, h) do { _Pragma("unroll") for (int m = 0; m < 4; ++m) _Pragma("unroll") for (int k = 0; k < 2; ++k) dst[m][k] = *(const PG8_LAS bf16x8*)(lds + PG8_SA(b, h) + aoff + m * 2048 + k * 1024); } while (0)
; #define PG8_LDB(dst, b, h) do { _Pragma("unroll") for (int n = 0; n < 2; ++n) _Pragma("unroll") for (int k = 0; k < 2; ++k) dst[n][k] = *(const PG8_LAS bf16x8*)(lds + PG8_SB(b, h) + boff + n * 2048 + k * 1024); } while (0)
; #define PG8_MMA(ai, bj, At, Bt) do { __builtin_amdgcn_s_setprio(1); _Pragma("unroll") for (int m = 0; m < 4; ++m) _Pragma("unroll") for (int n = 0; n < 2; ++n) _Pragma("unroll") for (int k = 0; k < 2; ++k) \
;         acc[ai][bj][m][n] = __builtin_amdgcn_mfma_f32_16x16x32_bf16(Bt[n][k], At[m][k], acc[ai][bj][m][n], 0, 0, 0); __builtin_amdgcn_s_setprio(0); } while (0)
; #define PG8_WAIT_V(n) asm volatile("s_waitcnt vmcnt(" #n ")" ::: "memory")
; #define PG8_WAIT_L(n) asm volatile("s_waitcnt lgkmcnt(" #n ")" ::: "memory")
; #define PG8_BAR __builtin_amdgcn_s_barrier()
; #define PG8_SCHED __builtin_amdgcn_sched_barrier(0)
; template <class Epi, class Sched, bool ALIGN_EPI = false, bool SP2 = false>
; __device__ __forceinline__ void gemm_phase(PG8_LAS unsigned char* lds, const Gemm g, const Sched& S, const Epi& E) {
;     ...
;         for (int t = 0; t < nt; t += 2) {
;             const bool last = (t == nt - 2);
;             const char* a1 = cA + (size_t)(t + 1) * kstep;
;             const char* a2 = last ? nA : cA + (size_t)(t + 2) * kstep; const char* b2 = last ? nB : cB + (size_t)(t + 2) * kstep;
;             const char* a3 = a2 + kstep; const char* b3 = b2 + kstep;
;             if (last && has_next) S.a_ready(nxt);
;             if constexpr (SP2) {
;             PG8_LDB(B0, 0, 0); PG8_LDB(B1, 0, 1); PG8_SCHED; PG8_LDA(At, 0, 0); PG8_STAGE(PG8_SA(1, 1), a1 + hstep, voffA);
;             PG8_WAIT_V(8); PG8_WAIT_L(0); PG8_BAR; PG8_MMA(0, 0, At, B0); PG8_MMA(0, 1, At, B1); PG8_BAR; PG8_SCHED;
;             PG8_LDA(At, 0, 1); PG8_STAGE(PG8_SB(0, 0), b2, voffB); PG8_STAGE(PG8_SB(0, 1), b2 + hstep, voffB); PG8_STAGE(PG8_SA(0, 0), a2, voffA);
.LBB0_1940:
	v_add_u32_e32 v149, s54, v147
	ds_read_b128 v[150:153], v149
	ds_read_b128 v[154:157], v149 offset:1024
	ds_read_b128 v[158:161], v149 offset:2048
	ds_read_b128 v[162:165], v149 offset:3072
	v_add_u32_e32 v149, s55, v147
	s_add_u32 s28, s20, s26
	ds_read_b128 v[166:169], v149
	ds_read_b128 v[170:173], v149 offset:1024
	ds_read_b128 v[174:177], v149 offset:2048
	ds_read_b128 v[178:181], v149 offset:3072
	s_addc_u32 s29, s21, s27
	s_add_u32 s28, s28, 0x100
	s_addc_u32 s29, s29, 0
	s_add_u32 s60, s0, s26
	s_addc_u32 s61, s1, s27
	s_cmpk_eq_i32 s26, 0x1500
	s_cselect_b32 s31, s25, s29
	s_cselect_b32 s30, s24, s28
	s_cselect_b32 s29, s9, s61
	s_cselect_b32 s28, s8, s60
	v_lshl_add_u64 v[216:217], v[142:143], 0, s[26:27]
	s_add_i32 m0, s42, 0xc000
	ds_read_b128 v[182:185], v148
	ds_read_b128 v[188:191], v148 offset:1024
	ds_read_b128 v[192:195], v148 offset:2048
	ds_read_b128 v[196:199], v148 offset:3072
	ds_read_b128 v[200:203], v148 offset:4096
	ds_read_b128 v[204:207], v148 offset:5120
	ds_read_b128 v[208:211], v148 offset:6144
	ds_read_b128 v[212:215], v148 offset:7168
	global_load_lds_dwordx4 v[216:217], off
	v_lshl_add_u64 v[216:217], v[144:145], 0, s[26:27]
	s_add_i32 m0, s42, 0xe000
	s_nop 0
	global_load_lds_dwordx4 v[216:217], off
	s_waitcnt vmcnt(8)
	s_waitcnt lgkmcnt(0)
	s_barrier
	s_setprio 1
	s_waitcnt lgkmcnt(0)
	v_mfma_f32_16x16x32_bf16 v[114:117], v[150:153], v[182:185], v[114:117]
	v_mfma_f32_16x16x32_bf16 v[82:85], v[158:161], v[182:185], v[82:85]
	v_mfma_f32_16x16x32_bf16 v[122:125], v[150:153], v[192:195], v[122:125]
	v_mfma_f32_16x16x32_bf16 v[86:89], v[158:161], v[192:195], v[86:89]
	v_mfma_f32_16x16x32_bf16 v[126:129], v[150:153], v[200:203], v[126:129]
	v_mfma_f32_16x16x32_bf16 v[90:93], v[158:161], v[200:203], v[90:93]
	v_mfma_f32_16x16x32_bf16 v[118:121], v[150:153], v[208:211], v[118:121]
	v_mfma_f32_16x16x32_bf16 v[102:105], v[158:161], v[208:211], v[102:105]
	v_mfma_f32_16x16x32_bf16 v[114:117], v[154:157], v[188:191], v[114:117]
	v_mfma_f32_16x16x32_bf16 v[82:85], v[162:165], v[188:191], v[82:85]
	v_mfma_f32_16x16x32_bf16 v[122:125], v[154:157], v[196:199], v[122:125]
	v_mfma_f32_16x16x32_bf16 v[86:89], v[162:165], v[196:199], v[86:89]
	v_mfma_f32_16x16x32_bf16 v[126:129], v[154:157], v[204:207], v[126:129]
	v_mfma_f32_16x16x32_bf16 v[90:93], v[162:165], v[204:207], v[90:93]
	v_mfma_f32_16x16x32_bf16 v[118:121], v[154:157], v[212:215], v[118:121]
	v_mfma_f32_16x16x32_bf16 v[102:105], v[162:165], v[212:215], v[102:105]
	v_mfma_f32_16x16x32_bf16 v[26:29], v[166:169], v[182:185], v[26:29]
	v_mfma_f32_16x16x32_bf16 v[2:5], v[174:177], v[182:185], v[2:5]
	v_mfma_f32_16x16x32_bf16 v[30:33], v[166:169], v[192:195], v[30:33]
	v_mfma_f32_16x16x32_bf16 v[6:9], v[174:177], v[192:195], v[6:9]
	v_mfma_f32_16x16x32_bf16 v[42:45], v[166:169], v[200:203], v[42:45]
	v_mfma_f32_16x16x32_bf16 v[10:13], v[174:177], v[200:203], v[10:13]
	v_mfma_f32_16x16x32_bf16 v[58:61], v[166:169], v[208:211], v[58:61]
	v_mfma_f32_16x16x32_bf16 v[14:17], v[174:177], v[208:211], v[14:17]
	v_mfma_f32_16x16x32_bf16 v[26:29], v[170:173], v[188:191], v[26:29]
	v_mfma_f32_16x16x32_bf16 v[2:5], v[178:181], v[188:191], v[2:5]
	v_mfma_f32_16x16x32_bf16 v[30:33], v[170:173], v[196:199], v[30:33]
	v_mfma_f32_16x16x32_bf16 v[6:9], v[178:181], v[196:199], v[6:9]
	v_mfma_f32_16x16x32_bf16 v[42:45], v[170:173], v[204:207], v[42:45]
	v_mfma_f32_16x16x32_bf16 v[10:13], v[178:181], v[204:207], v[10:13]
	v_mfma_f32_16x16x32_bf16 v[58:61], v[170:173], v[212:215], v[58:61]
	v_mfma_f32_16x16x32_bf16 v[14:17], v[178:181], v[212:215], v[14:17]
	s_barrier
	s_setprio 0
	s_add_i32 s60, s54, s41
	v_lshl_add_u64 v[216:217], s[28:29], 0, v[130:131]
	s_mov_b32 m0, s60
	ds_read_b128 v[182:185], v148 offset:16384
	ds_read_b128 v[188:191], v148 offset:17408
	ds_read_b128 v[192:195], v148 offset:18432
	ds_read_b128 v[196:199], v148 offset:19456
	ds_read_b128 v[200:203], v148 offset:20480
	ds_read_b128 v[204:207], v148 offset:21504
	ds_read_b128 v[208:211], v148 offset:22528
	ds_read_b128 v[212:215], v148 offset:23552
	global_load_lds_dwordx4 v[216:217], off
	s_add_i32 m0, s60, 0x2000
	s_add_u32 s60, s28, 0xb0000
	v_lshl_add_u64 v[218:219], s[28:29], 0, v[132:133]
	s_addc_u32 s61, s29, 0
	s_add_i32 s62, s55, s41
	global_load_lds_dwordx4 v[218:219], off
	v_lshl_add_u64 v[220:221], s[60:61], 0, v[130:131]
	s_mov_b32 m0, s62
	v_lshl_add_u64 v[222:223], s[30:31], 0, v[132:133]
	global_load_lds_dwordx4 v[220:221], off
	v_lshl_add_u64 v[220:221], s[60:61], 0, v[132:133]
	s_add_i32 m0, s62, 0x2000
	s_nop 0
	global_load_lds_dwordx4 v[220:221], off
	v_lshl_add_u64 v[220:221], s[30:31], 0, v[130:131]
	s_mov_b32 m0, s42
	s_nop 0
	global_load_lds_dwordx4 v[220:221], off
	s_mov_b32 m0, s46
	s_nop 0
	global_load_lds_dwordx4 v[222:223], off
	s_waitcnt vmcnt(8)
	s_waitcnt lgkmcnt(0)
	s_barrier
; #define PG8_STAGE(bufoff, gbase, voff) do { _Pragma("unroll") for (int _i = 0; _i < 2; ++_i) \
;         __builtin_amdgcn_global_load_lds((const unsigned*)((const char*)(gbase) + (voff)[_i]), (PG8_LAS unsigned*)(lds + (bufoff) + ldsw + _i * 8192), 16, 0, 0); } while (0)
; #define PG8_LDA(dst, b, h) do { _Pragma("unroll") for (int m = 0; m < 4; ++m) _Pragma("unroll") for (int k = 0; k < 2; ++k) dst[m][k] = *(const PG8_LAS bf16x8*)(lds + PG8_SA(b, h) + aoff + m * 2048 + k * 1024); } while (0)
; #define PG8_LDB(dst, b, h) do { _Pragma("unroll") for (int n = 0; n < 2; ++n) _Pragma("unroll") for (int k = 0; k < 2; ++k) dst[n][k] = *(const PG8_LAS bf16x8*)(lds + PG8_SB(b, h) + boff + n * 2048 + k * 1024); } while (0)
; #define PG8_MMA(ai, bj, At, Bt) do { __builtin_amdgcn_s_setprio(1); _Pragma("unroll") for (int m = 0; m < 4; ++m) _Pragma("unroll") for (int n = 0; n < 2; ++n) _Pragma("unroll") for (int k = 0; k < 2; ++k) \
;         acc[ai][bj][m][n] = __builtin_amdgcn_mfma_f32_16x16x32_bf16(Bt[n][k], At[m][k], acc[ai][bj][m][n], 0, 0, 0); __builtin_amdgcn_s_setprio(0); } while (0)
; #define PG8_WAIT_V(n) asm volatile("s_waitcnt vmcnt(" #n ")" ::: "memory")
; #define PG8_WAIT_L(n) asm volatile("s_waitcnt lgkmcnt(" #n ")" ::: "memory")
; #define PG8_BAR __builtin_amdgcn_s_barrier()
; #define PG8_SCHED __builtin_amdgcn_sched_barrier(0)
; template <class Epi, class Sched, bool ALIGN_EPI = false, bool SP2 = false>
; __device__ __forceinline__ void gemm_phase(PG8_LAS unsigned char* lds, const Gemm g, const Sched& S, const Epi& E) {
;     ...
;             PG8_WAIT_V(8); PG8_WAIT_L(0); PG8_BAR; PG8_MMA(1, 0, At, B0); PG8_MMA(1, 1, At, B1); PG8_BAR; PG8_SCHED;
;             PG8_LDB(B0, 1, 0); PG8_LDB(B1, 1, 1); PG8_SCHED; PG8_LDA(At, 1, 0); PG8_STAGE(PG8_SA(0, 1), a2 + hstep, voffA);
;             PG8_WAIT_V(8); PG8_WAIT_L(0); PG8_BAR; PG8_MMA(0, 0, At, B0); PG8_MMA(0, 1, At, B1); PG8_BAR; PG8_SCHED;
	s_setprio 1
	s_waitcnt lgkmcnt(0)
	v_mfma_f32_16x16x32_bf16 v[110:113], v[150:153], v[182:185], v[110:113]
	v_mfma_f32_16x16x32_bf16 v[106:109], v[158:161], v[182:185], v[106:109]
	v_mfma_f32_16x16x32_bf16 v[98:101], v[150:153], v[192:195], v[98:101]
	v_mfma_f32_16x16x32_bf16 v[94:97], v[158:161], v[192:195], v[94:97]
	v_mfma_f32_16x16x32_bf16 v[74:77], v[150:153], v[200:203], v[74:77]
	v_mfma_f32_16x16x32_bf16 v[70:73], v[158:161], v[200:203], v[70:73]
	v_mfma_f32_16x16x32_bf16 v[54:57], v[150:153], v[208:211], v[54:57]
	v_mfma_f32_16x16x32_bf16 v[50:53], v[158:161], v[208:211], v[50:53]
	v_mfma_f32_16x16x32_bf16 v[110:113], v[154:157], v[188:191], v[110:113]
	v_mfma_f32_16x16x32_bf16 v[106:109], v[162:165], v[188:191], v[106:109]
	v_mfma_f32_16x16x32_bf16 v[98:101], v[154:157], v[196:199], v[98:101]
	v_mfma_f32_16x16x32_bf16 v[94:97], v[162:165], v[196:199], v[94:97]
	v_mfma_f32_16x16x32_bf16 v[74:77], v[154:157], v[204:207], v[74:77]
	v_mfma_f32_16x16x32_bf16 v[70:73], v[162:165], v[204:207], v[70:73]
	v_mfma_f32_16x16x32_bf16 v[54:57], v[154:157], v[212:215], v[54:57]
	v_mfma_f32_16x16x32_bf16 v[50:53], v[162:165], v[212:215], v[50:53]
	v_mfma_f32_16x16x32_bf16 v[66:69], v[166:169], v[182:185], v[66:69]
	v_mfma_f32_16x16x32_bf16 v[18:21], v[174:177], v[182:185], v[18:21]
	v_mfma_f32_16x16x32_bf16 v[78:81], v[166:169], v[192:195], v[78:81]
	v_mfma_f32_16x16x32_bf16 v[22:25], v[174:177], v[192:195], v[22:25]
	v_mfma_f32_16x16x32_bf16 v[62:65], v[166:169], v[200:203], v[62:65]
	v_mfma_f32_16x16x32_bf16 v[46:49], v[174:177], v[200:203], v[46:49]
	v_mfma_f32_16x16x32_bf16 v[38:41], v[166:169], v[208:211], v[38:41]
	v_mfma_f32_16x16x32_bf16 v[34:37], v[174:177], v[208:211], v[34:37]
	v_mfma_f32_16x16x32_bf16 v[66:69], v[170:173], v[188:191], v[66:69]
	v_mfma_f32_16x16x32_bf16 v[18:21], v[178:181], v[188:191], v[18:21]
	v_mfma_f32_16x16x32_bf16 v[78:81], v[170:173], v[196:199], v[78:81]
	v_mfma_f32_16x16x32_bf16 v[22:25], v[178:181], v[196:199], v[22:25]
	v_mfma_f32_16x16x32_bf16 v[62:65], v[170:173], v[204:207], v[62:65]
	v_mfma_f32_16x16x32_bf16 v[46:49], v[178:181], v[204:207], v[46:49]
	v_mfma_f32_16x16x32_bf16 v[38:41], v[170:173], v[212:215], v[38:41]
	v_mfma_f32_16x16x32_bf16 v[34:37], v[178:181], v[212:215], v[34:37]
	s_barrier
	s_setprio 0
	s_add_i32 s60, 0, 0x18000
	v_add_u32_e32 v149, s60, v147
	s_add_i32 s61, 0, 0x1c000
	ds_read_b128 v[150:153], v149
	ds_read_b128 v[154:157], v149 offset:1024
	ds_read_b128 v[158:161], v149 offset:2048
	ds_read_b128 v[162:165], v149 offset:3072
	v_add_u32_e32 v149, s61, v147
	ds_read_b128 v[166:169], v149
	ds_read_b128 v[170:173], v149 offset:1024
	ds_read_b128 v[174:177], v149 offset:2048
	ds_read_b128 v[178:181], v149 offset:3072
	s_add_u32 s30, s30, 0xb0000
	s_addc_u32 s31, s31, 0
	s_mov_b32 m0, s47
	v_lshl_add_u64 v[224:225], s[30:31], 0, v[130:131]
	ds_read_b128 v[182:185], v148 offset:32768
	ds_read_b128 v[188:191], v148 offset:33792
	ds_read_b128 v[192:195], v148 offset:34816
	ds_read_b128 v[196:199], v148 offset:35840
	ds_read_b128 v[200:203], v148 offset:36864
	ds_read_b128 v[204:207], v148 offset:37888
	ds_read_b128 v[208:211], v148 offset:38912
	ds_read_b128 v[212:215], v148 offset:39936
	global_load_lds_dwordx4 v[224:225], off
	v_lshl_add_u64 v[224:225], s[30:31], 0, v[132:133]
	s_mov_b32 m0, s48
	s_nop 0
	global_load_lds_dwordx4 v[224:225], off
	s_waitcnt vmcnt(8)
	s_waitcnt lgkmcnt(0)
	s_barrier
	s_setprio 1
	s_waitcnt lgkmcnt(0)
	v_mfma_f32_16x16x32_bf16 v[114:117], v[150:153], v[182:185], v[114:117]
	v_mfma_f32_16x16x32_bf16 v[82:85], v[158:161], v[182:185], v[82:85]
	v_mfma_f32_16x16x32_bf16 v[122:125], v[150:153], v[192:195], v[122:125]
	v_mfma_f32_16x16x32_bf16 v[86:89], v[158:161], v[192:195], v[86:89]
	v_mfma_f32_16x16x32_bf16 v[126:129], v[150:153], v[200:203], v[126:129]
	v_mfma_f32_16x16x32_bf16 v[90:93], v[158:161], v[200:203], v[90:93]
	v_mfma_f32_16x16x32_bf16 v[118:121], v[150:153], v[208:211], v[118:121]
	v_mfma_f32_16x16x32_bf16 v[102:105], v[158:161], v[208:211], v[102:105]
	v_mfma_f32_16x16x32_bf16 v[114:117], v[154:157], v[188:191], v[114:117]
	v_mfma_f32_16x16x32_bf16 v[82:85], v[162:165], v[188:191], v[82:85]
	v_mfma_f32_16x16x32_bf16 v[122:125], v[154:157], v[196:199], v[122:125]
	v_mfma_f32_16x16x32_bf16 v[86:89], v[162:165], v[196:199], v[86:89]
	v_mfma_f32_16x16x32_bf16 v[126:129], v[154:157], v[204:207], v[126:129]
	v_mfma_f32_16x16x32_bf16 v[90:93], v[162:165], v[204:207], v[90:93]
	v_mfma_f32_16x16x32_bf16 v[118:121], v[154:157], v[212:215], v[118:121]
	v_mfma_f32_16x16x32_bf16 v[102:105], v[162:165], v[212:215], v[102:105]
	v_mfma_f32_16x16x32_bf16 v[26:29], v[166:169], v[182:185], v[26:29]
	v_mfma_f32_16x16x32_bf16 v[2:5], v[174:177], v[182:185], v[2:5]
	v_mfma_f32_16x16x32_bf16 v[30:33], v[166:169], v[192:195], v[30:33]
	v_mfma_f32_16x16x32_bf16 v[6:9], v[174:177], v[192:195], v[6:9]
	v_mfma_f32_16x16x32_bf16 v[42:45], v[166:169], v[200:203], v[42:45]
	v_mfma_f32_16x16x32_bf16 v[10:13], v[174:177], v[200:203], v[10:13]
	v_mfma_f32_16x16x32_bf16 v[58:61], v[166:169], v[208:211], v[58:61]
	v_mfma_f32_16x16x32_bf16 v[14:17], v[174:177], v[208:211], v[14:17]
	v_mfma_f32_16x16x32_bf16 v[26:29], v[170:173], v[188:191], v[26:29]
	v_mfma_f32_16x16x32_bf16 v[2:5], v[178:181], v[188:191], v[2:5]
	v_mfma_f32_16x16x32_bf16 v[30:33], v[170:173], v[196:199], v[30:33]
	v_mfma_f32_16x16x32_bf16 v[6:9], v[178:181], v[196:199], v[6:9]
	v_mfma_f32_16x16x32_bf16 v[42:45], v[170:173], v[204:207], v[42:45]
	v_mfma_f32_16x16x32_bf16 v[10:13], v[178:181], v[204:207], v[10:13]
	v_mfma_f32_16x16x32_bf16 v[58:61], v[170:173], v[212:215], v[58:61]
	v_mfma_f32_16x16x32_bf16 v[14:17], v[178:181], v[212:215], v[14:17]
	s_barrier
; #define PG8_STAGE(bufoff, gbase, voff) do { _Pragma("unroll") for (int _i = 0; _i < 2; ++_i) \
;         __builtin_amdgcn_global_load_lds((const unsigned*)((const char*)(gbase) + (voff)[_i]), (PG8_LAS unsigned*)(lds + (bufoff) + ldsw + _i * 8192), 16, 0, 0); } while (0)
; #define PG8_LDA(dst, b, h) do { _Pragma("unroll") for (int m = 0; m < 4; ++m) _Pragma("unroll") for (int k = 0; k < 2; ++k) dst[m][k] = *(const PG8_LAS bf16x8*)(lds + PG8_SA(b, h) + aoff + m * 2048 + k * 1024); } while (0)
; #define PG8_MMA(ai, bj, At, Bt) do { __builtin_amdgcn_s_setprio(1); _Pragma("unroll") for (int m = 0; m < 4; ++m) _Pragma("unroll") for (int n = 0; n < 2; ++n) _Pragma("unroll") for (int k = 0; k < 2; ++k) \
;         acc[ai][bj][m][n] = __builtin_amdgcn_mfma_f32_16x16x32_bf16(Bt[n][k], At[m][k], acc[ai][bj][m][n], 0, 0, 0); __builtin_amdgcn_s_setprio(0); } while (0)
; #define PG8_WAIT_V(n) asm volatile("s_waitcnt vmcnt(" #n ")" ::: "memory")
; #define PG8_WAIT_L(n) asm volatile("s_waitcnt lgkmcnt(" #n ")" ::: "memory")
; #define PG8_BAR __builtin_amdgcn_s_barrier()
; #define PG8_SCHED __builtin_amdgcn_sched_barrier(0)
; template <class Epi, class Sched, bool ALIGN_EPI = false, bool SP2 = false>
; __device__ __forceinline__ void gemm_phase(PG8_LAS unsigned char* lds, const Gemm g, const Sched& S, const Epi& E) {
;     ...
;             PG8_LDA(At, 1, 1); PG8_STAGE(PG8_SB(1, 0), b3, voffB); PG8_STAGE(PG8_SB(1, 1), b3 + hstep, voffB); PG8_STAGE(PG8_SA(1, 0), a3, voffA);
;             PG8_WAIT_V(8); PG8_WAIT_L(0); PG8_BAR; PG8_MMA(1, 0, At, B0); PG8_MMA(1, 1, At, B1); PG8_BAR; PG8_SCHED;
;     ...
;         if (!has_next) break;
; #pragma unroll
;         for (int a = 0; a < 2; ++a)
; #pragma unroll
;             for (int b = 0; b < 2; ++b)
; #pragma unroll
;                 for (int m = 0; m < 4; ++m)
; #pragma unroll
;                     for (int n = 0; n < 2; ++n) acc[a][b][m][n] = (f32x4){0.f, 0.f, 0.f, 0.f};
	s_setprio 0
	s_add_i32 s30, s60, s41
	v_lshl_add_u64 v[216:217], v[216:217], 0, s[22:23]
	s_mov_b32 m0, s30
	ds_read_b128 v[182:185], v148 offset:49152
	ds_read_b128 v[188:191], v148 offset:50176
	ds_read_b128 v[192:195], v148 offset:51200
	ds_read_b128 v[196:199], v148 offset:52224
	ds_read_b128 v[200:203], v148 offset:53248
	ds_read_b128 v[204:207], v148 offset:54272
	ds_read_b128 v[208:211], v148 offset:55296
	ds_read_b128 v[212:215], v148 offset:56320
	global_load_lds_dwordx4 v[216:217], off
	s_add_i32 m0, s30, 0x2000
	s_add_u32 s28, s28, 0xb0080
	v_lshl_add_u64 v[216:217], v[218:219], 0, s[22:23]
	s_addc_u32 s29, s29, 0
	s_add_i32 s30, s61, s41
	global_load_lds_dwordx4 v[216:217], off
	v_lshl_add_u64 v[216:217], s[28:29], 0, v[130:131]
	s_mov_b32 m0, s30
	s_nop 0
	global_load_lds_dwordx4 v[216:217], off
	v_lshl_add_u64 v[216:217], s[28:29], 0, v[132:133]
	s_add_i32 m0, s30, 0x2000
	s_nop 0
	global_load_lds_dwordx4 v[216:217], off
	v_lshl_add_u64 v[216:217], v[220:221], 0, s[22:23]
	s_mov_b32 m0, s51
	s_nop 0
	global_load_lds_dwordx4 v[216:217], off
	v_lshl_add_u64 v[216:217], v[222:223], 0, s[22:23]
	s_mov_b32 m0, s52
	s_nop 0
	global_load_lds_dwordx4 v[216:217], off
	s_waitcnt vmcnt(8)
	s_waitcnt lgkmcnt(0)
	s_barrier
	s_setprio 1
	s_waitcnt lgkmcnt(0)
	v_mfma_f32_16x16x32_bf16 v[110:113], v[150:153], v[182:185], v[110:113]
	v_mfma_f32_16x16x32_bf16 v[106:109], v[158:161], v[182:185], v[106:109]
	v_mfma_f32_16x16x32_bf16 v[98:101], v[150:153], v[192:195], v[98:101]
	v_mfma_f32_16x16x32_bf16 v[94:97], v[158:161], v[192:195], v[94:97]
	v_mfma_f32_16x16x32_bf16 v[74:77], v[150:153], v[200:203], v[74:77]
	v_mfma_f32_16x16x32_bf16 v[70:73], v[158:161], v[200:203], v[70:73]
	v_mfma_f32_16x16x32_bf16 v[54:57], v[150:153], v[208:211], v[54:57]
	v_mfma_f32_16x16x32_bf16 v[50:53], v[158:161], v[208:211], v[50:53]
	v_mfma_f32_16x16x32_bf16 v[110:113], v[154:157], v[188:191], v[110:113]
	v_mfma_f32_16x16x32_bf16 v[106:109], v[162:165], v[188:191], v[106:109]
	v_mfma_f32_16x16x32_bf16 v[98:101], v[154:157], v[196:199], v[98:101]
	v_mfma_f32_16x16x32_bf16 v[94:97], v[162:165], v[196:199], v[94:97]
	v_mfma_f32_16x16x32_bf16 v[74:77], v[154:157], v[204:207], v[74:77]
	v_mfma_f32_16x16x32_bf16 v[70:73], v[162:165], v[204:207], v[70:73]
	v_mfma_f32_16x16x32_bf16 v[54:57], v[154:157], v[212:215], v[54:57]
	v_mfma_f32_16x16x32_bf16 v[50:53], v[162:165], v[212:215], v[50:53]
	v_mfma_f32_16x16x32_bf16 v[66:69], v[166:169], v[182:185], v[66:69]
	v_mfma_f32_16x16x32_bf16 v[18:21], v[174:177], v[182:185], v[18:21]
	v_mfma_f32_16x16x32_bf16 v[78:81], v[166:169], v[192:195], v[78:81]
	v_mfma_f32_16x16x32_bf16 v[22:25], v[174:177], v[192:195], v[22:25]
	v_mfma_f32_16x16x32_bf16 v[62:65], v[166:169], v[200:203], v[62:65]
	v_mfma_f32_16x16x32_bf16 v[46:49], v[174:177], v[200:203], v[46:49]
	v_mfma_f32_16x16x32_bf16 v[38:41], v[166:169], v[208:211], v[38:41]
	v_mfma_f32_16x16x32_bf16 v[34:37], v[174:177], v[208:211], v[34:37]
	v_mfma_f32_16x16x32_bf16 v[66:69], v[170:173], v[188:191], v[66:69]
	v_mfma_f32_16x16x32_bf16 v[18:21], v[178:181], v[188:191], v[18:21]
	v_mfma_f32_16x16x32_bf16 v[78:81], v[170:173], v[196:199], v[78:81]
	v_mfma_f32_16x16x32_bf16 v[22:25], v[178:181], v[196:199], v[22:25]
	v_mfma_f32_16x16x32_bf16 v[62:65], v[170:173], v[204:207], v[62:65]
	v_mfma_f32_16x16x32_bf16 v[46:49], v[178:181], v[204:207], v[46:49]
	v_mfma_f32_16x16x32_bf16 v[38:41], v[170:173], v[212:215], v[38:41]
	v_mfma_f32_16x16x32_bf16 v[34:37], v[178:181], v[212:215], v[34:37]
	s_barrier
	s_setprio 0
	s_add_i32 s59, s59, 2
	s_add_u32 s26, s26, 0x100
	s_addc_u32 s27, s27, 0
	s_cmp_gt_u32 s59, 41
	s_cbranch_scc0 .LBB0_1940
	s_add_u32 s0, s0, 0xffffff00
	s_addc_u32 s1, s1, -1
	s_and_b64 vcc, exec, s[6:7]
	s_cbranch_vccnz .LBB0_1943
	v_mov_b32_e32 v34, 0
	s_mov_b32 s18, s56
	s_mov_b32 s35, s57
	s_mov_b64 s[20:21], s[24:25]
	s_mov_b32 s50, s58
	v_mov_b32_e32 v35, v34
	v_mov_b32_e32 v36, v34
	v_mov_b32_e32 v37, v34
	v_mov_b32_e32 v38, v34
	v_mov_b32_e32 v39, v34
	v_mov_b32_e32 v40, v34
	v_mov_b32_e32 v41, v34
	v_mov_b32_e32 v46, v34
	v_mov_b32_e32 v47, v34
	v_mov_b32_e32 v48, v34
	v_mov_b32_e32 v49, v34
	v_mov_b32_e32 v62, v34
	v_mov_b32_e32 v63, v34
	v_mov_b32_e32 v64, v34
	v_mov_b32_e32 v65, v34
	v_mov_b32_e32 v22, v34
	v_mov_b32_e32 v23, v34
	v_mov_b32_e32 v24, v34
	v_mov_b32_e32 v25, v34
	v_mov_b32_e32 v78, v34
	v_mov_b32_e32 v79, v34
	v_mov_b32_e32 v80, v34
	v_mov_b32_e32 v81, v34
	v_mov_b32_e32 v18, v34
	v_mov_b32_e32 v19, v34
	v_mov_b32_e32 v20, v34
	v_mov_b32_e32 v21, v34
	v_mov_b32_e32 v66, v34
	v_mov_b32_e32 v67, v34
	v_mov_b32_e32 v68, v34
	v_mov_b32_e32 v69, v34
	v_mov_b32_e32 v50, v34
	v_mov_b32_e32 v51, v34
	v_mov_b32_e32 v52, v34
	v_mov_b32_e32 v53, v34
	v_mov_b32_e32 v54, v34
	v_mov_b32_e32 v55, v34
	v_mov_b32_e32 v56, v34
	v_mov_b32_e32 v57, v34
	v_mov_b32_e32 v70, v34
	v_mov_b32_e32 v71, v34
	v_mov_b32_e32 v72, v34
	v_mov_b32_e32 v73, v34
	v_mov_b32_e32 v74, v34
	v_mov_b32_e32 v75, v34
	v_mov_b32_e32 v76, v34
	v_mov_b32_e32 v77, v34
	v_mov_b32_e32 v94, v34
	v_mov_b32_e32 v95, v34
	v_mov_b32_e32 v96, v34
	v_mov_b32_e32 v97, v34
	v_mov_b32_e32 v98, v34
	v_mov_b32_e32 v99, v34
	v_mov_b32_e32 v100, v34
	v_mov_b32_e32 v101, v34
	v_mov_b32_e32 v106, v34
	v_mov_b32_e32 v107, v34
	v_mov_b32_e32 v108, v34
	v_mov_b32_e32 v109, v34
	v_mov_b32_e32 v110, v34
	v_mov_b32_e32 v111, v34
	v_mov_b32_e32 v112, v34
	v_mov_b32_e32 v113, v34
	v_mov_b32_e32 v14, v34
	v_mov_b32_e32 v15, v34
	v_mov_b32_e32 v16, v34
	v_mov_b32_e32 v17, v34
	v_mov_b32_e32 v58, v34
	v_mov_b32_e32 v59, v34
	v_mov_b32_e32 v60, v34
	v_mov_b32_e32 v61, v34
	v_mov_b32_e32 v10, v34
	v_mov_b32_e32 v11, v34
	v_mov_b32_e32 v12, v34
	v_mov_b32_e32 v13, v34
	v_mov_b32_e32 v42, v34
	v_mov_b32_e32 v43, v34
	v_mov_b32_e32 v44, v34
	v_mov_b32_e32 v45, v34
	v_mov_b32_e32 v6, v34
	v_mov_b32_e32 v7, v34
	v_mov_b32_e32 v8, v34
	v_mov_b32_e32 v9, v34
	v_mov_b32_e32 v30, v34
	v_mov_b32_e32 v31, v34
	v_mov_b32_e32 v32, v34
	v_mov_b32_e32 v33, v34
	v_mov_b32_e32 v2, v34
	v_mov_b32_e32 v3, v34
	v_mov_b32_e32 v4, v34
	v_mov_b32_e32 v5, v34
	v_mov_b32_e32 v26, v34
	v_mov_b32_e32 v27, v34
	v_mov_b32_e32 v28, v34
	v_mov_b32_e32 v29, v34
	v_mov_b32_e32 v102, v34
	v_mov_b32_e32 v103, v34
	v_mov_b32_e32 v104, v34
	v_mov_b32_e32 v105, v34
	v_mov_b32_e32 v118, v34
	v_mov_b32_e32 v119, v34
	v_mov_b32_e32 v120, v34
	v_mov_b32_e32 v121, v34
	v_mov_b32_e32 v90, v34
	v_mov_b32_e32 v91, v34
	v_mov_b32_e32 v92, v34
	v_mov_b32_e32 v93, v34
	v_mov_b32_e32 v126, v34
	v_mov_b32_e32 v127, v34
	v_mov_b32_e32 v128, v34
	v_mov_b32_e32 v129, v34
	v_mov_b32_e32 v86, v34
	v_mov_b32_e32 v87, v34
	v_mov_b32_e32 v88, v34
	v_mov_b32_e32 v89, v34
	v_mov_b32_e32 v122, v34
	v_mov_b32_e32 v123, v34
	v_mov_b32_e32 v124, v34
	v_mov_b32_e32 v125, v34
	v_mov_b32_e32 v82, v34
	v_mov_b32_e32 v83, v34
	v_mov_b32_e32 v84, v34
	v_mov_b32_e32 v85, v34
	v_mov_b32_e32 v114, v34
	v_mov_b32_e32 v115, v34
	v_mov_b32_e32 v116, v34
	v_mov_b32_e32 v117, v34
	s_andn2_b64 vcc, exec, s[4:5]
	s_cbranch_vccnz .LBB0_1944
	s_branch .LBB0_1945
